# speedup vs baseline: 1.0254x; 1.0108x over previous
; #define MFMA(a, b, c) __builtin_amdgcn_mfma_f32_16x16x32_bf16((a), (b), (c), 0, 0, 0)
; template <int AMODE>
; __device__ __forceinline__ void gemm_kloop(f32x4 (&acc)[4][4], const u16* __restrict__ A, int lda,
;                                            const u16* __restrict__ Bt, int ldb, int K, char* smem,
;                                            const float* __restrict__ ssq_rows) {
;     ...
;     for (int kt = 0; kt < nk; ++kt) {
;         const int buf = kt & 1;
;         if (kt + 1 < nk) GLOAD(kt + 1, buf ^ 1);
;         const char* ab = As + buf * 16384 + (wr * 64 + r) * 128;
;         const char* bb = Bs + buf * 16384 + (wc * 64 + r) * 128;
;         bf16x8 af[2][4], bfr[2][4];
; #pragma unroll
;         for (int ks = 0; ks < 2; ++ks) {
;             const int co = ((ks * 4 + g4) ^ (r & 7)) << 4;
; #pragma unroll
;             for (int i = 0; i < 4; ++i) af[ks][i] = ld_frag(ab + i * 2048 + co);
; #pragma unroll
;             for (int j = 0; j < 4; ++j) bfr[ks][j] = ld_frag(bb + j * 2048 + co);
;         }
;         __builtin_amdgcn_sched_barrier(0);
;         __builtin_amdgcn_s_setprio(1);
; #pragma unroll
;         for (int ks = 0; ks < 2; ++ks)
; #pragma unroll
;             for (int i = 0; i < 4; ++i)
; #pragma unroll
;                 for (int j = 0; j < 4; ++j) acc[i][j] = MFMA(bfr[ks][j], af[ks][i], acc[i][j]);
;         __builtin_amdgcn_s_setprio(0);
;         __builtin_amdgcn_sched_barrier(0);
;         if (kt + 1 < nk) LSTORE(buf ^ 1);
;         asm volatile("s_waitcnt vmcnt(0)" ::: "memory");
;         __syncthreads();
;     }
.LBB0_152:
	s_setprio 1
	v_add_u32_e32 v0, s2, v73
	v_or_b32_e32 v77, s2, v72
	v_add_u32_e32 v90, v0, v76
	v_add_u32_e32 v102, v77, v76
	v_add_u32_e32 v0, v0, v74
	ds_read_b128 v[78:81], v90
	ds_read_b128 v[82:85], v90 offset:2048
	ds_read_b128 v[86:89], v90 offset:4096
	ds_read_b128 v[90:93], v90 offset:6144
	ds_read_b128 v[94:97], v102 offset:32768
	ds_read_b128 v[98:101], v102 offset:34816
	ds_read_b128 v[110:113], v102 offset:36864
	ds_read_b128 v[114:117], v102 offset:38912
	ds_read_b128 v[118:121], v0
	ds_read_b128 v[122:125], v0 offset:2048
	ds_read_b128 v[126:129], v0 offset:4096
	ds_read_b128 v[130:133], v0 offset:6144
	v_add_u32_e32 v0, v77, v74
	ds_read_b128 v[134:137], v0 offset:32768
	ds_read_b128 v[142:145], v0 offset:34816
	ds_read_b128 v[146:149], v0 offset:36864
	ds_read_b128 v[150:153], v0 offset:38912
	s_xor_b32 s4, s2, 0x4000
	s_add_u32 s4, s4, s5
	s_add_u32 s100, s100, 0x80
	s_addc_u32 s101, s101, 0
	s_add_u32 s98, s98, 0x80
	s_addc_u32 s99, s99, 0
	s_add_u32 m0, s4, 0x8000
	s_nop 0
	global_load_lds_dwordx4 v216, s[100:101]
	s_add_u32 m0, s4, 0x0
	s_nop 0
	global_load_lds_dwordx4 v216, s[98:99]
	s_add_u32 m0, s4, 0x9000
	s_nop 0
	global_load_lds_dwordx4 v217, s[100:101]
	s_add_u32 m0, s4, 0x1000
	s_nop 0
	global_load_lds_dwordx4 v217, s[98:99]
	s_add_u32 m0, s4, 0xa000
	s_nop 0
	global_load_lds_dwordx4 v218, s[100:101]
	s_add_u32 m0, s4, 0x2000
	s_nop 0
	global_load_lds_dwordx4 v218, s[98:99]
	s_add_u32 m0, s4, 0xb000
	s_nop 0
	global_load_lds_dwordx4 v219, s[100:101]
	s_add_u32 m0, s4, 0x3000
	s_nop 0
	global_load_lds_dwordx4 v219, s[98:99]
	s_setprio 0
	s_waitcnt lgkmcnt(11)
	v_mfma_f32_16x16x32_bf16 v[62:65], v[94:97], v[78:81], v[62:65]
	s_waitcnt lgkmcnt(10)
	v_mfma_f32_16x16x32_bf16 v[58:61], v[98:101], v[78:81], v[58:61]
	s_waitcnt lgkmcnt(9)
	v_mfma_f32_16x16x32_bf16 v[54:57], v[110:113], v[78:81], v[54:57]
	s_waitcnt lgkmcnt(8)
	v_mfma_f32_16x16x32_bf16 v[50:53], v[114:117], v[78:81], v[50:53]
	v_mfma_f32_16x16x32_bf16 v[46:49], v[94:97], v[82:85], v[46:49]
	v_mfma_f32_16x16x32_bf16 v[42:45], v[98:101], v[82:85], v[42:45]
	v_mfma_f32_16x16x32_bf16 v[38:41], v[110:113], v[82:85], v[38:41]
	v_mfma_f32_16x16x32_bf16 v[34:37], v[114:117], v[82:85], v[34:37]
	v_mfma_f32_16x16x32_bf16 v[30:33], v[94:97], v[86:89], v[30:33]
	v_mfma_f32_16x16x32_bf16 v[26:29], v[98:101], v[86:89], v[26:29]
	v_mfma_f32_16x16x32_bf16 v[22:25], v[110:113], v[86:89], v[22:25]
	v_mfma_f32_16x16x32_bf16 v[18:21], v[114:117], v[86:89], v[18:21]
	v_mfma_f32_16x16x32_bf16 v[14:17], v[94:97], v[90:93], v[14:17]
	v_mfma_f32_16x16x32_bf16 v[10:13], v[98:101], v[90:93], v[10:13]
	v_mfma_f32_16x16x32_bf16 v[6:9], v[110:113], v[90:93], v[6:9]
	v_mfma_f32_16x16x32_bf16 v[2:5], v[114:117], v[90:93], v[2:5]
	s_waitcnt lgkmcnt(3)
	v_mfma_f32_16x16x32_bf16 v[62:65], v[134:137], v[118:121], v[62:65]
	s_waitcnt lgkmcnt(2)
	v_mfma_f32_16x16x32_bf16 v[58:61], v[142:145], v[118:121], v[58:61]
	s_waitcnt lgkmcnt(1)
	v_mfma_f32_16x16x32_bf16 v[54:57], v[146:149], v[118:121], v[54:57]
	s_waitcnt lgkmcnt(0)
	v_mfma_f32_16x16x32_bf16 v[50:53], v[150:153], v[118:121], v[50:53]
	v_mfma_f32_16x16x32_bf16 v[46:49], v[134:137], v[122:125], v[46:49]
	v_mfma_f32_16x16x32_bf16 v[42:45], v[142:145], v[122:125], v[42:45]
	v_mfma_f32_16x16x32_bf16 v[38:41], v[146:149], v[122:125], v[38:41]
	v_mfma_f32_16x16x32_bf16 v[34:37], v[150:153], v[122:125], v[34:37]
	v_mfma_f32_16x16x32_bf16 v[30:33], v[134:137], v[126:129], v[30:33]
	v_mfma_f32_16x16x32_bf16 v[26:29], v[142:145], v[126:129], v[26:29]
	v_mfma_f32_16x16x32_bf16 v[22:25], v[146:149], v[126:129], v[22:25]
	v_mfma_f32_16x16x32_bf16 v[18:21], v[150:153], v[126:129], v[18:21]
	v_mfma_f32_16x16x32_bf16 v[14:17], v[134:137], v[130:133], v[14:17]
	v_mfma_f32_16x16x32_bf16 v[10:13], v[142:145], v[130:133], v[10:13]
	v_mfma_f32_16x16x32_bf16 v[6:9], v[146:149], v[130:133], v[6:9]
	v_mfma_f32_16x16x32_bf16 v[2:5], v[150:153], v[130:133], v[2:5]
	s_nop 0
	s_xor_b32 s2, s2, 0x4000
	s_add_i32 s0, s0, 1
	s_cmp_eq_u32 s0, 15
	s_waitcnt vmcnt(0)
	s_barrier
	s_cbranch_scc0 .LBB0_152
	v_add_u32_e32 v0, v73, v76
	ds_read_b128 v[66:69], v0 offset:16384
	ds_read_b128 v[78:81], v0 offset:18432
	ds_read_b128 v[82:85], v0 offset:20480
	ds_read_b128 v[86:89], v0 offset:22528
	v_add_u32_e32 v0, v72, v76
	ds_read_b128 v[90:93], v0 offset:49152
	ds_read_b128 v[98:101], v0 offset:51200
	ds_read_b128 v[110:113], v0 offset:53248
	ds_read_b128 v[114:117], v0 offset:55296
	v_add_u32_e32 v0, v73, v74
	ds_read_b128 v[118:121], v0 offset:16384
	ds_read_b128 v[122:125], v0 offset:18432
	ds_read_b128 v[126:129], v0 offset:20480
	ds_read_b128 v[130:133], v0 offset:22528
	v_add_u32_e32 v0, v72, v74
	ds_read_b128 v[134:137], v0 offset:49152
	ds_read_b128 v[142:145], v0 offset:51200
	ds_read_b128 v[146:149], v0 offset:53248
	ds_read_b128 v[150:153], v0 offset:55296
	v_ashrrev_i32_e32 v96, 7, v70
	v_and_b32_e32 v72, 15, v70
	v_bfe_u32 v74, v70, 6, 1
	v_bfe_u32 v73, v70, 4, 2
	s_setprio 1
	s_waitcnt lgkmcnt(11)
	v_mfma_f32_16x16x32_bf16 v[62:65], v[90:93], v[66:69], v[62:65]
	s_waitcnt lgkmcnt(10)
	v_mfma_f32_16x16x32_bf16 v[58:61], v[98:101], v[66:69], v[58:61]
	s_waitcnt lgkmcnt(9)
	v_mfma_f32_16x16x32_bf16 v[54:57], v[110:113], v[66:69], v[54:57]
	s_waitcnt lgkmcnt(8)
; __device__ __forceinline__ float softplusf(float x) { return fmaxf(x, 0.f) + log1pf(__expf(-fabsf(x))); }
; #define MFMA(a, b, c) __builtin_amdgcn_mfma_f32_16x16x32_bf16((a), (b), (c), 0, 0, 0)
; template <int AMODE>
; __device__ __forceinline__ void gemm_kloop(f32x4 (&acc)[4][4], const u16* __restrict__ A, int lda,
;                                            const u16* __restrict__ Bt, int ldb, int K, char* smem,
;                                            const float* __restrict__ ssq_rows) {
;     ...
; #pragma unroll
;         for (int ks = 0; ks < 2; ++ks)
; #pragma unroll
;             for (int i = 0; i < 4; ++i)
; #pragma unroll
;                 for (int j = 0; j < 4; ++j) acc[i][j] = MFMA(bfr[ks][j], af[ks][i], acc[i][j]);
;         __builtin_amdgcn_s_setprio(0);
;         __builtin_amdgcn_sched_barrier(0);
; __device__ void phaseA_tile(const Params& p, int l, int mt, int nt, char* smem) {
;     ...
;     } else {
;         float* lf_s = (float*)smem;
;         if (wc == 0) {
; #pragma unroll
;             for (int i = 0; i < 4; ++i) {
;                 const int rl = wr * 64 + i * 16 + r;
;                 const int row = m0 + rl;
; #pragma unroll
;                 for (int j = 0; j < 2; ++j) {
;                     const int c = j * 16 + g4 * 4;
;                     const float4 db = *(const float4*)(p.dt_bias + l * 32 + c);
;                     const f32x4 v = acc[i][j];
;                     *(float4*)(p.dtb + (size_t)row * 32 + c) =
;                         make_float4(softplusf(v[0] + db.x), softplusf(v[1] + db.y), softplusf(v[2] + db.z), softplusf(v[3] + db.w));
;                 }
	v_mfma_f32_16x16x32_bf16 v[50:53], v[114:117], v[66:69], v[50:53]
	v_mfma_f32_16x16x32_bf16 v[46:49], v[90:93], v[78:81], v[46:49]
	v_mfma_f32_16x16x32_bf16 v[42:45], v[98:101], v[78:81], v[42:45]
	v_mfma_f32_16x16x32_bf16 v[38:41], v[110:113], v[78:81], v[38:41]
	v_mfma_f32_16x16x32_bf16 v[34:37], v[114:117], v[78:81], v[34:37]
	v_mfma_f32_16x16x32_bf16 v[30:33], v[90:93], v[82:85], v[30:33]
	v_mfma_f32_16x16x32_bf16 v[26:29], v[98:101], v[82:85], v[26:29]
	v_mfma_f32_16x16x32_bf16 v[22:25], v[110:113], v[82:85], v[22:25]
	v_mfma_f32_16x16x32_bf16 v[18:21], v[114:117], v[82:85], v[18:21]
	v_mfma_f32_16x16x32_bf16 v[14:17], v[90:93], v[86:89], v[14:17]
	v_mfma_f32_16x16x32_bf16 v[10:13], v[98:101], v[86:89], v[10:13]
	v_mfma_f32_16x16x32_bf16 v[6:9], v[110:113], v[86:89], v[6:9]
	v_mfma_f32_16x16x32_bf16 v[2:5], v[114:117], v[86:89], v[2:5]
	s_waitcnt lgkmcnt(3)
	v_mfma_f32_16x16x32_bf16 v[62:65], v[134:137], v[118:121], v[62:65]
	s_waitcnt lgkmcnt(2)
	v_mfma_f32_16x16x32_bf16 v[58:61], v[142:145], v[118:121], v[58:61]
	s_waitcnt lgkmcnt(1)
	v_mfma_f32_16x16x32_bf16 v[54:57], v[146:149], v[118:121], v[54:57]
	s_waitcnt lgkmcnt(0)
	v_mfma_f32_16x16x32_bf16 v[50:53], v[150:153], v[118:121], v[50:53]
	v_mfma_f32_16x16x32_bf16 v[46:49], v[134:137], v[122:125], v[46:49]
	v_mfma_f32_16x16x32_bf16 v[42:45], v[142:145], v[122:125], v[42:45]
	v_mfma_f32_16x16x32_bf16 v[38:41], v[146:149], v[122:125], v[38:41]
	v_mfma_f32_16x16x32_bf16 v[34:37], v[150:153], v[122:125], v[34:37]
	v_mfma_f32_16x16x32_bf16 v[30:33], v[134:137], v[126:129], v[30:33]
	v_mfma_f32_16x16x32_bf16 v[26:29], v[142:145], v[126:129], v[26:29]
	v_mfma_f32_16x16x32_bf16 v[22:25], v[146:149], v[126:129], v[22:25]
	v_mfma_f32_16x16x32_bf16 v[18:21], v[150:153], v[126:129], v[18:21]
	v_mfma_f32_16x16x32_bf16 v[14:17], v[134:137], v[130:133], v[14:17]
	v_mfma_f32_16x16x32_bf16 v[10:13], v[142:145], v[130:133], v[10:13]
	v_mfma_f32_16x16x32_bf16 v[6:9], v[146:149], v[130:133], v[6:9]
	v_mfma_f32_16x16x32_bf16 v[2:5], v[150:153], v[130:133], v[2:5]
	s_setprio 0
	s_waitcnt vmcnt(0)
	s_cmpk_eq_i32 s52, 0x100
	s_cselect_b64 s[60:61], -1, 0
	s_cmpk_lg_i32 s52, 0x100
	s_cselect_b64 s[24:25], -1, 0
	s_cmpk_gt_i32 s53, 0x5f
	s_mov_b64 s[0:1], -1
	s_barrier
	s_cbranch_scc0 .LBB0_182
	v_cmp_eq_u32_e32 vcc, 0, v74
	s_and_saveexec_b64 s[4:5], vcc
	s_cbranch_execz .LBB0_156
	v_lshlrev_b32_e32 v0, 4, v73
	global_load_dwordx4 v[66:69], v0, s[74:75]
	s_mov_b32 s2, 0xbfb8aa3b
	s_mov_b32 s26, 0x3f2aaaab
	s_mov_b32 s0, 0x3ecc95a3
	s_mov_b32 s28, 0x3e9b6dac
	s_mov_b32 s30, 0x3f2aaada
	v_lshl_or_b32 v71, v96, 6, v72
	v_add_u32_e32 v76, s54, v71
	v_ashrrev_i32_e32 v77, 31, v76
	v_readlane_b32 s8, v213, 4
	v_lshlrev_b64 v[80:81], 7, v[76:77]
	v_readlane_b32 s10, v213, 6
	v_readlane_b32 s11, v213, 7
	v_readlane_b32 s12, v213, 8
	v_readlane_b32 s13, v213, 9
	s_mov_b32 s12, 0x3f317218
	v_readlane_b32 s14, v213, 10
	v_readlane_b32 s15, v213, 11
	s_mov_b32 s14, 0xb102e308
	s_mov_b32 s8, 0x7f800000
	v_readlane_b32 s9, v213, 5
	s_mov_b32 s9, 0x33800000
	v_readlane_b32 s16, v213, 12
	v_readlane_b32 s17, v213, 13
	v_readlane_b32 s18, v213, 14
	v_readlane_b32 s19, v213, 15
	v_readlane_b32 s20, v213, 16
	v_readlane_b32 s21, v213, 17
	v_readlane_b32 s22, v213, 18
	v_readlane_b32 s23, v213, 19
	s_waitcnt vmcnt(0)
	v_add_f32_e32 v66, v62, v66
	v_max_f32_e32 v78, 0, v66
	v_mul_f32_e64 v66, |v66|, s2
	v_exp_f32_e32 v97, v66
	v_add_f32_e32 v67, v63, v67
	v_add_f32_e32 v68, v64, v68
	v_add_f32_e32 v69, v65, v69
	v_add_f32_e32 v66, 1.0, v97
	v_add_f32_e32 v79, -1.0, v66
	v_sub_f32_e32 v82, v79, v66
	v_add_f32_e32 v82, 1.0, v82
	v_sub_f32_e32 v79, v97, v79
	v_add_f32_e32 v79, v79, v82
	v_frexp_mant_f32_e32 v82, v66
	v_cmp_gt_f32_e32 vcc, s26, v82
	v_cvt_f64_f32_e32 v[82:83], v66
	v_frexp_exp_i32_f64_e32 v82, v[82:83]
	v_subbrev_co_u32_e32 v88, vcc, 0, v82, vcc
	v_sub_u32_e32 v82, 0, v88
	v_ldexp_f32 v66, v66, v82
	v_ldexp_f32 v82, v79, v82
	v_max_f32_e32 v79, 0, v67
	v_mul_f32_e64 v67, |v67|, s2
	v_exp_f32_e32 v98, v67
	s_nop 0
	v_add_f32_e32 v67, 1.0, v98
	v_add_f32_e32 v83, -1.0, v67
	v_sub_f32_e32 v84, v83, v67
	v_add_f32_e32 v84, 1.0, v84
	v_sub_f32_e32 v83, v98, v83
	v_add_f32_e32 v83, v83, v84
	v_frexp_mant_f32_e32 v84, v67
	v_cmp_gt_f32_e32 vcc, s26, v84
	v_cvt_f64_f32_e32 v[84:85], v67
	v_frexp_exp_i32_f64_e32 v84, v[84:85]
	v_subbrev_co_u32_e32 v99, vcc, 0, v84, vcc
	v_sub_u32_e32 v84, 0, v99
	v_ldexp_f32 v67, v67, v84
	v_ldexp_f32 v83, v83, v84
	v_pk_add_f32 v[84:85], v[66:67], 1.0 op_sel_hi:[1,0]
	v_pk_add_f32 v[94:95], v[66:67], -1.0 op_sel_hi:[1,0]
	v_pk_add_f32 v[86:87], v[84:85], -1.0 op_sel_hi:[1,0]
	v_pk_add_f32 v[100:101], v[94:95], 1.0 op_sel_hi:[1,0]
	v_pk_add_f32 v[86:87], v[66:67], v[86:87] neg_lo:[0,1] neg_hi:[0,1]
	v_pk_add_f32 v[66:67], v[66:67], v[100:101] neg_lo:[0,1] neg_hi:[0,1]
	v_pk_add_f32 v[86:87], v[82:83], v[86:87]
	v_pk_add_f32 v[66:67], v[82:83], v[66:67]
	v_pk_add_f32 v[90:91], v[84:85], v[86:87]
	v_pk_add_f32 v[82:83], v[94:95], v[66:67]
	v_rcp_f32_e32 v92, v90
	v_rcp_f32_e32 v93, v91
	v_pk_add_f32 v[84:85], v[90:91], v[84:85] neg_lo:[0,1] neg_hi:[0,1]
	v_pk_add_f32 v[94:95], v[82:83], v[94:95] neg_lo:[0,1] neg_hi:[0,1]
	v_pk_add_f32 v[84:85], v[86:87], v[84:85] neg_lo:[0,1] neg_hi:[0,1]
	v_pk_mul_f32 v[86:87], v[82:83], v[92:93]
	v_pk_add_f32 v[66:67], v[66:67], v[94:95] neg_lo:[0,1] neg_hi:[0,1]
	v_pk_mul_f32 v[94:95], v[90:91], v[86:87]
	s_nop 0
	v_pk_fma_f32 v[100:101], v[86:87], v[90:91], v[94:95] neg_lo:[0,0,1] neg_hi:[0,0,1]
	s_nop 0
	v_pk_fma_f32 v[100:101], v[86:87], v[84:85], v[100:101]
	s_nop 0
	v_pk_add_f32 v[102:103], v[94:95], v[100:101]
	s_nop 0
; __device__ __forceinline__ float softplusf(float x) { return fmaxf(x, 0.f) + log1pf(__expf(-fabsf(x))); }
; __device__ void phaseA_tile(const Params& p, int l, int mt, int nt, char* smem) {
;     ...
;         if (wc == 0) {
; #pragma unroll
;             for (int i = 0; i < 4; ++i) {
;                 const int rl = wr * 64 + i * 16 + r;
;                 const int row = m0 + rl;
; #pragma unroll
;                 for (int j = 0; j < 2; ++j) {
;                     const int c = j * 16 + g4 * 4;
;                     const float4 db = *(const float4*)(p.dt_bias + l * 32 + c);
;                     const f32x4 v = acc[i][j];
;                     *(float4*)(p.dtb + (size_t)row * 32 + c) =
;                         make_float4(softplusf(v[0] + db.x), softplusf(v[1] + db.y), softplusf(v[2] + db.z), softplusf(v[3] + db.w));
;                 }
	v_pk_add_f32 v[110:111], v[82:83], v[102:103] neg_lo:[0,1] neg_hi:[0,1]
	v_pk_add_f32 v[94:95], v[102:103], v[94:95] neg_lo:[0,1] neg_hi:[0,1]
	v_pk_add_f32 v[82:83], v[82:83], v[110:111] neg_lo:[0,1] neg_hi:[0,1]
	s_nop 0
	v_pk_add_f32 v[82:83], v[82:83], v[102:103] neg_lo:[0,1] neg_hi:[0,1]
	s_nop 0
	v_pk_add_f32 v[66:67], v[66:67], v[82:83]
	v_pk_add_f32 v[82:83], v[94:95], v[100:101] neg_lo:[0,1] neg_hi:[0,1]
	s_nop 0
	v_pk_add_f32 v[66:67], v[82:83], v[66:67]
	s_nop 0
	v_pk_add_f32 v[82:83], v[110:111], v[66:67]
	s_nop 0
	v_pk_mul_f32 v[94:95], v[92:93], v[82:83]
	s_nop 0
	v_pk_mul_f32 v[100:101], v[90:91], v[94:95]
	s_nop 0
	v_pk_fma_f32 v[90:91], v[94:95], v[90:91], v[100:101] neg_lo:[0,0,1] neg_hi:[0,0,1]
	s_nop 0
	v_pk_fma_f32 v[84:85], v[94:95], v[84:85], v[90:91]
	v_pk_add_f32 v[90:91], v[110:111], v[82:83] neg_lo:[0,1] neg_hi:[0,1]
	s_nop 0
	v_pk_add_f32 v[66:67], v[66:67], v[90:91]
	v_pk_add_f32 v[90:91], v[100:101], v[84:85]
	s_nop 0
	v_pk_add_f32 v[102:103], v[82:83], v[90:91] neg_lo:[0,1] neg_hi:[0,1]
	v_pk_add_f32 v[100:101], v[90:91], v[100:101] neg_lo:[0,1] neg_hi:[0,1]
	v_pk_add_f32 v[82:83], v[82:83], v[102:103] neg_lo:[0,1] neg_hi:[0,1]
	s_nop 0
	v_pk_add_f32 v[82:83], v[82:83], v[90:91] neg_lo:[0,1] neg_hi:[0,1]
	s_nop 0
	v_pk_add_f32 v[66:67], v[66:67], v[82:83]
	v_pk_add_f32 v[82:83], v[100:101], v[84:85] neg_lo:[0,1] neg_hi:[0,1]
	s_nop 0
	v_pk_add_f32 v[66:67], v[82:83], v[66:67]
	v_pk_add_f32 v[82:83], v[86:87], v[94:95]
	v_pk_add_f32 v[66:67], v[102:103], v[66:67]
	v_pk_add_f32 v[84:85], v[82:83], v[86:87] neg_lo:[0,1] neg_hi:[0,1]
	v_pk_mul_f32 v[66:67], v[92:93], v[66:67]
	v_pk_add_f32 v[84:85], v[94:95], v[84:85] neg_lo:[0,1] neg_hi:[0,1]
	s_nop 0
	v_pk_add_f32 v[66:67], v[84:85], v[66:67]
	s_nop 0
	v_pk_add_f32 v[86:87], v[82:83], v[66:67]
	s_nop 0
	v_pk_add_f32 v[82:83], v[86:87], v[82:83] neg_lo:[0,1] neg_hi:[0,1]
	v_pk_mul_f32 v[92:93], v[86:87], v[86:87]
	v_pk_add_f32 v[82:83], v[66:67], v[82:83] neg_lo:[0,1] neg_hi:[0,1]
	v_mov_b64_e32 v[66:67], s[0:1]
	v_pk_fma_f32 v[90:91], v[92:93], s[28:29], v[66:67] op_sel_hi:[1,0,0]
	v_ldexp_f32 v84, v86, 1
	v_pk_fma_f32 v[90:91], v[92:93], v[90:91], s[30:31] op_sel_hi:[1,1,0]
	v_pk_mul_f32 v[92:93], v[86:87], v[92:93]
	v_max_f32_e32 v86, 0, v68
	v_mul_f32_e64 v68, |v68|, s2
	v_exp_f32_e32 v100, v68
	v_ldexp_f32 v89, v83, 1
	v_ldexp_f32 v85, v87, 1
	v_pk_mul_f32 v[90:91], v[92:93], v[90:91]
	v_add_f32_e32 v68, 1.0, v100
	v_add_f32_e32 v83, -1.0, v68
	v_sub_f32_e32 v87, v83, v68
	v_add_f32_e32 v87, 1.0, v87
	v_sub_f32_e32 v83, v100, v83
	v_add_f32_e32 v83, v83, v87
	v_frexp_mant_f32_e32 v87, v68
	v_cvt_f64_f32_e32 v[94:95], v68
	v_cmp_gt_f32_e32 vcc, s26, v87
	v_frexp_exp_i32_f64_e32 v87, v[94:95]
	v_pk_add_f32 v[92:93], v[84:85], v[90:91]
	v_subbrev_co_u32_e32 v102, vcc, 0, v87, vcc
	v_sub_u32_e32 v87, 0, v102
	v_ldexp_f32 v94, v68, v87
	v_ldexp_f32 v68, v83, v87
	v_max_f32_e32 v87, 0, v69
	v_mul_f32_e64 v69, |v69|, s2
	v_exp_f32_e32 v101, v69
	v_pk_add_f32 v[84:85], v[92:93], v[84:85] neg_lo:[0,1] neg_hi:[0,1]
	v_ldexp_f32 v82, v82, 1
	v_pk_add_f32 v[84:85], v[90:91], v[84:85] neg_lo:[0,1] neg_hi:[0,1]
	v_add_f32_e32 v69, 1.0, v101
	v_add_f32_e32 v83, -1.0, v69
	v_sub_f32_e32 v95, v83, v69
	v_add_f32_e32 v95, 1.0, v95
	v_sub_f32_e32 v83, v101, v83
	v_add_f32_e32 v83, v83, v95
	v_frexp_mant_f32_e32 v95, v69
	v_cvt_f64_f32_e32 v[110:111], v69
	v_cmp_gt_f32_e32 vcc, s26, v95
	v_frexp_exp_i32_f64_e32 v95, v[110:111]
	v_mov_b32_e32 v91, v85
	v_subbrev_co_u32_e32 v132, vcc, 0, v95, vcc
	v_sub_u32_e32 v103, 0, v132
	v_ldexp_f32 v95, v69, v103
	v_pk_add_f32 v[110:111], v[94:95], 1.0 op_sel_hi:[1,0]
	v_ldexp_f32 v69, v83, v103
	v_pk_add_f32 v[112:113], v[110:111], -1.0 op_sel_hi:[1,0]
	v_pk_add_f32 v[118:119], v[94:95], -1.0 op_sel_hi:[1,0]
	v_pk_add_f32 v[112:113], v[94:95], v[112:113] neg_lo:[0,1] neg_hi:[0,1]
	v_pk_add_f32 v[120:121], v[118:119], 1.0 op_sel_hi:[1,0]
	v_pk_add_f32 v[112:113], v[68:69], v[112:113]
	v_pk_add_f32 v[94:95], v[94:95], v[120:121] neg_lo:[0,1] neg_hi:[0,1]
	v_pk_add_f32 v[114:115], v[110:111], v[112:113]
	v_pk_add_f32 v[68:69], v[68:69], v[94:95]
	v_rcp_f32_e32 v116, v114
	v_rcp_f32_e32 v117, v115
	v_pk_add_f32 v[94:95], v[118:119], v[68:69]
	v_pk_add_f32 v[110:111], v[114:115], v[110:111] neg_lo:[0,1] neg_hi:[0,1]
	v_pk_add_f32 v[118:119], v[94:95], v[118:119] neg_lo:[0,1] neg_hi:[0,1]
	v_pk_add_f32 v[110:111], v[112:113], v[110:111] neg_lo:[0,1] neg_hi:[0,1]
	v_pk_mul_f32 v[112:113], v[94:95], v[116:117]
	v_pk_add_f32 v[68:69], v[68:69], v[118:119] neg_lo:[0,1] neg_hi:[0,1]
	v_pk_mul_f32 v[118:119], v[114:115], v[112:113]
	v_mov_b32_e32 v83, v89
	v_pk_fma_f32 v[120:121], v[112:113], v[114:115], v[118:119] neg_lo:[0,0,1] neg_hi:[0,0,1]
	v_mov_b32_e32 v128, v92
	v_pk_fma_f32 v[120:121], v[112:113], v[110:111], v[120:121]
	v_cmp_neq_f32_e32 vcc, s8, v97
	v_pk_add_f32 v[122:123], v[118:119], v[120:121]
	v_cmp_lt_f32_e64 s[0:1], |v98|, s9
	v_pk_add_f32 v[124:125], v[94:95], v[122:123] neg_lo:[0,1] neg_hi:[0,1]
	v_pk_add_f32 v[118:119], v[122:123], v[118:119] neg_lo:[0,1] neg_hi:[0,1]
	v_pk_add_f32 v[94:95], v[94:95], v[124:125] neg_lo:[0,1] neg_hi:[0,1]
	s_nop 0
	v_pk_add_f32 v[94:95], v[94:95], v[122:123] neg_lo:[0,1] neg_hi:[0,1]
	s_nop 0
	v_pk_add_f32 v[68:69], v[68:69], v[94:95]
	v_pk_add_f32 v[94:95], v[118:119], v[120:121] neg_lo:[0,1] neg_hi:[0,1]
	s_nop 0
	v_pk_add_f32 v[68:69], v[94:95], v[68:69]
	s_nop 0
	v_pk_add_f32 v[94:95], v[124:125], v[68:69]
	s_nop 0
	v_pk_mul_f32 v[118:119], v[116:117], v[94:95]
	s_nop 0
	v_pk_mul_f32 v[120:121], v[114:115], v[118:119]
	s_nop 0
	v_pk_fma_f32 v[114:115], v[118:119], v[114:115], v[120:121] neg_lo:[0,0,1] neg_hi:[0,0,1]
; __device__ __forceinline__ float softplusf(float x) { return fmaxf(x, 0.f) + log1pf(__expf(-fabsf(x))); }
; __device__ void phaseA_tile(const Params& p, int l, int mt, int nt, char* smem) {
;     ...
;         if (wc == 0) {
; #pragma unroll
;             for (int i = 0; i < 4; ++i) {
;                 const int rl = wr * 64 + i * 16 + r;
;                 const int row = m0 + rl;
; #pragma unroll
;                 for (int j = 0; j < 2; ++j) {
;                     const int c = j * 16 + g4 * 4;
;                     const float4 db = *(const float4*)(p.dt_bias + l * 32 + c);
;                     const f32x4 v = acc[i][j];
;                     *(float4*)(p.dtb + (size_t)row * 32 + c) =
;                         make_float4(softplusf(v[0] + db.x), softplusf(v[1] + db.y), softplusf(v[2] + db.z), softplusf(v[3] + db.w));
;                 }
	s_nop 0
	v_pk_fma_f32 v[110:111], v[118:119], v[110:111], v[114:115]
	v_pk_add_f32 v[114:115], v[124:125], v[94:95] neg_lo:[0,1] neg_hi:[0,1]
	s_nop 0
	v_pk_add_f32 v[68:69], v[68:69], v[114:115]
	v_pk_add_f32 v[114:115], v[120:121], v[110:111]
	s_nop 0
	v_pk_add_f32 v[122:123], v[94:95], v[114:115] neg_lo:[0,1] neg_hi:[0,1]
	v_pk_add_f32 v[120:121], v[114:115], v[120:121] neg_lo:[0,1] neg_hi:[0,1]
	v_pk_add_f32 v[94:95], v[94:95], v[122:123] neg_lo:[0,1] neg_hi:[0,1]
	s_nop 0
	v_pk_add_f32 v[94:95], v[94:95], v[114:115] neg_lo:[0,1] neg_hi:[0,1]
	s_nop 0
	v_pk_add_f32 v[68:69], v[68:69], v[94:95]
	v_pk_add_f32 v[94:95], v[120:121], v[110:111] neg_lo:[0,1] neg_hi:[0,1]
	s_nop 0
	v_pk_add_f32 v[68:69], v[94:95], v[68:69]
	v_pk_add_f32 v[94:95], v[112:113], v[118:119]
	v_pk_add_f32 v[68:69], v[122:123], v[68:69]
	v_pk_add_f32 v[110:111], v[94:95], v[112:113] neg_lo:[0,1] neg_hi:[0,1]
	v_pk_mul_f32 v[68:69], v[116:117], v[68:69]
	v_pk_add_f32 v[110:111], v[118:119], v[110:111] neg_lo:[0,1] neg_hi:[0,1]
	s_nop 0
	v_pk_add_f32 v[68:69], v[110:111], v[68:69]
	s_nop 0
	v_pk_add_f32 v[110:111], v[94:95], v[68:69]
	s_nop 0
	v_pk_add_f32 v[94:95], v[110:111], v[94:95] neg_lo:[0,1] neg_hi:[0,1]
	v_pk_mul_f32 v[114:115], v[110:111], v[110:111]
	v_pk_add_f32 v[68:69], v[68:69], v[94:95] neg_lo:[0,1] neg_hi:[0,1]
	v_pk_fma_f32 v[116:117], v[114:115], s[28:29], v[66:67] op_sel_hi:[1,0,0]
	v_ldexp_f32 v112, v68, 1
	v_ldexp_f32 v103, v69, 1
	v_lshl_add_u64 v[68:69], s[10:11], 0, v[80:81]
	v_cvt_f32_i32_e32 v81, v99
	v_cvt_f32_i32_e32 v80, v88
	v_ldexp_f32 v94, v110, 1
	v_pk_fma_f32 v[116:117], v[114:115], v[116:117], s[30:31] op_sel_hi:[1,1,0]
	v_ldexp_f32 v95, v111, 1
	v_pk_mul_f32 v[110:111], v[110:111], v[114:115]
	v_pk_mul_f32 v[114:115], v[80:81], s[12:13] op_sel_hi:[1,0]
	v_mov_b32_e32 v113, v103
	v_pk_fma_f32 v[118:119], v[80:81], s[12:13], v[114:115] op_sel_hi:[1,0,1] neg_lo:[0,0,1] neg_hi:[0,0,1]
	v_mov_b32_e32 v90, v114
	v_pk_fma_f32 v[80:81], v[80:81], s[14:15], v[118:119] op_sel_hi:[1,0,1]
	v_mov_b32_e32 v125, v115
	v_mov_b32_e32 v88, v80
	v_pk_add_f32 v[90:91], v[90:91], v[88:89]
	v_pk_add_f32 v[88:89], v[82:83], v[84:85]
	v_mov_b32_e32 v85, v93
	v_mov_b32_e32 v83, v89
	v_pk_add_f32 v[118:119], v[114:115], v[80:81]
	v_pk_add_f32 v[82:83], v[82:83], v[84:85]
	v_pk_add_f32 v[84:85], v[92:93], v[88:89]
	v_mov_b32_e32 v129, v119
	v_pk_add_f32 v[120:121], v[118:119], v[84:85]
	v_mov_b32_e32 v126, v84
	v_mov_b32_e32 v127, v121
	v_pk_add_f32 v[126:127], v[126:127], v[128:129] neg_lo:[0,1] neg_hi:[0,1]
	v_mov_b32_e32 v122, v120
	v_mov_b32_e32 v123, v119
	v_mov_b32_e32 v124, v118
	v_mov_b32_e32 v128, v118
	v_mov_b32_e32 v129, v121
	v_mov_b32_e32 v115, v127
	v_pk_add_f32 v[122:123], v[122:123], v[124:125] neg_lo:[0,1] neg_hi:[0,1]
	v_mov_b32_e32 v124, v84
	v_mov_b32_e32 v125, v81
	v_pk_add_f32 v[114:115], v[128:129], v[114:115] neg_lo:[0,1] neg_hi:[0,1]
	v_pk_add_f32 v[124:125], v[124:125], v[122:123] neg_lo:[0,1] neg_hi:[0,1]
	v_mov_b32_e32 v128, v114
	v_mov_b32_e32 v129, v123
	v_mov_b32_e32 v130, v120
	v_mov_b32_e32 v131, v85
	v_mov_b32_e32 v123, v93
	v_pk_add_f32 v[128:129], v[80:81], v[128:129] neg_lo:[0,1] neg_hi:[0,1]
	v_pk_add_f32 v[122:123], v[130:131], v[122:123] neg_lo:[0,1] neg_hi:[0,1]
	v_mov_b32_e32 v81, v119
	v_pk_add_f32 v[84:85], v[84:85], v[92:93] neg_lo:[0,1] neg_hi:[0,1]
	v_pk_add_f32 v[90:91], v[90:91], v[122:123] neg_lo:[0,1] neg_hi:[0,1]
	v_pk_add_f32 v[80:81], v[80:81], v[114:115] neg_lo:[0,1] neg_hi:[0,1]
	v_pk_add_f32 v[82:83], v[82:83], v[126:127] neg_lo:[0,1] neg_hi:[0,1]
	v_pk_add_f32 v[84:85], v[88:89], v[84:85] neg_lo:[0,1] neg_hi:[0,1]
	v_pk_add_f32 v[88:89], v[82:83], v[80:81]
	v_mov_b32_e32 v81, v125
	v_mov_b32_e32 v83, v91
	v_pk_add_f32 v[92:93], v[124:125], v[90:91]
	v_pk_add_f32 v[82:83], v[80:81], v[82:83]
	v_mov_b32_e32 v90, v88
	v_pk_add_f32 v[82:83], v[82:83], v[128:129] neg_lo:[0,1] neg_hi:[0,1]
	v_mov_b32_e32 v91, v93
	v_pk_add_f32 v[90:91], v[90:91], v[82:83] neg_lo:[0,1] neg_hi:[0,1]
	v_pk_add_f32 v[82:83], v[84:85], v[82:83] neg_lo:[0,1] neg_hi:[0,1]
	v_pk_add_f32 v[80:81], v[80:81], v[90:91] neg_lo:[0,1] neg_hi:[0,1]
	v_lshl_add_u64 v[68:69], v[68:69], 0, v[0:1]
	v_pk_add_f32 v[80:81], v[82:83], v[80:81]
	v_pk_add_f32 v[82:83], v[92:93], v[88:89]
	s_nop 0
	v_pk_add_f32 v[84:85], v[120:121], v[82:83]
	s_nop 0
	v_pk_add_f32 v[88:89], v[84:85], v[120:121] neg_lo:[0,1] neg_hi:[0,1]
	s_nop 0
	v_pk_add_f32 v[82:83], v[82:83], v[88:89] neg_lo:[0,1] neg_hi:[0,1]
	s_nop 0
	v_pk_add_f32 v[80:81], v[80:81], v[82:83]
	s_nop 0
	v_pk_add_f32 v[80:81], v[84:85], v[80:81]
	v_pk_mul_f32 v[84:85], v[110:111], v[116:117]
	v_cndmask_b32_e32 v80, v160, v80, vcc
	v_cmp_neq_f32_e32 vcc, s8, v98
	v_pk_add_f32 v[88:89], v[94:95], v[84:85]
	s_nop 0
	v_cndmask_b32_e32 v81, v160, v81, vcc
	v_cmp_ngt_f32_e32 vcc, -1.0, v98
	v_pk_add_f32 v[92:93], v[88:89], v[94:95] neg_lo:[0,1] neg_hi:[0,1]
	v_mov_b32_e32 v116, v88
	v_cndmask_b32_e32 v81, v161, v81, vcc
	v_cmp_ngt_f32_e32 vcc, -1.0, v97
	v_pk_add_f32 v[84:85], v[84:85], v[92:93] neg_lo:[0,1] neg_hi:[0,1]
	s_nop 0
	v_cndmask_b32_e32 v80, v161, v80, vcc
	v_cmp_neq_f32_e32 vcc, -1.0, v97
	v_pk_add_f32 v[94:95], v[112:113], v[84:85]
	v_mov_b32_e32 v93, v85
	v_cndmask_b32_e32 v80, v162, v80, vcc
	v_cmp_neq_f32_e32 vcc, -1.0, v98
	v_mov_b32_e32 v113, v95
	v_mov_b32_e32 v85, v89
	v_cndmask_b32_e32 v81, v162, v81, vcc
	v_cmp_lt_f32_e64 vcc, |v97|, s9
	v_cndmask_b32_e64 v81, v81, v98, s[0:1]
	v_pk_add_f32 v[98:99], v[88:89], v[94:95]
	v_cndmask_b32_e32 v80, v80, v97, vcc
	v_pk_add_f32 v[78:79], v[78:79], v[80:81]
	v_cvt_f32_i32_e32 v81, v132
	v_cvt_f32_i32_e32 v80, v102
	v_mov_b32_e32 v114, v98
; __device__ __forceinline__ float softplusf(float x) { return fmaxf(x, 0.f) + log1pf(__expf(-fabsf(x))); }
; __device__ void phaseA_tile(const Params& p, int l, int mt, int nt, char* smem) {
;     ...
;         if (wc == 0) {
; #pragma unroll
;             for (int i = 0; i < 4; ++i) {
;                 const int rl = wr * 64 + i * 16 + r;
;                 const int row = m0 + rl;
; #pragma unroll
;                 for (int j = 0; j < 2; ++j) {
;                     const int c = j * 16 + g4 * 4;
;                     const float4 db = *(const float4*)(p.dt_bias + l * 32 + c);
;                     const f32x4 v = acc[i][j];
;                     *(float4*)(p.dtb + (size_t)row * 32 + c) =
;                         make_float4(softplusf(v[0] + db.x), softplusf(v[1] + db.y), softplusf(v[2] + db.z), softplusf(v[3] + db.w));
;                 }
	v_pk_add_f32 v[84:85], v[112:113], v[84:85]
	v_mov_b32_e32 v119, v99
	v_pk_mul_f32 v[82:83], v[80:81], s[12:13] op_sel_hi:[1,0]
	v_cmp_neq_f32_e32 vcc, s8, v100
	v_pk_fma_f32 v[90:91], v[80:81], s[12:13], v[82:83] op_sel_hi:[1,0,1] neg_lo:[0,0,1] neg_hi:[0,0,1]
	v_mov_b32_e32 v92, v82
	v_pk_fma_f32 v[80:81], v[80:81], s[14:15], v[90:91] op_sel_hi:[1,0,1]
	v_mov_b32_e32 v113, v83
	v_pk_add_f32 v[90:91], v[82:83], v[80:81]
	v_mov_b32_e32 v102, v80
	v_pk_add_f32 v[92:93], v[92:93], v[102:103]
	v_pk_add_f32 v[102:103], v[90:91], v[98:99]
	v_mov_b32_e32 v117, v91
	v_mov_b32_e32 v115, v103
	v_pk_add_f32 v[114:115], v[114:115], v[116:117] neg_lo:[0,1] neg_hi:[0,1]
	v_mov_b32_e32 v110, v102
	v_mov_b32_e32 v111, v91
	v_mov_b32_e32 v112, v90
	v_mov_b32_e32 v116, v90
	v_mov_b32_e32 v117, v103
	v_mov_b32_e32 v83, v115
	v_pk_add_f32 v[110:111], v[110:111], v[112:113] neg_lo:[0,1] neg_hi:[0,1]
	v_mov_b32_e32 v112, v98
	v_mov_b32_e32 v113, v81
	v_pk_add_f32 v[82:83], v[116:117], v[82:83] neg_lo:[0,1] neg_hi:[0,1]
	v_pk_add_f32 v[112:113], v[112:113], v[110:111] neg_lo:[0,1] neg_hi:[0,1]
	v_mov_b32_e32 v116, v82
	v_mov_b32_e32 v117, v111
	v_mov_b32_e32 v118, v102
	v_mov_b32_e32 v111, v89
	v_pk_add_f32 v[116:117], v[80:81], v[116:117] neg_lo:[0,1] neg_hi:[0,1]
	v_pk_add_f32 v[110:111], v[118:119], v[110:111] neg_lo:[0,1] neg_hi:[0,1]
	v_mov_b32_e32 v81, v91
	v_pk_add_f32 v[92:93], v[92:93], v[110:111] neg_lo:[0,1] neg_hi:[0,1]
	v_pk_add_f32 v[80:81], v[80:81], v[82:83] neg_lo:[0,1] neg_hi:[0,1]
	v_pk_add_f32 v[82:83], v[84:85], v[114:115] neg_lo:[0,1] neg_hi:[0,1]
	v_pk_add_f32 v[90:91], v[112:113], v[92:93]
	v_pk_add_f32 v[84:85], v[82:83], v[80:81]
	v_mov_b32_e32 v81, v113
	v_mov_b32_e32 v83, v93
	v_pk_add_f32 v[82:83], v[80:81], v[82:83]
	v_pk_add_f32 v[88:89], v[98:99], v[88:89] neg_lo:[0,1] neg_hi:[0,1]
	v_pk_add_f32 v[82:83], v[82:83], v[116:117] neg_lo:[0,1] neg_hi:[0,1]
	v_mov_b32_e32 v92, v84
	v_mov_b32_e32 v93, v91
	v_pk_add_f32 v[88:89], v[94:95], v[88:89] neg_lo:[0,1] neg_hi:[0,1]
	v_pk_add_f32 v[92:93], v[92:93], v[82:83] neg_lo:[0,1] neg_hi:[0,1]
	v_pk_add_f32 v[82:83], v[88:89], v[82:83] neg_lo:[0,1] neg_hi:[0,1]
	v_pk_add_f32 v[80:81], v[80:81], v[92:93] neg_lo:[0,1] neg_hi:[0,1]
	v_cmp_lt_f32_e64 s[0:1], |v101|, s9
	v_pk_add_f32 v[80:81], v[82:83], v[80:81]
	v_pk_add_f32 v[82:83], v[90:91], v[84:85]
	s_nop 0
	v_pk_add_f32 v[84:85], v[102:103], v[82:83]
	s_nop 0
	v_pk_add_f32 v[88:89], v[84:85], v[102:103] neg_lo:[0,1] neg_hi:[0,1]
	s_nop 0
	v_pk_add_f32 v[82:83], v[82:83], v[88:89] neg_lo:[0,1] neg_hi:[0,1]
	s_nop 0
	v_pk_add_f32 v[80:81], v[80:81], v[82:83]
	s_nop 0
	v_pk_add_f32 v[80:81], v[84:85], v[80:81]
	s_nop 0
	v_cndmask_b32_e32 v80, v160, v80, vcc
	v_cmp_neq_f32_e32 vcc, s8, v101
	s_nop 1
	v_cndmask_b32_e32 v81, v160, v81, vcc
	v_cmp_ngt_f32_e32 vcc, -1.0, v101
	s_nop 1
	v_cndmask_b32_e32 v81, v161, v81, vcc
	v_cmp_ngt_f32_e32 vcc, -1.0, v100
	s_nop 1
	v_cndmask_b32_e32 v80, v161, v80, vcc
	v_cmp_neq_f32_e32 vcc, -1.0, v100
	s_nop 1
	v_cndmask_b32_e32 v80, v162, v80, vcc
	v_cmp_neq_f32_e32 vcc, -1.0, v101
	s_nop 1
	v_cndmask_b32_e32 v81, v162, v81, vcc
	v_cmp_lt_f32_e64 vcc, |v100|, s9
	v_cndmask_b32_e64 v81, v81, v101, s[0:1]
	s_nop 0
	v_cndmask_b32_e32 v80, v80, v100, vcc
	v_pk_add_f32 v[80:81], v[86:87], v[80:81]
	global_store_dwordx4 v[68:69], v[78:81], off
	global_load_dwordx4 v[78:81], v0, s[74:75] offset:64
	s_waitcnt vmcnt(0)
	v_add_f32_e32 v82, v58, v78
	v_max_f32_e32 v78, 0, v82
	v_mul_f32_e64 v82, |v82|, s2
	v_exp_f32_e32 v97, v82
	s_nop 0
	v_add_f32_e32 v84, 1.0, v97
	v_add_f32_e32 v82, -1.0, v84
	v_sub_f32_e32 v83, v82, v84
	v_add_f32_e32 v83, 1.0, v83
	v_sub_f32_e32 v82, v97, v82
	v_add_f32_e32 v85, v82, v83
	v_frexp_mant_f32_e32 v82, v84
	v_cmp_gt_f32_e32 vcc, s26, v82
	v_cvt_f64_f32_e32 v[82:83], v84
	v_frexp_exp_i32_f64_e32 v82, v[82:83]
	v_subbrev_co_u32_e32 v120, vcc, 0, v82, vcc
	v_sub_u32_e32 v83, 0, v120
	v_ldexp_f32 v82, v84, v83
	v_ldexp_f32 v84, v85, v83
	v_add_f32_e32 v83, v59, v79
	v_max_f32_e32 v79, 0, v83
	v_mul_f32_e64 v83, |v83|, s2
	v_exp_f32_e32 v128, v83
	s_nop 0
	v_add_f32_e32 v83, 1.0, v128
	v_add_f32_e32 v85, -1.0, v83
	v_sub_f32_e32 v86, v85, v83
	v_add_f32_e32 v86, 1.0, v86
	v_sub_f32_e32 v85, v128, v85
	v_add_f32_e32 v85, v85, v86
	v_frexp_mant_f32_e32 v86, v83
	v_cmp_gt_f32_e32 vcc, s26, v86
	v_cvt_f64_f32_e32 v[86:87], v83
	v_frexp_exp_i32_f64_e32 v86, v[86:87]
	v_subbrev_co_u32_e32 v121, vcc, 0, v86, vcc
	v_sub_u32_e32 v86, 0, v121
	v_ldexp_f32 v83, v83, v86
	v_ldexp_f32 v85, v85, v86
	v_pk_add_f32 v[86:87], v[82:83], 1.0 op_sel_hi:[1,0]
	v_pk_add_f32 v[94:95], v[82:83], -1.0 op_sel_hi:[1,0]
	v_pk_add_f32 v[88:89], v[86:87], -1.0 op_sel_hi:[1,0]
	v_pk_add_f32 v[98:99], v[94:95], 1.0 op_sel_hi:[1,0]
	v_pk_add_f32 v[88:89], v[82:83], v[88:89] neg_lo:[0,1] neg_hi:[0,1]
	v_pk_add_f32 v[82:83], v[82:83], v[98:99] neg_lo:[0,1] neg_hi:[0,1]
	v_pk_add_f32 v[88:89], v[84:85], v[88:89]
	v_pk_add_f32 v[82:83], v[84:85], v[82:83]
	v_pk_add_f32 v[90:91], v[86:87], v[88:89]
	v_pk_add_f32 v[84:85], v[94:95], v[82:83]
	v_rcp_f32_e32 v92, v90
	v_rcp_f32_e32 v93, v91
	v_pk_add_f32 v[86:87], v[90:91], v[86:87] neg_lo:[0,1] neg_hi:[0,1]
	v_pk_add_f32 v[94:95], v[84:85], v[94:95] neg_lo:[0,1] neg_hi:[0,1]
	v_pk_add_f32 v[86:87], v[88:89], v[86:87] neg_lo:[0,1] neg_hi:[0,1]
	v_pk_mul_f32 v[88:89], v[84:85], v[92:93]
	v_pk_add_f32 v[82:83], v[82:83], v[94:95] neg_lo:[0,1] neg_hi:[0,1]
	v_pk_mul_f32 v[94:95], v[90:91], v[88:89]
	v_cmp_lt_f32_e64 s[0:1], |v128|, s9
	v_pk_fma_f32 v[98:99], v[88:89], v[90:91], v[94:95] neg_lo:[0,0,1] neg_hi:[0,0,1]
	s_nop 0
	v_pk_fma_f32 v[98:99], v[88:89], v[86:87], v[98:99]
; __device__ __forceinline__ float softplusf(float x) { return fmaxf(x, 0.f) + log1pf(__expf(-fabsf(x))); }
; __device__ void phaseA_tile(const Params& p, int l, int mt, int nt, char* smem) {
;     ...
;         if (wc == 0) {
; #pragma unroll
;             for (int i = 0; i < 4; ++i) {
;                 const int rl = wr * 64 + i * 16 + r;
;                 const int row = m0 + rl;
; #pragma unroll
;                 for (int j = 0; j < 2; ++j) {
;                     const int c = j * 16 + g4 * 4;
;                     const float4 db = *(const float4*)(p.dt_bias + l * 32 + c);
;                     const f32x4 v = acc[i][j];
;                     *(float4*)(p.dtb + (size_t)row * 32 + c) =
;                         make_float4(softplusf(v[0] + db.x), softplusf(v[1] + db.y), softplusf(v[2] + db.z), softplusf(v[3] + db.w));
;                 }
	s_nop 0
	v_pk_add_f32 v[100:101], v[94:95], v[98:99]
	s_nop 0
	v_pk_add_f32 v[102:103], v[84:85], v[100:101] neg_lo:[0,1] neg_hi:[0,1]
	v_pk_add_f32 v[94:95], v[100:101], v[94:95] neg_lo:[0,1] neg_hi:[0,1]
	v_pk_add_f32 v[84:85], v[84:85], v[102:103] neg_lo:[0,1] neg_hi:[0,1]
	s_nop 0
	v_pk_add_f32 v[84:85], v[84:85], v[100:101] neg_lo:[0,1] neg_hi:[0,1]
	s_nop 0
	v_pk_add_f32 v[82:83], v[82:83], v[84:85]
	v_pk_add_f32 v[84:85], v[94:95], v[98:99] neg_lo:[0,1] neg_hi:[0,1]
	s_nop 0
	v_pk_add_f32 v[82:83], v[84:85], v[82:83]
	s_nop 0
	v_pk_add_f32 v[84:85], v[102:103], v[82:83]
	s_nop 0
	v_pk_mul_f32 v[94:95], v[92:93], v[84:85]
	s_nop 0
	v_pk_mul_f32 v[98:99], v[90:91], v[94:95]
	s_nop 0
	v_pk_fma_f32 v[90:91], v[94:95], v[90:91], v[98:99] neg_lo:[0,0,1] neg_hi:[0,0,1]
	s_nop 0
	v_pk_fma_f32 v[86:87], v[94:95], v[86:87], v[90:91]
	v_pk_add_f32 v[90:91], v[102:103], v[84:85] neg_lo:[0,1] neg_hi:[0,1]
	s_nop 0
	v_pk_add_f32 v[82:83], v[82:83], v[90:91]
	v_pk_add_f32 v[90:91], v[98:99], v[86:87]
	s_nop 0
	v_pk_add_f32 v[100:101], v[84:85], v[90:91] neg_lo:[0,1] neg_hi:[0,1]
	v_pk_add_f32 v[98:99], v[90:91], v[98:99] neg_lo:[0,1] neg_hi:[0,1]
	v_pk_add_f32 v[84:85], v[84:85], v[100:101] neg_lo:[0,1] neg_hi:[0,1]
	s_nop 0
	v_pk_add_f32 v[84:85], v[84:85], v[90:91] neg_lo:[0,1] neg_hi:[0,1]
	s_nop 0
	v_pk_add_f32 v[82:83], v[82:83], v[84:85]
	v_pk_add_f32 v[84:85], v[98:99], v[86:87] neg_lo:[0,1] neg_hi:[0,1]
	s_nop 0
	v_pk_add_f32 v[82:83], v[84:85], v[82:83]
	v_pk_add_f32 v[84:85], v[88:89], v[94:95]
	v_pk_add_f32 v[82:83], v[100:101], v[82:83]
	v_pk_add_f32 v[86:87], v[84:85], v[88:89] neg_lo:[0,1] neg_hi:[0,1]
	v_pk_mul_f32 v[82:83], v[92:93], v[82:83]
	v_pk_add_f32 v[86:87], v[94:95], v[86:87] neg_lo:[0,1] neg_hi:[0,1]
	s_nop 0
	v_pk_add_f32 v[82:83], v[86:87], v[82:83]
	s_nop 0
	v_pk_add_f32 v[86:87], v[84:85], v[82:83]
	s_nop 0
	v_pk_add_f32 v[84:85], v[86:87], v[84:85] neg_lo:[0,1] neg_hi:[0,1]
	v_pk_mul_f32 v[88:89], v[86:87], v[86:87]
	v_pk_add_f32 v[82:83], v[82:83], v[84:85] neg_lo:[0,1] neg_hi:[0,1]
	v_pk_fma_f32 v[90:91], v[88:89], s[28:29], v[66:67] op_sel_hi:[1,0,0]
	v_ldexp_f32 v93, v83, 1
	v_add_f32_e32 v83, v60, v80
	v_max_f32_e32 v80, 0, v83
	v_mul_f32_e64 v83, |v83|, s2
	v_exp_f32_e32 v129, v83
	v_ldexp_f32 v84, v86, 1
	v_pk_fma_f32 v[90:91], v[88:89], v[90:91], s[30:31] op_sel_hi:[1,1,0]
	v_ldexp_f32 v85, v87, 1
	v_add_f32_e32 v83, 1.0, v129
	v_pk_mul_f32 v[86:87], v[86:87], v[88:89]
	v_add_f32_e32 v88, -1.0, v83
	v_sub_f32_e32 v89, v88, v83
	v_add_f32_e32 v89, 1.0, v89
	v_sub_f32_e32 v88, v129, v88
	v_add_f32_e32 v92, v88, v89
	v_frexp_mant_f32_e32 v88, v83
	v_cmp_gt_f32_e32 vcc, s26, v88
	v_cvt_f64_f32_e32 v[88:89], v83
	v_frexp_exp_i32_f64_e32 v88, v[88:89]
	v_subbrev_co_u32_e32 v130, vcc, 0, v88, vcc
	v_sub_u32_e32 v89, 0, v130
	v_ldexp_f32 v88, v83, v89
	v_add_f32_e32 v83, v61, v81
	v_max_f32_e32 v81, 0, v83
	v_mul_f32_e64 v83, |v83|, s2
	v_exp_f32_e32 v131, v83
	v_ldexp_f32 v94, v92, v89
	v_pk_mul_f32 v[86:87], v[86:87], v[90:91]
	v_ldexp_f32 v82, v82, 1
	v_add_f32_e32 v83, 1.0, v131
	v_add_f32_e32 v89, -1.0, v83
	v_sub_f32_e32 v92, v89, v83
	v_add_f32_e32 v92, 1.0, v92
	v_sub_f32_e32 v89, v131, v89
	v_add_f32_e32 v92, v89, v92
	v_frexp_mant_f32_e32 v89, v83
	v_cvt_f64_f32_e32 v[98:99], v83
	v_cmp_gt_f32_e32 vcc, s26, v89
	v_frexp_exp_i32_f64_e32 v89, v[98:99]
	v_pk_add_f32 v[90:91], v[84:85], v[86:87]
	v_subbrev_co_u32_e32 v132, vcc, 0, v89, vcc
	v_sub_u32_e32 v95, 0, v132
	v_ldexp_f32 v89, v83, v95
	v_pk_add_f32 v[98:99], v[88:89], 1.0 op_sel_hi:[1,0]
	v_ldexp_f32 v95, v92, v95
	v_pk_add_f32 v[100:101], v[98:99], -1.0 op_sel_hi:[1,0]
	v_pk_add_f32 v[112:113], v[88:89], -1.0 op_sel_hi:[1,0]
	v_pk_add_f32 v[100:101], v[88:89], v[100:101] neg_lo:[0,1] neg_hi:[0,1]
	v_pk_add_f32 v[114:115], v[112:113], 1.0 op_sel_hi:[1,0]
	v_pk_add_f32 v[100:101], v[94:95], v[100:101]
	v_pk_add_f32 v[88:89], v[88:89], v[114:115] neg_lo:[0,1] neg_hi:[0,1]
	v_pk_add_f32 v[102:103], v[98:99], v[100:101]
	v_pk_add_f32 v[88:89], v[94:95], v[88:89]
	v_rcp_f32_e32 v110, v102
	v_rcp_f32_e32 v111, v103
	v_pk_add_f32 v[94:95], v[112:113], v[88:89]
	v_pk_add_f32 v[98:99], v[102:103], v[98:99] neg_lo:[0,1] neg_hi:[0,1]
	v_pk_add_f32 v[112:113], v[94:95], v[112:113] neg_lo:[0,1] neg_hi:[0,1]
	v_pk_add_f32 v[98:99], v[100:101], v[98:99] neg_lo:[0,1] neg_hi:[0,1]
	v_pk_mul_f32 v[100:101], v[94:95], v[110:111]
	v_pk_add_f32 v[88:89], v[88:89], v[112:113] neg_lo:[0,1] neg_hi:[0,1]
	v_pk_mul_f32 v[112:113], v[102:103], v[100:101]
	v_pk_add_f32 v[84:85], v[90:91], v[84:85] neg_lo:[0,1] neg_hi:[0,1]
	v_pk_fma_f32 v[114:115], v[100:101], v[102:103], v[112:113] neg_lo:[0,0,1] neg_hi:[0,0,1]
	v_pk_add_f32 v[84:85], v[86:87], v[84:85] neg_lo:[0,1] neg_hi:[0,1]
	v_pk_fma_f32 v[114:115], v[100:101], v[98:99], v[114:115]
	v_mov_b32_e32 v87, v85
	v_pk_add_f32 v[116:117], v[112:113], v[114:115]
	v_mov_b32_e32 v83, v93
	v_pk_add_f32 v[118:119], v[94:95], v[116:117] neg_lo:[0,1] neg_hi:[0,1]
	v_pk_add_f32 v[112:113], v[116:117], v[112:113] neg_lo:[0,1] neg_hi:[0,1]
	v_pk_add_f32 v[94:95], v[94:95], v[118:119] neg_lo:[0,1] neg_hi:[0,1]
	v_mov_b32_e32 v124, v90
	v_pk_add_f32 v[94:95], v[94:95], v[116:117] neg_lo:[0,1] neg_hi:[0,1]
	v_cmp_neq_f32_e32 vcc, s8, v97
	v_pk_add_f32 v[88:89], v[88:89], v[94:95]
	v_pk_add_f32 v[94:95], v[112:113], v[114:115] neg_lo:[0,1] neg_hi:[0,1]
	s_nop 0
	v_pk_add_f32 v[88:89], v[94:95], v[88:89]
	s_nop 0
	v_pk_add_f32 v[94:95], v[118:119], v[88:89]
	s_nop 0
	v_pk_mul_f32 v[112:113], v[110:111], v[94:95]
	s_nop 0
	v_pk_mul_f32 v[114:115], v[102:103], v[112:113]
	s_nop 0
	v_pk_fma_f32 v[102:103], v[112:113], v[102:103], v[114:115] neg_lo:[0,0,1] neg_hi:[0,0,1]
; __device__ __forceinline__ float softplusf(float x) { return fmaxf(x, 0.f) + log1pf(__expf(-fabsf(x))); }
; __device__ void phaseA_tile(const Params& p, int l, int mt, int nt, char* smem) {
;     ...
;         if (wc == 0) {
; #pragma unroll
;             for (int i = 0; i < 4; ++i) {
;                 const int rl = wr * 64 + i * 16 + r;
;                 const int row = m0 + rl;
; #pragma unroll
;                 for (int j = 0; j < 2; ++j) {
;                     const int c = j * 16 + g4 * 4;
;                     const float4 db = *(const float4*)(p.dt_bias + l * 32 + c);
;                     const f32x4 v = acc[i][j];
;                     *(float4*)(p.dtb + (size_t)row * 32 + c) =
;                         make_float4(softplusf(v[0] + db.x), softplusf(v[1] + db.y), softplusf(v[2] + db.z), softplusf(v[3] + db.w));
;                 }
	s_nop 0
	v_pk_fma_f32 v[98:99], v[112:113], v[98:99], v[102:103]
	v_pk_add_f32 v[102:103], v[118:119], v[94:95] neg_lo:[0,1] neg_hi:[0,1]
	s_nop 0
	v_pk_add_f32 v[88:89], v[88:89], v[102:103]
	v_pk_add_f32 v[102:103], v[114:115], v[98:99]
	s_nop 0
	v_pk_add_f32 v[116:117], v[94:95], v[102:103] neg_lo:[0,1] neg_hi:[0,1]
	v_pk_add_f32 v[114:115], v[102:103], v[114:115] neg_lo:[0,1] neg_hi:[0,1]
	v_pk_add_f32 v[94:95], v[94:95], v[116:117] neg_lo:[0,1] neg_hi:[0,1]
	s_nop 0
	v_pk_add_f32 v[94:95], v[94:95], v[102:103] neg_lo:[0,1] neg_hi:[0,1]
	s_nop 0
	v_pk_add_f32 v[88:89], v[88:89], v[94:95]
	v_pk_add_f32 v[94:95], v[114:115], v[98:99] neg_lo:[0,1] neg_hi:[0,1]
	s_nop 0
	v_pk_add_f32 v[88:89], v[94:95], v[88:89]
	v_pk_add_f32 v[94:95], v[100:101], v[112:113]
	v_pk_add_f32 v[88:89], v[116:117], v[88:89]
	v_pk_add_f32 v[98:99], v[94:95], v[100:101] neg_lo:[0,1] neg_hi:[0,1]
	v_pk_mul_f32 v[88:89], v[110:111], v[88:89]
	v_pk_add_f32 v[98:99], v[112:113], v[98:99] neg_lo:[0,1] neg_hi:[0,1]
	s_nop 0
	v_pk_add_f32 v[88:89], v[98:99], v[88:89]
	s_nop 0
	v_pk_add_f32 v[98:99], v[94:95], v[88:89]
	s_nop 0
	v_pk_mul_f32 v[100:101], v[98:99], v[98:99]
	v_pk_add_f32 v[94:95], v[98:99], v[94:95] neg_lo:[0,1] neg_hi:[0,1]
	v_pk_fma_f32 v[102:103], v[100:101], s[28:29], v[66:67] op_sel_hi:[1,0,0]
	v_pk_add_f32 v[88:89], v[88:89], v[94:95] neg_lo:[0,1] neg_hi:[0,1]
	v_ldexp_f32 v94, v98, 1
	v_pk_fma_f32 v[102:103], v[100:101], v[102:103], s[30:31] op_sel_hi:[1,1,0]
	v_ldexp_f32 v95, v99, 1
	v_pk_mul_f32 v[98:99], v[98:99], v[100:101]
	v_cvt_f32_i32_e32 v101, v121
	v_cvt_f32_i32_e32 v100, v120
	v_ldexp_f32 v111, v89, 1
	v_ldexp_f32 v88, v88, 1
	v_mov_b32_e32 v89, v111
	v_pk_mul_f32 v[112:113], v[100:101], s[12:13] op_sel_hi:[1,0]
	s_nop 0
	v_pk_fma_f32 v[114:115], v[100:101], s[12:13], v[112:113] op_sel_hi:[1,0,1] neg_lo:[0,0,1] neg_hi:[0,0,1]
	v_mov_b32_e32 v86, v112
	v_pk_fma_f32 v[100:101], v[100:101], s[14:15], v[114:115] op_sel_hi:[1,0,1]
	v_mov_b32_e32 v121, v113
	v_mov_b32_e32 v92, v100
	v_pk_add_f32 v[86:87], v[86:87], v[92:93]
	v_pk_add_f32 v[92:93], v[82:83], v[84:85]
	v_mov_b32_e32 v85, v91
	v_mov_b32_e32 v83, v93
	v_pk_add_f32 v[114:115], v[112:113], v[100:101]
	v_pk_add_f32 v[82:83], v[82:83], v[84:85]
	v_pk_add_f32 v[84:85], v[90:91], v[92:93]
	v_mov_b32_e32 v125, v115
	v_pk_add_f32 v[116:117], v[114:115], v[84:85]
	v_mov_b32_e32 v122, v84
	v_mov_b32_e32 v123, v117
	v_pk_add_f32 v[122:123], v[122:123], v[124:125] neg_lo:[0,1] neg_hi:[0,1]
	v_mov_b32_e32 v118, v116
	v_mov_b32_e32 v119, v115
	v_mov_b32_e32 v120, v114
	v_mov_b32_e32 v124, v114
	v_mov_b32_e32 v125, v117
	v_mov_b32_e32 v113, v123
	v_pk_add_f32 v[118:119], v[118:119], v[120:121] neg_lo:[0,1] neg_hi:[0,1]
	v_mov_b32_e32 v120, v84
	v_mov_b32_e32 v121, v101
	v_pk_add_f32 v[112:113], v[124:125], v[112:113] neg_lo:[0,1] neg_hi:[0,1]
	v_pk_add_f32 v[120:121], v[120:121], v[118:119] neg_lo:[0,1] neg_hi:[0,1]
	v_mov_b32_e32 v124, v112
	v_mov_b32_e32 v125, v119
	v_mov_b32_e32 v126, v116
	v_mov_b32_e32 v127, v85
	v_mov_b32_e32 v119, v91
	v_pk_add_f32 v[124:125], v[100:101], v[124:125] neg_lo:[0,1] neg_hi:[0,1]
	v_pk_add_f32 v[118:119], v[126:127], v[118:119] neg_lo:[0,1] neg_hi:[0,1]
	v_mov_b32_e32 v101, v115
	v_pk_add_f32 v[84:85], v[84:85], v[90:91] neg_lo:[0,1] neg_hi:[0,1]
	v_pk_add_f32 v[86:87], v[86:87], v[118:119] neg_lo:[0,1] neg_hi:[0,1]
	v_pk_add_f32 v[90:91], v[100:101], v[112:113] neg_lo:[0,1] neg_hi:[0,1]
	v_pk_add_f32 v[82:83], v[82:83], v[122:123] neg_lo:[0,1] neg_hi:[0,1]
	v_pk_add_f32 v[84:85], v[92:93], v[84:85] neg_lo:[0,1] neg_hi:[0,1]
	v_pk_add_f32 v[92:93], v[82:83], v[90:91]
	v_mov_b32_e32 v91, v121
	v_mov_b32_e32 v83, v87
	v_pk_add_f32 v[100:101], v[120:121], v[86:87]
	v_pk_add_f32 v[82:83], v[90:91], v[82:83]
	v_mov_b32_e32 v86, v92
	v_pk_add_f32 v[82:83], v[82:83], v[124:125] neg_lo:[0,1] neg_hi:[0,1]
	v_mov_b32_e32 v87, v101
	v_pk_add_f32 v[86:87], v[86:87], v[82:83] neg_lo:[0,1] neg_hi:[0,1]
	v_pk_add_f32 v[82:83], v[84:85], v[82:83] neg_lo:[0,1] neg_hi:[0,1]
	v_pk_add_f32 v[86:87], v[90:91], v[86:87] neg_lo:[0,1] neg_hi:[0,1]
	v_pk_add_f32 v[84:85], v[100:101], v[92:93]
	v_pk_add_f32 v[82:83], v[82:83], v[86:87]
	v_pk_add_f32 v[86:87], v[116:117], v[84:85]
	s_nop 0
	v_pk_add_f32 v[90:91], v[86:87], v[116:117] neg_lo:[0,1] neg_hi:[0,1]
	s_nop 0
	v_pk_add_f32 v[84:85], v[84:85], v[90:91] neg_lo:[0,1] neg_hi:[0,1]
	s_nop 0
	v_pk_add_f32 v[82:83], v[82:83], v[84:85]
	s_nop 0
	v_pk_add_f32 v[82:83], v[86:87], v[82:83]
	v_pk_mul_f32 v[86:87], v[98:99], v[102:103]
	v_cndmask_b32_e32 v82, v160, v82, vcc
	v_cmp_neq_f32_e32 vcc, s8, v128
	v_pk_add_f32 v[90:91], v[94:95], v[86:87]
	s_nop 0
	v_cndmask_b32_e32 v83, v160, v83, vcc
	v_cmp_ngt_f32_e32 vcc, -1.0, v128
	v_pk_add_f32 v[94:95], v[90:91], v[94:95] neg_lo:[0,1] neg_hi:[0,1]
	v_mov_b32_e32 v114, v90
	v_cndmask_b32_e32 v83, v161, v83, vcc
	v_cmp_ngt_f32_e32 vcc, -1.0, v97
	v_pk_add_f32 v[86:87], v[86:87], v[94:95] neg_lo:[0,1] neg_hi:[0,1]
	s_nop 0
	v_cndmask_b32_e32 v82, v161, v82, vcc
	v_cmp_neq_f32_e32 vcc, -1.0, v97
	v_pk_add_f32 v[98:99], v[88:89], v[86:87]
	v_mov_b32_e32 v95, v87
	v_cndmask_b32_e32 v82, v162, v82, vcc
	v_cmp_neq_f32_e32 vcc, -1.0, v128
	v_mov_b32_e32 v89, v99
	v_mov_b32_e32 v87, v91
	v_cndmask_b32_e32 v83, v162, v83, vcc
	v_cmp_lt_f32_e64 vcc, |v97|, s9
	v_cndmask_b32_e64 v83, v83, v128, s[0:1]
	v_pk_add_f32 v[86:87], v[88:89], v[86:87]
	v_cndmask_b32_e32 v82, v82, v97, vcc
	v_pk_add_f32 v[78:79], v[78:79], v[82:83]
	v_cvt_f32_i32_e32 v83, v132
	v_cvt_f32_i32_e32 v82, v130
	v_pk_add_f32 v[88:89], v[90:91], v[98:99]
	v_cmp_neq_f32_e32 vcc, s8, v129
	v_mov_b32_e32 v112, v88
; __device__ __forceinline__ float softplusf(float x) { return fmaxf(x, 0.f) + log1pf(__expf(-fabsf(x))); }
; __device__ __forceinline__ float logsigf(float x) { return fminf(x, 0.f) - log1pf(__expf(-fabsf(x))); }
; __device__ void phaseA_tile(const Params& p, int l, int mt, int nt, char* smem) {
;     ...
;             for (int i = 0; i < 4; ++i) {
;                 const int rl = wr * 64 + i * 16 + r;
;                 const int row = m0 + rl;
; #pragma unroll
;                 for (int j = 0; j < 2; ++j) {
;                     const int c = j * 16 + g4 * 4;
;                     const float4 db = *(const float4*)(p.dt_bias + l * 32 + c);
;                     const f32x4 v = acc[i][j];
;                     *(float4*)(p.dtb + (size_t)row * 32 + c) =
;                         make_float4(softplusf(v[0] + db.x), softplusf(v[1] + db.y), softplusf(v[2] + db.z), softplusf(v[3] + db.w));
;                 }
;                 {
;                     const int c = g4 * 4;
;                     const float4 fb = *(const float4*)(p.b_f + l * 16 + c);
;                     const f32x4 v = acc[i][2];
;                     float4 lf = make_float4(logsigf(v[0] + fb.x), logsigf(v[1] + fb.y), logsigf(v[2] + fb.z), logsigf(v[3] + fb.w));
;                     float* o = samp ? (p.out + O_LFS + ((size_t)l * TSM + (row - TP)) * 16 + c)
;                                     : (p.out + O_LFP + ((size_t)l * TP + row) * 16 + c);
;                     *(float4*)o = lf;
;                     *(float4*)(lf_s + rl * 16 + c) = lf;
;                 }
	v_pk_mul_f32 v[84:85], v[82:83], s[12:13] op_sel_hi:[1,0]
	v_mov_b32_e32 v117, v89
	v_pk_fma_f32 v[92:93], v[82:83], s[12:13], v[84:85] op_sel_hi:[1,0,1] neg_lo:[0,0,1] neg_hi:[0,0,1]
	v_mov_b32_e32 v94, v84
	v_pk_fma_f32 v[82:83], v[82:83], s[14:15], v[92:93] op_sel_hi:[1,0,1]
	v_cmp_lt_f32_e64 s[0:1], |v131|, s9
	v_pk_add_f32 v[92:93], v[84:85], v[82:83]
	v_mov_b32_e32 v110, v82
	v_pk_add_f32 v[100:101], v[92:93], v[88:89]
	v_mov_b32_e32 v115, v93
	v_mov_b32_e32 v113, v101
	v_pk_add_f32 v[112:113], v[112:113], v[114:115] neg_lo:[0,1] neg_hi:[0,1]
	v_pk_add_f32 v[94:95], v[94:95], v[110:111]
	v_mov_b32_e32 v102, v100
	v_mov_b32_e32 v103, v93
	v_mov_b32_e32 v110, v92
	v_mov_b32_e32 v111, v85
	v_mov_b32_e32 v114, v92
	v_mov_b32_e32 v115, v101
	v_mov_b32_e32 v85, v113
	v_pk_add_f32 v[102:103], v[102:103], v[110:111] neg_lo:[0,1] neg_hi:[0,1]
	v_mov_b32_e32 v110, v88
	v_mov_b32_e32 v111, v83
	v_pk_add_f32 v[84:85], v[114:115], v[84:85] neg_lo:[0,1] neg_hi:[0,1]
	v_pk_add_f32 v[110:111], v[110:111], v[102:103] neg_lo:[0,1] neg_hi:[0,1]
	v_mov_b32_e32 v114, v84
	v_mov_b32_e32 v115, v103
	v_mov_b32_e32 v116, v100
	v_mov_b32_e32 v103, v91
	v_pk_add_f32 v[114:115], v[82:83], v[114:115] neg_lo:[0,1] neg_hi:[0,1]
	v_pk_add_f32 v[102:103], v[116:117], v[102:103] neg_lo:[0,1] neg_hi:[0,1]
	v_mov_b32_e32 v83, v93
	v_pk_add_f32 v[88:89], v[88:89], v[90:91] neg_lo:[0,1] neg_hi:[0,1]
	v_pk_add_f32 v[90:91], v[94:95], v[102:103] neg_lo:[0,1] neg_hi:[0,1]
	v_pk_add_f32 v[82:83], v[82:83], v[84:85] neg_lo:[0,1] neg_hi:[0,1]
	v_pk_add_f32 v[84:85], v[86:87], v[112:113] neg_lo:[0,1] neg_hi:[0,1]
	v_pk_add_f32 v[92:93], v[110:111], v[90:91]
	v_pk_add_f32 v[86:87], v[84:85], v[82:83]
	v_mov_b32_e32 v83, v111
	v_mov_b32_e32 v85, v91
	v_pk_add_f32 v[84:85], v[82:83], v[84:85]
	v_mov_b32_e32 v90, v86
	v_pk_add_f32 v[84:85], v[84:85], v[114:115] neg_lo:[0,1] neg_hi:[0,1]
	v_mov_b32_e32 v91, v93
	v_pk_add_f32 v[88:89], v[98:99], v[88:89] neg_lo:[0,1] neg_hi:[0,1]
	v_pk_add_f32 v[90:91], v[90:91], v[84:85] neg_lo:[0,1] neg_hi:[0,1]
	v_pk_add_f32 v[84:85], v[88:89], v[84:85] neg_lo:[0,1] neg_hi:[0,1]
	v_pk_add_f32 v[82:83], v[82:83], v[90:91] neg_lo:[0,1] neg_hi:[0,1]
	s_nop 0
	v_pk_add_f32 v[82:83], v[84:85], v[82:83]
	v_pk_add_f32 v[84:85], v[92:93], v[86:87]
	s_nop 0
	v_pk_add_f32 v[86:87], v[100:101], v[84:85]
	s_nop 0
	v_pk_add_f32 v[88:89], v[86:87], v[100:101] neg_lo:[0,1] neg_hi:[0,1]
	s_nop 0
	v_pk_add_f32 v[84:85], v[84:85], v[88:89] neg_lo:[0,1] neg_hi:[0,1]
	s_nop 0
	v_pk_add_f32 v[82:83], v[82:83], v[84:85]
	s_nop 0
	v_pk_add_f32 v[82:83], v[86:87], v[82:83]
	s_nop 0
	v_cndmask_b32_e32 v82, v160, v82, vcc
	v_cmp_neq_f32_e32 vcc, s8, v131
	s_nop 1
	v_cndmask_b32_e32 v83, v160, v83, vcc
	v_cmp_ngt_f32_e32 vcc, -1.0, v131
	s_nop 1
	v_cndmask_b32_e32 v83, v161, v83, vcc
	v_cmp_ngt_f32_e32 vcc, -1.0, v129
	s_nop 1
	v_cndmask_b32_e32 v82, v161, v82, vcc
	v_cmp_neq_f32_e32 vcc, -1.0, v129
	s_nop 1
	v_cndmask_b32_e32 v82, v162, v82, vcc
	v_cmp_neq_f32_e32 vcc, -1.0, v131
	s_nop 1
	v_cndmask_b32_e32 v83, v162, v83, vcc
	v_cmp_lt_f32_e64 vcc, |v129|, s9
	v_cndmask_b32_e64 v83, v83, v131, s[0:1]
	s_and_b64 s[0:1], s[60:61], exec
	v_cndmask_b32_e32 v82, v82, v129, vcc
	v_pk_add_f32 v[80:81], v[80:81], v[82:83]
	global_store_dwordx4 v[68:69], v[78:81], off offset:64
	global_load_dwordx4 v[78:81], v0, s[78:79]
	s_cselect_b32 s7, s46, s42
	s_cselect_b32 s6, s43, s59
	s_waitcnt vmcnt(0)
	v_add_f32_e32 v69, v54, v78
	v_min_f32_e32 v68, 0, v69
	v_mul_f32_e64 v69, |v69|, s2
	v_exp_f32_e32 v97, v69
	v_add_f32_e32 v79, v55, v79
	v_add_f32_e32 v81, v57, v81
	v_add_f32_e32 v69, 1.0, v97
	v_add_f32_e32 v78, -1.0, v69
	v_sub_f32_e32 v82, v78, v69
	v_add_f32_e32 v82, 1.0, v82
	v_sub_f32_e32 v78, v97, v78
	v_add_f32_e32 v84, v78, v82
	v_frexp_mant_f32_e32 v78, v69
	v_cvt_f64_f32_e32 v[82:83], v69
	v_cmp_gt_f32_e32 vcc, s26, v78
	v_frexp_exp_i32_f64_e32 v78, v[82:83]
	s_nop 0
	v_subbrev_co_u32_e32 v118, vcc, 0, v78, vcc
	v_sub_u32_e32 v82, 0, v118
	v_ldexp_f32 v78, v69, v82
	v_min_f32_e32 v69, 0, v79
	v_mul_f32_e64 v79, |v79|, s2
	v_exp_f32_e32 v126, v79
	v_ldexp_f32 v82, v84, v82
	v_add_f32_e32 v79, 1.0, v126
	v_add_f32_e32 v83, -1.0, v79
	v_sub_f32_e32 v84, v83, v79
	v_add_f32_e32 v84, 1.0, v84
	v_sub_f32_e32 v83, v126, v83
	v_add_f32_e32 v83, v83, v84
	v_frexp_mant_f32_e32 v84, v79
	v_cmp_gt_f32_e32 vcc, s26, v84
	v_cvt_f64_f32_e32 v[84:85], v79
	v_frexp_exp_i32_f64_e32 v84, v[84:85]
	v_subbrev_co_u32_e32 v119, vcc, 0, v84, vcc
	v_sub_u32_e32 v84, 0, v119
	v_ldexp_f32 v79, v79, v84
	v_ldexp_f32 v83, v83, v84
	v_pk_add_f32 v[84:85], v[78:79], 1.0 op_sel_hi:[1,0]
	v_pk_add_f32 v[92:93], v[78:79], -1.0 op_sel_hi:[1,0]
	v_pk_add_f32 v[86:87], v[84:85], -1.0 op_sel_hi:[1,0]
	v_pk_add_f32 v[94:95], v[92:93], 1.0 op_sel_hi:[1,0]
	v_pk_add_f32 v[86:87], v[78:79], v[86:87] neg_lo:[0,1] neg_hi:[0,1]
	v_pk_add_f32 v[78:79], v[78:79], v[94:95] neg_lo:[0,1] neg_hi:[0,1]
	v_pk_add_f32 v[86:87], v[82:83], v[86:87]
	v_pk_add_f32 v[78:79], v[82:83], v[78:79]
	v_pk_add_f32 v[88:89], v[84:85], v[86:87]
	v_pk_add_f32 v[82:83], v[92:93], v[78:79]
	v_rcp_f32_e32 v90, v88
	v_rcp_f32_e32 v91, v89
	v_pk_add_f32 v[84:85], v[88:89], v[84:85] neg_lo:[0,1] neg_hi:[0,1]
	v_pk_add_f32 v[92:93], v[82:83], v[92:93] neg_lo:[0,1] neg_hi:[0,1]
	v_pk_add_f32 v[84:85], v[86:87], v[84:85] neg_lo:[0,1] neg_hi:[0,1]
	v_pk_mul_f32 v[86:87], v[82:83], v[90:91]
	v_pk_add_f32 v[78:79], v[78:79], v[92:93] neg_lo:[0,1] neg_hi:[0,1]
	v_pk_mul_f32 v[92:93], v[88:89], v[86:87]
	v_cmp_lt_f32_e64 s[0:1], |v126|, s9
	v_pk_fma_f32 v[94:95], v[86:87], v[88:89], v[92:93] neg_lo:[0,0,1] neg_hi:[0,0,1]
	s_nop 0
; __device__ __forceinline__ float softplusf(float x) { return fmaxf(x, 0.f) + log1pf(__expf(-fabsf(x))); }
; __device__ __forceinline__ float logsigf(float x) { return fminf(x, 0.f) - log1pf(__expf(-fabsf(x))); }
; __device__ void phaseA_tile(const Params& p, int l, int mt, int nt, char* smem) {
;     ...
;             for (int i = 0; i < 4; ++i) {
;                 const int rl = wr * 64 + i * 16 + r;
;                 const int row = m0 + rl;
; #pragma unroll
;                 for (int j = 0; j < 2; ++j) {
;                     const int c = j * 16 + g4 * 4;
;                     const float4 db = *(const float4*)(p.dt_bias + l * 32 + c);
;                     const f32x4 v = acc[i][j];
;                     *(float4*)(p.dtb + (size_t)row * 32 + c) =
;                         make_float4(softplusf(v[0] + db.x), softplusf(v[1] + db.y), softplusf(v[2] + db.z), softplusf(v[3] + db.w));
;                 }
;                 {
;                     const int c = g4 * 4;
;                     const float4 fb = *(const float4*)(p.b_f + l * 16 + c);
;                     const f32x4 v = acc[i][2];
;                     float4 lf = make_float4(logsigf(v[0] + fb.x), logsigf(v[1] + fb.y), logsigf(v[2] + fb.z), logsigf(v[3] + fb.w));
;                     float* o = samp ? (p.out + O_LFS + ((size_t)l * TSM + (row - TP)) * 16 + c)
;                                     : (p.out + O_LFP + ((size_t)l * TP + row) * 16 + c);
;                     *(float4*)o = lf;
;                     *(float4*)(lf_s + rl * 16 + c) = lf;
;                 }
	v_pk_fma_f32 v[94:95], v[86:87], v[84:85], v[94:95]
	s_nop 0
	v_pk_add_f32 v[98:99], v[92:93], v[94:95]
	s_nop 0
	v_pk_add_f32 v[100:101], v[82:83], v[98:99] neg_lo:[0,1] neg_hi:[0,1]
	v_pk_add_f32 v[92:93], v[98:99], v[92:93] neg_lo:[0,1] neg_hi:[0,1]
	v_pk_add_f32 v[82:83], v[82:83], v[100:101] neg_lo:[0,1] neg_hi:[0,1]
	s_nop 0
	v_pk_add_f32 v[82:83], v[82:83], v[98:99] neg_lo:[0,1] neg_hi:[0,1]
	s_nop 0
	v_pk_add_f32 v[78:79], v[78:79], v[82:83]
	v_pk_add_f32 v[82:83], v[92:93], v[94:95] neg_lo:[0,1] neg_hi:[0,1]
	s_nop 0
	v_pk_add_f32 v[78:79], v[82:83], v[78:79]
	s_nop 0
	v_pk_add_f32 v[82:83], v[100:101], v[78:79]
	s_nop 0
	v_pk_mul_f32 v[92:93], v[90:91], v[82:83]
	s_nop 0
	v_pk_mul_f32 v[94:95], v[88:89], v[92:93]
	s_nop 0
	v_pk_fma_f32 v[88:89], v[92:93], v[88:89], v[94:95] neg_lo:[0,0,1] neg_hi:[0,0,1]
	s_nop 0
	v_pk_fma_f32 v[84:85], v[92:93], v[84:85], v[88:89]
	v_pk_add_f32 v[88:89], v[100:101], v[82:83] neg_lo:[0,1] neg_hi:[0,1]
	s_nop 0
	v_pk_add_f32 v[78:79], v[78:79], v[88:89]
	v_pk_add_f32 v[88:89], v[94:95], v[84:85]
	s_nop 0
	v_pk_add_f32 v[98:99], v[82:83], v[88:89] neg_lo:[0,1] neg_hi:[0,1]
	v_pk_add_f32 v[94:95], v[88:89], v[94:95] neg_lo:[0,1] neg_hi:[0,1]
	v_pk_add_f32 v[82:83], v[82:83], v[98:99] neg_lo:[0,1] neg_hi:[0,1]
	s_nop 0
	v_pk_add_f32 v[82:83], v[82:83], v[88:89] neg_lo:[0,1] neg_hi:[0,1]
	s_nop 0
	v_pk_add_f32 v[78:79], v[78:79], v[82:83]
	v_pk_add_f32 v[82:83], v[94:95], v[84:85] neg_lo:[0,1] neg_hi:[0,1]
	s_nop 0
	v_pk_add_f32 v[78:79], v[82:83], v[78:79]
	v_pk_add_f32 v[82:83], v[86:87], v[92:93]
	v_pk_add_f32 v[78:79], v[98:99], v[78:79]
	v_pk_add_f32 v[84:85], v[82:83], v[86:87] neg_lo:[0,1] neg_hi:[0,1]
	v_pk_mul_f32 v[78:79], v[90:91], v[78:79]
	v_pk_add_f32 v[84:85], v[92:93], v[84:85] neg_lo:[0,1] neg_hi:[0,1]
	s_nop 0
	v_pk_add_f32 v[78:79], v[84:85], v[78:79]
	s_nop 0
	v_pk_add_f32 v[84:85], v[82:83], v[78:79]
	s_nop 0
	v_pk_add_f32 v[82:83], v[84:85], v[82:83] neg_lo:[0,1] neg_hi:[0,1]
	v_pk_mul_f32 v[88:89], v[84:85], v[84:85]
	v_pk_add_f32 v[78:79], v[78:79], v[82:83] neg_lo:[0,1] neg_hi:[0,1]
	v_pk_fma_f32 v[90:91], v[88:89], s[28:29], v[66:67] op_sel_hi:[1,0,0]
	v_ldexp_f32 v93, v79, 1
	v_add_f32_e32 v79, v56, v80
	v_ldexp_f32 v86, v78, 1
	v_min_f32_e32 v78, 0, v79
	v_mul_f32_e64 v79, |v79|, s2
	v_exp_f32_e32 v127, v79
	v_ldexp_f32 v82, v84, 1
	v_pk_fma_f32 v[90:91], v[88:89], v[90:91], s[30:31] op_sel_hi:[1,1,0]
	v_ldexp_f32 v83, v85, 1
	v_add_f32_e32 v79, 1.0, v127
	v_add_f32_e32 v80, -1.0, v79
	v_sub_f32_e32 v87, v80, v79
	v_add_f32_e32 v87, 1.0, v87
	v_sub_f32_e32 v80, v127, v80
	v_pk_mul_f32 v[84:85], v[84:85], v[88:89]
	v_add_f32_e32 v87, v80, v87
	v_frexp_mant_f32_e32 v80, v79
	v_cvt_f64_f32_e32 v[88:89], v79
	v_cmp_gt_f32_e32 vcc, s26, v80
	v_frexp_exp_i32_f64_e32 v80, v[88:89]
	v_pk_mul_f32 v[84:85], v[84:85], v[90:91]
	v_subbrev_co_u32_e32 v128, vcc, 0, v80, vcc
	v_sub_u32_e32 v88, 0, v128
	v_ldexp_f32 v80, v79, v88
	v_min_f32_e32 v79, 0, v81
	v_mul_f32_e64 v81, |v81|, s2
	v_exp_f32_e32 v129, v81
	v_ldexp_f32 v88, v87, v88
	v_pk_add_f32 v[90:91], v[82:83], v[84:85]
	v_add_f32_e32 v81, 1.0, v129
	v_add_f32_e32 v87, -1.0, v81
	v_sub_f32_e32 v89, v87, v81
	v_add_f32_e32 v89, 1.0, v89
	v_sub_f32_e32 v87, v129, v87
	v_add_f32_e32 v87, v87, v89
	v_frexp_mant_f32_e32 v89, v81
	v_cvt_f64_f32_e32 v[94:95], v81
	v_cmp_gt_f32_e32 vcc, s26, v89
	v_frexp_exp_i32_f64_e32 v89, v[94:95]
	v_pk_add_f32 v[82:83], v[90:91], v[82:83] neg_lo:[0,1] neg_hi:[0,1]
	v_subbrev_co_u32_e32 v130, vcc, 0, v89, vcc
	v_sub_u32_e32 v89, 0, v130
	v_ldexp_f32 v81, v81, v89
	v_pk_add_f32 v[94:95], v[80:81], 1.0 op_sel_hi:[1,0]
	v_ldexp_f32 v89, v87, v89
	v_pk_add_f32 v[98:99], v[94:95], -1.0 op_sel_hi:[1,0]
	v_pk_add_f32 v[110:111], v[80:81], -1.0 op_sel_hi:[1,0]
	v_pk_add_f32 v[98:99], v[80:81], v[98:99] neg_lo:[0,1] neg_hi:[0,1]
	v_pk_add_f32 v[112:113], v[110:111], 1.0 op_sel_hi:[1,0]
	v_pk_add_f32 v[98:99], v[88:89], v[98:99]
	v_pk_add_f32 v[80:81], v[80:81], v[112:113] neg_lo:[0,1] neg_hi:[0,1]
	v_pk_add_f32 v[100:101], v[94:95], v[98:99]
	v_pk_add_f32 v[80:81], v[88:89], v[80:81]
	v_rcp_f32_e32 v102, v100
	v_rcp_f32_e32 v103, v101
	v_pk_add_f32 v[88:89], v[110:111], v[80:81]
	v_pk_add_f32 v[94:95], v[100:101], v[94:95] neg_lo:[0,1] neg_hi:[0,1]
	v_pk_add_f32 v[110:111], v[88:89], v[110:111] neg_lo:[0,1] neg_hi:[0,1]
	v_pk_add_f32 v[94:95], v[98:99], v[94:95] neg_lo:[0,1] neg_hi:[0,1]
	v_pk_mul_f32 v[98:99], v[88:89], v[102:103]
	v_pk_add_f32 v[80:81], v[80:81], v[110:111] neg_lo:[0,1] neg_hi:[0,1]
	v_pk_mul_f32 v[110:111], v[100:101], v[98:99]
	v_pk_add_f32 v[82:83], v[84:85], v[82:83] neg_lo:[0,1] neg_hi:[0,1]
	v_pk_fma_f32 v[112:113], v[98:99], v[100:101], v[110:111] neg_lo:[0,0,1] neg_hi:[0,0,1]
	v_mov_b32_e32 v85, v83
	v_pk_fma_f32 v[112:113], v[98:99], v[94:95], v[112:113]
	v_mov_b32_e32 v87, v93
	v_pk_add_f32 v[114:115], v[110:111], v[112:113]
	v_mov_b32_e32 v122, v90
	v_pk_add_f32 v[116:117], v[88:89], v[114:115] neg_lo:[0,1] neg_hi:[0,1]
	v_pk_add_f32 v[110:111], v[114:115], v[110:111] neg_lo:[0,1] neg_hi:[0,1]
	v_pk_add_f32 v[88:89], v[88:89], v[116:117] neg_lo:[0,1] neg_hi:[0,1]
	v_cmp_neq_f32_e32 vcc, s8, v97
	v_pk_add_f32 v[88:89], v[88:89], v[114:115] neg_lo:[0,1] neg_hi:[0,1]
	s_nop 0
	v_pk_add_f32 v[80:81], v[80:81], v[88:89]
	v_pk_add_f32 v[88:89], v[110:111], v[112:113] neg_lo:[0,1] neg_hi:[0,1]
	s_nop 0
	v_pk_add_f32 v[80:81], v[88:89], v[80:81]
	s_nop 0
	v_pk_add_f32 v[88:89], v[116:117], v[80:81]
	s_nop 0
	v_pk_mul_f32 v[110:111], v[102:103], v[88:89]
	s_nop 0
	v_pk_mul_f32 v[112:113], v[100:101], v[110:111]
	s_nop 0
	v_pk_fma_f32 v[100:101], v[110:111], v[100:101], v[112:113] neg_lo:[0,0,1] neg_hi:[0,0,1]
; __device__ __forceinline__ float softplusf(float x) { return fmaxf(x, 0.f) + log1pf(__expf(-fabsf(x))); }
; __device__ __forceinline__ float logsigf(float x) { return fminf(x, 0.f) - log1pf(__expf(-fabsf(x))); }
; __device__ void phaseA_tile(const Params& p, int l, int mt, int nt, char* smem) {
;     ...
;             for (int i = 0; i < 4; ++i) {
;                 const int rl = wr * 64 + i * 16 + r;
;                 const int row = m0 + rl;
; #pragma unroll
;                 for (int j = 0; j < 2; ++j) {
;                     const int c = j * 16 + g4 * 4;
;                     const float4 db = *(const float4*)(p.dt_bias + l * 32 + c);
;                     const f32x4 v = acc[i][j];
;                     *(float4*)(p.dtb + (size_t)row * 32 + c) =
;                         make_float4(softplusf(v[0] + db.x), softplusf(v[1] + db.y), softplusf(v[2] + db.z), softplusf(v[3] + db.w));
;                 }
;                 {
;                     const int c = g4 * 4;
;                     const float4 fb = *(const float4*)(p.b_f + l * 16 + c);
;                     const f32x4 v = acc[i][2];
;                     float4 lf = make_float4(logsigf(v[0] + fb.x), logsigf(v[1] + fb.y), logsigf(v[2] + fb.z), logsigf(v[3] + fb.w));
;                     float* o = samp ? (p.out + O_LFS + ((size_t)l * TSM + (row - TP)) * 16 + c)
;                                     : (p.out + O_LFP + ((size_t)l * TP + row) * 16 + c);
;                     *(float4*)o = lf;
;                     *(float4*)(lf_s + rl * 16 + c) = lf;
;                 }
	s_nop 0
	v_pk_fma_f32 v[94:95], v[110:111], v[94:95], v[100:101]
	v_pk_add_f32 v[100:101], v[116:117], v[88:89] neg_lo:[0,1] neg_hi:[0,1]
	s_nop 0
	v_pk_add_f32 v[80:81], v[80:81], v[100:101]
	v_pk_add_f32 v[100:101], v[112:113], v[94:95]
	s_nop 0
	v_pk_add_f32 v[114:115], v[88:89], v[100:101] neg_lo:[0,1] neg_hi:[0,1]
	v_pk_add_f32 v[112:113], v[100:101], v[112:113] neg_lo:[0,1] neg_hi:[0,1]
	v_pk_add_f32 v[88:89], v[88:89], v[114:115] neg_lo:[0,1] neg_hi:[0,1]
	s_nop 0
	v_pk_add_f32 v[88:89], v[88:89], v[100:101] neg_lo:[0,1] neg_hi:[0,1]
	s_nop 0
	v_pk_add_f32 v[80:81], v[80:81], v[88:89]
	v_pk_add_f32 v[88:89], v[112:113], v[94:95] neg_lo:[0,1] neg_hi:[0,1]
	s_nop 0
	v_pk_add_f32 v[80:81], v[88:89], v[80:81]
	v_pk_add_f32 v[88:89], v[98:99], v[110:111]
	v_pk_add_f32 v[80:81], v[114:115], v[80:81]
	v_pk_add_f32 v[94:95], v[88:89], v[98:99] neg_lo:[0,1] neg_hi:[0,1]
	v_pk_mul_f32 v[80:81], v[102:103], v[80:81]
	v_pk_add_f32 v[94:95], v[110:111], v[94:95] neg_lo:[0,1] neg_hi:[0,1]
	s_nop 0
	v_pk_add_f32 v[80:81], v[94:95], v[80:81]
	s_nop 0
	v_pk_add_f32 v[94:95], v[88:89], v[80:81]
	s_nop 0
	v_pk_add_f32 v[88:89], v[94:95], v[88:89] neg_lo:[0,1] neg_hi:[0,1]
	v_pk_mul_f32 v[100:101], v[94:95], v[94:95]
	v_pk_add_f32 v[80:81], v[80:81], v[88:89] neg_lo:[0,1] neg_hi:[0,1]
	v_pk_fma_f32 v[102:103], v[100:101], s[28:29], v[66:67] op_sel_hi:[1,0,0]
	v_ldexp_f32 v98, v80, 1
	v_add_u32_e32 v80, 0xffff8000, v76
	v_ldexp_f32 v111, v81, 1
	v_ashrrev_i32_e32 v81, 31, v80
	v_cndmask_b32_e64 v77, v77, v81, s[60:61]
	v_cndmask_b32_e64 v76, v76, v80, s[60:61]
	v_cvt_f32_i32_e32 v81, v119
	v_cvt_f32_i32_e32 v80, v118
	v_ldexp_f32 v88, v94, 1
	v_pk_fma_f32 v[102:103], v[100:101], v[102:103], s[30:31] op_sel_hi:[1,1,0]
	v_ldexp_f32 v89, v95, 1
	v_pk_mul_f32 v[94:95], v[94:95], v[100:101]
	v_pk_mul_f32 v[100:101], v[80:81], s[12:13] op_sel_hi:[1,0]
	v_mov_b32_e32 v99, v111
	v_pk_fma_f32 v[112:113], v[80:81], s[12:13], v[100:101] op_sel_hi:[1,0,1] neg_lo:[0,0,1] neg_hi:[0,0,1]
	v_mov_b32_e32 v84, v100
	v_pk_fma_f32 v[80:81], v[80:81], s[14:15], v[112:113] op_sel_hi:[1,0,1]
	v_mov_b32_e32 v119, v101
	v_mov_b32_e32 v92, v80
	v_pk_add_f32 v[84:85], v[84:85], v[92:93]
	v_pk_add_f32 v[92:93], v[86:87], v[82:83]
	v_mov_b32_e32 v83, v91
	v_mov_b32_e32 v87, v93
	v_pk_add_f32 v[112:113], v[100:101], v[80:81]
	v_pk_add_f32 v[82:83], v[86:87], v[82:83]
	v_pk_add_f32 v[86:87], v[90:91], v[92:93]
	v_mov_b32_e32 v123, v113
	v_pk_add_f32 v[114:115], v[112:113], v[86:87]
	v_mov_b32_e32 v120, v86
	v_mov_b32_e32 v121, v115
	v_pk_add_f32 v[120:121], v[120:121], v[122:123] neg_lo:[0,1] neg_hi:[0,1]
	v_mov_b32_e32 v116, v114
	v_mov_b32_e32 v117, v113
	v_mov_b32_e32 v118, v112
	v_mov_b32_e32 v122, v112
	v_mov_b32_e32 v123, v115
	v_mov_b32_e32 v101, v121
	v_pk_add_f32 v[116:117], v[116:117], v[118:119] neg_lo:[0,1] neg_hi:[0,1]
	v_mov_b32_e32 v118, v86
	v_mov_b32_e32 v119, v81
	v_pk_add_f32 v[100:101], v[122:123], v[100:101] neg_lo:[0,1] neg_hi:[0,1]
	v_pk_add_f32 v[118:119], v[118:119], v[116:117] neg_lo:[0,1] neg_hi:[0,1]
	v_mov_b32_e32 v122, v100
	v_mov_b32_e32 v123, v117
	v_mov_b32_e32 v124, v114
	v_mov_b32_e32 v125, v87
	v_mov_b32_e32 v117, v91
	v_pk_add_f32 v[122:123], v[80:81], v[122:123] neg_lo:[0,1] neg_hi:[0,1]
	v_pk_add_f32 v[116:117], v[124:125], v[116:117] neg_lo:[0,1] neg_hi:[0,1]
	v_mov_b32_e32 v81, v113
	v_pk_add_f32 v[84:85], v[84:85], v[116:117] neg_lo:[0,1] neg_hi:[0,1]
	v_pk_add_f32 v[80:81], v[80:81], v[100:101] neg_lo:[0,1] neg_hi:[0,1]
	v_pk_add_f32 v[82:83], v[82:83], v[120:121] neg_lo:[0,1] neg_hi:[0,1]
	v_pk_add_f32 v[86:87], v[86:87], v[90:91] neg_lo:[0,1] neg_hi:[0,1]
	v_pk_add_f32 v[90:91], v[82:83], v[80:81]
	v_mov_b32_e32 v81, v119
	v_mov_b32_e32 v83, v85
	v_pk_add_f32 v[86:87], v[92:93], v[86:87] neg_lo:[0,1] neg_hi:[0,1]
	v_pk_add_f32 v[92:93], v[118:119], v[84:85]
	v_pk_add_f32 v[82:83], v[80:81], v[82:83]
	v_mov_b32_e32 v84, v90
	v_pk_add_f32 v[82:83], v[82:83], v[122:123] neg_lo:[0,1] neg_hi:[0,1]
	v_mov_b32_e32 v85, v93
	v_pk_add_f32 v[84:85], v[84:85], v[82:83] neg_lo:[0,1] neg_hi:[0,1]
	v_pk_add_f32 v[82:83], v[86:87], v[82:83] neg_lo:[0,1] neg_hi:[0,1]
	v_pk_add_f32 v[80:81], v[80:81], v[84:85] neg_lo:[0,1] neg_hi:[0,1]
	v_lshlrev_b64 v[76:77], 6, v[76:77]
	v_pk_add_f32 v[80:81], v[82:83], v[80:81]
	v_pk_add_f32 v[82:83], v[92:93], v[90:91]
	v_lshl_add_u64 v[76:77], s[6:7], 0, v[76:77]
	v_pk_add_f32 v[84:85], v[114:115], v[82:83]
	v_lshl_add_u64 v[76:77], v[76:77], 0, v[0:1]
	v_pk_add_f32 v[86:87], v[84:85], v[114:115] neg_lo:[0,1] neg_hi:[0,1]
	s_nop 0
	v_pk_add_f32 v[82:83], v[82:83], v[86:87] neg_lo:[0,1] neg_hi:[0,1]
	s_nop 0
	v_pk_add_f32 v[80:81], v[80:81], v[82:83]
	s_nop 0
	v_pk_add_f32 v[80:81], v[84:85], v[80:81]
	v_pk_mul_f32 v[84:85], v[94:95], v[102:103]
	v_cndmask_b32_e32 v80, v160, v80, vcc
	v_cmp_neq_f32_e32 vcc, s8, v126
	v_pk_add_f32 v[86:87], v[88:89], v[84:85]
	s_nop 0
	v_cndmask_b32_e32 v81, v160, v81, vcc
	v_cmp_ngt_f32_e32 vcc, -1.0, v126
	v_pk_add_f32 v[88:89], v[86:87], v[88:89] neg_lo:[0,1] neg_hi:[0,1]
	v_mov_b32_e32 v112, v86
	v_cndmask_b32_e32 v81, v161, v81, vcc
	v_cmp_ngt_f32_e32 vcc, -1.0, v97
	v_pk_add_f32 v[84:85], v[84:85], v[88:89] neg_lo:[0,1] neg_hi:[0,1]
	s_nop 0
	v_cndmask_b32_e32 v80, v161, v80, vcc
	v_cmp_neq_f32_e32 vcc, -1.0, v97
	v_pk_add_f32 v[92:93], v[98:99], v[84:85]
	v_mov_b32_e32 v89, v85
	v_cndmask_b32_e32 v80, v162, v80, vcc
	v_cmp_neq_f32_e32 vcc, -1.0, v126
	v_mov_b32_e32 v99, v93
	v_mov_b32_e32 v85, v87
	v_cndmask_b32_e32 v81, v162, v81, vcc
	v_cmp_lt_f32_e64 vcc, |v97|, s9
	v_cndmask_b32_e64 v81, v81, v126, s[0:1]
	v_pk_add_f32 v[94:95], v[86:87], v[92:93]
	v_cndmask_b32_e32 v80, v80, v97, vcc
; __device__ __forceinline__ float softplusf(float x) { return fmaxf(x, 0.f) + log1pf(__expf(-fabsf(x))); }
; __device__ __forceinline__ float logsigf(float x) { return fminf(x, 0.f) - log1pf(__expf(-fabsf(x))); }
; __device__ void phaseA_tile(const Params& p, int l, int mt, int nt, char* smem) {
;     ...
;             for (int i = 0; i < 4; ++i) {
;                 const int rl = wr * 64 + i * 16 + r;
;                 const int row = m0 + rl;
; #pragma unroll
;                 for (int j = 0; j < 2; ++j) {
;                     const int c = j * 16 + g4 * 4;
;                     const float4 db = *(const float4*)(p.dt_bias + l * 32 + c);
;                     const f32x4 v = acc[i][j];
;                     *(float4*)(p.dtb + (size_t)row * 32 + c) =
;                         make_float4(softplusf(v[0] + db.x), softplusf(v[1] + db.y), softplusf(v[2] + db.z), softplusf(v[3] + db.w));
;                 }
;                 {
;                     const int c = g4 * 4;
;                     const float4 fb = *(const float4*)(p.b_f + l * 16 + c);
;                     const f32x4 v = acc[i][2];
;                     float4 lf = make_float4(logsigf(v[0] + fb.x), logsigf(v[1] + fb.y), logsigf(v[2] + fb.z), logsigf(v[3] + fb.w));
;                     float* o = samp ? (p.out + O_LFS + ((size_t)l * TSM + (row - TP)) * 16 + c)
;                                     : (p.out + O_LFP + ((size_t)l * TP + row) * 16 + c);
;                     *(float4*)o = lf;
;                     *(float4*)(lf_s + rl * 16 + c) = lf;
;                 }
	v_pk_add_f32 v[80:81], v[68:69], v[80:81] neg_lo:[0,1] neg_hi:[0,1]
	v_cvt_f32_i32_e32 v69, v130
	v_cvt_f32_i32_e32 v68, v128
	v_pk_add_f32 v[84:85], v[98:99], v[84:85]
	v_mov_b32_e32 v115, v95
	v_cmp_neq_f32_e32 vcc, s8, v127
	v_pk_mul_f32 v[82:83], v[68:69], s[12:13] op_sel_hi:[1,0]
	v_cmp_lt_f32_e64 s[0:1], |v129|, s9
	v_pk_fma_f32 v[90:91], v[68:69], s[12:13], v[82:83] op_sel_hi:[1,0,1] neg_lo:[0,0,1] neg_hi:[0,0,1]
	v_mov_b32_e32 v88, v82
	v_pk_fma_f32 v[68:69], v[68:69], s[14:15], v[90:91] op_sel_hi:[1,0,1]
	v_mov_b32_e32 v103, v83
	v_pk_add_f32 v[90:91], v[82:83], v[68:69]
	v_mov_b32_e32 v110, v68
	v_pk_add_f32 v[98:99], v[90:91], v[94:95]
	v_pk_add_f32 v[88:89], v[88:89], v[110:111]
	v_mov_b32_e32 v110, v94
	v_mov_b32_e32 v111, v99
	v_mov_b32_e32 v113, v91
	v_pk_add_f32 v[110:111], v[110:111], v[112:113] neg_lo:[0,1] neg_hi:[0,1]
	v_mov_b32_e32 v100, v98
	v_mov_b32_e32 v101, v91
	v_mov_b32_e32 v102, v90
	v_mov_b32_e32 v112, v90
	v_mov_b32_e32 v113, v99
	v_mov_b32_e32 v83, v111
	v_pk_add_f32 v[100:101], v[100:101], v[102:103] neg_lo:[0,1] neg_hi:[0,1]
	v_mov_b32_e32 v102, v94
	v_mov_b32_e32 v103, v69
	v_pk_add_f32 v[82:83], v[112:113], v[82:83] neg_lo:[0,1] neg_hi:[0,1]
	v_pk_add_f32 v[102:103], v[102:103], v[100:101] neg_lo:[0,1] neg_hi:[0,1]
	v_mov_b32_e32 v112, v82
	v_mov_b32_e32 v113, v101
	v_mov_b32_e32 v114, v98
	v_mov_b32_e32 v101, v87
	v_pk_add_f32 v[112:113], v[68:69], v[112:113] neg_lo:[0,1] neg_hi:[0,1]
	v_pk_add_f32 v[100:101], v[114:115], v[100:101] neg_lo:[0,1] neg_hi:[0,1]
	v_mov_b32_e32 v69, v91
	v_pk_add_f32 v[88:89], v[88:89], v[100:101] neg_lo:[0,1] neg_hi:[0,1]
	v_pk_add_f32 v[68:69], v[68:69], v[82:83] neg_lo:[0,1] neg_hi:[0,1]
	v_pk_add_f32 v[82:83], v[84:85], v[110:111] neg_lo:[0,1] neg_hi:[0,1]
	v_pk_add_f32 v[90:91], v[102:103], v[88:89]
	v_pk_add_f32 v[84:85], v[82:83], v[68:69]
	v_mov_b32_e32 v69, v103
	v_mov_b32_e32 v83, v89
	v_pk_add_f32 v[82:83], v[68:69], v[82:83]
	v_pk_add_f32 v[86:87], v[94:95], v[86:87] neg_lo:[0,1] neg_hi:[0,1]
	v_pk_add_f32 v[82:83], v[82:83], v[112:113] neg_lo:[0,1] neg_hi:[0,1]
	v_mov_b32_e32 v88, v84
	v_mov_b32_e32 v89, v91
	v_pk_add_f32 v[86:87], v[92:93], v[86:87] neg_lo:[0,1] neg_hi:[0,1]
	v_pk_add_f32 v[88:89], v[88:89], v[82:83] neg_lo:[0,1] neg_hi:[0,1]
	v_pk_add_f32 v[82:83], v[86:87], v[82:83] neg_lo:[0,1] neg_hi:[0,1]
	v_pk_add_f32 v[68:69], v[68:69], v[88:89] neg_lo:[0,1] neg_hi:[0,1]
	s_nop 0
	v_pk_add_f32 v[68:69], v[82:83], v[68:69]
	v_pk_add_f32 v[82:83], v[90:91], v[84:85]
	s_nop 0
	v_pk_add_f32 v[84:85], v[98:99], v[82:83]
	s_nop 0
	v_pk_add_f32 v[86:87], v[84:85], v[98:99] neg_lo:[0,1] neg_hi:[0,1]
	s_nop 0
	v_pk_add_f32 v[82:83], v[82:83], v[86:87] neg_lo:[0,1] neg_hi:[0,1]
	s_nop 0
	v_pk_add_f32 v[68:69], v[68:69], v[82:83]
	s_nop 0
	v_pk_add_f32 v[68:69], v[84:85], v[68:69]
	s_nop 0
	v_cndmask_b32_e32 v68, v160, v68, vcc
	v_cmp_neq_f32_e32 vcc, s8, v129
	s_nop 1
	v_cndmask_b32_e32 v69, v160, v69, vcc
	v_cmp_ngt_f32_e32 vcc, -1.0, v129
	s_nop 1
	v_cndmask_b32_e32 v69, v161, v69, vcc
	v_cmp_ngt_f32_e32 vcc, -1.0, v127
	s_nop 1
	v_cndmask_b32_e32 v68, v161, v68, vcc
	v_cmp_neq_f32_e32 vcc, -1.0, v127
	s_nop 1
	v_cndmask_b32_e32 v68, v162, v68, vcc
	v_cmp_neq_f32_e32 vcc, -1.0, v129
	s_nop 1
	v_cndmask_b32_e32 v69, v162, v69, vcc
	v_cmp_lt_f32_e64 vcc, |v127|, s9
	v_cndmask_b32_e64 v69, v69, v129, s[0:1]
	s_nop 0
	v_cndmask_b32_e32 v68, v68, v127, vcc
	v_pk_add_f32 v[82:83], v[78:79], v[68:69] neg_lo:[0,1] neg_hi:[0,1]
	global_store_dwordx4 v[76:77], v[80:83], off
	v_lshl_or_b32 v68, v71, 6, v0
	ds_write_b128 v68, v[80:83]
	global_load_dwordx4 v[78:81], v0, s[74:75]
	v_or_b32_e32 v82, 16, v71
	v_add_u32_e32 v68, s54, v82
	v_ashrrev_i32_e32 v69, 31, v68
	v_lshlrev_b64 v[76:77], 7, v[68:69]
	v_lshl_add_u64 v[76:77], s[10:11], 0, v[76:77]
	v_lshl_add_u64 v[76:77], v[76:77], 0, v[0:1]
	s_waitcnt vmcnt(0)
	v_add_f32_e32 v83, v46, v78
	v_max_f32_e32 v78, 0, v83
	v_mul_f32_e64 v83, |v83|, s2
	v_exp_f32_e32 v83, v83
	s_nop 0
	v_add_f32_e32 v86, 1.0, v83
	v_add_f32_e32 v84, -1.0, v86
	v_sub_f32_e32 v85, v84, v86
	v_add_f32_e32 v85, 1.0, v85
	v_sub_f32_e32 v84, v83, v84
	v_add_f32_e32 v87, v84, v85
	v_frexp_mant_f32_e32 v84, v86
	v_cmp_gt_f32_e32 vcc, s26, v84
	v_cvt_f64_f32_e32 v[84:85], v86
	v_frexp_exp_i32_f64_e32 v84, v[84:85]
	v_subbrev_co_u32_e32 v97, vcc, 0, v84, vcc
	v_sub_u32_e32 v85, 0, v97
	v_ldexp_f32 v84, v86, v85
	v_ldexp_f32 v86, v87, v85
	v_add_f32_e32 v85, v47, v79
	v_max_f32_e32 v79, 0, v85
	v_mul_f32_e64 v85, |v85|, s2
	v_exp_f32_e32 v130, v85
	s_nop 0
	v_add_f32_e32 v85, 1.0, v130
	v_add_f32_e32 v87, -1.0, v85
	v_sub_f32_e32 v88, v87, v85
	v_add_f32_e32 v88, 1.0, v88
	v_sub_f32_e32 v87, v130, v87
	v_add_f32_e32 v87, v87, v88
	v_frexp_mant_f32_e32 v88, v85
	v_cmp_gt_f32_e32 vcc, s26, v88
	v_cvt_f64_f32_e32 v[88:89], v85
	v_frexp_exp_i32_f64_e32 v88, v[88:89]
	v_subbrev_co_u32_e32 v122, vcc, 0, v88, vcc
	v_sub_u32_e32 v88, 0, v122
	v_ldexp_f32 v85, v85, v88
	v_ldexp_f32 v87, v87, v88
	v_pk_add_f32 v[88:89], v[84:85], 1.0 op_sel_hi:[1,0]
	v_pk_add_f32 v[98:99], v[84:85], -1.0 op_sel_hi:[1,0]
	v_pk_add_f32 v[90:91], v[88:89], -1.0 op_sel_hi:[1,0]
	v_pk_add_f32 v[100:101], v[98:99], 1.0 op_sel_hi:[1,0]
	v_pk_add_f32 v[90:91], v[84:85], v[90:91] neg_lo:[0,1] neg_hi:[0,1]
	v_pk_add_f32 v[84:85], v[84:85], v[100:101] neg_lo:[0,1] neg_hi:[0,1]
	v_pk_add_f32 v[90:91], v[86:87], v[90:91]
	v_pk_add_f32 v[84:85], v[86:87], v[84:85]
	v_pk_add_f32 v[92:93], v[88:89], v[90:91]
	v_pk_add_f32 v[86:87], v[98:99], v[84:85]
	v_rcp_f32_e32 v94, v92
	v_rcp_f32_e32 v95, v93
	v_pk_add_f32 v[88:89], v[92:93], v[88:89] neg_lo:[0,1] neg_hi:[0,1]
; __device__ __forceinline__ float softplusf(float x) { return fmaxf(x, 0.f) + log1pf(__expf(-fabsf(x))); }
; __device__ void phaseA_tile(const Params& p, int l, int mt, int nt, char* smem) {
;     ...
;             for (int i = 0; i < 4; ++i) {
;                 const int rl = wr * 64 + i * 16 + r;
;                 const int row = m0 + rl;
; #pragma unroll
;                 for (int j = 0; j < 2; ++j) {
;                     const int c = j * 16 + g4 * 4;
;                     const float4 db = *(const float4*)(p.dt_bias + l * 32 + c);
;                     const f32x4 v = acc[i][j];
;                     *(float4*)(p.dtb + (size_t)row * 32 + c) =
;                         make_float4(softplusf(v[0] + db.x), softplusf(v[1] + db.y), softplusf(v[2] + db.z), softplusf(v[3] + db.w));
;                 }
	v_pk_add_f32 v[98:99], v[86:87], v[98:99] neg_lo:[0,1] neg_hi:[0,1]
	v_pk_add_f32 v[88:89], v[90:91], v[88:89] neg_lo:[0,1] neg_hi:[0,1]
	v_pk_mul_f32 v[90:91], v[86:87], v[94:95]
	v_pk_add_f32 v[84:85], v[84:85], v[98:99] neg_lo:[0,1] neg_hi:[0,1]
	v_pk_mul_f32 v[98:99], v[92:93], v[90:91]
	v_cmp_lt_f32_e64 s[0:1], |v130|, s9
	v_pk_fma_f32 v[100:101], v[90:91], v[92:93], v[98:99] neg_lo:[0,0,1] neg_hi:[0,0,1]
	s_nop 0
	v_pk_fma_f32 v[100:101], v[90:91], v[88:89], v[100:101]
	s_nop 0
	v_pk_add_f32 v[102:103], v[98:99], v[100:101]
	s_nop 0
	v_pk_add_f32 v[110:111], v[86:87], v[102:103] neg_lo:[0,1] neg_hi:[0,1]
	v_pk_add_f32 v[98:99], v[102:103], v[98:99] neg_lo:[0,1] neg_hi:[0,1]
	v_pk_add_f32 v[86:87], v[86:87], v[110:111] neg_lo:[0,1] neg_hi:[0,1]
	s_nop 0
	v_pk_add_f32 v[86:87], v[86:87], v[102:103] neg_lo:[0,1] neg_hi:[0,1]
	s_nop 0
	v_pk_add_f32 v[84:85], v[84:85], v[86:87]
	v_pk_add_f32 v[86:87], v[98:99], v[100:101] neg_lo:[0,1] neg_hi:[0,1]
	s_nop 0
	v_pk_add_f32 v[84:85], v[86:87], v[84:85]
	s_nop 0
	v_pk_add_f32 v[86:87], v[110:111], v[84:85]
	s_nop 0
	v_pk_mul_f32 v[98:99], v[94:95], v[86:87]
	s_nop 0
	v_pk_mul_f32 v[100:101], v[92:93], v[98:99]
	s_nop 0
	v_pk_fma_f32 v[92:93], v[98:99], v[92:93], v[100:101] neg_lo:[0,0,1] neg_hi:[0,0,1]
	s_nop 0
	v_pk_fma_f32 v[88:89], v[98:99], v[88:89], v[92:93]
	v_pk_add_f32 v[92:93], v[110:111], v[86:87] neg_lo:[0,1] neg_hi:[0,1]
	s_nop 0
	v_pk_add_f32 v[84:85], v[84:85], v[92:93]
	v_pk_add_f32 v[92:93], v[100:101], v[88:89]
	s_nop 0
	v_pk_add_f32 v[102:103], v[86:87], v[92:93] neg_lo:[0,1] neg_hi:[0,1]
	v_pk_add_f32 v[100:101], v[92:93], v[100:101] neg_lo:[0,1] neg_hi:[0,1]
	v_pk_add_f32 v[86:87], v[86:87], v[102:103] neg_lo:[0,1] neg_hi:[0,1]
	s_nop 0
	v_pk_add_f32 v[86:87], v[86:87], v[92:93] neg_lo:[0,1] neg_hi:[0,1]
	s_nop 0
	v_pk_add_f32 v[84:85], v[84:85], v[86:87]
	v_pk_add_f32 v[86:87], v[100:101], v[88:89] neg_lo:[0,1] neg_hi:[0,1]
	s_nop 0
	v_pk_add_f32 v[84:85], v[86:87], v[84:85]
	v_pk_add_f32 v[86:87], v[90:91], v[98:99]
	v_pk_add_f32 v[84:85], v[102:103], v[84:85]
	v_pk_add_f32 v[88:89], v[86:87], v[90:91] neg_lo:[0,1] neg_hi:[0,1]
	v_pk_mul_f32 v[84:85], v[94:95], v[84:85]
	v_pk_add_f32 v[88:89], v[98:99], v[88:89] neg_lo:[0,1] neg_hi:[0,1]
	s_nop 0
	v_pk_add_f32 v[84:85], v[88:89], v[84:85]
	s_nop 0
	v_pk_add_f32 v[88:89], v[86:87], v[84:85]
	s_nop 0
	v_pk_add_f32 v[86:87], v[88:89], v[86:87] neg_lo:[0,1] neg_hi:[0,1]
	v_pk_mul_f32 v[90:91], v[88:89], v[88:89]
	v_pk_add_f32 v[84:85], v[84:85], v[86:87] neg_lo:[0,1] neg_hi:[0,1]
	v_pk_fma_f32 v[92:93], v[90:91], s[28:29], v[66:67] op_sel_hi:[1,0,0]
	v_ldexp_f32 v95, v85, 1
	v_add_f32_e32 v85, v48, v80
	v_max_f32_e32 v80, 0, v85
	v_mul_f32_e64 v85, |v85|, s2
	v_exp_f32_e32 v131, v85
	v_ldexp_f32 v86, v88, 1
	v_pk_fma_f32 v[92:93], v[90:91], v[92:93], s[30:31] op_sel_hi:[1,1,0]
	v_ldexp_f32 v87, v89, 1
	v_add_f32_e32 v85, 1.0, v131
	v_pk_mul_f32 v[88:89], v[88:89], v[90:91]
	v_add_f32_e32 v90, -1.0, v85
	v_sub_f32_e32 v91, v90, v85
	v_add_f32_e32 v91, 1.0, v91
	v_sub_f32_e32 v90, v131, v90
	v_add_f32_e32 v94, v90, v91
	v_frexp_mant_f32_e32 v90, v85
	v_cmp_gt_f32_e32 vcc, s26, v90
	v_cvt_f64_f32_e32 v[90:91], v85
	v_frexp_exp_i32_f64_e32 v90, v[90:91]
	v_subbrev_co_u32_e32 v132, vcc, 0, v90, vcc
	v_sub_u32_e32 v91, 0, v132
	v_ldexp_f32 v90, v85, v91
	v_add_f32_e32 v85, v49, v81
	v_max_f32_e32 v81, 0, v85
	v_mul_f32_e64 v85, |v85|, s2
	v_exp_f32_e32 v133, v85
	v_ldexp_f32 v98, v94, v91
	v_pk_mul_f32 v[88:89], v[88:89], v[92:93]
	v_ldexp_f32 v84, v84, 1
	v_add_f32_e32 v85, 1.0, v133
	v_add_f32_e32 v91, -1.0, v85
	v_sub_f32_e32 v94, v91, v85
	v_add_f32_e32 v94, 1.0, v94
	v_sub_f32_e32 v91, v133, v91
	v_add_f32_e32 v94, v91, v94
	v_frexp_mant_f32_e32 v91, v85
	v_cvt_f64_f32_e32 v[100:101], v85
	v_cmp_gt_f32_e32 vcc, s26, v91
	v_frexp_exp_i32_f64_e32 v91, v[100:101]
	v_pk_add_f32 v[92:93], v[86:87], v[88:89]
	v_subbrev_co_u32_e32 v134, vcc, 0, v91, vcc
	v_sub_u32_e32 v99, 0, v134
	v_ldexp_f32 v91, v85, v99
	v_pk_add_f32 v[100:101], v[90:91], 1.0 op_sel_hi:[1,0]
	v_ldexp_f32 v99, v94, v99
	v_pk_add_f32 v[102:103], v[100:101], -1.0 op_sel_hi:[1,0]
	v_pk_add_f32 v[114:115], v[90:91], -1.0 op_sel_hi:[1,0]
	v_pk_add_f32 v[102:103], v[90:91], v[102:103] neg_lo:[0,1] neg_hi:[0,1]
	v_pk_add_f32 v[116:117], v[114:115], 1.0 op_sel_hi:[1,0]
	v_pk_add_f32 v[102:103], v[98:99], v[102:103]
	v_pk_add_f32 v[90:91], v[90:91], v[116:117] neg_lo:[0,1] neg_hi:[0,1]
	v_pk_add_f32 v[110:111], v[100:101], v[102:103]
	v_pk_add_f32 v[90:91], v[98:99], v[90:91]
	v_rcp_f32_e32 v112, v110
	v_rcp_f32_e32 v113, v111
	v_pk_add_f32 v[98:99], v[114:115], v[90:91]
	v_pk_add_f32 v[100:101], v[110:111], v[100:101] neg_lo:[0,1] neg_hi:[0,1]
	v_pk_add_f32 v[114:115], v[98:99], v[114:115] neg_lo:[0,1] neg_hi:[0,1]
	v_pk_add_f32 v[100:101], v[102:103], v[100:101] neg_lo:[0,1] neg_hi:[0,1]
	v_pk_mul_f32 v[102:103], v[98:99], v[112:113]
	v_pk_add_f32 v[90:91], v[90:91], v[114:115] neg_lo:[0,1] neg_hi:[0,1]
	v_pk_mul_f32 v[114:115], v[110:111], v[102:103]
	v_pk_add_f32 v[86:87], v[92:93], v[86:87] neg_lo:[0,1] neg_hi:[0,1]
	v_pk_fma_f32 v[116:117], v[102:103], v[110:111], v[114:115] neg_lo:[0,0,1] neg_hi:[0,0,1]
	v_pk_add_f32 v[86:87], v[88:89], v[86:87] neg_lo:[0,1] neg_hi:[0,1]
	v_pk_fma_f32 v[116:117], v[102:103], v[100:101], v[116:117]
	v_mov_b32_e32 v89, v87
	v_pk_add_f32 v[118:119], v[114:115], v[116:117]
	v_mov_b32_e32 v85, v95
	v_pk_add_f32 v[120:121], v[98:99], v[118:119] neg_lo:[0,1] neg_hi:[0,1]
	v_pk_add_f32 v[114:115], v[118:119], v[114:115] neg_lo:[0,1] neg_hi:[0,1]
	v_pk_add_f32 v[98:99], v[98:99], v[120:121] neg_lo:[0,1] neg_hi:[0,1]
	v_mov_b32_e32 v126, v92
; __device__ __forceinline__ float softplusf(float x) { return fmaxf(x, 0.f) + log1pf(__expf(-fabsf(x))); }
; __device__ void phaseA_tile(const Params& p, int l, int mt, int nt, char* smem) {
;     ...
;             for (int i = 0; i < 4; ++i) {
;                 const int rl = wr * 64 + i * 16 + r;
;                 const int row = m0 + rl;
; #pragma unroll
;                 for (int j = 0; j < 2; ++j) {
;                     const int c = j * 16 + g4 * 4;
;                     const float4 db = *(const float4*)(p.dt_bias + l * 32 + c);
;                     const f32x4 v = acc[i][j];
;                     *(float4*)(p.dtb + (size_t)row * 32 + c) =
;                         make_float4(softplusf(v[0] + db.x), softplusf(v[1] + db.y), softplusf(v[2] + db.z), softplusf(v[3] + db.w));
;                 }
	v_pk_add_f32 v[98:99], v[98:99], v[118:119] neg_lo:[0,1] neg_hi:[0,1]
	v_cmp_neq_f32_e32 vcc, s8, v83
	v_pk_add_f32 v[90:91], v[90:91], v[98:99]
	v_pk_add_f32 v[98:99], v[114:115], v[116:117] neg_lo:[0,1] neg_hi:[0,1]
	s_nop 0
	v_pk_add_f32 v[90:91], v[98:99], v[90:91]
	s_nop 0
	v_pk_add_f32 v[98:99], v[120:121], v[90:91]
	s_nop 0
	v_pk_mul_f32 v[114:115], v[112:113], v[98:99]
	s_nop 0
	v_pk_mul_f32 v[116:117], v[110:111], v[114:115]
	s_nop 0
	v_pk_fma_f32 v[110:111], v[114:115], v[110:111], v[116:117] neg_lo:[0,0,1] neg_hi:[0,0,1]
	s_nop 0
	v_pk_fma_f32 v[100:101], v[114:115], v[100:101], v[110:111]
	v_pk_add_f32 v[110:111], v[120:121], v[98:99] neg_lo:[0,1] neg_hi:[0,1]
	s_nop 0
	v_pk_add_f32 v[90:91], v[90:91], v[110:111]
	v_pk_add_f32 v[110:111], v[116:117], v[100:101]
	s_nop 0
	v_pk_add_f32 v[118:119], v[98:99], v[110:111] neg_lo:[0,1] neg_hi:[0,1]
	v_pk_add_f32 v[116:117], v[110:111], v[116:117] neg_lo:[0,1] neg_hi:[0,1]
	v_pk_add_f32 v[98:99], v[98:99], v[118:119] neg_lo:[0,1] neg_hi:[0,1]
	s_nop 0
	v_pk_add_f32 v[98:99], v[98:99], v[110:111] neg_lo:[0,1] neg_hi:[0,1]
	s_nop 0
	v_pk_add_f32 v[90:91], v[90:91], v[98:99]
	v_pk_add_f32 v[98:99], v[116:117], v[100:101] neg_lo:[0,1] neg_hi:[0,1]
	s_nop 0
	v_pk_add_f32 v[90:91], v[98:99], v[90:91]
	v_pk_add_f32 v[98:99], v[102:103], v[114:115]
	v_pk_add_f32 v[90:91], v[118:119], v[90:91]
	v_pk_add_f32 v[100:101], v[98:99], v[102:103] neg_lo:[0,1] neg_hi:[0,1]
	v_pk_mul_f32 v[90:91], v[112:113], v[90:91]
	v_pk_add_f32 v[100:101], v[114:115], v[100:101] neg_lo:[0,1] neg_hi:[0,1]
	s_nop 0
	v_pk_add_f32 v[90:91], v[100:101], v[90:91]
	s_nop 0
	v_pk_add_f32 v[100:101], v[98:99], v[90:91]
	s_nop 0
	v_pk_mul_f32 v[102:103], v[100:101], v[100:101]
	v_pk_add_f32 v[98:99], v[100:101], v[98:99] neg_lo:[0,1] neg_hi:[0,1]
	v_pk_fma_f32 v[110:111], v[102:103], s[28:29], v[66:67] op_sel_hi:[1,0,0]
	v_pk_add_f32 v[90:91], v[90:91], v[98:99] neg_lo:[0,1] neg_hi:[0,1]
	v_ldexp_f32 v98, v100, 1
	v_pk_fma_f32 v[110:111], v[102:103], v[110:111], s[30:31] op_sel_hi:[1,1,0]
	v_ldexp_f32 v99, v101, 1
	v_pk_mul_f32 v[100:101], v[100:101], v[102:103]
	v_cvt_f32_i32_e32 v103, v122
	v_cvt_f32_i32_e32 v102, v97
	v_ldexp_f32 v113, v91, 1
	v_ldexp_f32 v90, v90, 1
	v_mov_b32_e32 v91, v113
	v_pk_mul_f32 v[114:115], v[102:103], s[12:13] op_sel_hi:[1,0]
	s_nop 0
	v_pk_fma_f32 v[116:117], v[102:103], s[12:13], v[114:115] op_sel_hi:[1,0,1] neg_lo:[0,0,1] neg_hi:[0,0,1]
	v_mov_b32_e32 v88, v114
	v_pk_fma_f32 v[102:103], v[102:103], s[14:15], v[116:117] op_sel_hi:[1,0,1]
	v_mov_b32_e32 v123, v115
	v_mov_b32_e32 v94, v102
	v_pk_add_f32 v[88:89], v[88:89], v[94:95]
	v_pk_add_f32 v[94:95], v[84:85], v[86:87]
	v_mov_b32_e32 v87, v93
	v_mov_b32_e32 v85, v95
	v_pk_add_f32 v[116:117], v[114:115], v[102:103]
	v_pk_add_f32 v[84:85], v[84:85], v[86:87]
	v_pk_add_f32 v[86:87], v[92:93], v[94:95]
	v_mov_b32_e32 v127, v117
	v_pk_add_f32 v[118:119], v[116:117], v[86:87]
	v_mov_b32_e32 v124, v86
	v_mov_b32_e32 v125, v119
	v_pk_add_f32 v[124:125], v[124:125], v[126:127] neg_lo:[0,1] neg_hi:[0,1]
	v_mov_b32_e32 v120, v118
	v_mov_b32_e32 v121, v117
	v_mov_b32_e32 v122, v116
	v_mov_b32_e32 v126, v116
	v_mov_b32_e32 v127, v119
	v_mov_b32_e32 v115, v125
	v_pk_add_f32 v[120:121], v[120:121], v[122:123] neg_lo:[0,1] neg_hi:[0,1]
	v_mov_b32_e32 v122, v86
	v_mov_b32_e32 v123, v103
	v_pk_add_f32 v[114:115], v[126:127], v[114:115] neg_lo:[0,1] neg_hi:[0,1]
	v_pk_add_f32 v[122:123], v[122:123], v[120:121] neg_lo:[0,1] neg_hi:[0,1]
	v_mov_b32_e32 v126, v114
	v_mov_b32_e32 v127, v121
	v_mov_b32_e32 v128, v118
	v_mov_b32_e32 v129, v87
	v_mov_b32_e32 v121, v93
	v_pk_add_f32 v[126:127], v[102:103], v[126:127] neg_lo:[0,1] neg_hi:[0,1]
	v_pk_add_f32 v[120:121], v[128:129], v[120:121] neg_lo:[0,1] neg_hi:[0,1]
	v_mov_b32_e32 v103, v117
	v_pk_add_f32 v[86:87], v[86:87], v[92:93] neg_lo:[0,1] neg_hi:[0,1]
	v_pk_add_f32 v[88:89], v[88:89], v[120:121] neg_lo:[0,1] neg_hi:[0,1]
	v_pk_add_f32 v[92:93], v[102:103], v[114:115] neg_lo:[0,1] neg_hi:[0,1]
	v_pk_add_f32 v[84:85], v[84:85], v[124:125] neg_lo:[0,1] neg_hi:[0,1]
	v_pk_add_f32 v[86:87], v[94:95], v[86:87] neg_lo:[0,1] neg_hi:[0,1]
	v_pk_add_f32 v[94:95], v[84:85], v[92:93]
	v_mov_b32_e32 v93, v123
	v_mov_b32_e32 v85, v89
	v_pk_add_f32 v[102:103], v[122:123], v[88:89]
	v_pk_add_f32 v[84:85], v[92:93], v[84:85]
	v_mov_b32_e32 v88, v94
	v_pk_add_f32 v[84:85], v[84:85], v[126:127] neg_lo:[0,1] neg_hi:[0,1]
	v_mov_b32_e32 v89, v103
	v_pk_add_f32 v[88:89], v[88:89], v[84:85] neg_lo:[0,1] neg_hi:[0,1]
	v_pk_add_f32 v[84:85], v[86:87], v[84:85] neg_lo:[0,1] neg_hi:[0,1]
	v_pk_add_f32 v[88:89], v[92:93], v[88:89] neg_lo:[0,1] neg_hi:[0,1]
	v_pk_add_f32 v[86:87], v[102:103], v[94:95]
	v_pk_add_f32 v[84:85], v[84:85], v[88:89]
	v_pk_add_f32 v[88:89], v[118:119], v[86:87]
	s_nop 0
	v_pk_add_f32 v[92:93], v[88:89], v[118:119] neg_lo:[0,1] neg_hi:[0,1]
	s_nop 0
	v_pk_add_f32 v[86:87], v[86:87], v[92:93] neg_lo:[0,1] neg_hi:[0,1]
	s_nop 0
	v_pk_add_f32 v[84:85], v[84:85], v[86:87]
	s_nop 0
	v_pk_add_f32 v[84:85], v[88:89], v[84:85]
	v_pk_mul_f32 v[88:89], v[100:101], v[110:111]
	v_cndmask_b32_e32 v84, v160, v84, vcc
	v_cmp_neq_f32_e32 vcc, s8, v130
	v_pk_add_f32 v[92:93], v[98:99], v[88:89]
	s_nop 0
	v_cndmask_b32_e32 v85, v160, v85, vcc
	v_cmp_ngt_f32_e32 vcc, -1.0, v130
	v_pk_add_f32 v[98:99], v[92:93], v[98:99] neg_lo:[0,1] neg_hi:[0,1]
	v_mov_b32_e32 v116, v92
	v_cndmask_b32_e32 v85, v161, v85, vcc
	v_cmp_ngt_f32_e32 vcc, -1.0, v83
	v_pk_add_f32 v[88:89], v[88:89], v[98:99] neg_lo:[0,1] neg_hi:[0,1]
	s_nop 0
	v_cndmask_b32_e32 v84, v161, v84, vcc
	v_cmp_neq_f32_e32 vcc, -1.0, v83
	v_pk_add_f32 v[100:101], v[90:91], v[88:89]
; __device__ __forceinline__ float softplusf(float x) { return fmaxf(x, 0.f) + log1pf(__expf(-fabsf(x))); }
; __device__ void phaseA_tile(const Params& p, int l, int mt, int nt, char* smem) {
;     ...
;             for (int i = 0; i < 4; ++i) {
;                 const int rl = wr * 64 + i * 16 + r;
;                 const int row = m0 + rl;
; #pragma unroll
;                 for (int j = 0; j < 2; ++j) {
;                     const int c = j * 16 + g4 * 4;
;                     const float4 db = *(const float4*)(p.dt_bias + l * 32 + c);
;                     const f32x4 v = acc[i][j];
;                     *(float4*)(p.dtb + (size_t)row * 32 + c) =
;                         make_float4(softplusf(v[0] + db.x), softplusf(v[1] + db.y), softplusf(v[2] + db.z), softplusf(v[3] + db.w));
;                 }
	v_mov_b32_e32 v99, v89
	v_cndmask_b32_e32 v84, v162, v84, vcc
	v_cmp_neq_f32_e32 vcc, -1.0, v130
	v_mov_b32_e32 v91, v101
	v_mov_b32_e32 v89, v93
	v_cndmask_b32_e32 v85, v162, v85, vcc
	v_cmp_lt_f32_e64 vcc, |v83|, s9
	v_cndmask_b32_e64 v85, v85, v130, s[0:1]
	v_pk_add_f32 v[88:89], v[90:91], v[88:89]
	v_cndmask_b32_e32 v84, v84, v83, vcc
	v_pk_add_f32 v[78:79], v[78:79], v[84:85]
	v_cvt_f32_i32_e32 v85, v134
	v_cvt_f32_i32_e32 v84, v132
	v_pk_add_f32 v[90:91], v[92:93], v[100:101]
	v_cmp_neq_f32_e32 vcc, s8, v131
	v_mov_b32_e32 v114, v90
	v_pk_mul_f32 v[86:87], v[84:85], s[12:13] op_sel_hi:[1,0]
	v_mov_b32_e32 v119, v91
	v_pk_fma_f32 v[94:95], v[84:85], s[12:13], v[86:87] op_sel_hi:[1,0,1] neg_lo:[0,0,1] neg_hi:[0,0,1]
	v_mov_b32_e32 v98, v86
	v_pk_fma_f32 v[84:85], v[84:85], s[14:15], v[94:95] op_sel_hi:[1,0,1]
	v_cmp_lt_f32_e64 s[0:1], |v133|, s9
	v_pk_add_f32 v[94:95], v[86:87], v[84:85]
	v_mov_b32_e32 v112, v84
	v_pk_add_f32 v[102:103], v[94:95], v[90:91]
	v_mov_b32_e32 v117, v95
	v_mov_b32_e32 v115, v103
	v_pk_add_f32 v[114:115], v[114:115], v[116:117] neg_lo:[0,1] neg_hi:[0,1]
	v_pk_add_f32 v[98:99], v[98:99], v[112:113]
	v_mov_b32_e32 v110, v102
	v_mov_b32_e32 v111, v95
	v_mov_b32_e32 v112, v94
	v_mov_b32_e32 v113, v87
	v_mov_b32_e32 v116, v94
	v_mov_b32_e32 v117, v103
	v_mov_b32_e32 v87, v115
	v_pk_add_f32 v[110:111], v[110:111], v[112:113] neg_lo:[0,1] neg_hi:[0,1]
	v_mov_b32_e32 v112, v90
	v_mov_b32_e32 v113, v85
	v_pk_add_f32 v[86:87], v[116:117], v[86:87] neg_lo:[0,1] neg_hi:[0,1]
	v_pk_add_f32 v[112:113], v[112:113], v[110:111] neg_lo:[0,1] neg_hi:[0,1]
	v_mov_b32_e32 v116, v86
	v_mov_b32_e32 v117, v111
	v_mov_b32_e32 v118, v102
	v_mov_b32_e32 v111, v93
	v_pk_add_f32 v[116:117], v[84:85], v[116:117] neg_lo:[0,1] neg_hi:[0,1]
	v_pk_add_f32 v[110:111], v[118:119], v[110:111] neg_lo:[0,1] neg_hi:[0,1]
	v_mov_b32_e32 v85, v95
	v_pk_add_f32 v[90:91], v[90:91], v[92:93] neg_lo:[0,1] neg_hi:[0,1]
	v_pk_add_f32 v[92:93], v[98:99], v[110:111] neg_lo:[0,1] neg_hi:[0,1]
	v_pk_add_f32 v[84:85], v[84:85], v[86:87] neg_lo:[0,1] neg_hi:[0,1]
	v_pk_add_f32 v[86:87], v[88:89], v[114:115] neg_lo:[0,1] neg_hi:[0,1]
	v_pk_add_f32 v[94:95], v[112:113], v[92:93]
	v_pk_add_f32 v[88:89], v[86:87], v[84:85]
	v_mov_b32_e32 v85, v113
	v_mov_b32_e32 v87, v93
	v_pk_add_f32 v[86:87], v[84:85], v[86:87]
	v_mov_b32_e32 v92, v88
	v_pk_add_f32 v[86:87], v[86:87], v[116:117] neg_lo:[0,1] neg_hi:[0,1]
	v_mov_b32_e32 v93, v95
	v_pk_add_f32 v[90:91], v[100:101], v[90:91] neg_lo:[0,1] neg_hi:[0,1]
	v_pk_add_f32 v[92:93], v[92:93], v[86:87] neg_lo:[0,1] neg_hi:[0,1]
	v_pk_add_f32 v[86:87], v[90:91], v[86:87] neg_lo:[0,1] neg_hi:[0,1]
	v_pk_add_f32 v[84:85], v[84:85], v[92:93] neg_lo:[0,1] neg_hi:[0,1]
	s_nop 0
	v_pk_add_f32 v[84:85], v[86:87], v[84:85]
	v_pk_add_f32 v[86:87], v[94:95], v[88:89]
	s_nop 0
	v_pk_add_f32 v[88:89], v[102:103], v[86:87]
	s_nop 0
	v_pk_add_f32 v[90:91], v[88:89], v[102:103] neg_lo:[0,1] neg_hi:[0,1]
	s_nop 0
	v_pk_add_f32 v[86:87], v[86:87], v[90:91] neg_lo:[0,1] neg_hi:[0,1]
	s_nop 0
	v_pk_add_f32 v[84:85], v[84:85], v[86:87]
	s_nop 0
	v_pk_add_f32 v[84:85], v[88:89], v[84:85]
	s_nop 0
	v_cndmask_b32_e32 v83, v160, v84, vcc
	v_cmp_neq_f32_e32 vcc, s8, v133
	s_nop 1
	v_cndmask_b32_e32 v84, v160, v85, vcc
	v_cmp_ngt_f32_e32 vcc, -1.0, v133
	s_nop 1
	v_cndmask_b32_e32 v84, v161, v84, vcc
	v_cmp_ngt_f32_e32 vcc, -1.0, v131
	s_nop 1
	v_cndmask_b32_e32 v83, v161, v83, vcc
	v_cmp_neq_f32_e32 vcc, -1.0, v131
	s_nop 1
	v_cndmask_b32_e32 v83, v162, v83, vcc
	v_cmp_neq_f32_e32 vcc, -1.0, v133
	s_nop 1
	v_cndmask_b32_e32 v84, v162, v84, vcc
	v_cmp_lt_f32_e64 vcc, |v131|, s9
	v_cndmask_b32_e64 v85, v84, v133, s[0:1]
	s_nop 0
	v_cndmask_b32_e32 v84, v83, v131, vcc
	v_pk_add_f32 v[80:81], v[80:81], v[84:85]
	global_store_dwordx4 v[76:77], v[78:81], off
	global_load_dwordx4 v[78:81], v0, s[74:75] offset:64
	s_waitcnt vmcnt(0)
	v_add_f32_e32 v83, v42, v78
	v_max_f32_e32 v78, 0, v83
	v_mul_f32_e64 v83, |v83|, s2
	v_exp_f32_e32 v83, v83
	s_nop 0
	v_add_f32_e32 v86, 1.0, v83
	v_add_f32_e32 v84, -1.0, v86
	v_sub_f32_e32 v85, v84, v86
	v_add_f32_e32 v85, 1.0, v85
	v_sub_f32_e32 v84, v83, v84
	v_add_f32_e32 v87, v84, v85
	v_frexp_mant_f32_e32 v84, v86
	v_cmp_gt_f32_e32 vcc, s26, v84
	v_cvt_f64_f32_e32 v[84:85], v86
	v_frexp_exp_i32_f64_e32 v84, v[84:85]
	v_subbrev_co_u32_e32 v97, vcc, 0, v84, vcc
	v_sub_u32_e32 v85, 0, v97
	v_ldexp_f32 v84, v86, v85
	v_ldexp_f32 v86, v87, v85
	v_add_f32_e32 v85, v43, v79
	v_max_f32_e32 v79, 0, v85
	v_mul_f32_e64 v85, |v85|, s2
	v_exp_f32_e32 v130, v85
	s_nop 0
	v_add_f32_e32 v85, 1.0, v130
	v_add_f32_e32 v87, -1.0, v85
	v_sub_f32_e32 v88, v87, v85
	v_add_f32_e32 v88, 1.0, v88
	v_sub_f32_e32 v87, v130, v87
	v_add_f32_e32 v87, v87, v88
	v_frexp_mant_f32_e32 v88, v85
	v_cmp_gt_f32_e32 vcc, s26, v88
	v_cvt_f64_f32_e32 v[88:89], v85
	v_frexp_exp_i32_f64_e32 v88, v[88:89]
	v_subbrev_co_u32_e32 v122, vcc, 0, v88, vcc
	v_sub_u32_e32 v88, 0, v122
	v_ldexp_f32 v85, v85, v88
	v_ldexp_f32 v87, v87, v88
	v_pk_add_f32 v[88:89], v[84:85], 1.0 op_sel_hi:[1,0]
	v_pk_add_f32 v[98:99], v[84:85], -1.0 op_sel_hi:[1,0]
	v_pk_add_f32 v[90:91], v[88:89], -1.0 op_sel_hi:[1,0]
	v_pk_add_f32 v[100:101], v[98:99], 1.0 op_sel_hi:[1,0]
	v_pk_add_f32 v[90:91], v[84:85], v[90:91] neg_lo:[0,1] neg_hi:[0,1]
	v_pk_add_f32 v[84:85], v[84:85], v[100:101] neg_lo:[0,1] neg_hi:[0,1]
	v_pk_add_f32 v[90:91], v[86:87], v[90:91]
	v_pk_add_f32 v[84:85], v[86:87], v[84:85]
	v_pk_add_f32 v[92:93], v[88:89], v[90:91]
	v_pk_add_f32 v[86:87], v[98:99], v[84:85]
	v_rcp_f32_e32 v94, v92
	v_rcp_f32_e32 v95, v93
	v_pk_add_f32 v[88:89], v[92:93], v[88:89] neg_lo:[0,1] neg_hi:[0,1]
; __device__ __forceinline__ float softplusf(float x) { return fmaxf(x, 0.f) + log1pf(__expf(-fabsf(x))); }
; __device__ void phaseA_tile(const Params& p, int l, int mt, int nt, char* smem) {
;     ...
;             for (int i = 0; i < 4; ++i) {
;                 const int rl = wr * 64 + i * 16 + r;
;                 const int row = m0 + rl;
; #pragma unroll
;                 for (int j = 0; j < 2; ++j) {
;                     const int c = j * 16 + g4 * 4;
;                     const float4 db = *(const float4*)(p.dt_bias + l * 32 + c);
;                     const f32x4 v = acc[i][j];
;                     *(float4*)(p.dtb + (size_t)row * 32 + c) =
;                         make_float4(softplusf(v[0] + db.x), softplusf(v[1] + db.y), softplusf(v[2] + db.z), softplusf(v[3] + db.w));
;                 }
	v_pk_add_f32 v[98:99], v[86:87], v[98:99] neg_lo:[0,1] neg_hi:[0,1]
	v_pk_add_f32 v[88:89], v[90:91], v[88:89] neg_lo:[0,1] neg_hi:[0,1]
	v_pk_mul_f32 v[90:91], v[86:87], v[94:95]
	v_pk_add_f32 v[84:85], v[84:85], v[98:99] neg_lo:[0,1] neg_hi:[0,1]
	v_pk_mul_f32 v[98:99], v[92:93], v[90:91]
	v_cmp_lt_f32_e64 s[0:1], |v130|, s9
	v_pk_fma_f32 v[100:101], v[90:91], v[92:93], v[98:99] neg_lo:[0,0,1] neg_hi:[0,0,1]
	s_nop 0
	v_pk_fma_f32 v[100:101], v[90:91], v[88:89], v[100:101]
	s_nop 0
	v_pk_add_f32 v[102:103], v[98:99], v[100:101]
	s_nop 0
	v_pk_add_f32 v[110:111], v[86:87], v[102:103] neg_lo:[0,1] neg_hi:[0,1]
	v_pk_add_f32 v[98:99], v[102:103], v[98:99] neg_lo:[0,1] neg_hi:[0,1]
	v_pk_add_f32 v[86:87], v[86:87], v[110:111] neg_lo:[0,1] neg_hi:[0,1]
	s_nop 0
	v_pk_add_f32 v[86:87], v[86:87], v[102:103] neg_lo:[0,1] neg_hi:[0,1]
	s_nop 0
	v_pk_add_f32 v[84:85], v[84:85], v[86:87]
	v_pk_add_f32 v[86:87], v[98:99], v[100:101] neg_lo:[0,1] neg_hi:[0,1]
	s_nop 0
	v_pk_add_f32 v[84:85], v[86:87], v[84:85]
	s_nop 0
	v_pk_add_f32 v[86:87], v[110:111], v[84:85]
	s_nop 0
	v_pk_mul_f32 v[98:99], v[94:95], v[86:87]
	s_nop 0
	v_pk_mul_f32 v[100:101], v[92:93], v[98:99]
	s_nop 0
	v_pk_fma_f32 v[92:93], v[98:99], v[92:93], v[100:101] neg_lo:[0,0,1] neg_hi:[0,0,1]
	s_nop 0
	v_pk_fma_f32 v[88:89], v[98:99], v[88:89], v[92:93]
	v_pk_add_f32 v[92:93], v[110:111], v[86:87] neg_lo:[0,1] neg_hi:[0,1]
	s_nop 0
	v_pk_add_f32 v[84:85], v[84:85], v[92:93]
	v_pk_add_f32 v[92:93], v[100:101], v[88:89]
	s_nop 0
	v_pk_add_f32 v[102:103], v[86:87], v[92:93] neg_lo:[0,1] neg_hi:[0,1]
	v_pk_add_f32 v[100:101], v[92:93], v[100:101] neg_lo:[0,1] neg_hi:[0,1]
	v_pk_add_f32 v[86:87], v[86:87], v[102:103] neg_lo:[0,1] neg_hi:[0,1]
	s_nop 0
	v_pk_add_f32 v[86:87], v[86:87], v[92:93] neg_lo:[0,1] neg_hi:[0,1]
	s_nop 0
	v_pk_add_f32 v[84:85], v[84:85], v[86:87]
	v_pk_add_f32 v[86:87], v[100:101], v[88:89] neg_lo:[0,1] neg_hi:[0,1]
	s_nop 0
	v_pk_add_f32 v[84:85], v[86:87], v[84:85]
	v_pk_add_f32 v[86:87], v[90:91], v[98:99]
	v_pk_add_f32 v[84:85], v[102:103], v[84:85]
	v_pk_add_f32 v[88:89], v[86:87], v[90:91] neg_lo:[0,1] neg_hi:[0,1]
	v_pk_mul_f32 v[84:85], v[94:95], v[84:85]
	v_pk_add_f32 v[88:89], v[98:99], v[88:89] neg_lo:[0,1] neg_hi:[0,1]
	s_nop 0
	v_pk_add_f32 v[84:85], v[88:89], v[84:85]
	s_nop 0
	v_pk_add_f32 v[88:89], v[86:87], v[84:85]
	s_nop 0
	v_pk_add_f32 v[86:87], v[88:89], v[86:87] neg_lo:[0,1] neg_hi:[0,1]
	v_pk_mul_f32 v[90:91], v[88:89], v[88:89]
	v_pk_add_f32 v[84:85], v[84:85], v[86:87] neg_lo:[0,1] neg_hi:[0,1]
	v_pk_fma_f32 v[92:93], v[90:91], s[28:29], v[66:67] op_sel_hi:[1,0,0]
	v_ldexp_f32 v95, v85, 1
	v_add_f32_e32 v85, v44, v80
	v_max_f32_e32 v80, 0, v85
	v_mul_f32_e64 v85, |v85|, s2
	v_exp_f32_e32 v131, v85
	v_ldexp_f32 v86, v88, 1
	v_pk_fma_f32 v[92:93], v[90:91], v[92:93], s[30:31] op_sel_hi:[1,1,0]
	v_ldexp_f32 v87, v89, 1
	v_add_f32_e32 v85, 1.0, v131
	v_pk_mul_f32 v[88:89], v[88:89], v[90:91]
	v_add_f32_e32 v90, -1.0, v85
	v_sub_f32_e32 v91, v90, v85
	v_add_f32_e32 v91, 1.0, v91
	v_sub_f32_e32 v90, v131, v90
	v_add_f32_e32 v94, v90, v91
	v_frexp_mant_f32_e32 v90, v85
	v_cmp_gt_f32_e32 vcc, s26, v90
	v_cvt_f64_f32_e32 v[90:91], v85
	v_frexp_exp_i32_f64_e32 v90, v[90:91]
	v_subbrev_co_u32_e32 v132, vcc, 0, v90, vcc
	v_sub_u32_e32 v91, 0, v132
	v_ldexp_f32 v90, v85, v91
	v_add_f32_e32 v85, v45, v81
	v_max_f32_e32 v81, 0, v85
	v_mul_f32_e64 v85, |v85|, s2
	v_exp_f32_e32 v133, v85
	v_ldexp_f32 v98, v94, v91
	v_pk_mul_f32 v[88:89], v[88:89], v[92:93]
	v_ldexp_f32 v84, v84, 1
	v_add_f32_e32 v85, 1.0, v133
	v_add_f32_e32 v91, -1.0, v85
	v_sub_f32_e32 v94, v91, v85
	v_add_f32_e32 v94, 1.0, v94
	v_sub_f32_e32 v91, v133, v91
	v_add_f32_e32 v94, v91, v94
	v_frexp_mant_f32_e32 v91, v85
	v_cvt_f64_f32_e32 v[100:101], v85
	v_cmp_gt_f32_e32 vcc, s26, v91
	v_frexp_exp_i32_f64_e32 v91, v[100:101]
	v_pk_add_f32 v[92:93], v[86:87], v[88:89]
	v_subbrev_co_u32_e32 v134, vcc, 0, v91, vcc
	v_sub_u32_e32 v99, 0, v134
	v_ldexp_f32 v91, v85, v99
	v_pk_add_f32 v[100:101], v[90:91], 1.0 op_sel_hi:[1,0]
	v_ldexp_f32 v99, v94, v99
	v_pk_add_f32 v[102:103], v[100:101], -1.0 op_sel_hi:[1,0]
	v_pk_add_f32 v[114:115], v[90:91], -1.0 op_sel_hi:[1,0]
	v_pk_add_f32 v[102:103], v[90:91], v[102:103] neg_lo:[0,1] neg_hi:[0,1]
	v_pk_add_f32 v[116:117], v[114:115], 1.0 op_sel_hi:[1,0]
	v_pk_add_f32 v[102:103], v[98:99], v[102:103]
	v_pk_add_f32 v[90:91], v[90:91], v[116:117] neg_lo:[0,1] neg_hi:[0,1]
	v_pk_add_f32 v[110:111], v[100:101], v[102:103]
	v_pk_add_f32 v[90:91], v[98:99], v[90:91]
	v_rcp_f32_e32 v112, v110
	v_rcp_f32_e32 v113, v111
	v_pk_add_f32 v[98:99], v[114:115], v[90:91]
	v_pk_add_f32 v[100:101], v[110:111], v[100:101] neg_lo:[0,1] neg_hi:[0,1]
	v_pk_add_f32 v[114:115], v[98:99], v[114:115] neg_lo:[0,1] neg_hi:[0,1]
	v_pk_add_f32 v[100:101], v[102:103], v[100:101] neg_lo:[0,1] neg_hi:[0,1]
	v_pk_mul_f32 v[102:103], v[98:99], v[112:113]
	v_pk_add_f32 v[90:91], v[90:91], v[114:115] neg_lo:[0,1] neg_hi:[0,1]
	v_pk_mul_f32 v[114:115], v[110:111], v[102:103]
	v_pk_add_f32 v[86:87], v[92:93], v[86:87] neg_lo:[0,1] neg_hi:[0,1]
	v_pk_fma_f32 v[116:117], v[102:103], v[110:111], v[114:115] neg_lo:[0,0,1] neg_hi:[0,0,1]
	v_pk_add_f32 v[86:87], v[88:89], v[86:87] neg_lo:[0,1] neg_hi:[0,1]
	v_pk_fma_f32 v[116:117], v[102:103], v[100:101], v[116:117]
	v_mov_b32_e32 v89, v87
	v_pk_add_f32 v[118:119], v[114:115], v[116:117]
	v_mov_b32_e32 v85, v95
	v_pk_add_f32 v[120:121], v[98:99], v[118:119] neg_lo:[0,1] neg_hi:[0,1]
	v_pk_add_f32 v[114:115], v[118:119], v[114:115] neg_lo:[0,1] neg_hi:[0,1]
	v_pk_add_f32 v[98:99], v[98:99], v[120:121] neg_lo:[0,1] neg_hi:[0,1]
	v_mov_b32_e32 v126, v92
; __device__ __forceinline__ float softplusf(float x) { return fmaxf(x, 0.f) + log1pf(__expf(-fabsf(x))); }
; __device__ void phaseA_tile(const Params& p, int l, int mt, int nt, char* smem) {
;     ...
;             for (int i = 0; i < 4; ++i) {
;                 const int rl = wr * 64 + i * 16 + r;
;                 const int row = m0 + rl;
; #pragma unroll
;                 for (int j = 0; j < 2; ++j) {
;                     const int c = j * 16 + g4 * 4;
;                     const float4 db = *(const float4*)(p.dt_bias + l * 32 + c);
;                     const f32x4 v = acc[i][j];
;                     *(float4*)(p.dtb + (size_t)row * 32 + c) =
;                         make_float4(softplusf(v[0] + db.x), softplusf(v[1] + db.y), softplusf(v[2] + db.z), softplusf(v[3] + db.w));
;                 }
	v_pk_add_f32 v[98:99], v[98:99], v[118:119] neg_lo:[0,1] neg_hi:[0,1]
	v_cmp_neq_f32_e32 vcc, s8, v83
	v_pk_add_f32 v[90:91], v[90:91], v[98:99]
	v_pk_add_f32 v[98:99], v[114:115], v[116:117] neg_lo:[0,1] neg_hi:[0,1]
	s_nop 0
	v_pk_add_f32 v[90:91], v[98:99], v[90:91]
	s_nop 0
	v_pk_add_f32 v[98:99], v[120:121], v[90:91]
	s_nop 0
	v_pk_mul_f32 v[114:115], v[112:113], v[98:99]
	s_nop 0
	v_pk_mul_f32 v[116:117], v[110:111], v[114:115]
	s_nop 0
	v_pk_fma_f32 v[110:111], v[114:115], v[110:111], v[116:117] neg_lo:[0,0,1] neg_hi:[0,0,1]
	s_nop 0
	v_pk_fma_f32 v[100:101], v[114:115], v[100:101], v[110:111]
	v_pk_add_f32 v[110:111], v[120:121], v[98:99] neg_lo:[0,1] neg_hi:[0,1]
	s_nop 0
	v_pk_add_f32 v[90:91], v[90:91], v[110:111]
	v_pk_add_f32 v[110:111], v[116:117], v[100:101]
	s_nop 0
	v_pk_add_f32 v[118:119], v[98:99], v[110:111] neg_lo:[0,1] neg_hi:[0,1]
	v_pk_add_f32 v[116:117], v[110:111], v[116:117] neg_lo:[0,1] neg_hi:[0,1]
	v_pk_add_f32 v[98:99], v[98:99], v[118:119] neg_lo:[0,1] neg_hi:[0,1]
	s_nop 0
	v_pk_add_f32 v[98:99], v[98:99], v[110:111] neg_lo:[0,1] neg_hi:[0,1]
	s_nop 0
	v_pk_add_f32 v[90:91], v[90:91], v[98:99]
	v_pk_add_f32 v[98:99], v[116:117], v[100:101] neg_lo:[0,1] neg_hi:[0,1]
	s_nop 0
	v_pk_add_f32 v[90:91], v[98:99], v[90:91]
	v_pk_add_f32 v[98:99], v[102:103], v[114:115]
	v_pk_add_f32 v[90:91], v[118:119], v[90:91]
	v_pk_add_f32 v[100:101], v[98:99], v[102:103] neg_lo:[0,1] neg_hi:[0,1]
	v_pk_mul_f32 v[90:91], v[112:113], v[90:91]
	v_pk_add_f32 v[100:101], v[114:115], v[100:101] neg_lo:[0,1] neg_hi:[0,1]
	s_nop 0
	v_pk_add_f32 v[90:91], v[100:101], v[90:91]
	s_nop 0
	v_pk_add_f32 v[100:101], v[98:99], v[90:91]
	s_nop 0
	v_pk_mul_f32 v[102:103], v[100:101], v[100:101]
	v_pk_add_f32 v[98:99], v[100:101], v[98:99] neg_lo:[0,1] neg_hi:[0,1]
	v_pk_fma_f32 v[110:111], v[102:103], s[28:29], v[66:67] op_sel_hi:[1,0,0]
	v_pk_add_f32 v[90:91], v[90:91], v[98:99] neg_lo:[0,1] neg_hi:[0,1]
	v_ldexp_f32 v98, v100, 1
	v_pk_fma_f32 v[110:111], v[102:103], v[110:111], s[30:31] op_sel_hi:[1,1,0]
	v_ldexp_f32 v99, v101, 1
	v_pk_mul_f32 v[100:101], v[100:101], v[102:103]
	v_cvt_f32_i32_e32 v103, v122
	v_cvt_f32_i32_e32 v102, v97
	v_ldexp_f32 v113, v91, 1
	v_ldexp_f32 v90, v90, 1
	v_mov_b32_e32 v91, v113
	v_pk_mul_f32 v[114:115], v[102:103], s[12:13] op_sel_hi:[1,0]
	s_nop 0
	v_pk_fma_f32 v[116:117], v[102:103], s[12:13], v[114:115] op_sel_hi:[1,0,1] neg_lo:[0,0,1] neg_hi:[0,0,1]
	v_mov_b32_e32 v88, v114
	v_pk_fma_f32 v[102:103], v[102:103], s[14:15], v[116:117] op_sel_hi:[1,0,1]
	v_mov_b32_e32 v123, v115
	v_mov_b32_e32 v94, v102
	v_pk_add_f32 v[88:89], v[88:89], v[94:95]
	v_pk_add_f32 v[94:95], v[84:85], v[86:87]
	v_mov_b32_e32 v87, v93
	v_mov_b32_e32 v85, v95
	v_pk_add_f32 v[116:117], v[114:115], v[102:103]
	v_pk_add_f32 v[84:85], v[84:85], v[86:87]
	v_pk_add_f32 v[86:87], v[92:93], v[94:95]
	v_mov_b32_e32 v127, v117
	v_pk_add_f32 v[118:119], v[116:117], v[86:87]
	v_mov_b32_e32 v124, v86
	v_mov_b32_e32 v125, v119
	v_pk_add_f32 v[124:125], v[124:125], v[126:127] neg_lo:[0,1] neg_hi:[0,1]
	v_mov_b32_e32 v120, v118
	v_mov_b32_e32 v121, v117
	v_mov_b32_e32 v122, v116
	v_mov_b32_e32 v126, v116
	v_mov_b32_e32 v127, v119
	v_mov_b32_e32 v115, v125
	v_pk_add_f32 v[120:121], v[120:121], v[122:123] neg_lo:[0,1] neg_hi:[0,1]
	v_mov_b32_e32 v122, v86
	v_mov_b32_e32 v123, v103
	v_pk_add_f32 v[114:115], v[126:127], v[114:115] neg_lo:[0,1] neg_hi:[0,1]
	v_pk_add_f32 v[122:123], v[122:123], v[120:121] neg_lo:[0,1] neg_hi:[0,1]
	v_mov_b32_e32 v126, v114
	v_mov_b32_e32 v127, v121
	v_mov_b32_e32 v128, v118
	v_mov_b32_e32 v129, v87
	v_mov_b32_e32 v121, v93
	v_pk_add_f32 v[126:127], v[102:103], v[126:127] neg_lo:[0,1] neg_hi:[0,1]
	v_pk_add_f32 v[120:121], v[128:129], v[120:121] neg_lo:[0,1] neg_hi:[0,1]
	v_mov_b32_e32 v103, v117
	v_pk_add_f32 v[86:87], v[86:87], v[92:93] neg_lo:[0,1] neg_hi:[0,1]
	v_pk_add_f32 v[88:89], v[88:89], v[120:121] neg_lo:[0,1] neg_hi:[0,1]
	v_pk_add_f32 v[92:93], v[102:103], v[114:115] neg_lo:[0,1] neg_hi:[0,1]
	v_pk_add_f32 v[84:85], v[84:85], v[124:125] neg_lo:[0,1] neg_hi:[0,1]
	v_pk_add_f32 v[86:87], v[94:95], v[86:87] neg_lo:[0,1] neg_hi:[0,1]
	v_pk_add_f32 v[94:95], v[84:85], v[92:93]
	v_mov_b32_e32 v93, v123
	v_mov_b32_e32 v85, v89
	v_pk_add_f32 v[102:103], v[122:123], v[88:89]
	v_pk_add_f32 v[84:85], v[92:93], v[84:85]
	v_mov_b32_e32 v88, v94
	v_pk_add_f32 v[84:85], v[84:85], v[126:127] neg_lo:[0,1] neg_hi:[0,1]
	v_mov_b32_e32 v89, v103
	v_pk_add_f32 v[88:89], v[88:89], v[84:85] neg_lo:[0,1] neg_hi:[0,1]
	v_pk_add_f32 v[84:85], v[86:87], v[84:85] neg_lo:[0,1] neg_hi:[0,1]
	v_pk_add_f32 v[88:89], v[92:93], v[88:89] neg_lo:[0,1] neg_hi:[0,1]
	v_pk_add_f32 v[86:87], v[102:103], v[94:95]
	v_pk_add_f32 v[84:85], v[84:85], v[88:89]
	v_pk_add_f32 v[88:89], v[118:119], v[86:87]
	s_nop 0
	v_pk_add_f32 v[92:93], v[88:89], v[118:119] neg_lo:[0,1] neg_hi:[0,1]
	s_nop 0
	v_pk_add_f32 v[86:87], v[86:87], v[92:93] neg_lo:[0,1] neg_hi:[0,1]
	s_nop 0
	v_pk_add_f32 v[84:85], v[84:85], v[86:87]
	s_nop 0
	v_pk_add_f32 v[84:85], v[88:89], v[84:85]
	v_pk_mul_f32 v[88:89], v[100:101], v[110:111]
	v_cndmask_b32_e32 v84, v160, v84, vcc
	v_cmp_neq_f32_e32 vcc, s8, v130
	v_pk_add_f32 v[92:93], v[98:99], v[88:89]
	s_nop 0
	v_cndmask_b32_e32 v85, v160, v85, vcc
	v_cmp_ngt_f32_e32 vcc, -1.0, v130
	v_pk_add_f32 v[98:99], v[92:93], v[98:99] neg_lo:[0,1] neg_hi:[0,1]
	v_mov_b32_e32 v116, v92
	v_cndmask_b32_e32 v85, v161, v85, vcc
	v_cmp_ngt_f32_e32 vcc, -1.0, v83
	v_pk_add_f32 v[88:89], v[88:89], v[98:99] neg_lo:[0,1] neg_hi:[0,1]
	s_nop 0
	v_cndmask_b32_e32 v84, v161, v84, vcc
	v_cmp_neq_f32_e32 vcc, -1.0, v83
	v_pk_add_f32 v[100:101], v[90:91], v[88:89]
; __device__ __forceinline__ float softplusf(float x) { return fmaxf(x, 0.f) + log1pf(__expf(-fabsf(x))); }
; __device__ __forceinline__ float logsigf(float x) { return fminf(x, 0.f) - log1pf(__expf(-fabsf(x))); }
; __device__ void phaseA_tile(const Params& p, int l, int mt, int nt, char* smem) {
;     ...
;             for (int i = 0; i < 4; ++i) {
;                 const int rl = wr * 64 + i * 16 + r;
;                 const int row = m0 + rl;
; #pragma unroll
;                 for (int j = 0; j < 2; ++j) {
;                     const int c = j * 16 + g4 * 4;
;                     const float4 db = *(const float4*)(p.dt_bias + l * 32 + c);
;                     const f32x4 v = acc[i][j];
;                     *(float4*)(p.dtb + (size_t)row * 32 + c) =
;                         make_float4(softplusf(v[0] + db.x), softplusf(v[1] + db.y), softplusf(v[2] + db.z), softplusf(v[3] + db.w));
;                 }
;                 {
;                     const int c = g4 * 4;
;                     const float4 fb = *(const float4*)(p.b_f + l * 16 + c);
;                     const f32x4 v = acc[i][2];
;                     float4 lf = make_float4(logsigf(v[0] + fb.x), logsigf(v[1] + fb.y), logsigf(v[2] + fb.z), logsigf(v[3] + fb.w));
;                     float* o = samp ? (p.out + O_LFS + ((size_t)l * TSM + (row - TP)) * 16 + c)
;                                     : (p.out + O_LFP + ((size_t)l * TP + row) * 16 + c);
;                     *(float4*)o = lf;
;                     *(float4*)(lf_s + rl * 16 + c) = lf;
;                 }
	v_mov_b32_e32 v99, v89
	v_cndmask_b32_e32 v84, v162, v84, vcc
	v_cmp_neq_f32_e32 vcc, -1.0, v130
	v_mov_b32_e32 v91, v101
	v_mov_b32_e32 v89, v93
	v_cndmask_b32_e32 v85, v162, v85, vcc
	v_cmp_lt_f32_e64 vcc, |v83|, s9
	v_cndmask_b32_e64 v85, v85, v130, s[0:1]
	v_pk_add_f32 v[88:89], v[90:91], v[88:89]
	v_cndmask_b32_e32 v84, v84, v83, vcc
	v_pk_add_f32 v[78:79], v[78:79], v[84:85]
	v_cvt_f32_i32_e32 v85, v134
	v_cvt_f32_i32_e32 v84, v132
	v_pk_add_f32 v[90:91], v[92:93], v[100:101]
	v_cmp_neq_f32_e32 vcc, s8, v131
	v_mov_b32_e32 v114, v90
	v_pk_mul_f32 v[86:87], v[84:85], s[12:13] op_sel_hi:[1,0]
	v_mov_b32_e32 v119, v91
	v_pk_fma_f32 v[94:95], v[84:85], s[12:13], v[86:87] op_sel_hi:[1,0,1] neg_lo:[0,0,1] neg_hi:[0,0,1]
	v_mov_b32_e32 v98, v86
	v_pk_fma_f32 v[84:85], v[84:85], s[14:15], v[94:95] op_sel_hi:[1,0,1]
	v_cmp_lt_f32_e64 s[0:1], |v133|, s9
	v_pk_add_f32 v[94:95], v[86:87], v[84:85]
	v_mov_b32_e32 v112, v84
	v_pk_add_f32 v[102:103], v[94:95], v[90:91]
	v_mov_b32_e32 v117, v95
	v_mov_b32_e32 v115, v103
	v_pk_add_f32 v[114:115], v[114:115], v[116:117] neg_lo:[0,1] neg_hi:[0,1]
	v_pk_add_f32 v[98:99], v[98:99], v[112:113]
	v_mov_b32_e32 v110, v102
	v_mov_b32_e32 v111, v95
	v_mov_b32_e32 v112, v94
	v_mov_b32_e32 v113, v87
	v_mov_b32_e32 v116, v94
	v_mov_b32_e32 v117, v103
	v_mov_b32_e32 v87, v115
	v_pk_add_f32 v[110:111], v[110:111], v[112:113] neg_lo:[0,1] neg_hi:[0,1]
	v_mov_b32_e32 v112, v90
	v_mov_b32_e32 v113, v85
	v_pk_add_f32 v[86:87], v[116:117], v[86:87] neg_lo:[0,1] neg_hi:[0,1]
	v_pk_add_f32 v[112:113], v[112:113], v[110:111] neg_lo:[0,1] neg_hi:[0,1]
	v_mov_b32_e32 v116, v86
	v_mov_b32_e32 v117, v111
	v_mov_b32_e32 v118, v102
	v_mov_b32_e32 v111, v93
	v_pk_add_f32 v[116:117], v[84:85], v[116:117] neg_lo:[0,1] neg_hi:[0,1]
	v_pk_add_f32 v[110:111], v[118:119], v[110:111] neg_lo:[0,1] neg_hi:[0,1]
	v_mov_b32_e32 v85, v95
	v_pk_add_f32 v[90:91], v[90:91], v[92:93] neg_lo:[0,1] neg_hi:[0,1]
	v_pk_add_f32 v[92:93], v[98:99], v[110:111] neg_lo:[0,1] neg_hi:[0,1]
	v_pk_add_f32 v[84:85], v[84:85], v[86:87] neg_lo:[0,1] neg_hi:[0,1]
	v_pk_add_f32 v[86:87], v[88:89], v[114:115] neg_lo:[0,1] neg_hi:[0,1]
	v_pk_add_f32 v[94:95], v[112:113], v[92:93]
	v_pk_add_f32 v[88:89], v[86:87], v[84:85]
	v_mov_b32_e32 v85, v113
	v_mov_b32_e32 v87, v93
	v_pk_add_f32 v[86:87], v[84:85], v[86:87]
	v_mov_b32_e32 v92, v88
	v_pk_add_f32 v[86:87], v[86:87], v[116:117] neg_lo:[0,1] neg_hi:[0,1]
	v_mov_b32_e32 v93, v95
	v_pk_add_f32 v[90:91], v[100:101], v[90:91] neg_lo:[0,1] neg_hi:[0,1]
	v_pk_add_f32 v[92:93], v[92:93], v[86:87] neg_lo:[0,1] neg_hi:[0,1]
	v_pk_add_f32 v[86:87], v[90:91], v[86:87] neg_lo:[0,1] neg_hi:[0,1]
	v_pk_add_f32 v[84:85], v[84:85], v[92:93] neg_lo:[0,1] neg_hi:[0,1]
	s_nop 0
	v_pk_add_f32 v[84:85], v[86:87], v[84:85]
	v_pk_add_f32 v[86:87], v[94:95], v[88:89]
	s_nop 0
	v_pk_add_f32 v[88:89], v[102:103], v[86:87]
	s_nop 0
	v_pk_add_f32 v[90:91], v[88:89], v[102:103] neg_lo:[0,1] neg_hi:[0,1]
	s_nop 0
	v_pk_add_f32 v[86:87], v[86:87], v[90:91] neg_lo:[0,1] neg_hi:[0,1]
	s_nop 0
	v_pk_add_f32 v[84:85], v[84:85], v[86:87]
	s_nop 0
	v_pk_add_f32 v[84:85], v[88:89], v[84:85]
	s_nop 0
	v_cndmask_b32_e32 v83, v160, v84, vcc
	v_cmp_neq_f32_e32 vcc, s8, v133
	s_nop 1
	v_cndmask_b32_e32 v84, v160, v85, vcc
	v_cmp_ngt_f32_e32 vcc, -1.0, v133
	s_nop 1
	v_cndmask_b32_e32 v84, v161, v84, vcc
	v_cmp_ngt_f32_e32 vcc, -1.0, v131
	s_nop 1
	v_cndmask_b32_e32 v83, v161, v83, vcc
	v_cmp_neq_f32_e32 vcc, -1.0, v131
	s_nop 1
	v_cndmask_b32_e32 v83, v162, v83, vcc
	v_cmp_neq_f32_e32 vcc, -1.0, v133
	s_nop 1
	v_cndmask_b32_e32 v84, v162, v84, vcc
	v_cmp_lt_f32_e64 vcc, |v131|, s9
	v_cndmask_b32_e64 v85, v84, v133, s[0:1]
	s_nop 0
	v_cndmask_b32_e32 v84, v83, v131, vcc
	v_pk_add_f32 v[80:81], v[80:81], v[84:85]
	global_store_dwordx4 v[76:77], v[78:81], off offset:64
	global_load_dwordx4 v[76:79], v0, s[78:79]
	s_waitcnt vmcnt(0)
	v_add_f32_e32 v80, v38, v76
	v_min_f32_e32 v76, 0, v80
	v_mul_f32_e64 v80, |v80|, s2
	v_exp_f32_e32 v83, v80
	s_nop 0
	v_add_f32_e32 v84, 1.0, v83
	v_add_f32_e32 v80, -1.0, v84
	v_sub_f32_e32 v81, v80, v84
	v_add_f32_e32 v81, 1.0, v81
	v_sub_f32_e32 v80, v83, v80
	v_add_f32_e32 v85, v80, v81
	v_frexp_mant_f32_e32 v80, v84
	v_cmp_gt_f32_e32 vcc, s26, v80
	v_cvt_f64_f32_e32 v[80:81], v84
	v_frexp_exp_i32_f64_e32 v80, v[80:81]
	v_subbrev_co_u32_e32 v97, vcc, 0, v80, vcc
	v_sub_u32_e32 v81, 0, v97
	v_ldexp_f32 v80, v84, v81
	v_ldexp_f32 v84, v85, v81
	v_add_f32_e32 v81, v39, v77
	v_min_f32_e32 v77, 0, v81
	v_mul_f32_e64 v81, |v81|, s2
	v_exp_f32_e32 v128, v81
	s_nop 0
	v_add_f32_e32 v81, 1.0, v128
	v_add_f32_e32 v85, -1.0, v81
	v_sub_f32_e32 v86, v85, v81
	v_add_f32_e32 v86, 1.0, v86
	v_sub_f32_e32 v85, v128, v85
	v_add_f32_e32 v85, v85, v86
	v_frexp_mant_f32_e32 v86, v81
	v_cmp_gt_f32_e32 vcc, s26, v86
	v_cvt_f64_f32_e32 v[86:87], v81
	v_frexp_exp_i32_f64_e32 v86, v[86:87]
	v_subbrev_co_u32_e32 v120, vcc, 0, v86, vcc
	v_sub_u32_e32 v86, 0, v120
	v_ldexp_f32 v81, v81, v86
	v_ldexp_f32 v85, v85, v86
	v_pk_add_f32 v[86:87], v[80:81], 1.0 op_sel_hi:[1,0]
	v_pk_add_f32 v[94:95], v[80:81], -1.0 op_sel_hi:[1,0]
	v_pk_add_f32 v[88:89], v[86:87], -1.0 op_sel_hi:[1,0]
	v_pk_add_f32 v[98:99], v[94:95], 1.0 op_sel_hi:[1,0]
	v_pk_add_f32 v[88:89], v[80:81], v[88:89] neg_lo:[0,1] neg_hi:[0,1]
	v_pk_add_f32 v[80:81], v[80:81], v[98:99] neg_lo:[0,1] neg_hi:[0,1]
	v_pk_add_f32 v[88:89], v[84:85], v[88:89]
	v_pk_add_f32 v[80:81], v[84:85], v[80:81]
	v_pk_add_f32 v[90:91], v[86:87], v[88:89]
	v_pk_add_f32 v[84:85], v[94:95], v[80:81]
	v_rcp_f32_e32 v92, v90
	v_rcp_f32_e32 v93, v91
	v_pk_add_f32 v[86:87], v[90:91], v[86:87] neg_lo:[0,1] neg_hi:[0,1]
; __device__ __forceinline__ float logsigf(float x) { return fminf(x, 0.f) - log1pf(__expf(-fabsf(x))); }
; __device__ void phaseA_tile(const Params& p, int l, int mt, int nt, char* smem) {
;     ...
;                     const int c = g4 * 4;
;                     const float4 fb = *(const float4*)(p.b_f + l * 16 + c);
;                     const f32x4 v = acc[i][2];
;                     float4 lf = make_float4(logsigf(v[0] + fb.x), logsigf(v[1] + fb.y), logsigf(v[2] + fb.z), logsigf(v[3] + fb.w));
;                     float* o = samp ? (p.out + O_LFS + ((size_t)l * TSM + (row - TP)) * 16 + c)
;                                     : (p.out + O_LFP + ((size_t)l * TP + row) * 16 + c);
;                     *(float4*)o = lf;
;                     *(float4*)(lf_s + rl * 16 + c) = lf;
;                 }
	v_pk_add_f32 v[94:95], v[84:85], v[94:95] neg_lo:[0,1] neg_hi:[0,1]
	v_pk_add_f32 v[86:87], v[88:89], v[86:87] neg_lo:[0,1] neg_hi:[0,1]
	v_pk_mul_f32 v[88:89], v[84:85], v[92:93]
	v_pk_add_f32 v[80:81], v[80:81], v[94:95] neg_lo:[0,1] neg_hi:[0,1]
	v_pk_mul_f32 v[94:95], v[90:91], v[88:89]
	v_cmp_lt_f32_e64 s[0:1], |v128|, s9
	v_pk_fma_f32 v[98:99], v[88:89], v[90:91], v[94:95] neg_lo:[0,0,1] neg_hi:[0,0,1]
	s_nop 0
	v_pk_fma_f32 v[98:99], v[88:89], v[86:87], v[98:99]
	s_nop 0
	v_pk_add_f32 v[100:101], v[94:95], v[98:99]
	s_nop 0
	v_pk_add_f32 v[102:103], v[84:85], v[100:101] neg_lo:[0,1] neg_hi:[0,1]
	v_pk_add_f32 v[94:95], v[100:101], v[94:95] neg_lo:[0,1] neg_hi:[0,1]
	v_pk_add_f32 v[84:85], v[84:85], v[102:103] neg_lo:[0,1] neg_hi:[0,1]
	s_nop 0
	v_pk_add_f32 v[84:85], v[84:85], v[100:101] neg_lo:[0,1] neg_hi:[0,1]
	s_nop 0
	v_pk_add_f32 v[80:81], v[80:81], v[84:85]
	v_pk_add_f32 v[84:85], v[94:95], v[98:99] neg_lo:[0,1] neg_hi:[0,1]
	s_nop 0
	v_pk_add_f32 v[80:81], v[84:85], v[80:81]
	s_nop 0
	v_pk_add_f32 v[84:85], v[102:103], v[80:81]
	s_nop 0
	v_pk_mul_f32 v[94:95], v[92:93], v[84:85]
	s_nop 0
	v_pk_mul_f32 v[98:99], v[90:91], v[94:95]
	s_nop 0
	v_pk_fma_f32 v[90:91], v[94:95], v[90:91], v[98:99] neg_lo:[0,0,1] neg_hi:[0,0,1]
	s_nop 0
	v_pk_fma_f32 v[86:87], v[94:95], v[86:87], v[90:91]
	v_pk_add_f32 v[90:91], v[102:103], v[84:85] neg_lo:[0,1] neg_hi:[0,1]
	s_nop 0
	v_pk_add_f32 v[80:81], v[80:81], v[90:91]
	v_pk_add_f32 v[90:91], v[98:99], v[86:87]
	s_nop 0
	v_pk_add_f32 v[100:101], v[84:85], v[90:91] neg_lo:[0,1] neg_hi:[0,1]
	v_pk_add_f32 v[98:99], v[90:91], v[98:99] neg_lo:[0,1] neg_hi:[0,1]
	v_pk_add_f32 v[84:85], v[84:85], v[100:101] neg_lo:[0,1] neg_hi:[0,1]
	s_nop 0
	v_pk_add_f32 v[84:85], v[84:85], v[90:91] neg_lo:[0,1] neg_hi:[0,1]
	s_nop 0
	v_pk_add_f32 v[80:81], v[80:81], v[84:85]
	v_pk_add_f32 v[84:85], v[98:99], v[86:87] neg_lo:[0,1] neg_hi:[0,1]
	s_nop 0
	v_pk_add_f32 v[80:81], v[84:85], v[80:81]
	v_pk_add_f32 v[84:85], v[88:89], v[94:95]
	v_pk_add_f32 v[80:81], v[100:101], v[80:81]
	v_pk_add_f32 v[86:87], v[84:85], v[88:89] neg_lo:[0,1] neg_hi:[0,1]
	v_pk_mul_f32 v[80:81], v[92:93], v[80:81]
	v_pk_add_f32 v[86:87], v[94:95], v[86:87] neg_lo:[0,1] neg_hi:[0,1]
	s_nop 0
	v_pk_add_f32 v[80:81], v[86:87], v[80:81]
	s_nop 0
	v_pk_add_f32 v[86:87], v[84:85], v[80:81]
	s_nop 0
	v_pk_add_f32 v[84:85], v[86:87], v[84:85] neg_lo:[0,1] neg_hi:[0,1]
	v_pk_mul_f32 v[88:89], v[86:87], v[86:87]
	v_pk_add_f32 v[80:81], v[80:81], v[84:85] neg_lo:[0,1] neg_hi:[0,1]
	v_pk_fma_f32 v[90:91], v[88:89], s[28:29], v[66:67] op_sel_hi:[1,0,0]
	v_ldexp_f32 v93, v81, 1
	v_add_f32_e32 v81, v40, v78
	v_min_f32_e32 v78, 0, v81
	v_mul_f32_e64 v81, |v81|, s2
	v_exp_f32_e32 v129, v81
	v_ldexp_f32 v84, v86, 1
	v_pk_fma_f32 v[90:91], v[88:89], v[90:91], s[30:31] op_sel_hi:[1,1,0]
	v_ldexp_f32 v85, v87, 1
	v_add_f32_e32 v81, 1.0, v129
	v_pk_mul_f32 v[86:87], v[86:87], v[88:89]
	v_add_f32_e32 v88, -1.0, v81
	v_sub_f32_e32 v89, v88, v81
	v_add_f32_e32 v89, 1.0, v89
	v_sub_f32_e32 v88, v129, v88
	v_add_f32_e32 v92, v88, v89
	v_frexp_mant_f32_e32 v88, v81
	v_cmp_gt_f32_e32 vcc, s26, v88
	v_cvt_f64_f32_e32 v[88:89], v81
	v_frexp_exp_i32_f64_e32 v88, v[88:89]
	v_subbrev_co_u32_e32 v130, vcc, 0, v88, vcc
	v_sub_u32_e32 v89, 0, v130
	v_ldexp_f32 v88, v81, v89
	v_add_f32_e32 v81, v41, v79
	v_min_f32_e32 v79, 0, v81
	v_mul_f32_e64 v81, |v81|, s2
	v_exp_f32_e32 v131, v81
	v_ldexp_f32 v94, v92, v89
	v_pk_mul_f32 v[86:87], v[86:87], v[90:91]
	v_ldexp_f32 v80, v80, 1
	v_add_f32_e32 v81, 1.0, v131
	v_add_f32_e32 v89, -1.0, v81
	v_sub_f32_e32 v92, v89, v81
	v_add_f32_e32 v92, 1.0, v92
	v_sub_f32_e32 v89, v131, v89
	v_add_f32_e32 v92, v89, v92
	v_frexp_mant_f32_e32 v89, v81
	v_cvt_f64_f32_e32 v[98:99], v81
	v_cmp_gt_f32_e32 vcc, s26, v89
	v_frexp_exp_i32_f64_e32 v89, v[98:99]
	v_pk_add_f32 v[90:91], v[84:85], v[86:87]
	v_subbrev_co_u32_e32 v132, vcc, 0, v89, vcc
	v_sub_u32_e32 v95, 0, v132
	v_ldexp_f32 v89, v81, v95
	v_pk_add_f32 v[98:99], v[88:89], 1.0 op_sel_hi:[1,0]
	v_ldexp_f32 v95, v92, v95
	v_pk_add_f32 v[100:101], v[98:99], -1.0 op_sel_hi:[1,0]
	v_pk_add_f32 v[112:113], v[88:89], -1.0 op_sel_hi:[1,0]
	v_pk_add_f32 v[100:101], v[88:89], v[100:101] neg_lo:[0,1] neg_hi:[0,1]
	v_pk_add_f32 v[114:115], v[112:113], 1.0 op_sel_hi:[1,0]
	v_pk_add_f32 v[100:101], v[94:95], v[100:101]
	v_pk_add_f32 v[88:89], v[88:89], v[114:115] neg_lo:[0,1] neg_hi:[0,1]
	v_pk_add_f32 v[102:103], v[98:99], v[100:101]
	v_pk_add_f32 v[88:89], v[94:95], v[88:89]
	v_rcp_f32_e32 v110, v102
	v_rcp_f32_e32 v111, v103
	v_pk_add_f32 v[94:95], v[112:113], v[88:89]
	v_pk_add_f32 v[98:99], v[102:103], v[98:99] neg_lo:[0,1] neg_hi:[0,1]
	v_pk_add_f32 v[112:113], v[94:95], v[112:113] neg_lo:[0,1] neg_hi:[0,1]
	v_pk_add_f32 v[98:99], v[100:101], v[98:99] neg_lo:[0,1] neg_hi:[0,1]
	v_pk_mul_f32 v[100:101], v[94:95], v[110:111]
	v_pk_add_f32 v[88:89], v[88:89], v[112:113] neg_lo:[0,1] neg_hi:[0,1]
	v_pk_mul_f32 v[112:113], v[102:103], v[100:101]
	v_pk_add_f32 v[84:85], v[90:91], v[84:85] neg_lo:[0,1] neg_hi:[0,1]
	v_pk_fma_f32 v[114:115], v[100:101], v[102:103], v[112:113] neg_lo:[0,0,1] neg_hi:[0,0,1]
	v_add_u32_e32 v81, 0xffff8000, v68
	v_pk_fma_f32 v[114:115], v[100:101], v[98:99], v[114:115]
	v_pk_add_f32 v[84:85], v[86:87], v[84:85] neg_lo:[0,1] neg_hi:[0,1]
	v_pk_add_f32 v[116:117], v[112:113], v[114:115]
	v_cndmask_b32_e64 v68, v68, v81, s[60:61]
	v_pk_add_f32 v[118:119], v[94:95], v[116:117] neg_lo:[0,1] neg_hi:[0,1]
	v_pk_add_f32 v[112:113], v[116:117], v[112:113] neg_lo:[0,1] neg_hi:[0,1]
	v_pk_add_f32 v[94:95], v[94:95], v[118:119] neg_lo:[0,1] neg_hi:[0,1]
	v_mov_b32_e32 v87, v85
; __device__ __forceinline__ float logsigf(float x) { return fminf(x, 0.f) - log1pf(__expf(-fabsf(x))); }
; __device__ void phaseA_tile(const Params& p, int l, int mt, int nt, char* smem) {
;     ...
;                     const int c = g4 * 4;
;                     const float4 fb = *(const float4*)(p.b_f + l * 16 + c);
;                     const f32x4 v = acc[i][2];
;                     float4 lf = make_float4(logsigf(v[0] + fb.x), logsigf(v[1] + fb.y), logsigf(v[2] + fb.z), logsigf(v[3] + fb.w));
;                     float* o = samp ? (p.out + O_LFS + ((size_t)l * TSM + (row - TP)) * 16 + c)
;                                     : (p.out + O_LFP + ((size_t)l * TP + row) * 16 + c);
;                     *(float4*)o = lf;
;                     *(float4*)(lf_s + rl * 16 + c) = lf;
;                 }
	v_pk_add_f32 v[94:95], v[94:95], v[116:117] neg_lo:[0,1] neg_hi:[0,1]
	v_mov_b32_e32 v124, v90
	v_pk_add_f32 v[88:89], v[88:89], v[94:95]
	v_pk_add_f32 v[94:95], v[112:113], v[114:115] neg_lo:[0,1] neg_hi:[0,1]
	v_cmp_neq_f32_e32 vcc, s8, v83
	v_pk_add_f32 v[88:89], v[94:95], v[88:89]
	s_nop 0
	v_pk_add_f32 v[94:95], v[118:119], v[88:89]
	s_nop 0
	v_pk_mul_f32 v[112:113], v[110:111], v[94:95]
	s_nop 0
	v_pk_mul_f32 v[114:115], v[102:103], v[112:113]
	s_nop 0
	v_pk_fma_f32 v[102:103], v[112:113], v[102:103], v[114:115] neg_lo:[0,0,1] neg_hi:[0,0,1]
	s_nop 0
	v_pk_fma_f32 v[98:99], v[112:113], v[98:99], v[102:103]
	v_pk_add_f32 v[102:103], v[118:119], v[94:95] neg_lo:[0,1] neg_hi:[0,1]
	s_nop 0
	v_pk_add_f32 v[88:89], v[88:89], v[102:103]
	v_pk_add_f32 v[102:103], v[114:115], v[98:99]
	s_nop 0
	v_pk_add_f32 v[116:117], v[94:95], v[102:103] neg_lo:[0,1] neg_hi:[0,1]
	v_pk_add_f32 v[114:115], v[102:103], v[114:115] neg_lo:[0,1] neg_hi:[0,1]
	v_pk_add_f32 v[94:95], v[94:95], v[116:117] neg_lo:[0,1] neg_hi:[0,1]
	s_nop 0
	v_pk_add_f32 v[94:95], v[94:95], v[102:103] neg_lo:[0,1] neg_hi:[0,1]
	s_nop 0
	v_pk_add_f32 v[88:89], v[88:89], v[94:95]
	v_pk_add_f32 v[94:95], v[114:115], v[98:99] neg_lo:[0,1] neg_hi:[0,1]
	s_nop 0
	v_pk_add_f32 v[88:89], v[94:95], v[88:89]
	v_pk_add_f32 v[94:95], v[100:101], v[112:113]
	v_pk_add_f32 v[88:89], v[116:117], v[88:89]
	v_pk_add_f32 v[98:99], v[94:95], v[100:101] neg_lo:[0,1] neg_hi:[0,1]
	v_pk_mul_f32 v[88:89], v[110:111], v[88:89]
	v_pk_add_f32 v[98:99], v[112:113], v[98:99] neg_lo:[0,1] neg_hi:[0,1]
	s_nop 0
	v_pk_add_f32 v[88:89], v[98:99], v[88:89]
	s_nop 0
	v_pk_add_f32 v[98:99], v[94:95], v[88:89]
	s_nop 0
	v_pk_mul_f32 v[100:101], v[98:99], v[98:99]
	v_pk_add_f32 v[94:95], v[98:99], v[94:95] neg_lo:[0,1] neg_hi:[0,1]
	v_pk_fma_f32 v[102:103], v[100:101], s[28:29], v[66:67] op_sel_hi:[1,0,0]
	v_pk_add_f32 v[88:89], v[88:89], v[94:95] neg_lo:[0,1] neg_hi:[0,1]
	v_ldexp_f32 v94, v98, 1
	v_pk_fma_f32 v[102:103], v[100:101], v[102:103], s[30:31] op_sel_hi:[1,1,0]
	v_ldexp_f32 v95, v99, 1
	v_pk_mul_f32 v[98:99], v[98:99], v[100:101]
	v_cvt_f32_i32_e32 v101, v120
	v_cvt_f32_i32_e32 v100, v97
	v_ldexp_f32 v111, v89, 1
	v_ashrrev_i32_e32 v89, 31, v81
	v_mov_b32_e32 v81, v93
	v_pk_mul_f32 v[112:113], v[100:101], s[12:13] op_sel_hi:[1,0]
	v_ldexp_f32 v88, v88, 1
	v_pk_fma_f32 v[114:115], v[100:101], s[12:13], v[112:113] op_sel_hi:[1,0,1] neg_lo:[0,0,1] neg_hi:[0,0,1]
	v_mov_b32_e32 v86, v112
	v_pk_fma_f32 v[100:101], v[100:101], s[14:15], v[114:115] op_sel_hi:[1,0,1]
	v_mov_b32_e32 v121, v113
	v_mov_b32_e32 v92, v100
	v_pk_add_f32 v[86:87], v[86:87], v[92:93]
	v_pk_add_f32 v[92:93], v[80:81], v[84:85]
	v_mov_b32_e32 v85, v91
	v_mov_b32_e32 v81, v93
	v_pk_add_f32 v[114:115], v[112:113], v[100:101]
	v_pk_add_f32 v[80:81], v[80:81], v[84:85]
	v_pk_add_f32 v[84:85], v[90:91], v[92:93]
	v_mov_b32_e32 v125, v115
	v_pk_add_f32 v[116:117], v[114:115], v[84:85]
	v_mov_b32_e32 v122, v84
	v_mov_b32_e32 v123, v117
	v_pk_add_f32 v[122:123], v[122:123], v[124:125] neg_lo:[0,1] neg_hi:[0,1]
	v_mov_b32_e32 v118, v116
	v_mov_b32_e32 v119, v115
	v_mov_b32_e32 v120, v114
	v_mov_b32_e32 v124, v114
	v_mov_b32_e32 v125, v117
	v_mov_b32_e32 v113, v123
	v_pk_add_f32 v[118:119], v[118:119], v[120:121] neg_lo:[0,1] neg_hi:[0,1]
	v_mov_b32_e32 v120, v84
	v_mov_b32_e32 v121, v101
	v_pk_add_f32 v[112:113], v[124:125], v[112:113] neg_lo:[0,1] neg_hi:[0,1]
	v_pk_add_f32 v[120:121], v[120:121], v[118:119] neg_lo:[0,1] neg_hi:[0,1]
	v_mov_b32_e32 v124, v112
	v_mov_b32_e32 v125, v119
	v_mov_b32_e32 v126, v116
	v_mov_b32_e32 v127, v85
	v_mov_b32_e32 v119, v91
	v_pk_add_f32 v[124:125], v[100:101], v[124:125] neg_lo:[0,1] neg_hi:[0,1]
	v_pk_add_f32 v[118:119], v[126:127], v[118:119] neg_lo:[0,1] neg_hi:[0,1]
	v_mov_b32_e32 v101, v115
	v_pk_add_f32 v[84:85], v[84:85], v[90:91] neg_lo:[0,1] neg_hi:[0,1]
	v_pk_add_f32 v[86:87], v[86:87], v[118:119] neg_lo:[0,1] neg_hi:[0,1]
	v_pk_add_f32 v[90:91], v[100:101], v[112:113] neg_lo:[0,1] neg_hi:[0,1]
	v_pk_add_f32 v[80:81], v[80:81], v[122:123] neg_lo:[0,1] neg_hi:[0,1]
	v_pk_add_f32 v[84:85], v[92:93], v[84:85] neg_lo:[0,1] neg_hi:[0,1]
	v_pk_add_f32 v[92:93], v[80:81], v[90:91]
	v_mov_b32_e32 v91, v121
	v_mov_b32_e32 v81, v87
	v_pk_add_f32 v[100:101], v[120:121], v[86:87]
	v_pk_add_f32 v[80:81], v[90:91], v[80:81]
	v_mov_b32_e32 v86, v92
	v_pk_add_f32 v[80:81], v[80:81], v[124:125] neg_lo:[0,1] neg_hi:[0,1]
	v_mov_b32_e32 v87, v101
	v_pk_add_f32 v[86:87], v[86:87], v[80:81] neg_lo:[0,1] neg_hi:[0,1]
	v_pk_add_f32 v[80:81], v[84:85], v[80:81] neg_lo:[0,1] neg_hi:[0,1]
	v_pk_add_f32 v[86:87], v[90:91], v[86:87] neg_lo:[0,1] neg_hi:[0,1]
	v_pk_add_f32 v[84:85], v[100:101], v[92:93]
	v_pk_add_f32 v[80:81], v[80:81], v[86:87]
	v_pk_add_f32 v[86:87], v[116:117], v[84:85]
	v_cndmask_b32_e64 v69, v69, v89, s[60:61]
	v_pk_add_f32 v[90:91], v[86:87], v[116:117] neg_lo:[0,1] neg_hi:[0,1]
	v_mov_b32_e32 v89, v111
	v_pk_add_f32 v[84:85], v[84:85], v[90:91] neg_lo:[0,1] neg_hi:[0,1]
	v_lshlrev_b64 v[68:69], 6, v[68:69]
	v_pk_add_f32 v[80:81], v[80:81], v[84:85]
	v_lshl_add_u64 v[68:69], s[6:7], 0, v[68:69]
	v_pk_add_f32 v[80:81], v[86:87], v[80:81]
	v_pk_mul_f32 v[86:87], v[98:99], v[102:103]
	v_cndmask_b32_e32 v80, v160, v80, vcc
	v_cmp_neq_f32_e32 vcc, s8, v128
	v_pk_add_f32 v[90:91], v[94:95], v[86:87]
	v_lshl_add_u64 v[68:69], v[68:69], 0, v[0:1]
	v_cndmask_b32_e32 v81, v160, v81, vcc
	v_cmp_ngt_f32_e32 vcc, -1.0, v128
	v_pk_add_f32 v[94:95], v[90:91], v[94:95] neg_lo:[0,1] neg_hi:[0,1]
	v_mov_b32_e32 v114, v90
	v_cndmask_b32_e32 v81, v161, v81, vcc
	v_cmp_ngt_f32_e32 vcc, -1.0, v83
; __device__ __forceinline__ float softplusf(float x) { return fmaxf(x, 0.f) + log1pf(__expf(-fabsf(x))); }
; __device__ __forceinline__ float logsigf(float x) { return fminf(x, 0.f) - log1pf(__expf(-fabsf(x))); }
; __device__ void phaseA_tile(const Params& p, int l, int mt, int nt, char* smem) {
;     ...
;             for (int i = 0; i < 4; ++i) {
;                 const int rl = wr * 64 + i * 16 + r;
;                 const int row = m0 + rl;
; #pragma unroll
;                 for (int j = 0; j < 2; ++j) {
;                     const int c = j * 16 + g4 * 4;
;                     const float4 db = *(const float4*)(p.dt_bias + l * 32 + c);
;                     const f32x4 v = acc[i][j];
;                     *(float4*)(p.dtb + (size_t)row * 32 + c) =
;                         make_float4(softplusf(v[0] + db.x), softplusf(v[1] + db.y), softplusf(v[2] + db.z), softplusf(v[3] + db.w));
;                 }
;                 {
;                     const int c = g4 * 4;
;                     const float4 fb = *(const float4*)(p.b_f + l * 16 + c);
;                     const f32x4 v = acc[i][2];
;                     float4 lf = make_float4(logsigf(v[0] + fb.x), logsigf(v[1] + fb.y), logsigf(v[2] + fb.z), logsigf(v[3] + fb.w));
;                     float* o = samp ? (p.out + O_LFS + ((size_t)l * TSM + (row - TP)) * 16 + c)
;                                     : (p.out + O_LFP + ((size_t)l * TP + row) * 16 + c);
;                     *(float4*)o = lf;
;                     *(float4*)(lf_s + rl * 16 + c) = lf;
;                 }
	v_pk_add_f32 v[86:87], v[86:87], v[94:95] neg_lo:[0,1] neg_hi:[0,1]
	s_nop 0
	v_cndmask_b32_e32 v80, v161, v80, vcc
	v_cmp_neq_f32_e32 vcc, -1.0, v83
	v_pk_add_f32 v[98:99], v[88:89], v[86:87]
	v_mov_b32_e32 v95, v87
	v_cndmask_b32_e32 v80, v162, v80, vcc
	v_cmp_neq_f32_e32 vcc, -1.0, v128
	v_mov_b32_e32 v89, v99
	v_mov_b32_e32 v87, v91
	v_cndmask_b32_e32 v81, v162, v81, vcc
	v_cmp_lt_f32_e64 vcc, |v83|, s9
	v_cndmask_b32_e64 v81, v81, v128, s[0:1]
	v_pk_add_f32 v[86:87], v[88:89], v[86:87]
	v_cndmask_b32_e32 v80, v80, v83, vcc
	v_pk_add_f32 v[76:77], v[76:77], v[80:81] neg_lo:[0,1] neg_hi:[0,1]
	v_cvt_f32_i32_e32 v81, v132
	v_cvt_f32_i32_e32 v80, v130
	v_pk_add_f32 v[88:89], v[90:91], v[98:99]
	v_cmp_neq_f32_e32 vcc, s8, v129
	v_mov_b32_e32 v112, v88
	v_pk_mul_f32 v[84:85], v[80:81], s[12:13] op_sel_hi:[1,0]
	v_mov_b32_e32 v117, v89
	v_pk_fma_f32 v[92:93], v[80:81], s[12:13], v[84:85] op_sel_hi:[1,0,1] neg_lo:[0,0,1] neg_hi:[0,0,1]
	v_mov_b32_e32 v94, v84
	v_pk_fma_f32 v[80:81], v[80:81], s[14:15], v[92:93] op_sel_hi:[1,0,1]
	v_cmp_lt_f32_e64 s[0:1], |v131|, s9
	v_pk_add_f32 v[92:93], v[84:85], v[80:81]
	v_mov_b32_e32 v110, v80
	v_pk_add_f32 v[100:101], v[92:93], v[88:89]
	v_mov_b32_e32 v115, v93
	v_mov_b32_e32 v113, v101
	v_pk_add_f32 v[112:113], v[112:113], v[114:115] neg_lo:[0,1] neg_hi:[0,1]
	v_pk_add_f32 v[94:95], v[94:95], v[110:111]
	v_mov_b32_e32 v102, v100
	v_mov_b32_e32 v103, v93
	v_mov_b32_e32 v110, v92
	v_mov_b32_e32 v111, v85
	v_mov_b32_e32 v114, v92
	v_mov_b32_e32 v115, v101
	v_mov_b32_e32 v85, v113
	v_pk_add_f32 v[102:103], v[102:103], v[110:111] neg_lo:[0,1] neg_hi:[0,1]
	v_mov_b32_e32 v110, v88
	v_mov_b32_e32 v111, v81
	v_pk_add_f32 v[84:85], v[114:115], v[84:85] neg_lo:[0,1] neg_hi:[0,1]
	v_pk_add_f32 v[110:111], v[110:111], v[102:103] neg_lo:[0,1] neg_hi:[0,1]
	v_mov_b32_e32 v114, v84
	v_mov_b32_e32 v115, v103
	v_mov_b32_e32 v116, v100
	v_mov_b32_e32 v103, v91
	v_pk_add_f32 v[114:115], v[80:81], v[114:115] neg_lo:[0,1] neg_hi:[0,1]
	v_pk_add_f32 v[102:103], v[116:117], v[102:103] neg_lo:[0,1] neg_hi:[0,1]
	v_mov_b32_e32 v81, v93
	v_pk_add_f32 v[88:89], v[88:89], v[90:91] neg_lo:[0,1] neg_hi:[0,1]
	v_pk_add_f32 v[90:91], v[94:95], v[102:103] neg_lo:[0,1] neg_hi:[0,1]
	v_pk_add_f32 v[80:81], v[80:81], v[84:85] neg_lo:[0,1] neg_hi:[0,1]
	v_pk_add_f32 v[84:85], v[86:87], v[112:113] neg_lo:[0,1] neg_hi:[0,1]
	v_pk_add_f32 v[92:93], v[110:111], v[90:91]
	v_pk_add_f32 v[86:87], v[84:85], v[80:81]
	v_mov_b32_e32 v81, v111
	v_mov_b32_e32 v85, v91
	v_pk_add_f32 v[84:85], v[80:81], v[84:85]
	v_mov_b32_e32 v90, v86
	v_pk_add_f32 v[84:85], v[84:85], v[114:115] neg_lo:[0,1] neg_hi:[0,1]
	v_mov_b32_e32 v91, v93
	v_pk_add_f32 v[88:89], v[98:99], v[88:89] neg_lo:[0,1] neg_hi:[0,1]
	v_pk_add_f32 v[90:91], v[90:91], v[84:85] neg_lo:[0,1] neg_hi:[0,1]
	v_pk_add_f32 v[84:85], v[88:89], v[84:85] neg_lo:[0,1] neg_hi:[0,1]
	v_pk_add_f32 v[80:81], v[80:81], v[90:91] neg_lo:[0,1] neg_hi:[0,1]
	s_nop 0
	v_pk_add_f32 v[80:81], v[84:85], v[80:81]
	v_pk_add_f32 v[84:85], v[92:93], v[86:87]
	s_nop 0
	v_pk_add_f32 v[86:87], v[100:101], v[84:85]
	s_nop 0
	v_pk_add_f32 v[88:89], v[86:87], v[100:101] neg_lo:[0,1] neg_hi:[0,1]
	s_nop 0
	v_pk_add_f32 v[84:85], v[84:85], v[88:89] neg_lo:[0,1] neg_hi:[0,1]
	s_nop 0
	v_pk_add_f32 v[80:81], v[80:81], v[84:85]
	s_nop 0
	v_pk_add_f32 v[80:81], v[86:87], v[80:81]
	s_nop 0
	v_cndmask_b32_e32 v80, v160, v80, vcc
	v_cmp_neq_f32_e32 vcc, s8, v131
	s_nop 1
	v_cndmask_b32_e32 v81, v160, v81, vcc
	v_cmp_ngt_f32_e32 vcc, -1.0, v131
	s_nop 1
	v_cndmask_b32_e32 v81, v161, v81, vcc
	v_cmp_ngt_f32_e32 vcc, -1.0, v129
	s_nop 1
	v_cndmask_b32_e32 v80, v161, v80, vcc
	v_cmp_neq_f32_e32 vcc, -1.0, v129
	s_nop 1
	v_cndmask_b32_e32 v80, v162, v80, vcc
	v_cmp_neq_f32_e32 vcc, -1.0, v131
	s_nop 1
	v_cndmask_b32_e32 v81, v162, v81, vcc
	v_cmp_lt_f32_e64 vcc, |v129|, s9
	v_cndmask_b32_e64 v81, v81, v131, s[0:1]
	s_nop 0
	v_cndmask_b32_e32 v80, v80, v129, vcc
	v_pk_add_f32 v[78:79], v[78:79], v[80:81] neg_lo:[0,1] neg_hi:[0,1]
	global_store_dwordx4 v[68:69], v[76:79], off
	v_lshl_or_b32 v68, v82, 6, v0
	ds_write_b128 v68, v[76:79]
	global_load_dwordx4 v[78:81], v0, s[74:75]
	v_or_b32_e32 v82, 32, v71
	v_add_u32_e32 v68, s54, v82
	v_ashrrev_i32_e32 v69, 31, v68
	v_lshlrev_b64 v[76:77], 7, v[68:69]
	v_lshl_add_u64 v[76:77], s[10:11], 0, v[76:77]
	v_lshl_add_u64 v[76:77], v[76:77], 0, v[0:1]
	v_or_b32_e32 v71, 48, v71
	s_waitcnt vmcnt(0)
; __device__ __forceinline__ float softplusf(float x) { return fmaxf(x, 0.f) + log1pf(__expf(-fabsf(x))); }
; __device__ void phaseA_tile(const Params& p, int l, int mt, int nt, char* smem) {
;     ...
;             for (int i = 0; i < 4; ++i) {
;                 const int rl = wr * 64 + i * 16 + r;
;                 const int row = m0 + rl;
; #pragma unroll
;                 for (int j = 0; j < 2; ++j) {
;                     const int c = j * 16 + g4 * 4;
;                     const float4 db = *(const float4*)(p.dt_bias + l * 32 + c);
;                     const f32x4 v = acc[i][j];
;                     *(float4*)(p.dtb + (size_t)row * 32 + c) =
;                         make_float4(softplusf(v[0] + db.x), softplusf(v[1] + db.y), softplusf(v[2] + db.z), softplusf(v[3] + db.w));
;                 }
	v_add_f32_e32 v83, v30, v78
	v_max_f32_e32 v78, 0, v83
	v_mul_f32_e64 v83, |v83|, s2
	v_exp_f32_e32 v83, v83
	s_nop 0
	v_add_f32_e32 v86, 1.0, v83
	v_add_f32_e32 v84, -1.0, v86
	v_sub_f32_e32 v85, v84, v86
	v_add_f32_e32 v85, 1.0, v85
	v_sub_f32_e32 v84, v83, v84
	v_add_f32_e32 v87, v84, v85
	v_frexp_mant_f32_e32 v84, v86
	v_cmp_gt_f32_e32 vcc, s26, v84
	v_cvt_f64_f32_e32 v[84:85], v86
	v_frexp_exp_i32_f64_e32 v84, v[84:85]
	v_subbrev_co_u32_e32 v97, vcc, 0, v84, vcc
	v_sub_u32_e32 v85, 0, v97
	v_ldexp_f32 v84, v86, v85
	v_ldexp_f32 v86, v87, v85
	v_add_f32_e32 v85, v31, v79
	v_max_f32_e32 v79, 0, v85
	v_mul_f32_e64 v85, |v85|, s2
	v_exp_f32_e32 v130, v85
	s_nop 0
	v_add_f32_e32 v85, 1.0, v130
	v_add_f32_e32 v87, -1.0, v85
	v_sub_f32_e32 v88, v87, v85
	v_add_f32_e32 v88, 1.0, v88
	v_sub_f32_e32 v87, v130, v87
	v_add_f32_e32 v87, v87, v88
	v_frexp_mant_f32_e32 v88, v85
	v_cmp_gt_f32_e32 vcc, s26, v88
	v_cvt_f64_f32_e32 v[88:89], v85
	v_frexp_exp_i32_f64_e32 v88, v[88:89]
	v_subbrev_co_u32_e32 v122, vcc, 0, v88, vcc
	v_sub_u32_e32 v88, 0, v122
	v_ldexp_f32 v85, v85, v88
	v_ldexp_f32 v87, v87, v88
	v_pk_add_f32 v[88:89], v[84:85], 1.0 op_sel_hi:[1,0]
	v_pk_add_f32 v[98:99], v[84:85], -1.0 op_sel_hi:[1,0]
	v_pk_add_f32 v[90:91], v[88:89], -1.0 op_sel_hi:[1,0]
	v_pk_add_f32 v[100:101], v[98:99], 1.0 op_sel_hi:[1,0]
	v_pk_add_f32 v[90:91], v[84:85], v[90:91] neg_lo:[0,1] neg_hi:[0,1]
	v_pk_add_f32 v[84:85], v[84:85], v[100:101] neg_lo:[0,1] neg_hi:[0,1]
	v_pk_add_f32 v[90:91], v[86:87], v[90:91]
	v_pk_add_f32 v[84:85], v[86:87], v[84:85]
	v_pk_add_f32 v[92:93], v[88:89], v[90:91]
	v_pk_add_f32 v[86:87], v[98:99], v[84:85]
	v_rcp_f32_e32 v94, v92
	v_rcp_f32_e32 v95, v93
	v_pk_add_f32 v[88:89], v[92:93], v[88:89] neg_lo:[0,1] neg_hi:[0,1]
	v_pk_add_f32 v[98:99], v[86:87], v[98:99] neg_lo:[0,1] neg_hi:[0,1]
	v_pk_add_f32 v[88:89], v[90:91], v[88:89] neg_lo:[0,1] neg_hi:[0,1]
	v_pk_mul_f32 v[90:91], v[86:87], v[94:95]
	v_pk_add_f32 v[84:85], v[84:85], v[98:99] neg_lo:[0,1] neg_hi:[0,1]
	v_pk_mul_f32 v[98:99], v[92:93], v[90:91]
	v_cmp_lt_f32_e64 s[0:1], |v130|, s9
	v_pk_fma_f32 v[100:101], v[90:91], v[92:93], v[98:99] neg_lo:[0,0,1] neg_hi:[0,0,1]
	s_nop 0
	v_pk_fma_f32 v[100:101], v[90:91], v[88:89], v[100:101]
	s_nop 0
	v_pk_add_f32 v[102:103], v[98:99], v[100:101]
	s_nop 0
	v_pk_add_f32 v[110:111], v[86:87], v[102:103] neg_lo:[0,1] neg_hi:[0,1]
	v_pk_add_f32 v[98:99], v[102:103], v[98:99] neg_lo:[0,1] neg_hi:[0,1]
	v_pk_add_f32 v[86:87], v[86:87], v[110:111] neg_lo:[0,1] neg_hi:[0,1]
	s_nop 0
	v_pk_add_f32 v[86:87], v[86:87], v[102:103] neg_lo:[0,1] neg_hi:[0,1]
	s_nop 0
	v_pk_add_f32 v[84:85], v[84:85], v[86:87]
	v_pk_add_f32 v[86:87], v[98:99], v[100:101] neg_lo:[0,1] neg_hi:[0,1]
	s_nop 0
	v_pk_add_f32 v[84:85], v[86:87], v[84:85]
	s_nop 0
	v_pk_add_f32 v[86:87], v[110:111], v[84:85]
	s_nop 0
	v_pk_mul_f32 v[98:99], v[94:95], v[86:87]
	s_nop 0
	v_pk_mul_f32 v[100:101], v[92:93], v[98:99]
	s_nop 0
	v_pk_fma_f32 v[92:93], v[98:99], v[92:93], v[100:101] neg_lo:[0,0,1] neg_hi:[0,0,1]
	s_nop 0
	v_pk_fma_f32 v[88:89], v[98:99], v[88:89], v[92:93]
	v_pk_add_f32 v[92:93], v[110:111], v[86:87] neg_lo:[0,1] neg_hi:[0,1]
	s_nop 0
	v_pk_add_f32 v[84:85], v[84:85], v[92:93]
	v_pk_add_f32 v[92:93], v[100:101], v[88:89]
	s_nop 0
	v_pk_add_f32 v[102:103], v[86:87], v[92:93] neg_lo:[0,1] neg_hi:[0,1]
	v_pk_add_f32 v[100:101], v[92:93], v[100:101] neg_lo:[0,1] neg_hi:[0,1]
	v_pk_add_f32 v[86:87], v[86:87], v[102:103] neg_lo:[0,1] neg_hi:[0,1]
	s_nop 0
	v_pk_add_f32 v[86:87], v[86:87], v[92:93] neg_lo:[0,1] neg_hi:[0,1]
	s_nop 0
	v_pk_add_f32 v[84:85], v[84:85], v[86:87]
	v_pk_add_f32 v[86:87], v[100:101], v[88:89] neg_lo:[0,1] neg_hi:[0,1]
	s_nop 0
	v_pk_add_f32 v[84:85], v[86:87], v[84:85]
	v_pk_add_f32 v[86:87], v[90:91], v[98:99]
	v_pk_add_f32 v[84:85], v[102:103], v[84:85]
	v_pk_add_f32 v[88:89], v[86:87], v[90:91] neg_lo:[0,1] neg_hi:[0,1]
	v_pk_mul_f32 v[84:85], v[94:95], v[84:85]
	v_pk_add_f32 v[88:89], v[98:99], v[88:89] neg_lo:[0,1] neg_hi:[0,1]
	s_nop 0
	v_pk_add_f32 v[84:85], v[88:89], v[84:85]
	s_nop 0
	v_pk_add_f32 v[88:89], v[86:87], v[84:85]
	s_nop 0
	v_pk_add_f32 v[86:87], v[88:89], v[86:87] neg_lo:[0,1] neg_hi:[0,1]
	v_pk_mul_f32 v[90:91], v[88:89], v[88:89]
	v_pk_add_f32 v[84:85], v[84:85], v[86:87] neg_lo:[0,1] neg_hi:[0,1]
	v_pk_fma_f32 v[92:93], v[90:91], s[28:29], v[66:67] op_sel_hi:[1,0,0]
	v_ldexp_f32 v95, v85, 1
	v_add_f32_e32 v85, v32, v80
	v_max_f32_e32 v80, 0, v85
	v_mul_f32_e64 v85, |v85|, s2
	v_exp_f32_e32 v131, v85
	v_ldexp_f32 v86, v88, 1
	v_pk_fma_f32 v[92:93], v[90:91], v[92:93], s[30:31] op_sel_hi:[1,1,0]
	v_ldexp_f32 v87, v89, 1
	v_add_f32_e32 v85, 1.0, v131
	v_pk_mul_f32 v[88:89], v[88:89], v[90:91]
	v_add_f32_e32 v90, -1.0, v85
	v_sub_f32_e32 v91, v90, v85
	v_add_f32_e32 v91, 1.0, v91
	v_sub_f32_e32 v90, v131, v90
	v_add_f32_e32 v94, v90, v91
	v_frexp_mant_f32_e32 v90, v85
	v_cmp_gt_f32_e32 vcc, s26, v90
	v_cvt_f64_f32_e32 v[90:91], v85
	v_frexp_exp_i32_f64_e32 v90, v[90:91]
	v_subbrev_co_u32_e32 v132, vcc, 0, v90, vcc
	v_sub_u32_e32 v91, 0, v132
	v_ldexp_f32 v90, v85, v91
	v_add_f32_e32 v85, v33, v81
	v_max_f32_e32 v81, 0, v85
	v_mul_f32_e64 v85, |v85|, s2
	v_exp_f32_e32 v133, v85
	v_ldexp_f32 v98, v94, v91
	v_pk_mul_f32 v[88:89], v[88:89], v[92:93]
	v_ldexp_f32 v84, v84, 1
	v_add_f32_e32 v85, 1.0, v133
	v_add_f32_e32 v91, -1.0, v85
	v_sub_f32_e32 v94, v91, v85
	v_add_f32_e32 v94, 1.0, v94
	v_sub_f32_e32 v91, v133, v91
	v_add_f32_e32 v94, v91, v94
	v_frexp_mant_f32_e32 v91, v85
	v_cvt_f64_f32_e32 v[100:101], v85
	v_cmp_gt_f32_e32 vcc, s26, v91
	v_frexp_exp_i32_f64_e32 v91, v[100:101]
	v_pk_add_f32 v[92:93], v[86:87], v[88:89]
; __device__ __forceinline__ float softplusf(float x) { return fmaxf(x, 0.f) + log1pf(__expf(-fabsf(x))); }
; __device__ void phaseA_tile(const Params& p, int l, int mt, int nt, char* smem) {
;     ...
;             for (int i = 0; i < 4; ++i) {
;                 const int rl = wr * 64 + i * 16 + r;
;                 const int row = m0 + rl;
; #pragma unroll
;                 for (int j = 0; j < 2; ++j) {
;                     const int c = j * 16 + g4 * 4;
;                     const float4 db = *(const float4*)(p.dt_bias + l * 32 + c);
;                     const f32x4 v = acc[i][j];
;                     *(float4*)(p.dtb + (size_t)row * 32 + c) =
;                         make_float4(softplusf(v[0] + db.x), softplusf(v[1] + db.y), softplusf(v[2] + db.z), softplusf(v[3] + db.w));
;                 }
	v_subbrev_co_u32_e32 v134, vcc, 0, v91, vcc
	v_sub_u32_e32 v99, 0, v134
	v_ldexp_f32 v91, v85, v99
	v_pk_add_f32 v[100:101], v[90:91], 1.0 op_sel_hi:[1,0]
	v_ldexp_f32 v99, v94, v99
	v_pk_add_f32 v[102:103], v[100:101], -1.0 op_sel_hi:[1,0]
	v_pk_add_f32 v[114:115], v[90:91], -1.0 op_sel_hi:[1,0]
	v_pk_add_f32 v[102:103], v[90:91], v[102:103] neg_lo:[0,1] neg_hi:[0,1]
	v_pk_add_f32 v[116:117], v[114:115], 1.0 op_sel_hi:[1,0]
	v_pk_add_f32 v[102:103], v[98:99], v[102:103]
	v_pk_add_f32 v[90:91], v[90:91], v[116:117] neg_lo:[0,1] neg_hi:[0,1]
	v_pk_add_f32 v[110:111], v[100:101], v[102:103]
	v_pk_add_f32 v[90:91], v[98:99], v[90:91]
	v_rcp_f32_e32 v112, v110
	v_rcp_f32_e32 v113, v111
	v_pk_add_f32 v[98:99], v[114:115], v[90:91]
	v_pk_add_f32 v[100:101], v[110:111], v[100:101] neg_lo:[0,1] neg_hi:[0,1]
	v_pk_add_f32 v[114:115], v[98:99], v[114:115] neg_lo:[0,1] neg_hi:[0,1]
	v_pk_add_f32 v[100:101], v[102:103], v[100:101] neg_lo:[0,1] neg_hi:[0,1]
	v_pk_mul_f32 v[102:103], v[98:99], v[112:113]
	v_pk_add_f32 v[90:91], v[90:91], v[114:115] neg_lo:[0,1] neg_hi:[0,1]
	v_pk_mul_f32 v[114:115], v[110:111], v[102:103]
	v_pk_add_f32 v[86:87], v[92:93], v[86:87] neg_lo:[0,1] neg_hi:[0,1]
	v_pk_fma_f32 v[116:117], v[102:103], v[110:111], v[114:115] neg_lo:[0,0,1] neg_hi:[0,0,1]
	v_pk_add_f32 v[86:87], v[88:89], v[86:87] neg_lo:[0,1] neg_hi:[0,1]
	v_pk_fma_f32 v[116:117], v[102:103], v[100:101], v[116:117]
	v_mov_b32_e32 v89, v87
	v_pk_add_f32 v[118:119], v[114:115], v[116:117]
	v_mov_b32_e32 v85, v95
	v_pk_add_f32 v[120:121], v[98:99], v[118:119] neg_lo:[0,1] neg_hi:[0,1]
	v_pk_add_f32 v[114:115], v[118:119], v[114:115] neg_lo:[0,1] neg_hi:[0,1]
	v_pk_add_f32 v[98:99], v[98:99], v[120:121] neg_lo:[0,1] neg_hi:[0,1]
	v_mov_b32_e32 v126, v92
	v_pk_add_f32 v[98:99], v[98:99], v[118:119] neg_lo:[0,1] neg_hi:[0,1]
	v_cmp_neq_f32_e32 vcc, s8, v83
	v_pk_add_f32 v[90:91], v[90:91], v[98:99]
	v_pk_add_f32 v[98:99], v[114:115], v[116:117] neg_lo:[0,1] neg_hi:[0,1]
	s_nop 0
	v_pk_add_f32 v[90:91], v[98:99], v[90:91]
	s_nop 0
	v_pk_add_f32 v[98:99], v[120:121], v[90:91]
	s_nop 0
	v_pk_mul_f32 v[114:115], v[112:113], v[98:99]
	s_nop 0
	v_pk_mul_f32 v[116:117], v[110:111], v[114:115]
	s_nop 0
	v_pk_fma_f32 v[110:111], v[114:115], v[110:111], v[116:117] neg_lo:[0,0,1] neg_hi:[0,0,1]
	s_nop 0
	v_pk_fma_f32 v[100:101], v[114:115], v[100:101], v[110:111]
	v_pk_add_f32 v[110:111], v[120:121], v[98:99] neg_lo:[0,1] neg_hi:[0,1]
	s_nop 0
	v_pk_add_f32 v[90:91], v[90:91], v[110:111]
	v_pk_add_f32 v[110:111], v[116:117], v[100:101]
	s_nop 0
	v_pk_add_f32 v[118:119], v[98:99], v[110:111] neg_lo:[0,1] neg_hi:[0,1]
	v_pk_add_f32 v[116:117], v[110:111], v[116:117] neg_lo:[0,1] neg_hi:[0,1]
	v_pk_add_f32 v[98:99], v[98:99], v[118:119] neg_lo:[0,1] neg_hi:[0,1]
	s_nop 0
	v_pk_add_f32 v[98:99], v[98:99], v[110:111] neg_lo:[0,1] neg_hi:[0,1]
	s_nop 0
	v_pk_add_f32 v[90:91], v[90:91], v[98:99]
	v_pk_add_f32 v[98:99], v[116:117], v[100:101] neg_lo:[0,1] neg_hi:[0,1]
	s_nop 0
	v_pk_add_f32 v[90:91], v[98:99], v[90:91]
	v_pk_add_f32 v[98:99], v[102:103], v[114:115]
	v_pk_add_f32 v[90:91], v[118:119], v[90:91]
	v_pk_add_f32 v[100:101], v[98:99], v[102:103] neg_lo:[0,1] neg_hi:[0,1]
	v_pk_mul_f32 v[90:91], v[112:113], v[90:91]
	v_pk_add_f32 v[100:101], v[114:115], v[100:101] neg_lo:[0,1] neg_hi:[0,1]
	s_nop 0
	v_pk_add_f32 v[90:91], v[100:101], v[90:91]
	s_nop 0
	v_pk_add_f32 v[100:101], v[98:99], v[90:91]
	s_nop 0
	v_pk_mul_f32 v[102:103], v[100:101], v[100:101]
	v_pk_add_f32 v[98:99], v[100:101], v[98:99] neg_lo:[0,1] neg_hi:[0,1]
	v_pk_fma_f32 v[110:111], v[102:103], s[28:29], v[66:67] op_sel_hi:[1,0,0]
	v_pk_add_f32 v[90:91], v[90:91], v[98:99] neg_lo:[0,1] neg_hi:[0,1]
	v_ldexp_f32 v98, v100, 1
	v_pk_fma_f32 v[110:111], v[102:103], v[110:111], s[30:31] op_sel_hi:[1,1,0]
	v_ldexp_f32 v99, v101, 1
	v_pk_mul_f32 v[100:101], v[100:101], v[102:103]
	v_cvt_f32_i32_e32 v103, v122
	v_cvt_f32_i32_e32 v102, v97
	v_ldexp_f32 v113, v91, 1
	v_ldexp_f32 v90, v90, 1
	v_mov_b32_e32 v91, v113
	v_pk_mul_f32 v[114:115], v[102:103], s[12:13] op_sel_hi:[1,0]
	s_nop 0
	v_pk_fma_f32 v[116:117], v[102:103], s[12:13], v[114:115] op_sel_hi:[1,0,1] neg_lo:[0,0,1] neg_hi:[0,0,1]
	v_mov_b32_e32 v88, v114
	v_pk_fma_f32 v[102:103], v[102:103], s[14:15], v[116:117] op_sel_hi:[1,0,1]
	v_mov_b32_e32 v123, v115
	v_mov_b32_e32 v94, v102
	v_pk_add_f32 v[88:89], v[88:89], v[94:95]
	v_pk_add_f32 v[94:95], v[84:85], v[86:87]
	v_mov_b32_e32 v87, v93
	v_mov_b32_e32 v85, v95
	v_pk_add_f32 v[116:117], v[114:115], v[102:103]
	v_pk_add_f32 v[84:85], v[84:85], v[86:87]
	v_pk_add_f32 v[86:87], v[92:93], v[94:95]
	v_mov_b32_e32 v127, v117
	v_pk_add_f32 v[118:119], v[116:117], v[86:87]
	v_mov_b32_e32 v124, v86
	v_mov_b32_e32 v125, v119
	v_pk_add_f32 v[124:125], v[124:125], v[126:127] neg_lo:[0,1] neg_hi:[0,1]
	v_mov_b32_e32 v120, v118
	v_mov_b32_e32 v121, v117
	v_mov_b32_e32 v122, v116
	v_mov_b32_e32 v126, v116
	v_mov_b32_e32 v127, v119
	v_mov_b32_e32 v115, v125
	v_pk_add_f32 v[120:121], v[120:121], v[122:123] neg_lo:[0,1] neg_hi:[0,1]
	v_mov_b32_e32 v122, v86
	v_mov_b32_e32 v123, v103
	v_pk_add_f32 v[114:115], v[126:127], v[114:115] neg_lo:[0,1] neg_hi:[0,1]
	v_pk_add_f32 v[122:123], v[122:123], v[120:121] neg_lo:[0,1] neg_hi:[0,1]
	v_mov_b32_e32 v126, v114
	v_mov_b32_e32 v127, v121
	v_mov_b32_e32 v128, v118
	v_mov_b32_e32 v129, v87
	v_mov_b32_e32 v121, v93
	v_pk_add_f32 v[126:127], v[102:103], v[126:127] neg_lo:[0,1] neg_hi:[0,1]
	v_pk_add_f32 v[120:121], v[128:129], v[120:121] neg_lo:[0,1] neg_hi:[0,1]
	v_mov_b32_e32 v103, v117
	v_pk_add_f32 v[86:87], v[86:87], v[92:93] neg_lo:[0,1] neg_hi:[0,1]
; __device__ __forceinline__ float softplusf(float x) { return fmaxf(x, 0.f) + log1pf(__expf(-fabsf(x))); }
; __device__ void phaseA_tile(const Params& p, int l, int mt, int nt, char* smem) {
;     ...
;             for (int i = 0; i < 4; ++i) {
;                 const int rl = wr * 64 + i * 16 + r;
;                 const int row = m0 + rl;
; #pragma unroll
;                 for (int j = 0; j < 2; ++j) {
;                     const int c = j * 16 + g4 * 4;
;                     const float4 db = *(const float4*)(p.dt_bias + l * 32 + c);
;                     const f32x4 v = acc[i][j];
;                     *(float4*)(p.dtb + (size_t)row * 32 + c) =
;                         make_float4(softplusf(v[0] + db.x), softplusf(v[1] + db.y), softplusf(v[2] + db.z), softplusf(v[3] + db.w));
;                 }
	v_pk_add_f32 v[88:89], v[88:89], v[120:121] neg_lo:[0,1] neg_hi:[0,1]
	v_pk_add_f32 v[92:93], v[102:103], v[114:115] neg_lo:[0,1] neg_hi:[0,1]
	v_pk_add_f32 v[84:85], v[84:85], v[124:125] neg_lo:[0,1] neg_hi:[0,1]
	v_pk_add_f32 v[86:87], v[94:95], v[86:87] neg_lo:[0,1] neg_hi:[0,1]
	v_pk_add_f32 v[94:95], v[84:85], v[92:93]
	v_mov_b32_e32 v93, v123
	v_mov_b32_e32 v85, v89
	v_pk_add_f32 v[102:103], v[122:123], v[88:89]
	v_pk_add_f32 v[84:85], v[92:93], v[84:85]
	v_mov_b32_e32 v88, v94
	v_pk_add_f32 v[84:85], v[84:85], v[126:127] neg_lo:[0,1] neg_hi:[0,1]
	v_mov_b32_e32 v89, v103
	v_pk_add_f32 v[88:89], v[88:89], v[84:85] neg_lo:[0,1] neg_hi:[0,1]
	v_pk_add_f32 v[84:85], v[86:87], v[84:85] neg_lo:[0,1] neg_hi:[0,1]
	v_pk_add_f32 v[88:89], v[92:93], v[88:89] neg_lo:[0,1] neg_hi:[0,1]
	v_pk_add_f32 v[86:87], v[102:103], v[94:95]
	v_pk_add_f32 v[84:85], v[84:85], v[88:89]
	v_pk_add_f32 v[88:89], v[118:119], v[86:87]
	s_nop 0
	v_pk_add_f32 v[92:93], v[88:89], v[118:119] neg_lo:[0,1] neg_hi:[0,1]
	s_nop 0
	v_pk_add_f32 v[86:87], v[86:87], v[92:93] neg_lo:[0,1] neg_hi:[0,1]
	s_nop 0
	v_pk_add_f32 v[84:85], v[84:85], v[86:87]
	s_nop 0
	v_pk_add_f32 v[84:85], v[88:89], v[84:85]
	v_pk_mul_f32 v[88:89], v[100:101], v[110:111]
	v_cndmask_b32_e32 v84, v160, v84, vcc
	v_cmp_neq_f32_e32 vcc, s8, v130
	v_pk_add_f32 v[92:93], v[98:99], v[88:89]
	s_nop 0
	v_cndmask_b32_e32 v85, v160, v85, vcc
	v_cmp_ngt_f32_e32 vcc, -1.0, v130
	v_pk_add_f32 v[98:99], v[92:93], v[98:99] neg_lo:[0,1] neg_hi:[0,1]
	v_mov_b32_e32 v116, v92
	v_cndmask_b32_e32 v85, v161, v85, vcc
	v_cmp_ngt_f32_e32 vcc, -1.0, v83
	v_pk_add_f32 v[88:89], v[88:89], v[98:99] neg_lo:[0,1] neg_hi:[0,1]
	s_nop 0
	v_cndmask_b32_e32 v84, v161, v84, vcc
	v_cmp_neq_f32_e32 vcc, -1.0, v83
	v_pk_add_f32 v[100:101], v[90:91], v[88:89]
	v_mov_b32_e32 v99, v89
	v_cndmask_b32_e32 v84, v162, v84, vcc
	v_cmp_neq_f32_e32 vcc, -1.0, v130
	v_mov_b32_e32 v91, v101
	v_mov_b32_e32 v89, v93
	v_cndmask_b32_e32 v85, v162, v85, vcc
	v_cmp_lt_f32_e64 vcc, |v83|, s9
	v_cndmask_b32_e64 v85, v85, v130, s[0:1]
	v_pk_add_f32 v[88:89], v[90:91], v[88:89]
	v_cndmask_b32_e32 v84, v84, v83, vcc
	v_pk_add_f32 v[78:79], v[78:79], v[84:85]
	v_cvt_f32_i32_e32 v85, v134
	v_cvt_f32_i32_e32 v84, v132
	v_pk_add_f32 v[90:91], v[92:93], v[100:101]
	v_cmp_neq_f32_e32 vcc, s8, v131
	v_mov_b32_e32 v114, v90
	v_pk_mul_f32 v[86:87], v[84:85], s[12:13] op_sel_hi:[1,0]
	v_mov_b32_e32 v119, v91
	v_pk_fma_f32 v[94:95], v[84:85], s[12:13], v[86:87] op_sel_hi:[1,0,1] neg_lo:[0,0,1] neg_hi:[0,0,1]
	v_mov_b32_e32 v98, v86
	v_pk_fma_f32 v[84:85], v[84:85], s[14:15], v[94:95] op_sel_hi:[1,0,1]
	v_cmp_lt_f32_e64 s[0:1], |v133|, s9
	v_pk_add_f32 v[94:95], v[86:87], v[84:85]
	v_mov_b32_e32 v112, v84
	v_pk_add_f32 v[102:103], v[94:95], v[90:91]
	v_mov_b32_e32 v117, v95
	v_mov_b32_e32 v115, v103
	v_pk_add_f32 v[114:115], v[114:115], v[116:117] neg_lo:[0,1] neg_hi:[0,1]
	v_pk_add_f32 v[98:99], v[98:99], v[112:113]
	v_mov_b32_e32 v110, v102
	v_mov_b32_e32 v111, v95
	v_mov_b32_e32 v112, v94
	v_mov_b32_e32 v113, v87
	v_mov_b32_e32 v116, v94
	v_mov_b32_e32 v117, v103
	v_mov_b32_e32 v87, v115
	v_pk_add_f32 v[110:111], v[110:111], v[112:113] neg_lo:[0,1] neg_hi:[0,1]
	v_mov_b32_e32 v112, v90
	v_mov_b32_e32 v113, v85
	v_pk_add_f32 v[86:87], v[116:117], v[86:87] neg_lo:[0,1] neg_hi:[0,1]
	v_pk_add_f32 v[112:113], v[112:113], v[110:111] neg_lo:[0,1] neg_hi:[0,1]
	v_mov_b32_e32 v116, v86
	v_mov_b32_e32 v117, v111
	v_mov_b32_e32 v118, v102
	v_mov_b32_e32 v111, v93
	v_pk_add_f32 v[116:117], v[84:85], v[116:117] neg_lo:[0,1] neg_hi:[0,1]
	v_pk_add_f32 v[110:111], v[118:119], v[110:111] neg_lo:[0,1] neg_hi:[0,1]
	v_mov_b32_e32 v85, v95
	v_pk_add_f32 v[90:91], v[90:91], v[92:93] neg_lo:[0,1] neg_hi:[0,1]
	v_pk_add_f32 v[92:93], v[98:99], v[110:111] neg_lo:[0,1] neg_hi:[0,1]
	v_pk_add_f32 v[84:85], v[84:85], v[86:87] neg_lo:[0,1] neg_hi:[0,1]
	v_pk_add_f32 v[86:87], v[88:89], v[114:115] neg_lo:[0,1] neg_hi:[0,1]
	v_pk_add_f32 v[94:95], v[112:113], v[92:93]
	v_pk_add_f32 v[88:89], v[86:87], v[84:85]
	v_mov_b32_e32 v85, v113
	v_mov_b32_e32 v87, v93
	v_pk_add_f32 v[86:87], v[84:85], v[86:87]
	v_mov_b32_e32 v92, v88
	v_pk_add_f32 v[86:87], v[86:87], v[116:117] neg_lo:[0,1] neg_hi:[0,1]
	v_mov_b32_e32 v93, v95
	v_pk_add_f32 v[90:91], v[100:101], v[90:91] neg_lo:[0,1] neg_hi:[0,1]
	v_pk_add_f32 v[92:93], v[92:93], v[86:87] neg_lo:[0,1] neg_hi:[0,1]
	v_pk_add_f32 v[86:87], v[90:91], v[86:87] neg_lo:[0,1] neg_hi:[0,1]
	v_pk_add_f32 v[84:85], v[84:85], v[92:93] neg_lo:[0,1] neg_hi:[0,1]
	s_nop 0
	v_pk_add_f32 v[84:85], v[86:87], v[84:85]
	v_pk_add_f32 v[86:87], v[94:95], v[88:89]
	s_nop 0
	v_pk_add_f32 v[88:89], v[102:103], v[86:87]
	s_nop 0
	v_pk_add_f32 v[90:91], v[88:89], v[102:103] neg_lo:[0,1] neg_hi:[0,1]
	s_nop 0
	v_pk_add_f32 v[86:87], v[86:87], v[90:91] neg_lo:[0,1] neg_hi:[0,1]
	s_nop 0
	v_pk_add_f32 v[84:85], v[84:85], v[86:87]
	s_nop 0
	v_pk_add_f32 v[84:85], v[88:89], v[84:85]
	s_nop 0
	v_cndmask_b32_e32 v83, v160, v84, vcc
	v_cmp_neq_f32_e32 vcc, s8, v133
	s_nop 1
	v_cndmask_b32_e32 v84, v160, v85, vcc
	v_cmp_ngt_f32_e32 vcc, -1.0, v133
	s_nop 1
	v_cndmask_b32_e32 v84, v161, v84, vcc
	v_cmp_ngt_f32_e32 vcc, -1.0, v131
	s_nop 1
	v_cndmask_b32_e32 v83, v161, v83, vcc
	v_cmp_neq_f32_e32 vcc, -1.0, v131
	s_nop 1
	v_cndmask_b32_e32 v83, v162, v83, vcc
	v_cmp_neq_f32_e32 vcc, -1.0, v133
	s_nop 1
	v_cndmask_b32_e32 v84, v162, v84, vcc
	v_cmp_lt_f32_e64 vcc, |v131|, s9
	v_cndmask_b32_e64 v85, v84, v133, s[0:1]
	s_nop 0
	v_cndmask_b32_e32 v84, v83, v131, vcc
	v_pk_add_f32 v[80:81], v[80:81], v[84:85]
	global_store_dwordx4 v[76:77], v[78:81], off
	global_load_dwordx4 v[78:81], v0, s[74:75] offset:64
	s_waitcnt vmcnt(0)
; __device__ __forceinline__ float softplusf(float x) { return fmaxf(x, 0.f) + log1pf(__expf(-fabsf(x))); }
; __device__ void phaseA_tile(const Params& p, int l, int mt, int nt, char* smem) {
;     ...
;             for (int i = 0; i < 4; ++i) {
;                 const int rl = wr * 64 + i * 16 + r;
;                 const int row = m0 + rl;
; #pragma unroll
;                 for (int j = 0; j < 2; ++j) {
;                     const int c = j * 16 + g4 * 4;
;                     const float4 db = *(const float4*)(p.dt_bias + l * 32 + c);
;                     const f32x4 v = acc[i][j];
;                     *(float4*)(p.dtb + (size_t)row * 32 + c) =
;                         make_float4(softplusf(v[0] + db.x), softplusf(v[1] + db.y), softplusf(v[2] + db.z), softplusf(v[3] + db.w));
;                 }
	v_add_f32_e32 v83, v26, v78
	v_max_f32_e32 v78, 0, v83
	v_mul_f32_e64 v83, |v83|, s2
	v_exp_f32_e32 v83, v83
	s_nop 0
	v_add_f32_e32 v86, 1.0, v83
	v_add_f32_e32 v84, -1.0, v86
	v_sub_f32_e32 v85, v84, v86
	v_add_f32_e32 v85, 1.0, v85
	v_sub_f32_e32 v84, v83, v84
	v_add_f32_e32 v87, v84, v85
	v_frexp_mant_f32_e32 v84, v86
	v_cmp_gt_f32_e32 vcc, s26, v84
	v_cvt_f64_f32_e32 v[84:85], v86
	v_frexp_exp_i32_f64_e32 v84, v[84:85]
	v_subbrev_co_u32_e32 v97, vcc, 0, v84, vcc
	v_sub_u32_e32 v85, 0, v97
	v_ldexp_f32 v84, v86, v85
	v_ldexp_f32 v86, v87, v85
	v_add_f32_e32 v85, v27, v79
	v_max_f32_e32 v79, 0, v85
	v_mul_f32_e64 v85, |v85|, s2
	v_exp_f32_e32 v130, v85
	s_nop 0
	v_add_f32_e32 v85, 1.0, v130
	v_add_f32_e32 v87, -1.0, v85
	v_sub_f32_e32 v88, v87, v85
	v_add_f32_e32 v88, 1.0, v88
	v_sub_f32_e32 v87, v130, v87
	v_add_f32_e32 v87, v87, v88
	v_frexp_mant_f32_e32 v88, v85
	v_cmp_gt_f32_e32 vcc, s26, v88
	v_cvt_f64_f32_e32 v[88:89], v85
	v_frexp_exp_i32_f64_e32 v88, v[88:89]
	v_subbrev_co_u32_e32 v122, vcc, 0, v88, vcc
	v_sub_u32_e32 v88, 0, v122
	v_ldexp_f32 v85, v85, v88
	v_ldexp_f32 v87, v87, v88
	v_pk_add_f32 v[88:89], v[84:85], 1.0 op_sel_hi:[1,0]
	v_pk_add_f32 v[98:99], v[84:85], -1.0 op_sel_hi:[1,0]
	v_pk_add_f32 v[90:91], v[88:89], -1.0 op_sel_hi:[1,0]
	v_pk_add_f32 v[100:101], v[98:99], 1.0 op_sel_hi:[1,0]
	v_pk_add_f32 v[90:91], v[84:85], v[90:91] neg_lo:[0,1] neg_hi:[0,1]
	v_pk_add_f32 v[84:85], v[84:85], v[100:101] neg_lo:[0,1] neg_hi:[0,1]
	v_pk_add_f32 v[90:91], v[86:87], v[90:91]
	v_pk_add_f32 v[84:85], v[86:87], v[84:85]
	v_pk_add_f32 v[92:93], v[88:89], v[90:91]
	v_pk_add_f32 v[86:87], v[98:99], v[84:85]
	v_rcp_f32_e32 v94, v92
	v_rcp_f32_e32 v95, v93
	v_pk_add_f32 v[88:89], v[92:93], v[88:89] neg_lo:[0,1] neg_hi:[0,1]
	v_pk_add_f32 v[98:99], v[86:87], v[98:99] neg_lo:[0,1] neg_hi:[0,1]
	v_pk_add_f32 v[88:89], v[90:91], v[88:89] neg_lo:[0,1] neg_hi:[0,1]
	v_pk_mul_f32 v[90:91], v[86:87], v[94:95]
	v_pk_add_f32 v[84:85], v[84:85], v[98:99] neg_lo:[0,1] neg_hi:[0,1]
	v_pk_mul_f32 v[98:99], v[92:93], v[90:91]
	v_cmp_lt_f32_e64 s[0:1], |v130|, s9
	v_pk_fma_f32 v[100:101], v[90:91], v[92:93], v[98:99] neg_lo:[0,0,1] neg_hi:[0,0,1]
	s_nop 0
	v_pk_fma_f32 v[100:101], v[90:91], v[88:89], v[100:101]
	s_nop 0
	v_pk_add_f32 v[102:103], v[98:99], v[100:101]
	s_nop 0
	v_pk_add_f32 v[110:111], v[86:87], v[102:103] neg_lo:[0,1] neg_hi:[0,1]
	v_pk_add_f32 v[98:99], v[102:103], v[98:99] neg_lo:[0,1] neg_hi:[0,1]
	v_pk_add_f32 v[86:87], v[86:87], v[110:111] neg_lo:[0,1] neg_hi:[0,1]
	s_nop 0
	v_pk_add_f32 v[86:87], v[86:87], v[102:103] neg_lo:[0,1] neg_hi:[0,1]
	s_nop 0
	v_pk_add_f32 v[84:85], v[84:85], v[86:87]
	v_pk_add_f32 v[86:87], v[98:99], v[100:101] neg_lo:[0,1] neg_hi:[0,1]
	s_nop 0
	v_pk_add_f32 v[84:85], v[86:87], v[84:85]
	s_nop 0
	v_pk_add_f32 v[86:87], v[110:111], v[84:85]
	s_nop 0
	v_pk_mul_f32 v[98:99], v[94:95], v[86:87]
	s_nop 0
	v_pk_mul_f32 v[100:101], v[92:93], v[98:99]
	s_nop 0
	v_pk_fma_f32 v[92:93], v[98:99], v[92:93], v[100:101] neg_lo:[0,0,1] neg_hi:[0,0,1]
	s_nop 0
	v_pk_fma_f32 v[88:89], v[98:99], v[88:89], v[92:93]
	v_pk_add_f32 v[92:93], v[110:111], v[86:87] neg_lo:[0,1] neg_hi:[0,1]
	s_nop 0
	v_pk_add_f32 v[84:85], v[84:85], v[92:93]
	v_pk_add_f32 v[92:93], v[100:101], v[88:89]
	s_nop 0
	v_pk_add_f32 v[102:103], v[86:87], v[92:93] neg_lo:[0,1] neg_hi:[0,1]
	v_pk_add_f32 v[100:101], v[92:93], v[100:101] neg_lo:[0,1] neg_hi:[0,1]
	v_pk_add_f32 v[86:87], v[86:87], v[102:103] neg_lo:[0,1] neg_hi:[0,1]
	s_nop 0
	v_pk_add_f32 v[86:87], v[86:87], v[92:93] neg_lo:[0,1] neg_hi:[0,1]
	s_nop 0
	v_pk_add_f32 v[84:85], v[84:85], v[86:87]
	v_pk_add_f32 v[86:87], v[100:101], v[88:89] neg_lo:[0,1] neg_hi:[0,1]
	s_nop 0
	v_pk_add_f32 v[84:85], v[86:87], v[84:85]
	v_pk_add_f32 v[86:87], v[90:91], v[98:99]
	v_pk_add_f32 v[84:85], v[102:103], v[84:85]
	v_pk_add_f32 v[88:89], v[86:87], v[90:91] neg_lo:[0,1] neg_hi:[0,1]
	v_pk_mul_f32 v[84:85], v[94:95], v[84:85]
	v_pk_add_f32 v[88:89], v[98:99], v[88:89] neg_lo:[0,1] neg_hi:[0,1]
	s_nop 0
	v_pk_add_f32 v[84:85], v[88:89], v[84:85]
	s_nop 0
	v_pk_add_f32 v[88:89], v[86:87], v[84:85]
	s_nop 0
	v_pk_add_f32 v[86:87], v[88:89], v[86:87] neg_lo:[0,1] neg_hi:[0,1]
	v_pk_mul_f32 v[90:91], v[88:89], v[88:89]
	v_pk_add_f32 v[84:85], v[84:85], v[86:87] neg_lo:[0,1] neg_hi:[0,1]
	v_pk_fma_f32 v[92:93], v[90:91], s[28:29], v[66:67] op_sel_hi:[1,0,0]
	v_ldexp_f32 v95, v85, 1
	v_add_f32_e32 v85, v28, v80
	v_max_f32_e32 v80, 0, v85
	v_mul_f32_e64 v85, |v85|, s2
	v_exp_f32_e32 v131, v85
	v_ldexp_f32 v86, v88, 1
	v_pk_fma_f32 v[92:93], v[90:91], v[92:93], s[30:31] op_sel_hi:[1,1,0]
	v_ldexp_f32 v87, v89, 1
	v_add_f32_e32 v85, 1.0, v131
	v_pk_mul_f32 v[88:89], v[88:89], v[90:91]
	v_add_f32_e32 v90, -1.0, v85
	v_sub_f32_e32 v91, v90, v85
	v_add_f32_e32 v91, 1.0, v91
	v_sub_f32_e32 v90, v131, v90
	v_add_f32_e32 v94, v90, v91
	v_frexp_mant_f32_e32 v90, v85
	v_cmp_gt_f32_e32 vcc, s26, v90
	v_cvt_f64_f32_e32 v[90:91], v85
	v_frexp_exp_i32_f64_e32 v90, v[90:91]
	v_subbrev_co_u32_e32 v132, vcc, 0, v90, vcc
	v_sub_u32_e32 v91, 0, v132
	v_ldexp_f32 v90, v85, v91
	v_add_f32_e32 v85, v29, v81
	v_max_f32_e32 v81, 0, v85
	v_mul_f32_e64 v85, |v85|, s2
	v_exp_f32_e32 v133, v85
	v_ldexp_f32 v98, v94, v91
	v_pk_mul_f32 v[88:89], v[88:89], v[92:93]
	v_ldexp_f32 v84, v84, 1
	v_add_f32_e32 v85, 1.0, v133
	v_add_f32_e32 v91, -1.0, v85
	v_sub_f32_e32 v94, v91, v85
	v_add_f32_e32 v94, 1.0, v94
	v_sub_f32_e32 v91, v133, v91
	v_add_f32_e32 v94, v91, v94
	v_frexp_mant_f32_e32 v91, v85
	v_cvt_f64_f32_e32 v[100:101], v85
	v_cmp_gt_f32_e32 vcc, s26, v91
	v_frexp_exp_i32_f64_e32 v91, v[100:101]
	v_pk_add_f32 v[92:93], v[86:87], v[88:89]
; __device__ __forceinline__ float softplusf(float x) { return fmaxf(x, 0.f) + log1pf(__expf(-fabsf(x))); }
; __device__ void phaseA_tile(const Params& p, int l, int mt, int nt, char* smem) {
;     ...
;             for (int i = 0; i < 4; ++i) {
;                 const int rl = wr * 64 + i * 16 + r;
;                 const int row = m0 + rl;
; #pragma unroll
;                 for (int j = 0; j < 2; ++j) {
;                     const int c = j * 16 + g4 * 4;
;                     const float4 db = *(const float4*)(p.dt_bias + l * 32 + c);
;                     const f32x4 v = acc[i][j];
;                     *(float4*)(p.dtb + (size_t)row * 32 + c) =
;                         make_float4(softplusf(v[0] + db.x), softplusf(v[1] + db.y), softplusf(v[2] + db.z), softplusf(v[3] + db.w));
;                 }
	v_subbrev_co_u32_e32 v134, vcc, 0, v91, vcc
	v_sub_u32_e32 v99, 0, v134
	v_ldexp_f32 v91, v85, v99
	v_pk_add_f32 v[100:101], v[90:91], 1.0 op_sel_hi:[1,0]
	v_ldexp_f32 v99, v94, v99
	v_pk_add_f32 v[102:103], v[100:101], -1.0 op_sel_hi:[1,0]
	v_pk_add_f32 v[114:115], v[90:91], -1.0 op_sel_hi:[1,0]
	v_pk_add_f32 v[102:103], v[90:91], v[102:103] neg_lo:[0,1] neg_hi:[0,1]
	v_pk_add_f32 v[116:117], v[114:115], 1.0 op_sel_hi:[1,0]
	v_pk_add_f32 v[102:103], v[98:99], v[102:103]
	v_pk_add_f32 v[90:91], v[90:91], v[116:117] neg_lo:[0,1] neg_hi:[0,1]
	v_pk_add_f32 v[110:111], v[100:101], v[102:103]
	v_pk_add_f32 v[90:91], v[98:99], v[90:91]
	v_rcp_f32_e32 v112, v110
	v_rcp_f32_e32 v113, v111
	v_pk_add_f32 v[98:99], v[114:115], v[90:91]
	v_pk_add_f32 v[100:101], v[110:111], v[100:101] neg_lo:[0,1] neg_hi:[0,1]
	v_pk_add_f32 v[114:115], v[98:99], v[114:115] neg_lo:[0,1] neg_hi:[0,1]
	v_pk_add_f32 v[100:101], v[102:103], v[100:101] neg_lo:[0,1] neg_hi:[0,1]
	v_pk_mul_f32 v[102:103], v[98:99], v[112:113]
	v_pk_add_f32 v[90:91], v[90:91], v[114:115] neg_lo:[0,1] neg_hi:[0,1]
	v_pk_mul_f32 v[114:115], v[110:111], v[102:103]
	v_pk_add_f32 v[86:87], v[92:93], v[86:87] neg_lo:[0,1] neg_hi:[0,1]
	v_pk_fma_f32 v[116:117], v[102:103], v[110:111], v[114:115] neg_lo:[0,0,1] neg_hi:[0,0,1]
	v_pk_add_f32 v[86:87], v[88:89], v[86:87] neg_lo:[0,1] neg_hi:[0,1]
	v_pk_fma_f32 v[116:117], v[102:103], v[100:101], v[116:117]
	v_mov_b32_e32 v89, v87
	v_pk_add_f32 v[118:119], v[114:115], v[116:117]
	v_mov_b32_e32 v85, v95
	v_pk_add_f32 v[120:121], v[98:99], v[118:119] neg_lo:[0,1] neg_hi:[0,1]
	v_pk_add_f32 v[114:115], v[118:119], v[114:115] neg_lo:[0,1] neg_hi:[0,1]
	v_pk_add_f32 v[98:99], v[98:99], v[120:121] neg_lo:[0,1] neg_hi:[0,1]
	v_mov_b32_e32 v126, v92
	v_pk_add_f32 v[98:99], v[98:99], v[118:119] neg_lo:[0,1] neg_hi:[0,1]
	v_cmp_neq_f32_e32 vcc, s8, v83
	v_pk_add_f32 v[90:91], v[90:91], v[98:99]
	v_pk_add_f32 v[98:99], v[114:115], v[116:117] neg_lo:[0,1] neg_hi:[0,1]
	s_nop 0
	v_pk_add_f32 v[90:91], v[98:99], v[90:91]
	s_nop 0
	v_pk_add_f32 v[98:99], v[120:121], v[90:91]
	s_nop 0
	v_pk_mul_f32 v[114:115], v[112:113], v[98:99]
	s_nop 0
	v_pk_mul_f32 v[116:117], v[110:111], v[114:115]
	s_nop 0
	v_pk_fma_f32 v[110:111], v[114:115], v[110:111], v[116:117] neg_lo:[0,0,1] neg_hi:[0,0,1]
	s_nop 0
	v_pk_fma_f32 v[100:101], v[114:115], v[100:101], v[110:111]
	v_pk_add_f32 v[110:111], v[120:121], v[98:99] neg_lo:[0,1] neg_hi:[0,1]
	s_nop 0
	v_pk_add_f32 v[90:91], v[90:91], v[110:111]
	v_pk_add_f32 v[110:111], v[116:117], v[100:101]
	s_nop 0
	v_pk_add_f32 v[118:119], v[98:99], v[110:111] neg_lo:[0,1] neg_hi:[0,1]
	v_pk_add_f32 v[116:117], v[110:111], v[116:117] neg_lo:[0,1] neg_hi:[0,1]
	v_pk_add_f32 v[98:99], v[98:99], v[118:119] neg_lo:[0,1] neg_hi:[0,1]
	s_nop 0
	v_pk_add_f32 v[98:99], v[98:99], v[110:111] neg_lo:[0,1] neg_hi:[0,1]
	s_nop 0
	v_pk_add_f32 v[90:91], v[90:91], v[98:99]
	v_pk_add_f32 v[98:99], v[116:117], v[100:101] neg_lo:[0,1] neg_hi:[0,1]
	s_nop 0
	v_pk_add_f32 v[90:91], v[98:99], v[90:91]
	v_pk_add_f32 v[98:99], v[102:103], v[114:115]
	v_pk_add_f32 v[90:91], v[118:119], v[90:91]
	v_pk_add_f32 v[100:101], v[98:99], v[102:103] neg_lo:[0,1] neg_hi:[0,1]
	v_pk_mul_f32 v[90:91], v[112:113], v[90:91]
	v_pk_add_f32 v[100:101], v[114:115], v[100:101] neg_lo:[0,1] neg_hi:[0,1]
	s_nop 0
	v_pk_add_f32 v[90:91], v[100:101], v[90:91]
	s_nop 0
	v_pk_add_f32 v[100:101], v[98:99], v[90:91]
	s_nop 0
	v_pk_mul_f32 v[102:103], v[100:101], v[100:101]
	v_pk_add_f32 v[98:99], v[100:101], v[98:99] neg_lo:[0,1] neg_hi:[0,1]
	v_pk_fma_f32 v[110:111], v[102:103], s[28:29], v[66:67] op_sel_hi:[1,0,0]
	v_pk_add_f32 v[90:91], v[90:91], v[98:99] neg_lo:[0,1] neg_hi:[0,1]
	v_ldexp_f32 v98, v100, 1
	v_pk_fma_f32 v[110:111], v[102:103], v[110:111], s[30:31] op_sel_hi:[1,1,0]
	v_ldexp_f32 v99, v101, 1
	v_pk_mul_f32 v[100:101], v[100:101], v[102:103]
	v_cvt_f32_i32_e32 v103, v122
	v_cvt_f32_i32_e32 v102, v97
	v_ldexp_f32 v113, v91, 1
	v_ldexp_f32 v90, v90, 1
	v_mov_b32_e32 v91, v113
	v_pk_mul_f32 v[114:115], v[102:103], s[12:13] op_sel_hi:[1,0]
	s_nop 0
	v_pk_fma_f32 v[116:117], v[102:103], s[12:13], v[114:115] op_sel_hi:[1,0,1] neg_lo:[0,0,1] neg_hi:[0,0,1]
	v_mov_b32_e32 v88, v114
	v_pk_fma_f32 v[102:103], v[102:103], s[14:15], v[116:117] op_sel_hi:[1,0,1]
	v_mov_b32_e32 v123, v115
	v_mov_b32_e32 v94, v102
	v_pk_add_f32 v[88:89], v[88:89], v[94:95]
	v_pk_add_f32 v[94:95], v[84:85], v[86:87]
	v_mov_b32_e32 v87, v93
	v_mov_b32_e32 v85, v95
	v_pk_add_f32 v[116:117], v[114:115], v[102:103]
	v_pk_add_f32 v[84:85], v[84:85], v[86:87]
	v_pk_add_f32 v[86:87], v[92:93], v[94:95]
	v_mov_b32_e32 v127, v117
	v_pk_add_f32 v[118:119], v[116:117], v[86:87]
	v_mov_b32_e32 v124, v86
	v_mov_b32_e32 v125, v119
	v_pk_add_f32 v[124:125], v[124:125], v[126:127] neg_lo:[0,1] neg_hi:[0,1]
	v_mov_b32_e32 v120, v118
	v_mov_b32_e32 v121, v117
	v_mov_b32_e32 v122, v116
	v_mov_b32_e32 v126, v116
	v_mov_b32_e32 v127, v119
	v_mov_b32_e32 v115, v125
	v_pk_add_f32 v[120:121], v[120:121], v[122:123] neg_lo:[0,1] neg_hi:[0,1]
	v_mov_b32_e32 v122, v86
	v_mov_b32_e32 v123, v103
	v_pk_add_f32 v[114:115], v[126:127], v[114:115] neg_lo:[0,1] neg_hi:[0,1]
	v_pk_add_f32 v[122:123], v[122:123], v[120:121] neg_lo:[0,1] neg_hi:[0,1]
	v_mov_b32_e32 v126, v114
	v_mov_b32_e32 v127, v121
	v_mov_b32_e32 v128, v118
	v_mov_b32_e32 v129, v87
	v_mov_b32_e32 v121, v93
	v_pk_add_f32 v[126:127], v[102:103], v[126:127] neg_lo:[0,1] neg_hi:[0,1]
	v_pk_add_f32 v[120:121], v[128:129], v[120:121] neg_lo:[0,1] neg_hi:[0,1]
	v_mov_b32_e32 v103, v117
	v_pk_add_f32 v[86:87], v[86:87], v[92:93] neg_lo:[0,1] neg_hi:[0,1]
; __device__ __forceinline__ float softplusf(float x) { return fmaxf(x, 0.f) + log1pf(__expf(-fabsf(x))); }
; __device__ __forceinline__ float logsigf(float x) { return fminf(x, 0.f) - log1pf(__expf(-fabsf(x))); }
; __device__ void phaseA_tile(const Params& p, int l, int mt, int nt, char* smem) {
;     ...
;             for (int i = 0; i < 4; ++i) {
;                 const int rl = wr * 64 + i * 16 + r;
;                 const int row = m0 + rl;
; #pragma unroll
;                 for (int j = 0; j < 2; ++j) {
;                     const int c = j * 16 + g4 * 4;
;                     const float4 db = *(const float4*)(p.dt_bias + l * 32 + c);
;                     const f32x4 v = acc[i][j];
;                     *(float4*)(p.dtb + (size_t)row * 32 + c) =
;                         make_float4(softplusf(v[0] + db.x), softplusf(v[1] + db.y), softplusf(v[2] + db.z), softplusf(v[3] + db.w));
;                 }
;                 {
;                     const int c = g4 * 4;
;                     const float4 fb = *(const float4*)(p.b_f + l * 16 + c);
;                     const f32x4 v = acc[i][2];
;                     float4 lf = make_float4(logsigf(v[0] + fb.x), logsigf(v[1] + fb.y), logsigf(v[2] + fb.z), logsigf(v[3] + fb.w));
;                     float* o = samp ? (p.out + O_LFS + ((size_t)l * TSM + (row - TP)) * 16 + c)
;                                     : (p.out + O_LFP + ((size_t)l * TP + row) * 16 + c);
;                     *(float4*)o = lf;
;                     *(float4*)(lf_s + rl * 16 + c) = lf;
;                 }
	v_pk_add_f32 v[88:89], v[88:89], v[120:121] neg_lo:[0,1] neg_hi:[0,1]
	v_pk_add_f32 v[92:93], v[102:103], v[114:115] neg_lo:[0,1] neg_hi:[0,1]
	v_pk_add_f32 v[84:85], v[84:85], v[124:125] neg_lo:[0,1] neg_hi:[0,1]
	v_pk_add_f32 v[86:87], v[94:95], v[86:87] neg_lo:[0,1] neg_hi:[0,1]
	v_pk_add_f32 v[94:95], v[84:85], v[92:93]
	v_mov_b32_e32 v93, v123
	v_mov_b32_e32 v85, v89
	v_pk_add_f32 v[102:103], v[122:123], v[88:89]
	v_pk_add_f32 v[84:85], v[92:93], v[84:85]
	v_mov_b32_e32 v88, v94
	v_pk_add_f32 v[84:85], v[84:85], v[126:127] neg_lo:[0,1] neg_hi:[0,1]
	v_mov_b32_e32 v89, v103
	v_pk_add_f32 v[88:89], v[88:89], v[84:85] neg_lo:[0,1] neg_hi:[0,1]
	v_pk_add_f32 v[84:85], v[86:87], v[84:85] neg_lo:[0,1] neg_hi:[0,1]
	v_pk_add_f32 v[88:89], v[92:93], v[88:89] neg_lo:[0,1] neg_hi:[0,1]
	v_pk_add_f32 v[86:87], v[102:103], v[94:95]
	v_pk_add_f32 v[84:85], v[84:85], v[88:89]
	v_pk_add_f32 v[88:89], v[118:119], v[86:87]
	s_nop 0
	v_pk_add_f32 v[92:93], v[88:89], v[118:119] neg_lo:[0,1] neg_hi:[0,1]
	s_nop 0
	v_pk_add_f32 v[86:87], v[86:87], v[92:93] neg_lo:[0,1] neg_hi:[0,1]
	s_nop 0
	v_pk_add_f32 v[84:85], v[84:85], v[86:87]
	s_nop 0
	v_pk_add_f32 v[84:85], v[88:89], v[84:85]
	v_pk_mul_f32 v[88:89], v[100:101], v[110:111]
	v_cndmask_b32_e32 v84, v160, v84, vcc
	v_cmp_neq_f32_e32 vcc, s8, v130
	v_pk_add_f32 v[92:93], v[98:99], v[88:89]
	s_nop 0
	v_cndmask_b32_e32 v85, v160, v85, vcc
	v_cmp_ngt_f32_e32 vcc, -1.0, v130
	v_pk_add_f32 v[98:99], v[92:93], v[98:99] neg_lo:[0,1] neg_hi:[0,1]
	v_mov_b32_e32 v116, v92
	v_cndmask_b32_e32 v85, v161, v85, vcc
	v_cmp_ngt_f32_e32 vcc, -1.0, v83
	v_pk_add_f32 v[88:89], v[88:89], v[98:99] neg_lo:[0,1] neg_hi:[0,1]
	s_nop 0
	v_cndmask_b32_e32 v84, v161, v84, vcc
	v_cmp_neq_f32_e32 vcc, -1.0, v83
	v_pk_add_f32 v[100:101], v[90:91], v[88:89]
	v_mov_b32_e32 v99, v89
	v_cndmask_b32_e32 v84, v162, v84, vcc
	v_cmp_neq_f32_e32 vcc, -1.0, v130
	v_mov_b32_e32 v91, v101
	v_mov_b32_e32 v89, v93
	v_cndmask_b32_e32 v85, v162, v85, vcc
	v_cmp_lt_f32_e64 vcc, |v83|, s9
	v_cndmask_b32_e64 v85, v85, v130, s[0:1]
	v_pk_add_f32 v[88:89], v[90:91], v[88:89]
	v_cndmask_b32_e32 v84, v84, v83, vcc
	v_pk_add_f32 v[78:79], v[78:79], v[84:85]
	v_cvt_f32_i32_e32 v85, v134
	v_cvt_f32_i32_e32 v84, v132
	v_pk_add_f32 v[90:91], v[92:93], v[100:101]
	v_cmp_neq_f32_e32 vcc, s8, v131
	v_mov_b32_e32 v114, v90
	v_pk_mul_f32 v[86:87], v[84:85], s[12:13] op_sel_hi:[1,0]
	v_mov_b32_e32 v119, v91
	v_pk_fma_f32 v[94:95], v[84:85], s[12:13], v[86:87] op_sel_hi:[1,0,1] neg_lo:[0,0,1] neg_hi:[0,0,1]
	v_mov_b32_e32 v98, v86
	v_pk_fma_f32 v[84:85], v[84:85], s[14:15], v[94:95] op_sel_hi:[1,0,1]
	v_cmp_lt_f32_e64 s[0:1], |v133|, s9
	v_pk_add_f32 v[94:95], v[86:87], v[84:85]
	v_mov_b32_e32 v112, v84
	v_pk_add_f32 v[102:103], v[94:95], v[90:91]
	v_mov_b32_e32 v117, v95
	v_mov_b32_e32 v115, v103
	v_pk_add_f32 v[114:115], v[114:115], v[116:117] neg_lo:[0,1] neg_hi:[0,1]
	v_pk_add_f32 v[98:99], v[98:99], v[112:113]
	v_mov_b32_e32 v110, v102
	v_mov_b32_e32 v111, v95
	v_mov_b32_e32 v112, v94
	v_mov_b32_e32 v113, v87
	v_mov_b32_e32 v116, v94
	v_mov_b32_e32 v117, v103
	v_mov_b32_e32 v87, v115
	v_pk_add_f32 v[110:111], v[110:111], v[112:113] neg_lo:[0,1] neg_hi:[0,1]
	v_mov_b32_e32 v112, v90
	v_mov_b32_e32 v113, v85
	v_pk_add_f32 v[86:87], v[116:117], v[86:87] neg_lo:[0,1] neg_hi:[0,1]
	v_pk_add_f32 v[112:113], v[112:113], v[110:111] neg_lo:[0,1] neg_hi:[0,1]
	v_mov_b32_e32 v116, v86
	v_mov_b32_e32 v117, v111
	v_mov_b32_e32 v118, v102
	v_mov_b32_e32 v111, v93
	v_pk_add_f32 v[116:117], v[84:85], v[116:117] neg_lo:[0,1] neg_hi:[0,1]
	v_pk_add_f32 v[110:111], v[118:119], v[110:111] neg_lo:[0,1] neg_hi:[0,1]
	v_mov_b32_e32 v85, v95
	v_pk_add_f32 v[90:91], v[90:91], v[92:93] neg_lo:[0,1] neg_hi:[0,1]
	v_pk_add_f32 v[92:93], v[98:99], v[110:111] neg_lo:[0,1] neg_hi:[0,1]
	v_pk_add_f32 v[84:85], v[84:85], v[86:87] neg_lo:[0,1] neg_hi:[0,1]
	v_pk_add_f32 v[86:87], v[88:89], v[114:115] neg_lo:[0,1] neg_hi:[0,1]
	v_pk_add_f32 v[94:95], v[112:113], v[92:93]
	v_pk_add_f32 v[88:89], v[86:87], v[84:85]
	v_mov_b32_e32 v85, v113
	v_mov_b32_e32 v87, v93
	v_pk_add_f32 v[86:87], v[84:85], v[86:87]
	v_mov_b32_e32 v92, v88
	v_pk_add_f32 v[86:87], v[86:87], v[116:117] neg_lo:[0,1] neg_hi:[0,1]
	v_mov_b32_e32 v93, v95
	v_pk_add_f32 v[90:91], v[100:101], v[90:91] neg_lo:[0,1] neg_hi:[0,1]
	v_pk_add_f32 v[92:93], v[92:93], v[86:87] neg_lo:[0,1] neg_hi:[0,1]
	v_pk_add_f32 v[86:87], v[90:91], v[86:87] neg_lo:[0,1] neg_hi:[0,1]
	v_pk_add_f32 v[84:85], v[84:85], v[92:93] neg_lo:[0,1] neg_hi:[0,1]
	s_nop 0
	v_pk_add_f32 v[84:85], v[86:87], v[84:85]
	v_pk_add_f32 v[86:87], v[94:95], v[88:89]
	s_nop 0
	v_pk_add_f32 v[88:89], v[102:103], v[86:87]
	s_nop 0
	v_pk_add_f32 v[90:91], v[88:89], v[102:103] neg_lo:[0,1] neg_hi:[0,1]
	s_nop 0
	v_pk_add_f32 v[86:87], v[86:87], v[90:91] neg_lo:[0,1] neg_hi:[0,1]
	s_nop 0
	v_pk_add_f32 v[84:85], v[84:85], v[86:87]
	s_nop 0
	v_pk_add_f32 v[84:85], v[88:89], v[84:85]
	s_nop 0
	v_cndmask_b32_e32 v83, v160, v84, vcc
	v_cmp_neq_f32_e32 vcc, s8, v133
	s_nop 1
	v_cndmask_b32_e32 v84, v160, v85, vcc
	v_cmp_ngt_f32_e32 vcc, -1.0, v133
	s_nop 1
	v_cndmask_b32_e32 v84, v161, v84, vcc
	v_cmp_ngt_f32_e32 vcc, -1.0, v131
	s_nop 1
	v_cndmask_b32_e32 v83, v161, v83, vcc
	v_cmp_neq_f32_e32 vcc, -1.0, v131
	s_nop 1
	v_cndmask_b32_e32 v83, v162, v83, vcc
	v_cmp_neq_f32_e32 vcc, -1.0, v133
	s_nop 1
	v_cndmask_b32_e32 v84, v162, v84, vcc
	v_cmp_lt_f32_e64 vcc, |v131|, s9
	v_cndmask_b32_e64 v85, v84, v133, s[0:1]
	s_nop 0
	v_cndmask_b32_e32 v84, v83, v131, vcc
	v_pk_add_f32 v[80:81], v[80:81], v[84:85]
	global_store_dwordx4 v[76:77], v[78:81], off offset:64
	global_load_dwordx4 v[76:79], v0, s[78:79]
	s_waitcnt vmcnt(0)
; __device__ __forceinline__ float logsigf(float x) { return fminf(x, 0.f) - log1pf(__expf(-fabsf(x))); }
; __device__ void phaseA_tile(const Params& p, int l, int mt, int nt, char* smem) {
;     ...
;                     const int c = g4 * 4;
;                     const float4 fb = *(const float4*)(p.b_f + l * 16 + c);
;                     const f32x4 v = acc[i][2];
;                     float4 lf = make_float4(logsigf(v[0] + fb.x), logsigf(v[1] + fb.y), logsigf(v[2] + fb.z), logsigf(v[3] + fb.w));
;                     float* o = samp ? (p.out + O_LFS + ((size_t)l * TSM + (row - TP)) * 16 + c)
;                                     : (p.out + O_LFP + ((size_t)l * TP + row) * 16 + c);
;                     *(float4*)o = lf;
;                     *(float4*)(lf_s + rl * 16 + c) = lf;
;                 }
	v_add_f32_e32 v80, v22, v76
	v_min_f32_e32 v76, 0, v80
	v_mul_f32_e64 v80, |v80|, s2
	v_exp_f32_e32 v83, v80
	s_nop 0
	v_add_f32_e32 v84, 1.0, v83
	v_add_f32_e32 v80, -1.0, v84
	v_sub_f32_e32 v81, v80, v84
	v_add_f32_e32 v81, 1.0, v81
	v_sub_f32_e32 v80, v83, v80
	v_add_f32_e32 v85, v80, v81
	v_frexp_mant_f32_e32 v80, v84
	v_cmp_gt_f32_e32 vcc, s26, v80
	v_cvt_f64_f32_e32 v[80:81], v84
	v_frexp_exp_i32_f64_e32 v80, v[80:81]
	v_subbrev_co_u32_e32 v97, vcc, 0, v80, vcc
	v_sub_u32_e32 v81, 0, v97
	v_ldexp_f32 v80, v84, v81
	v_ldexp_f32 v84, v85, v81
	v_add_f32_e32 v81, v23, v77
	v_min_f32_e32 v77, 0, v81
	v_mul_f32_e64 v81, |v81|, s2
	v_exp_f32_e32 v128, v81
	s_nop 0
	v_add_f32_e32 v81, 1.0, v128
	v_add_f32_e32 v85, -1.0, v81
	v_sub_f32_e32 v86, v85, v81
	v_add_f32_e32 v86, 1.0, v86
	v_sub_f32_e32 v85, v128, v85
	v_add_f32_e32 v85, v85, v86
	v_frexp_mant_f32_e32 v86, v81
	v_cmp_gt_f32_e32 vcc, s26, v86
	v_cvt_f64_f32_e32 v[86:87], v81
	v_frexp_exp_i32_f64_e32 v86, v[86:87]
	v_subbrev_co_u32_e32 v120, vcc, 0, v86, vcc
	v_sub_u32_e32 v86, 0, v120
	v_ldexp_f32 v81, v81, v86
	v_ldexp_f32 v85, v85, v86
	v_pk_add_f32 v[86:87], v[80:81], 1.0 op_sel_hi:[1,0]
	v_pk_add_f32 v[94:95], v[80:81], -1.0 op_sel_hi:[1,0]
	v_pk_add_f32 v[88:89], v[86:87], -1.0 op_sel_hi:[1,0]
	v_pk_add_f32 v[98:99], v[94:95], 1.0 op_sel_hi:[1,0]
	v_pk_add_f32 v[88:89], v[80:81], v[88:89] neg_lo:[0,1] neg_hi:[0,1]
	v_pk_add_f32 v[80:81], v[80:81], v[98:99] neg_lo:[0,1] neg_hi:[0,1]
	v_pk_add_f32 v[88:89], v[84:85], v[88:89]
	v_pk_add_f32 v[80:81], v[84:85], v[80:81]
	v_pk_add_f32 v[90:91], v[86:87], v[88:89]
	v_pk_add_f32 v[84:85], v[94:95], v[80:81]
	v_rcp_f32_e32 v92, v90
	v_rcp_f32_e32 v93, v91
	v_pk_add_f32 v[86:87], v[90:91], v[86:87] neg_lo:[0,1] neg_hi:[0,1]
	v_pk_add_f32 v[94:95], v[84:85], v[94:95] neg_lo:[0,1] neg_hi:[0,1]
	v_pk_add_f32 v[86:87], v[88:89], v[86:87] neg_lo:[0,1] neg_hi:[0,1]
	v_pk_mul_f32 v[88:89], v[84:85], v[92:93]
	v_pk_add_f32 v[80:81], v[80:81], v[94:95] neg_lo:[0,1] neg_hi:[0,1]
	v_pk_mul_f32 v[94:95], v[90:91], v[88:89]
	v_cmp_lt_f32_e64 s[0:1], |v128|, s9
	v_pk_fma_f32 v[98:99], v[88:89], v[90:91], v[94:95] neg_lo:[0,0,1] neg_hi:[0,0,1]
	s_nop 0
	v_pk_fma_f32 v[98:99], v[88:89], v[86:87], v[98:99]
	s_nop 0
	v_pk_add_f32 v[100:101], v[94:95], v[98:99]
	s_nop 0
	v_pk_add_f32 v[102:103], v[84:85], v[100:101] neg_lo:[0,1] neg_hi:[0,1]
	v_pk_add_f32 v[94:95], v[100:101], v[94:95] neg_lo:[0,1] neg_hi:[0,1]
	v_pk_add_f32 v[84:85], v[84:85], v[102:103] neg_lo:[0,1] neg_hi:[0,1]
	s_nop 0
	v_pk_add_f32 v[84:85], v[84:85], v[100:101] neg_lo:[0,1] neg_hi:[0,1]
	s_nop 0
	v_pk_add_f32 v[80:81], v[80:81], v[84:85]
	v_pk_add_f32 v[84:85], v[94:95], v[98:99] neg_lo:[0,1] neg_hi:[0,1]
	s_nop 0
	v_pk_add_f32 v[80:81], v[84:85], v[80:81]
	s_nop 0
	v_pk_add_f32 v[84:85], v[102:103], v[80:81]
	s_nop 0
	v_pk_mul_f32 v[94:95], v[92:93], v[84:85]
	s_nop 0
	v_pk_mul_f32 v[98:99], v[90:91], v[94:95]
	s_nop 0
	v_pk_fma_f32 v[90:91], v[94:95], v[90:91], v[98:99] neg_lo:[0,0,1] neg_hi:[0,0,1]
	s_nop 0
	v_pk_fma_f32 v[86:87], v[94:95], v[86:87], v[90:91]
	v_pk_add_f32 v[90:91], v[102:103], v[84:85] neg_lo:[0,1] neg_hi:[0,1]
	s_nop 0
	v_pk_add_f32 v[80:81], v[80:81], v[90:91]
	v_pk_add_f32 v[90:91], v[98:99], v[86:87]
	s_nop 0
	v_pk_add_f32 v[100:101], v[84:85], v[90:91] neg_lo:[0,1] neg_hi:[0,1]
	v_pk_add_f32 v[98:99], v[90:91], v[98:99] neg_lo:[0,1] neg_hi:[0,1]
	v_pk_add_f32 v[84:85], v[84:85], v[100:101] neg_lo:[0,1] neg_hi:[0,1]
	s_nop 0
	v_pk_add_f32 v[84:85], v[84:85], v[90:91] neg_lo:[0,1] neg_hi:[0,1]
	s_nop 0
	v_pk_add_f32 v[80:81], v[80:81], v[84:85]
	v_pk_add_f32 v[84:85], v[98:99], v[86:87] neg_lo:[0,1] neg_hi:[0,1]
	s_nop 0
	v_pk_add_f32 v[80:81], v[84:85], v[80:81]
	v_pk_add_f32 v[84:85], v[88:89], v[94:95]
	v_pk_add_f32 v[80:81], v[100:101], v[80:81]
	v_pk_add_f32 v[86:87], v[84:85], v[88:89] neg_lo:[0,1] neg_hi:[0,1]
	v_pk_mul_f32 v[80:81], v[92:93], v[80:81]
	v_pk_add_f32 v[86:87], v[94:95], v[86:87] neg_lo:[0,1] neg_hi:[0,1]
	s_nop 0
	v_pk_add_f32 v[80:81], v[86:87], v[80:81]
	s_nop 0
	v_pk_add_f32 v[86:87], v[84:85], v[80:81]
	s_nop 0
	v_pk_add_f32 v[84:85], v[86:87], v[84:85] neg_lo:[0,1] neg_hi:[0,1]
	v_pk_mul_f32 v[88:89], v[86:87], v[86:87]
	v_pk_add_f32 v[80:81], v[80:81], v[84:85] neg_lo:[0,1] neg_hi:[0,1]
	v_pk_fma_f32 v[90:91], v[88:89], s[28:29], v[66:67] op_sel_hi:[1,0,0]
	v_ldexp_f32 v93, v81, 1
	v_add_f32_e32 v81, v24, v78
	v_min_f32_e32 v78, 0, v81
	v_mul_f32_e64 v81, |v81|, s2
	v_exp_f32_e32 v129, v81
	v_ldexp_f32 v84, v86, 1
	v_pk_fma_f32 v[90:91], v[88:89], v[90:91], s[30:31] op_sel_hi:[1,1,0]
	v_ldexp_f32 v85, v87, 1
	v_add_f32_e32 v81, 1.0, v129
	v_pk_mul_f32 v[86:87], v[86:87], v[88:89]
	v_add_f32_e32 v88, -1.0, v81
	v_sub_f32_e32 v89, v88, v81
	v_add_f32_e32 v89, 1.0, v89
	v_sub_f32_e32 v88, v129, v88
	v_add_f32_e32 v92, v88, v89
	v_frexp_mant_f32_e32 v88, v81
	v_cmp_gt_f32_e32 vcc, s26, v88
	v_cvt_f64_f32_e32 v[88:89], v81
	v_frexp_exp_i32_f64_e32 v88, v[88:89]
	v_subbrev_co_u32_e32 v130, vcc, 0, v88, vcc
	v_sub_u32_e32 v89, 0, v130
	v_ldexp_f32 v88, v81, v89
	v_add_f32_e32 v81, v25, v79
	v_min_f32_e32 v79, 0, v81
	v_mul_f32_e64 v81, |v81|, s2
	v_exp_f32_e32 v131, v81
	v_ldexp_f32 v94, v92, v89
	v_pk_mul_f32 v[86:87], v[86:87], v[90:91]
	v_ldexp_f32 v80, v80, 1
	v_add_f32_e32 v81, 1.0, v131
	v_add_f32_e32 v89, -1.0, v81
	v_sub_f32_e32 v92, v89, v81
	v_add_f32_e32 v92, 1.0, v92
	v_sub_f32_e32 v89, v131, v89
	v_add_f32_e32 v92, v89, v92
	v_frexp_mant_f32_e32 v89, v81
	v_cvt_f64_f32_e32 v[98:99], v81
	v_cmp_gt_f32_e32 vcc, s26, v89
	v_frexp_exp_i32_f64_e32 v89, v[98:99]
	v_pk_add_f32 v[90:91], v[84:85], v[86:87]
; __device__ __forceinline__ float logsigf(float x) { return fminf(x, 0.f) - log1pf(__expf(-fabsf(x))); }
; __device__ void phaseA_tile(const Params& p, int l, int mt, int nt, char* smem) {
;     ...
;                     const int c = g4 * 4;
;                     const float4 fb = *(const float4*)(p.b_f + l * 16 + c);
;                     const f32x4 v = acc[i][2];
;                     float4 lf = make_float4(logsigf(v[0] + fb.x), logsigf(v[1] + fb.y), logsigf(v[2] + fb.z), logsigf(v[3] + fb.w));
;                     float* o = samp ? (p.out + O_LFS + ((size_t)l * TSM + (row - TP)) * 16 + c)
;                                     : (p.out + O_LFP + ((size_t)l * TP + row) * 16 + c);
;                     *(float4*)o = lf;
;                     *(float4*)(lf_s + rl * 16 + c) = lf;
;                 }
	v_subbrev_co_u32_e32 v132, vcc, 0, v89, vcc
	v_sub_u32_e32 v95, 0, v132
	v_ldexp_f32 v89, v81, v95
	v_pk_add_f32 v[98:99], v[88:89], 1.0 op_sel_hi:[1,0]
	v_ldexp_f32 v95, v92, v95
	v_pk_add_f32 v[100:101], v[98:99], -1.0 op_sel_hi:[1,0]
	v_pk_add_f32 v[112:113], v[88:89], -1.0 op_sel_hi:[1,0]
	v_pk_add_f32 v[100:101], v[88:89], v[100:101] neg_lo:[0,1] neg_hi:[0,1]
	v_pk_add_f32 v[114:115], v[112:113], 1.0 op_sel_hi:[1,0]
	v_pk_add_f32 v[100:101], v[94:95], v[100:101]
	v_pk_add_f32 v[88:89], v[88:89], v[114:115] neg_lo:[0,1] neg_hi:[0,1]
	v_pk_add_f32 v[102:103], v[98:99], v[100:101]
	v_pk_add_f32 v[88:89], v[94:95], v[88:89]
	v_rcp_f32_e32 v110, v102
	v_rcp_f32_e32 v111, v103
	v_pk_add_f32 v[94:95], v[112:113], v[88:89]
	v_pk_add_f32 v[98:99], v[102:103], v[98:99] neg_lo:[0,1] neg_hi:[0,1]
	v_pk_add_f32 v[112:113], v[94:95], v[112:113] neg_lo:[0,1] neg_hi:[0,1]
	v_pk_add_f32 v[98:99], v[100:101], v[98:99] neg_lo:[0,1] neg_hi:[0,1]
	v_pk_mul_f32 v[100:101], v[94:95], v[110:111]
	v_pk_add_f32 v[88:89], v[88:89], v[112:113] neg_lo:[0,1] neg_hi:[0,1]
	v_pk_mul_f32 v[112:113], v[102:103], v[100:101]
	v_pk_add_f32 v[84:85], v[90:91], v[84:85] neg_lo:[0,1] neg_hi:[0,1]
	v_pk_fma_f32 v[114:115], v[100:101], v[102:103], v[112:113] neg_lo:[0,0,1] neg_hi:[0,0,1]
	v_add_u32_e32 v81, 0xffff8000, v68
	v_pk_fma_f32 v[114:115], v[100:101], v[98:99], v[114:115]
	v_pk_add_f32 v[84:85], v[86:87], v[84:85] neg_lo:[0,1] neg_hi:[0,1]
	v_pk_add_f32 v[116:117], v[112:113], v[114:115]
	v_cndmask_b32_e64 v68, v68, v81, s[60:61]
	v_pk_add_f32 v[118:119], v[94:95], v[116:117] neg_lo:[0,1] neg_hi:[0,1]
	v_pk_add_f32 v[112:113], v[116:117], v[112:113] neg_lo:[0,1] neg_hi:[0,1]
	v_pk_add_f32 v[94:95], v[94:95], v[118:119] neg_lo:[0,1] neg_hi:[0,1]
	v_mov_b32_e32 v87, v85
	v_pk_add_f32 v[94:95], v[94:95], v[116:117] neg_lo:[0,1] neg_hi:[0,1]
	v_mov_b32_e32 v124, v90
	v_pk_add_f32 v[88:89], v[88:89], v[94:95]
	v_pk_add_f32 v[94:95], v[112:113], v[114:115] neg_lo:[0,1] neg_hi:[0,1]
	v_cmp_neq_f32_e32 vcc, s8, v83
	v_pk_add_f32 v[88:89], v[94:95], v[88:89]
	s_nop 0
	v_pk_add_f32 v[94:95], v[118:119], v[88:89]
	s_nop 0
	v_pk_mul_f32 v[112:113], v[110:111], v[94:95]
	s_nop 0
	v_pk_mul_f32 v[114:115], v[102:103], v[112:113]
	s_nop 0
	v_pk_fma_f32 v[102:103], v[112:113], v[102:103], v[114:115] neg_lo:[0,0,1] neg_hi:[0,0,1]
	s_nop 0
	v_pk_fma_f32 v[98:99], v[112:113], v[98:99], v[102:103]
	v_pk_add_f32 v[102:103], v[118:119], v[94:95] neg_lo:[0,1] neg_hi:[0,1]
	s_nop 0
	v_pk_add_f32 v[88:89], v[88:89], v[102:103]
	v_pk_add_f32 v[102:103], v[114:115], v[98:99]
	s_nop 0
	v_pk_add_f32 v[116:117], v[94:95], v[102:103] neg_lo:[0,1] neg_hi:[0,1]
	v_pk_add_f32 v[114:115], v[102:103], v[114:115] neg_lo:[0,1] neg_hi:[0,1]
	v_pk_add_f32 v[94:95], v[94:95], v[116:117] neg_lo:[0,1] neg_hi:[0,1]
	s_nop 0
	v_pk_add_f32 v[94:95], v[94:95], v[102:103] neg_lo:[0,1] neg_hi:[0,1]
	s_nop 0
	v_pk_add_f32 v[88:89], v[88:89], v[94:95]
	v_pk_add_f32 v[94:95], v[114:115], v[98:99] neg_lo:[0,1] neg_hi:[0,1]
	s_nop 0
	v_pk_add_f32 v[88:89], v[94:95], v[88:89]
	v_pk_add_f32 v[94:95], v[100:101], v[112:113]
	v_pk_add_f32 v[88:89], v[116:117], v[88:89]
	v_pk_add_f32 v[98:99], v[94:95], v[100:101] neg_lo:[0,1] neg_hi:[0,1]
	v_pk_mul_f32 v[88:89], v[110:111], v[88:89]
	v_pk_add_f32 v[98:99], v[112:113], v[98:99] neg_lo:[0,1] neg_hi:[0,1]
	s_nop 0
	v_pk_add_f32 v[88:89], v[98:99], v[88:89]
	s_nop 0
	v_pk_add_f32 v[98:99], v[94:95], v[88:89]
	s_nop 0
	v_pk_mul_f32 v[100:101], v[98:99], v[98:99]
	v_pk_add_f32 v[94:95], v[98:99], v[94:95] neg_lo:[0,1] neg_hi:[0,1]
	v_pk_fma_f32 v[102:103], v[100:101], s[28:29], v[66:67] op_sel_hi:[1,0,0]
	v_pk_add_f32 v[88:89], v[88:89], v[94:95] neg_lo:[0,1] neg_hi:[0,1]
	v_ldexp_f32 v94, v98, 1
	v_pk_fma_f32 v[102:103], v[100:101], v[102:103], s[30:31] op_sel_hi:[1,1,0]
	v_ldexp_f32 v95, v99, 1
	v_pk_mul_f32 v[98:99], v[98:99], v[100:101]
	v_cvt_f32_i32_e32 v101, v120
	v_cvt_f32_i32_e32 v100, v97
	v_ldexp_f32 v111, v89, 1
	v_ashrrev_i32_e32 v89, 31, v81
	v_mov_b32_e32 v81, v93
	v_pk_mul_f32 v[112:113], v[100:101], s[12:13] op_sel_hi:[1,0]
	v_ldexp_f32 v88, v88, 1
	v_pk_fma_f32 v[114:115], v[100:101], s[12:13], v[112:113] op_sel_hi:[1,0,1] neg_lo:[0,0,1] neg_hi:[0,0,1]
	v_mov_b32_e32 v86, v112
	v_pk_fma_f32 v[100:101], v[100:101], s[14:15], v[114:115] op_sel_hi:[1,0,1]
	v_mov_b32_e32 v121, v113
	v_mov_b32_e32 v92, v100
	v_pk_add_f32 v[86:87], v[86:87], v[92:93]
	v_pk_add_f32 v[92:93], v[80:81], v[84:85]
	v_mov_b32_e32 v85, v91
	v_mov_b32_e32 v81, v93
	v_pk_add_f32 v[114:115], v[112:113], v[100:101]
	v_pk_add_f32 v[80:81], v[80:81], v[84:85]
	v_pk_add_f32 v[84:85], v[90:91], v[92:93]
	v_mov_b32_e32 v125, v115
	v_pk_add_f32 v[116:117], v[114:115], v[84:85]
	v_mov_b32_e32 v122, v84
	v_mov_b32_e32 v123, v117
	v_pk_add_f32 v[122:123], v[122:123], v[124:125] neg_lo:[0,1] neg_hi:[0,1]
	v_mov_b32_e32 v118, v116
	v_mov_b32_e32 v119, v115
	v_mov_b32_e32 v120, v114
	v_mov_b32_e32 v124, v114
	v_mov_b32_e32 v125, v117
	v_mov_b32_e32 v113, v123
	v_pk_add_f32 v[118:119], v[118:119], v[120:121] neg_lo:[0,1] neg_hi:[0,1]
	v_mov_b32_e32 v120, v84
	v_mov_b32_e32 v121, v101
	v_pk_add_f32 v[112:113], v[124:125], v[112:113] neg_lo:[0,1] neg_hi:[0,1]
	v_pk_add_f32 v[120:121], v[120:121], v[118:119] neg_lo:[0,1] neg_hi:[0,1]
	v_mov_b32_e32 v124, v112
	v_mov_b32_e32 v125, v119
	v_mov_b32_e32 v126, v116
	v_mov_b32_e32 v127, v85
	v_mov_b32_e32 v119, v91
	v_pk_add_f32 v[124:125], v[100:101], v[124:125] neg_lo:[0,1] neg_hi:[0,1]
	v_pk_add_f32 v[118:119], v[126:127], v[118:119] neg_lo:[0,1] neg_hi:[0,1]
	v_mov_b32_e32 v101, v115
	v_pk_add_f32 v[84:85], v[84:85], v[90:91] neg_lo:[0,1] neg_hi:[0,1]
; __device__ __forceinline__ float softplusf(float x) { return fmaxf(x, 0.f) + log1pf(__expf(-fabsf(x))); }
; __device__ __forceinline__ float logsigf(float x) { return fminf(x, 0.f) - log1pf(__expf(-fabsf(x))); }
; __device__ void phaseA_tile(const Params& p, int l, int mt, int nt, char* smem) {
;     ...
;             for (int i = 0; i < 4; ++i) {
;                 const int rl = wr * 64 + i * 16 + r;
;                 const int row = m0 + rl;
; #pragma unroll
;                 for (int j = 0; j < 2; ++j) {
;                     const int c = j * 16 + g4 * 4;
;                     const float4 db = *(const float4*)(p.dt_bias + l * 32 + c);
;                     const f32x4 v = acc[i][j];
;                     *(float4*)(p.dtb + (size_t)row * 32 + c) =
;                         make_float4(softplusf(v[0] + db.x), softplusf(v[1] + db.y), softplusf(v[2] + db.z), softplusf(v[3] + db.w));
;                 }
;                 {
;                     const int c = g4 * 4;
;                     const float4 fb = *(const float4*)(p.b_f + l * 16 + c);
;                     const f32x4 v = acc[i][2];
;                     float4 lf = make_float4(logsigf(v[0] + fb.x), logsigf(v[1] + fb.y), logsigf(v[2] + fb.z), logsigf(v[3] + fb.w));
;                     float* o = samp ? (p.out + O_LFS + ((size_t)l * TSM + (row - TP)) * 16 + c)
;                                     : (p.out + O_LFP + ((size_t)l * TP + row) * 16 + c);
;                     *(float4*)o = lf;
;                     *(float4*)(lf_s + rl * 16 + c) = lf;
;                 }
	v_pk_add_f32 v[86:87], v[86:87], v[118:119] neg_lo:[0,1] neg_hi:[0,1]
	v_pk_add_f32 v[90:91], v[100:101], v[112:113] neg_lo:[0,1] neg_hi:[0,1]
	v_pk_add_f32 v[80:81], v[80:81], v[122:123] neg_lo:[0,1] neg_hi:[0,1]
	v_pk_add_f32 v[84:85], v[92:93], v[84:85] neg_lo:[0,1] neg_hi:[0,1]
	v_pk_add_f32 v[92:93], v[80:81], v[90:91]
	v_mov_b32_e32 v91, v121
	v_mov_b32_e32 v81, v87
	v_pk_add_f32 v[100:101], v[120:121], v[86:87]
	v_pk_add_f32 v[80:81], v[90:91], v[80:81]
	v_mov_b32_e32 v86, v92
	v_pk_add_f32 v[80:81], v[80:81], v[124:125] neg_lo:[0,1] neg_hi:[0,1]
	v_mov_b32_e32 v87, v101
	v_pk_add_f32 v[86:87], v[86:87], v[80:81] neg_lo:[0,1] neg_hi:[0,1]
	v_pk_add_f32 v[80:81], v[84:85], v[80:81] neg_lo:[0,1] neg_hi:[0,1]
	v_pk_add_f32 v[86:87], v[90:91], v[86:87] neg_lo:[0,1] neg_hi:[0,1]
	v_pk_add_f32 v[84:85], v[100:101], v[92:93]
	v_pk_add_f32 v[80:81], v[80:81], v[86:87]
	v_pk_add_f32 v[86:87], v[116:117], v[84:85]
	v_cndmask_b32_e64 v69, v69, v89, s[60:61]
	v_pk_add_f32 v[90:91], v[86:87], v[116:117] neg_lo:[0,1] neg_hi:[0,1]
	v_mov_b32_e32 v89, v111
	v_pk_add_f32 v[84:85], v[84:85], v[90:91] neg_lo:[0,1] neg_hi:[0,1]
	v_lshlrev_b64 v[68:69], 6, v[68:69]
	v_pk_add_f32 v[80:81], v[80:81], v[84:85]
	v_lshl_add_u64 v[68:69], s[6:7], 0, v[68:69]
	v_pk_add_f32 v[80:81], v[86:87], v[80:81]
	v_pk_mul_f32 v[86:87], v[98:99], v[102:103]
	v_cndmask_b32_e32 v80, v160, v80, vcc
	v_cmp_neq_f32_e32 vcc, s8, v128
	v_pk_add_f32 v[90:91], v[94:95], v[86:87]
	v_lshl_add_u64 v[68:69], v[68:69], 0, v[0:1]
	v_cndmask_b32_e32 v81, v160, v81, vcc
	v_cmp_ngt_f32_e32 vcc, -1.0, v128
	v_pk_add_f32 v[94:95], v[90:91], v[94:95] neg_lo:[0,1] neg_hi:[0,1]
	v_mov_b32_e32 v114, v90
	v_cndmask_b32_e32 v81, v161, v81, vcc
	v_cmp_ngt_f32_e32 vcc, -1.0, v83
	v_pk_add_f32 v[86:87], v[86:87], v[94:95] neg_lo:[0,1] neg_hi:[0,1]
	s_nop 0
	v_cndmask_b32_e32 v80, v161, v80, vcc
	v_cmp_neq_f32_e32 vcc, -1.0, v83
	v_pk_add_f32 v[98:99], v[88:89], v[86:87]
	v_mov_b32_e32 v95, v87
	v_cndmask_b32_e32 v80, v162, v80, vcc
	v_cmp_neq_f32_e32 vcc, -1.0, v128
	v_mov_b32_e32 v89, v99
	v_mov_b32_e32 v87, v91
	v_cndmask_b32_e32 v81, v162, v81, vcc
	v_cmp_lt_f32_e64 vcc, |v83|, s9
	v_cndmask_b32_e64 v81, v81, v128, s[0:1]
	v_pk_add_f32 v[86:87], v[88:89], v[86:87]
	v_cndmask_b32_e32 v80, v80, v83, vcc
	v_pk_add_f32 v[76:77], v[76:77], v[80:81] neg_lo:[0,1] neg_hi:[0,1]
	v_cvt_f32_i32_e32 v81, v132
	v_cvt_f32_i32_e32 v80, v130
	v_pk_add_f32 v[88:89], v[90:91], v[98:99]
	v_cmp_neq_f32_e32 vcc, s8, v129
	v_mov_b32_e32 v112, v88
	v_pk_mul_f32 v[84:85], v[80:81], s[12:13] op_sel_hi:[1,0]
	v_mov_b32_e32 v117, v89
	v_pk_fma_f32 v[92:93], v[80:81], s[12:13], v[84:85] op_sel_hi:[1,0,1] neg_lo:[0,0,1] neg_hi:[0,0,1]
	v_mov_b32_e32 v94, v84
	v_pk_fma_f32 v[80:81], v[80:81], s[14:15], v[92:93] op_sel_hi:[1,0,1]
	v_cmp_lt_f32_e64 s[0:1], |v131|, s9
	v_pk_add_f32 v[92:93], v[84:85], v[80:81]
	v_mov_b32_e32 v110, v80
	v_pk_add_f32 v[100:101], v[92:93], v[88:89]
	v_mov_b32_e32 v115, v93
	v_mov_b32_e32 v113, v101
	v_pk_add_f32 v[112:113], v[112:113], v[114:115] neg_lo:[0,1] neg_hi:[0,1]
	v_pk_add_f32 v[94:95], v[94:95], v[110:111]
	v_mov_b32_e32 v102, v100
	v_mov_b32_e32 v103, v93
	v_mov_b32_e32 v110, v92
	v_mov_b32_e32 v111, v85
	v_mov_b32_e32 v114, v92
	v_mov_b32_e32 v115, v101
	v_mov_b32_e32 v85, v113
	v_pk_add_f32 v[102:103], v[102:103], v[110:111] neg_lo:[0,1] neg_hi:[0,1]
	v_mov_b32_e32 v110, v88
	v_mov_b32_e32 v111, v81
	v_pk_add_f32 v[84:85], v[114:115], v[84:85] neg_lo:[0,1] neg_hi:[0,1]
	v_pk_add_f32 v[110:111], v[110:111], v[102:103] neg_lo:[0,1] neg_hi:[0,1]
	v_mov_b32_e32 v114, v84
	v_mov_b32_e32 v115, v103
	v_mov_b32_e32 v116, v100
	v_mov_b32_e32 v103, v91
	v_pk_add_f32 v[114:115], v[80:81], v[114:115] neg_lo:[0,1] neg_hi:[0,1]
	v_pk_add_f32 v[102:103], v[116:117], v[102:103] neg_lo:[0,1] neg_hi:[0,1]
	v_mov_b32_e32 v81, v93
	v_pk_add_f32 v[88:89], v[88:89], v[90:91] neg_lo:[0,1] neg_hi:[0,1]
	v_pk_add_f32 v[90:91], v[94:95], v[102:103] neg_lo:[0,1] neg_hi:[0,1]
	v_pk_add_f32 v[80:81], v[80:81], v[84:85] neg_lo:[0,1] neg_hi:[0,1]
	v_pk_add_f32 v[84:85], v[86:87], v[112:113] neg_lo:[0,1] neg_hi:[0,1]
	v_pk_add_f32 v[92:93], v[110:111], v[90:91]
	v_pk_add_f32 v[86:87], v[84:85], v[80:81]
	v_mov_b32_e32 v81, v111
	v_mov_b32_e32 v85, v91
	v_pk_add_f32 v[84:85], v[80:81], v[84:85]
	v_mov_b32_e32 v90, v86
	v_pk_add_f32 v[84:85], v[84:85], v[114:115] neg_lo:[0,1] neg_hi:[0,1]
	v_mov_b32_e32 v91, v93
	v_pk_add_f32 v[88:89], v[98:99], v[88:89] neg_lo:[0,1] neg_hi:[0,1]
	v_pk_add_f32 v[90:91], v[90:91], v[84:85] neg_lo:[0,1] neg_hi:[0,1]
	v_pk_add_f32 v[84:85], v[88:89], v[84:85] neg_lo:[0,1] neg_hi:[0,1]
	v_pk_add_f32 v[80:81], v[80:81], v[90:91] neg_lo:[0,1] neg_hi:[0,1]
	s_nop 0
	v_pk_add_f32 v[80:81], v[84:85], v[80:81]
	v_pk_add_f32 v[84:85], v[92:93], v[86:87]
	s_nop 0
	v_pk_add_f32 v[86:87], v[100:101], v[84:85]
	s_nop 0
	v_pk_add_f32 v[88:89], v[86:87], v[100:101] neg_lo:[0,1] neg_hi:[0,1]
	s_nop 0
	v_pk_add_f32 v[84:85], v[84:85], v[88:89] neg_lo:[0,1] neg_hi:[0,1]
	s_nop 0
	v_pk_add_f32 v[80:81], v[80:81], v[84:85]
	s_nop 0
	v_pk_add_f32 v[80:81], v[86:87], v[80:81]
	s_nop 0
	v_cndmask_b32_e32 v80, v160, v80, vcc
	v_cmp_neq_f32_e32 vcc, s8, v131
	s_nop 1
	v_cndmask_b32_e32 v81, v160, v81, vcc
	v_cmp_ngt_f32_e32 vcc, -1.0, v131
	s_nop 1
	v_cndmask_b32_e32 v81, v161, v81, vcc
	v_cmp_ngt_f32_e32 vcc, -1.0, v129
	s_nop 1
	v_cndmask_b32_e32 v80, v161, v80, vcc
	v_cmp_neq_f32_e32 vcc, -1.0, v129
	s_nop 1
	v_cndmask_b32_e32 v80, v162, v80, vcc
	v_cmp_neq_f32_e32 vcc, -1.0, v131
	s_nop 1
	v_cndmask_b32_e32 v81, v162, v81, vcc
	v_cmp_lt_f32_e64 vcc, |v129|, s9
	v_cndmask_b32_e64 v81, v81, v131, s[0:1]
	s_nop 0
	v_cndmask_b32_e32 v80, v80, v129, vcc
	v_pk_add_f32 v[78:79], v[78:79], v[80:81] neg_lo:[0,1] neg_hi:[0,1]
	global_store_dwordx4 v[68:69], v[76:79], off
	v_lshl_or_b32 v68, v82, 6, v0
	ds_write_b128 v68, v[76:79]
	global_load_dwordx4 v[78:81], v0, s[74:75]
	v_add_u32_e32 v68, s54, v71
	v_ashrrev_i32_e32 v69, 31, v68
	v_lshlrev_b64 v[76:77], 7, v[68:69]
	v_lshl_add_u64 v[76:77], s[10:11], 0, v[76:77]
	v_lshl_add_u64 v[76:77], v[76:77], 0, v[0:1]
	s_waitcnt vmcnt(0)
; __device__ __forceinline__ float softplusf(float x) { return fmaxf(x, 0.f) + log1pf(__expf(-fabsf(x))); }
; __device__ void phaseA_tile(const Params& p, int l, int mt, int nt, char* smem) {
;     ...
;                 for (int j = 0; j < 2; ++j) {
;                     const int c = j * 16 + g4 * 4;
;                     const float4 db = *(const float4*)(p.dt_bias + l * 32 + c);
;                     const f32x4 v = acc[i][j];
;                     *(float4*)(p.dtb + (size_t)row * 32 + c) =
;                         make_float4(softplusf(v[0] + db.x), softplusf(v[1] + db.y), softplusf(v[2] + db.z), softplusf(v[3] + db.w));
;                 }
	v_add_f32_e32 v82, v14, v78
	v_max_f32_e32 v78, 0, v82
	v_mul_f32_e64 v82, |v82|, s2
	v_exp_f32_e32 v97, v82
	s_nop 0
	v_add_f32_e32 v84, 1.0, v97
	v_add_f32_e32 v82, -1.0, v84
	v_sub_f32_e32 v83, v82, v84
	v_add_f32_e32 v83, 1.0, v83
	v_sub_f32_e32 v82, v97, v82
	v_add_f32_e32 v85, v82, v83
	v_frexp_mant_f32_e32 v82, v84
	v_cmp_gt_f32_e32 vcc, s26, v82
	v_cvt_f64_f32_e32 v[82:83], v84
	v_frexp_exp_i32_f64_e32 v82, v[82:83]
	v_subbrev_co_u32_e32 v120, vcc, 0, v82, vcc
	v_sub_u32_e32 v83, 0, v120
	v_ldexp_f32 v82, v84, v83
	v_ldexp_f32 v84, v85, v83
	v_add_f32_e32 v83, v15, v79
	v_max_f32_e32 v79, 0, v83
	v_mul_f32_e64 v83, |v83|, s2
	v_exp_f32_e32 v128, v83
	s_nop 0
	v_add_f32_e32 v83, 1.0, v128
	v_add_f32_e32 v85, -1.0, v83
	v_sub_f32_e32 v86, v85, v83
	v_add_f32_e32 v86, 1.0, v86
	v_sub_f32_e32 v85, v128, v85
	v_add_f32_e32 v85, v85, v86
	v_frexp_mant_f32_e32 v86, v83
	v_cmp_gt_f32_e32 vcc, s26, v86
	v_cvt_f64_f32_e32 v[86:87], v83
	v_frexp_exp_i32_f64_e32 v86, v[86:87]
	v_subbrev_co_u32_e32 v121, vcc, 0, v86, vcc
	v_sub_u32_e32 v86, 0, v121
	v_ldexp_f32 v83, v83, v86
	v_ldexp_f32 v85, v85, v86
	v_pk_add_f32 v[86:87], v[82:83], 1.0 op_sel_hi:[1,0]
	v_pk_add_f32 v[94:95], v[82:83], -1.0 op_sel_hi:[1,0]
	v_pk_add_f32 v[88:89], v[86:87], -1.0 op_sel_hi:[1,0]
	v_pk_add_f32 v[98:99], v[94:95], 1.0 op_sel_hi:[1,0]
	v_pk_add_f32 v[88:89], v[82:83], v[88:89] neg_lo:[0,1] neg_hi:[0,1]
	v_pk_add_f32 v[82:83], v[82:83], v[98:99] neg_lo:[0,1] neg_hi:[0,1]
	v_pk_add_f32 v[88:89], v[84:85], v[88:89]
	v_pk_add_f32 v[82:83], v[84:85], v[82:83]
	v_pk_add_f32 v[90:91], v[86:87], v[88:89]
	v_pk_add_f32 v[84:85], v[94:95], v[82:83]
	v_rcp_f32_e32 v92, v90
	v_rcp_f32_e32 v93, v91
	v_pk_add_f32 v[86:87], v[90:91], v[86:87] neg_lo:[0,1] neg_hi:[0,1]
	v_pk_add_f32 v[94:95], v[84:85], v[94:95] neg_lo:[0,1] neg_hi:[0,1]
	v_pk_add_f32 v[86:87], v[88:89], v[86:87] neg_lo:[0,1] neg_hi:[0,1]
	v_pk_mul_f32 v[88:89], v[84:85], v[92:93]
	v_pk_add_f32 v[82:83], v[82:83], v[94:95] neg_lo:[0,1] neg_hi:[0,1]
	v_pk_mul_f32 v[94:95], v[90:91], v[88:89]
	v_cmp_lt_f32_e64 s[0:1], |v128|, s9
	v_pk_fma_f32 v[98:99], v[88:89], v[90:91], v[94:95] neg_lo:[0,0,1] neg_hi:[0,0,1]
	s_nop 0
	v_pk_fma_f32 v[98:99], v[88:89], v[86:87], v[98:99]
	s_nop 0
	v_pk_add_f32 v[100:101], v[94:95], v[98:99]
	s_nop 0
	v_pk_add_f32 v[102:103], v[84:85], v[100:101] neg_lo:[0,1] neg_hi:[0,1]
	v_pk_add_f32 v[94:95], v[100:101], v[94:95] neg_lo:[0,1] neg_hi:[0,1]
	v_pk_add_f32 v[84:85], v[84:85], v[102:103] neg_lo:[0,1] neg_hi:[0,1]
	s_nop 0
	v_pk_add_f32 v[84:85], v[84:85], v[100:101] neg_lo:[0,1] neg_hi:[0,1]
	s_nop 0
	v_pk_add_f32 v[82:83], v[82:83], v[84:85]
	v_pk_add_f32 v[84:85], v[94:95], v[98:99] neg_lo:[0,1] neg_hi:[0,1]
	s_nop 0
	v_pk_add_f32 v[82:83], v[84:85], v[82:83]
	s_nop 0
	v_pk_add_f32 v[84:85], v[102:103], v[82:83]
	s_nop 0
	v_pk_mul_f32 v[94:95], v[92:93], v[84:85]
	s_nop 0
	v_pk_mul_f32 v[98:99], v[90:91], v[94:95]
	s_nop 0
	v_pk_fma_f32 v[90:91], v[94:95], v[90:91], v[98:99] neg_lo:[0,0,1] neg_hi:[0,0,1]
	s_nop 0
	v_pk_fma_f32 v[86:87], v[94:95], v[86:87], v[90:91]
	v_pk_add_f32 v[90:91], v[102:103], v[84:85] neg_lo:[0,1] neg_hi:[0,1]
	s_nop 0
	v_pk_add_f32 v[82:83], v[82:83], v[90:91]
	v_pk_add_f32 v[90:91], v[98:99], v[86:87]
	s_nop 0
	v_pk_add_f32 v[100:101], v[84:85], v[90:91] neg_lo:[0,1] neg_hi:[0,1]
	v_pk_add_f32 v[98:99], v[90:91], v[98:99] neg_lo:[0,1] neg_hi:[0,1]
	v_pk_add_f32 v[84:85], v[84:85], v[100:101] neg_lo:[0,1] neg_hi:[0,1]
	s_nop 0
	v_pk_add_f32 v[84:85], v[84:85], v[90:91] neg_lo:[0,1] neg_hi:[0,1]
	s_nop 0
	v_pk_add_f32 v[82:83], v[82:83], v[84:85]
	v_pk_add_f32 v[84:85], v[98:99], v[86:87] neg_lo:[0,1] neg_hi:[0,1]
	s_nop 0
	v_pk_add_f32 v[82:83], v[84:85], v[82:83]
	v_pk_add_f32 v[84:85], v[88:89], v[94:95]
	v_pk_add_f32 v[82:83], v[100:101], v[82:83]
	v_pk_add_f32 v[86:87], v[84:85], v[88:89] neg_lo:[0,1] neg_hi:[0,1]
	v_pk_mul_f32 v[82:83], v[92:93], v[82:83]
	v_pk_add_f32 v[86:87], v[94:95], v[86:87] neg_lo:[0,1] neg_hi:[0,1]
	s_nop 0
	v_pk_add_f32 v[82:83], v[86:87], v[82:83]
	s_nop 0
	v_pk_add_f32 v[86:87], v[84:85], v[82:83]
	s_nop 0
	v_pk_add_f32 v[84:85], v[86:87], v[84:85] neg_lo:[0,1] neg_hi:[0,1]
	v_pk_mul_f32 v[88:89], v[86:87], v[86:87]
	v_pk_add_f32 v[82:83], v[82:83], v[84:85] neg_lo:[0,1] neg_hi:[0,1]
	v_pk_fma_f32 v[90:91], v[88:89], s[28:29], v[66:67] op_sel_hi:[1,0,0]
	v_ldexp_f32 v93, v83, 1
	v_add_f32_e32 v83, v16, v80
	v_max_f32_e32 v80, 0, v83
	v_mul_f32_e64 v83, |v83|, s2
	v_exp_f32_e32 v129, v83
	v_ldexp_f32 v84, v86, 1
	v_pk_fma_f32 v[90:91], v[88:89], v[90:91], s[30:31] op_sel_hi:[1,1,0]
	v_ldexp_f32 v85, v87, 1
	v_add_f32_e32 v83, 1.0, v129
	v_pk_mul_f32 v[86:87], v[86:87], v[88:89]
	v_add_f32_e32 v88, -1.0, v83
	v_sub_f32_e32 v89, v88, v83
	v_add_f32_e32 v89, 1.0, v89
	v_sub_f32_e32 v88, v129, v88
	v_add_f32_e32 v92, v88, v89
	v_frexp_mant_f32_e32 v88, v83
	v_cmp_gt_f32_e32 vcc, s26, v88
	v_cvt_f64_f32_e32 v[88:89], v83
	v_frexp_exp_i32_f64_e32 v88, v[88:89]
	v_subbrev_co_u32_e32 v130, vcc, 0, v88, vcc
	v_sub_u32_e32 v89, 0, v130
	v_ldexp_f32 v88, v83, v89
	v_add_f32_e32 v83, v17, v81
	v_max_f32_e32 v81, 0, v83
	v_mul_f32_e64 v83, |v83|, s2
	v_exp_f32_e32 v131, v83
	v_ldexp_f32 v94, v92, v89
	v_pk_mul_f32 v[86:87], v[86:87], v[90:91]
	v_ldexp_f32 v82, v82, 1
	v_add_f32_e32 v83, 1.0, v131
	v_add_f32_e32 v89, -1.0, v83
	v_sub_f32_e32 v92, v89, v83
	v_add_f32_e32 v92, 1.0, v92
	v_sub_f32_e32 v89, v131, v89
	v_add_f32_e32 v92, v89, v92
	v_frexp_mant_f32_e32 v89, v83
	v_cvt_f64_f32_e32 v[98:99], v83
	v_cmp_gt_f32_e32 vcc, s26, v89
	v_frexp_exp_i32_f64_e32 v89, v[98:99]
	v_pk_add_f32 v[90:91], v[84:85], v[86:87]
; __device__ __forceinline__ float softplusf(float x) { return fmaxf(x, 0.f) + log1pf(__expf(-fabsf(x))); }
; __device__ void phaseA_tile(const Params& p, int l, int mt, int nt, char* smem) {
;     ...
;                 for (int j = 0; j < 2; ++j) {
;                     const int c = j * 16 + g4 * 4;
;                     const float4 db = *(const float4*)(p.dt_bias + l * 32 + c);
;                     const f32x4 v = acc[i][j];
;                     *(float4*)(p.dtb + (size_t)row * 32 + c) =
;                         make_float4(softplusf(v[0] + db.x), softplusf(v[1] + db.y), softplusf(v[2] + db.z), softplusf(v[3] + db.w));
;                 }
	v_subbrev_co_u32_e32 v132, vcc, 0, v89, vcc
	v_sub_u32_e32 v95, 0, v132
	v_ldexp_f32 v89, v83, v95
	v_pk_add_f32 v[98:99], v[88:89], 1.0 op_sel_hi:[1,0]
	v_ldexp_f32 v95, v92, v95
	v_pk_add_f32 v[100:101], v[98:99], -1.0 op_sel_hi:[1,0]
	v_pk_add_f32 v[112:113], v[88:89], -1.0 op_sel_hi:[1,0]
	v_pk_add_f32 v[100:101], v[88:89], v[100:101] neg_lo:[0,1] neg_hi:[0,1]
	v_pk_add_f32 v[114:115], v[112:113], 1.0 op_sel_hi:[1,0]
	v_pk_add_f32 v[100:101], v[94:95], v[100:101]
	v_pk_add_f32 v[88:89], v[88:89], v[114:115] neg_lo:[0,1] neg_hi:[0,1]
	v_pk_add_f32 v[102:103], v[98:99], v[100:101]
	v_pk_add_f32 v[88:89], v[94:95], v[88:89]
	v_rcp_f32_e32 v110, v102
	v_rcp_f32_e32 v111, v103
	v_pk_add_f32 v[94:95], v[112:113], v[88:89]
	v_pk_add_f32 v[98:99], v[102:103], v[98:99] neg_lo:[0,1] neg_hi:[0,1]
	v_pk_add_f32 v[112:113], v[94:95], v[112:113] neg_lo:[0,1] neg_hi:[0,1]
	v_pk_add_f32 v[98:99], v[100:101], v[98:99] neg_lo:[0,1] neg_hi:[0,1]
	v_pk_mul_f32 v[100:101], v[94:95], v[110:111]
	v_pk_add_f32 v[88:89], v[88:89], v[112:113] neg_lo:[0,1] neg_hi:[0,1]
	v_pk_mul_f32 v[112:113], v[102:103], v[100:101]
	v_pk_add_f32 v[84:85], v[90:91], v[84:85] neg_lo:[0,1] neg_hi:[0,1]
	v_pk_fma_f32 v[114:115], v[100:101], v[102:103], v[112:113] neg_lo:[0,0,1] neg_hi:[0,0,1]
	v_pk_add_f32 v[84:85], v[86:87], v[84:85] neg_lo:[0,1] neg_hi:[0,1]
	v_pk_fma_f32 v[114:115], v[100:101], v[98:99], v[114:115]
	v_mov_b32_e32 v87, v85
	v_pk_add_f32 v[116:117], v[112:113], v[114:115]
	v_mov_b32_e32 v83, v93
	v_pk_add_f32 v[118:119], v[94:95], v[116:117] neg_lo:[0,1] neg_hi:[0,1]
	v_pk_add_f32 v[112:113], v[116:117], v[112:113] neg_lo:[0,1] neg_hi:[0,1]
	v_pk_add_f32 v[94:95], v[94:95], v[118:119] neg_lo:[0,1] neg_hi:[0,1]
	v_mov_b32_e32 v124, v90
	v_pk_add_f32 v[94:95], v[94:95], v[116:117] neg_lo:[0,1] neg_hi:[0,1]
	v_cmp_neq_f32_e32 vcc, s8, v97
	v_pk_add_f32 v[88:89], v[88:89], v[94:95]
	v_pk_add_f32 v[94:95], v[112:113], v[114:115] neg_lo:[0,1] neg_hi:[0,1]
	s_nop 0
	v_pk_add_f32 v[88:89], v[94:95], v[88:89]
	s_nop 0
	v_pk_add_f32 v[94:95], v[118:119], v[88:89]
	s_nop 0
	v_pk_mul_f32 v[112:113], v[110:111], v[94:95]
	s_nop 0
	v_pk_mul_f32 v[114:115], v[102:103], v[112:113]
	s_nop 0
	v_pk_fma_f32 v[102:103], v[112:113], v[102:103], v[114:115] neg_lo:[0,0,1] neg_hi:[0,0,1]
	s_nop 0
	v_pk_fma_f32 v[98:99], v[112:113], v[98:99], v[102:103]
	v_pk_add_f32 v[102:103], v[118:119], v[94:95] neg_lo:[0,1] neg_hi:[0,1]
	s_nop 0
	v_pk_add_f32 v[88:89], v[88:89], v[102:103]
	v_pk_add_f32 v[102:103], v[114:115], v[98:99]
	s_nop 0
	v_pk_add_f32 v[116:117], v[94:95], v[102:103] neg_lo:[0,1] neg_hi:[0,1]
	v_pk_add_f32 v[114:115], v[102:103], v[114:115] neg_lo:[0,1] neg_hi:[0,1]
	v_pk_add_f32 v[94:95], v[94:95], v[116:117] neg_lo:[0,1] neg_hi:[0,1]
	s_nop 0
	v_pk_add_f32 v[94:95], v[94:95], v[102:103] neg_lo:[0,1] neg_hi:[0,1]
	s_nop 0
	v_pk_add_f32 v[88:89], v[88:89], v[94:95]
	v_pk_add_f32 v[94:95], v[114:115], v[98:99] neg_lo:[0,1] neg_hi:[0,1]
	s_nop 0
	v_pk_add_f32 v[88:89], v[94:95], v[88:89]
	v_pk_add_f32 v[94:95], v[100:101], v[112:113]
	v_pk_add_f32 v[88:89], v[116:117], v[88:89]
	v_pk_add_f32 v[98:99], v[94:95], v[100:101] neg_lo:[0,1] neg_hi:[0,1]
	v_pk_mul_f32 v[88:89], v[110:111], v[88:89]
	v_pk_add_f32 v[98:99], v[112:113], v[98:99] neg_lo:[0,1] neg_hi:[0,1]
	s_nop 0
	v_pk_add_f32 v[88:89], v[98:99], v[88:89]
	s_nop 0
	v_pk_add_f32 v[98:99], v[94:95], v[88:89]
	s_nop 0
	v_pk_mul_f32 v[100:101], v[98:99], v[98:99]
	v_pk_add_f32 v[94:95], v[98:99], v[94:95] neg_lo:[0,1] neg_hi:[0,1]
	v_pk_fma_f32 v[102:103], v[100:101], s[28:29], v[66:67] op_sel_hi:[1,0,0]
	v_pk_add_f32 v[88:89], v[88:89], v[94:95] neg_lo:[0,1] neg_hi:[0,1]
	v_ldexp_f32 v94, v98, 1
	v_pk_fma_f32 v[102:103], v[100:101], v[102:103], s[30:31] op_sel_hi:[1,1,0]
	v_ldexp_f32 v95, v99, 1
	v_pk_mul_f32 v[98:99], v[98:99], v[100:101]
	v_cvt_f32_i32_e32 v101, v121
	v_cvt_f32_i32_e32 v100, v120
	v_ldexp_f32 v111, v89, 1
	v_ldexp_f32 v88, v88, 1
	v_mov_b32_e32 v89, v111
	v_pk_mul_f32 v[112:113], v[100:101], s[12:13] op_sel_hi:[1,0]
	s_nop 0
	v_pk_fma_f32 v[114:115], v[100:101], s[12:13], v[112:113] op_sel_hi:[1,0,1] neg_lo:[0,0,1] neg_hi:[0,0,1]
	v_mov_b32_e32 v86, v112
	v_pk_fma_f32 v[100:101], v[100:101], s[14:15], v[114:115] op_sel_hi:[1,0,1]
	v_mov_b32_e32 v121, v113
	v_mov_b32_e32 v92, v100
	v_pk_add_f32 v[86:87], v[86:87], v[92:93]
	v_pk_add_f32 v[92:93], v[82:83], v[84:85]
	v_mov_b32_e32 v85, v91
	v_mov_b32_e32 v83, v93
	v_pk_add_f32 v[114:115], v[112:113], v[100:101]
	v_pk_add_f32 v[82:83], v[82:83], v[84:85]
	v_pk_add_f32 v[84:85], v[90:91], v[92:93]
	v_mov_b32_e32 v125, v115
	v_pk_add_f32 v[116:117], v[114:115], v[84:85]
	v_mov_b32_e32 v122, v84
	v_mov_b32_e32 v123, v117
	v_pk_add_f32 v[122:123], v[122:123], v[124:125] neg_lo:[0,1] neg_hi:[0,1]
	v_mov_b32_e32 v118, v116
	v_mov_b32_e32 v119, v115
	v_mov_b32_e32 v120, v114
	v_mov_b32_e32 v124, v114
	v_mov_b32_e32 v125, v117
	v_mov_b32_e32 v113, v123
	v_pk_add_f32 v[118:119], v[118:119], v[120:121] neg_lo:[0,1] neg_hi:[0,1]
	v_mov_b32_e32 v120, v84
	v_mov_b32_e32 v121, v101
	v_pk_add_f32 v[112:113], v[124:125], v[112:113] neg_lo:[0,1] neg_hi:[0,1]
	v_pk_add_f32 v[120:121], v[120:121], v[118:119] neg_lo:[0,1] neg_hi:[0,1]
	v_mov_b32_e32 v124, v112
	v_mov_b32_e32 v125, v119
	v_mov_b32_e32 v126, v116
	v_mov_b32_e32 v127, v85
	v_mov_b32_e32 v119, v91
	v_pk_add_f32 v[124:125], v[100:101], v[124:125] neg_lo:[0,1] neg_hi:[0,1]
	v_pk_add_f32 v[118:119], v[126:127], v[118:119] neg_lo:[0,1] neg_hi:[0,1]
	v_mov_b32_e32 v101, v115
	v_pk_add_f32 v[84:85], v[84:85], v[90:91] neg_lo:[0,1] neg_hi:[0,1]
	v_pk_add_f32 v[86:87], v[86:87], v[118:119] neg_lo:[0,1] neg_hi:[0,1]
; __device__ __forceinline__ float softplusf(float x) { return fmaxf(x, 0.f) + log1pf(__expf(-fabsf(x))); }
; __device__ void phaseA_tile(const Params& p, int l, int mt, int nt, char* smem) {
;     ...
;                 for (int j = 0; j < 2; ++j) {
;                     const int c = j * 16 + g4 * 4;
;                     const float4 db = *(const float4*)(p.dt_bias + l * 32 + c);
;                     const f32x4 v = acc[i][j];
;                     *(float4*)(p.dtb + (size_t)row * 32 + c) =
;                         make_float4(softplusf(v[0] + db.x), softplusf(v[1] + db.y), softplusf(v[2] + db.z), softplusf(v[3] + db.w));
;                 }
	v_pk_add_f32 v[90:91], v[100:101], v[112:113] neg_lo:[0,1] neg_hi:[0,1]
	v_pk_add_f32 v[82:83], v[82:83], v[122:123] neg_lo:[0,1] neg_hi:[0,1]
	v_pk_add_f32 v[84:85], v[92:93], v[84:85] neg_lo:[0,1] neg_hi:[0,1]
	v_pk_add_f32 v[92:93], v[82:83], v[90:91]
	v_mov_b32_e32 v91, v121
	v_mov_b32_e32 v83, v87
	v_pk_add_f32 v[100:101], v[120:121], v[86:87]
	v_pk_add_f32 v[82:83], v[90:91], v[82:83]
	v_mov_b32_e32 v86, v92
	v_pk_add_f32 v[82:83], v[82:83], v[124:125] neg_lo:[0,1] neg_hi:[0,1]
	v_mov_b32_e32 v87, v101
	v_pk_add_f32 v[86:87], v[86:87], v[82:83] neg_lo:[0,1] neg_hi:[0,1]
	v_pk_add_f32 v[82:83], v[84:85], v[82:83] neg_lo:[0,1] neg_hi:[0,1]
	v_pk_add_f32 v[86:87], v[90:91], v[86:87] neg_lo:[0,1] neg_hi:[0,1]
	v_pk_add_f32 v[84:85], v[100:101], v[92:93]
	v_pk_add_f32 v[82:83], v[82:83], v[86:87]
	v_pk_add_f32 v[86:87], v[116:117], v[84:85]
	s_nop 0
	v_pk_add_f32 v[90:91], v[86:87], v[116:117] neg_lo:[0,1] neg_hi:[0,1]
	s_nop 0
	v_pk_add_f32 v[84:85], v[84:85], v[90:91] neg_lo:[0,1] neg_hi:[0,1]
	s_nop 0
	v_pk_add_f32 v[82:83], v[82:83], v[84:85]
	s_nop 0
	v_pk_add_f32 v[82:83], v[86:87], v[82:83]
	v_pk_mul_f32 v[86:87], v[98:99], v[102:103]
	v_cndmask_b32_e32 v82, v160, v82, vcc
	v_cmp_neq_f32_e32 vcc, s8, v128
	v_pk_add_f32 v[90:91], v[94:95], v[86:87]
	s_nop 0
	v_cndmask_b32_e32 v83, v160, v83, vcc
	v_cmp_ngt_f32_e32 vcc, -1.0, v128
	v_pk_add_f32 v[94:95], v[90:91], v[94:95] neg_lo:[0,1] neg_hi:[0,1]
	v_mov_b32_e32 v114, v90
	v_cndmask_b32_e32 v83, v161, v83, vcc
	v_cmp_ngt_f32_e32 vcc, -1.0, v97
	v_pk_add_f32 v[86:87], v[86:87], v[94:95] neg_lo:[0,1] neg_hi:[0,1]
	s_nop 0
	v_cndmask_b32_e32 v82, v161, v82, vcc
	v_cmp_neq_f32_e32 vcc, -1.0, v97
	v_pk_add_f32 v[98:99], v[88:89], v[86:87]
	v_mov_b32_e32 v95, v87
	v_cndmask_b32_e32 v82, v162, v82, vcc
	v_cmp_neq_f32_e32 vcc, -1.0, v128
	v_mov_b32_e32 v89, v99
	v_mov_b32_e32 v87, v91
	v_cndmask_b32_e32 v83, v162, v83, vcc
	v_cmp_lt_f32_e64 vcc, |v97|, s9
	v_cndmask_b32_e64 v83, v83, v128, s[0:1]
	v_pk_add_f32 v[86:87], v[88:89], v[86:87]
	v_cndmask_b32_e32 v82, v82, v97, vcc
	v_pk_add_f32 v[78:79], v[78:79], v[82:83]
	v_cvt_f32_i32_e32 v83, v132
	v_cvt_f32_i32_e32 v82, v130
	v_pk_add_f32 v[88:89], v[90:91], v[98:99]
	v_cmp_neq_f32_e32 vcc, s8, v129
	v_mov_b32_e32 v112, v88
	v_pk_mul_f32 v[84:85], v[82:83], s[12:13] op_sel_hi:[1,0]
	v_mov_b32_e32 v117, v89
	v_pk_fma_f32 v[92:93], v[82:83], s[12:13], v[84:85] op_sel_hi:[1,0,1] neg_lo:[0,0,1] neg_hi:[0,0,1]
	v_mov_b32_e32 v94, v84
	v_pk_fma_f32 v[82:83], v[82:83], s[14:15], v[92:93] op_sel_hi:[1,0,1]
	v_cmp_lt_f32_e64 s[0:1], |v131|, s9
	v_pk_add_f32 v[92:93], v[84:85], v[82:83]
	v_mov_b32_e32 v110, v82
	v_pk_add_f32 v[100:101], v[92:93], v[88:89]
	v_mov_b32_e32 v115, v93
	v_mov_b32_e32 v113, v101
	v_pk_add_f32 v[112:113], v[112:113], v[114:115] neg_lo:[0,1] neg_hi:[0,1]
	v_pk_add_f32 v[94:95], v[94:95], v[110:111]
	v_mov_b32_e32 v102, v100
	v_mov_b32_e32 v103, v93
	v_mov_b32_e32 v110, v92
	v_mov_b32_e32 v111, v85
	v_mov_b32_e32 v114, v92
	v_mov_b32_e32 v115, v101
	v_mov_b32_e32 v85, v113
	v_pk_add_f32 v[102:103], v[102:103], v[110:111] neg_lo:[0,1] neg_hi:[0,1]
	v_mov_b32_e32 v110, v88
	v_mov_b32_e32 v111, v83
	v_pk_add_f32 v[84:85], v[114:115], v[84:85] neg_lo:[0,1] neg_hi:[0,1]
	v_pk_add_f32 v[110:111], v[110:111], v[102:103] neg_lo:[0,1] neg_hi:[0,1]
	v_mov_b32_e32 v114, v84
	v_mov_b32_e32 v115, v103
	v_mov_b32_e32 v116, v100
	v_mov_b32_e32 v103, v91
	v_pk_add_f32 v[114:115], v[82:83], v[114:115] neg_lo:[0,1] neg_hi:[0,1]
	v_pk_add_f32 v[102:103], v[116:117], v[102:103] neg_lo:[0,1] neg_hi:[0,1]
	v_mov_b32_e32 v83, v93
	v_pk_add_f32 v[88:89], v[88:89], v[90:91] neg_lo:[0,1] neg_hi:[0,1]
	v_pk_add_f32 v[90:91], v[94:95], v[102:103] neg_lo:[0,1] neg_hi:[0,1]
	v_pk_add_f32 v[82:83], v[82:83], v[84:85] neg_lo:[0,1] neg_hi:[0,1]
	v_pk_add_f32 v[84:85], v[86:87], v[112:113] neg_lo:[0,1] neg_hi:[0,1]
	v_pk_add_f32 v[92:93], v[110:111], v[90:91]
	v_pk_add_f32 v[86:87], v[84:85], v[82:83]
	v_mov_b32_e32 v83, v111
	v_mov_b32_e32 v85, v91
	v_pk_add_f32 v[84:85], v[82:83], v[84:85]
	v_mov_b32_e32 v90, v86
	v_pk_add_f32 v[84:85], v[84:85], v[114:115] neg_lo:[0,1] neg_hi:[0,1]
	v_mov_b32_e32 v91, v93
	v_pk_add_f32 v[88:89], v[98:99], v[88:89] neg_lo:[0,1] neg_hi:[0,1]
	v_pk_add_f32 v[90:91], v[90:91], v[84:85] neg_lo:[0,1] neg_hi:[0,1]
	v_pk_add_f32 v[84:85], v[88:89], v[84:85] neg_lo:[0,1] neg_hi:[0,1]
	v_pk_add_f32 v[82:83], v[82:83], v[90:91] neg_lo:[0,1] neg_hi:[0,1]
	s_nop 0
	v_pk_add_f32 v[82:83], v[84:85], v[82:83]
	v_pk_add_f32 v[84:85], v[92:93], v[86:87]
	s_nop 0
	v_pk_add_f32 v[86:87], v[100:101], v[84:85]
	s_nop 0
	v_pk_add_f32 v[88:89], v[86:87], v[100:101] neg_lo:[0,1] neg_hi:[0,1]
	s_nop 0
	v_pk_add_f32 v[84:85], v[84:85], v[88:89] neg_lo:[0,1] neg_hi:[0,1]
	s_nop 0
	v_pk_add_f32 v[82:83], v[82:83], v[84:85]
	s_nop 0
	v_pk_add_f32 v[82:83], v[86:87], v[82:83]
	s_nop 0
	v_cndmask_b32_e32 v82, v160, v82, vcc
	v_cmp_neq_f32_e32 vcc, s8, v131
	s_nop 1
	v_cndmask_b32_e32 v83, v160, v83, vcc
	v_cmp_ngt_f32_e32 vcc, -1.0, v131
	s_nop 1
	v_cndmask_b32_e32 v83, v161, v83, vcc
	v_cmp_ngt_f32_e32 vcc, -1.0, v129
	s_nop 1
	v_cndmask_b32_e32 v82, v161, v82, vcc
	v_cmp_neq_f32_e32 vcc, -1.0, v129
	s_nop 1
	v_cndmask_b32_e32 v82, v162, v82, vcc
	v_cmp_neq_f32_e32 vcc, -1.0, v131
	s_nop 1
	v_cndmask_b32_e32 v83, v162, v83, vcc
	v_cmp_lt_f32_e64 vcc, |v129|, s9
	v_cndmask_b32_e64 v83, v83, v131, s[0:1]
	s_nop 0
	v_cndmask_b32_e32 v82, v82, v129, vcc
	v_pk_add_f32 v[80:81], v[80:81], v[82:83]
	global_store_dwordx4 v[76:77], v[78:81], off
	global_load_dwordx4 v[78:81], v0, s[74:75] offset:64
	s_waitcnt vmcnt(0)
; __device__ __forceinline__ float softplusf(float x) { return fmaxf(x, 0.f) + log1pf(__expf(-fabsf(x))); }
; __device__ void phaseA_tile(const Params& p, int l, int mt, int nt, char* smem) {
;     ...
;                 for (int j = 0; j < 2; ++j) {
;                     const int c = j * 16 + g4 * 4;
;                     const float4 db = *(const float4*)(p.dt_bias + l * 32 + c);
;                     const f32x4 v = acc[i][j];
;                     *(float4*)(p.dtb + (size_t)row * 32 + c) =
;                         make_float4(softplusf(v[0] + db.x), softplusf(v[1] + db.y), softplusf(v[2] + db.z), softplusf(v[3] + db.w));
;                 }
	v_add_f32_e32 v82, v10, v78
	v_max_f32_e32 v78, 0, v82
	v_mul_f32_e64 v82, |v82|, s2
	v_exp_f32_e32 v97, v82
	s_nop 0
	v_add_f32_e32 v84, 1.0, v97
	v_add_f32_e32 v82, -1.0, v84
	v_sub_f32_e32 v83, v82, v84
	v_add_f32_e32 v83, 1.0, v83
	v_sub_f32_e32 v82, v97, v82
	v_add_f32_e32 v85, v82, v83
	v_frexp_mant_f32_e32 v82, v84
	v_cmp_gt_f32_e32 vcc, s26, v82
	v_cvt_f64_f32_e32 v[82:83], v84
	v_frexp_exp_i32_f64_e32 v82, v[82:83]
	v_subbrev_co_u32_e32 v120, vcc, 0, v82, vcc
	v_sub_u32_e32 v83, 0, v120
	v_ldexp_f32 v82, v84, v83
	v_ldexp_f32 v84, v85, v83
	v_add_f32_e32 v83, v11, v79
	v_max_f32_e32 v79, 0, v83
	v_mul_f32_e64 v83, |v83|, s2
	v_exp_f32_e32 v128, v83
	s_nop 0
	v_add_f32_e32 v83, 1.0, v128
	v_add_f32_e32 v85, -1.0, v83
	v_sub_f32_e32 v86, v85, v83
	v_add_f32_e32 v86, 1.0, v86
	v_sub_f32_e32 v85, v128, v85
	v_add_f32_e32 v85, v85, v86
	v_frexp_mant_f32_e32 v86, v83
	v_cmp_gt_f32_e32 vcc, s26, v86
	v_cvt_f64_f32_e32 v[86:87], v83
	v_frexp_exp_i32_f64_e32 v86, v[86:87]
	v_subbrev_co_u32_e32 v121, vcc, 0, v86, vcc
	v_sub_u32_e32 v86, 0, v121
	v_ldexp_f32 v83, v83, v86
	v_ldexp_f32 v85, v85, v86
	v_pk_add_f32 v[86:87], v[82:83], 1.0 op_sel_hi:[1,0]
	v_pk_add_f32 v[94:95], v[82:83], -1.0 op_sel_hi:[1,0]
	v_pk_add_f32 v[88:89], v[86:87], -1.0 op_sel_hi:[1,0]
	v_pk_add_f32 v[98:99], v[94:95], 1.0 op_sel_hi:[1,0]
	v_pk_add_f32 v[88:89], v[82:83], v[88:89] neg_lo:[0,1] neg_hi:[0,1]
	v_pk_add_f32 v[82:83], v[82:83], v[98:99] neg_lo:[0,1] neg_hi:[0,1]
	v_pk_add_f32 v[88:89], v[84:85], v[88:89]
	v_pk_add_f32 v[82:83], v[84:85], v[82:83]
	v_pk_add_f32 v[90:91], v[86:87], v[88:89]
	v_pk_add_f32 v[84:85], v[94:95], v[82:83]
	v_rcp_f32_e32 v92, v90
	v_rcp_f32_e32 v93, v91
	v_pk_add_f32 v[86:87], v[90:91], v[86:87] neg_lo:[0,1] neg_hi:[0,1]
	v_pk_add_f32 v[94:95], v[84:85], v[94:95] neg_lo:[0,1] neg_hi:[0,1]
	v_pk_add_f32 v[86:87], v[88:89], v[86:87] neg_lo:[0,1] neg_hi:[0,1]
	v_pk_mul_f32 v[88:89], v[84:85], v[92:93]
	v_pk_add_f32 v[82:83], v[82:83], v[94:95] neg_lo:[0,1] neg_hi:[0,1]
	v_pk_mul_f32 v[94:95], v[90:91], v[88:89]
	v_cmp_lt_f32_e64 s[0:1], |v128|, s9
	v_pk_fma_f32 v[98:99], v[88:89], v[90:91], v[94:95] neg_lo:[0,0,1] neg_hi:[0,0,1]
	s_nop 0
	v_pk_fma_f32 v[98:99], v[88:89], v[86:87], v[98:99]
	s_nop 0
	v_pk_add_f32 v[100:101], v[94:95], v[98:99]
	s_nop 0
	v_pk_add_f32 v[102:103], v[84:85], v[100:101] neg_lo:[0,1] neg_hi:[0,1]
	v_pk_add_f32 v[94:95], v[100:101], v[94:95] neg_lo:[0,1] neg_hi:[0,1]
	v_pk_add_f32 v[84:85], v[84:85], v[102:103] neg_lo:[0,1] neg_hi:[0,1]
	s_nop 0
	v_pk_add_f32 v[84:85], v[84:85], v[100:101] neg_lo:[0,1] neg_hi:[0,1]
	s_nop 0
	v_pk_add_f32 v[82:83], v[82:83], v[84:85]
	v_pk_add_f32 v[84:85], v[94:95], v[98:99] neg_lo:[0,1] neg_hi:[0,1]
	s_nop 0
	v_pk_add_f32 v[82:83], v[84:85], v[82:83]
	s_nop 0
	v_pk_add_f32 v[84:85], v[102:103], v[82:83]
	s_nop 0
	v_pk_mul_f32 v[94:95], v[92:93], v[84:85]
	s_nop 0
	v_pk_mul_f32 v[98:99], v[90:91], v[94:95]
	s_nop 0
	v_pk_fma_f32 v[90:91], v[94:95], v[90:91], v[98:99] neg_lo:[0,0,1] neg_hi:[0,0,1]
	s_nop 0
	v_pk_fma_f32 v[86:87], v[94:95], v[86:87], v[90:91]
	v_pk_add_f32 v[90:91], v[102:103], v[84:85] neg_lo:[0,1] neg_hi:[0,1]
	s_nop 0
	v_pk_add_f32 v[82:83], v[82:83], v[90:91]
	v_pk_add_f32 v[90:91], v[98:99], v[86:87]
	s_nop 0
	v_pk_add_f32 v[100:101], v[84:85], v[90:91] neg_lo:[0,1] neg_hi:[0,1]
	v_pk_add_f32 v[98:99], v[90:91], v[98:99] neg_lo:[0,1] neg_hi:[0,1]
	v_pk_add_f32 v[84:85], v[84:85], v[100:101] neg_lo:[0,1] neg_hi:[0,1]
	s_nop 0
	v_pk_add_f32 v[84:85], v[84:85], v[90:91] neg_lo:[0,1] neg_hi:[0,1]
	s_nop 0
	v_pk_add_f32 v[82:83], v[82:83], v[84:85]
	v_pk_add_f32 v[84:85], v[98:99], v[86:87] neg_lo:[0,1] neg_hi:[0,1]
	s_nop 0
	v_pk_add_f32 v[82:83], v[84:85], v[82:83]
	v_pk_add_f32 v[84:85], v[88:89], v[94:95]
	v_pk_add_f32 v[82:83], v[100:101], v[82:83]
	v_pk_add_f32 v[86:87], v[84:85], v[88:89] neg_lo:[0,1] neg_hi:[0,1]
	v_pk_mul_f32 v[82:83], v[92:93], v[82:83]
	v_pk_add_f32 v[86:87], v[94:95], v[86:87] neg_lo:[0,1] neg_hi:[0,1]
	s_nop 0
	v_pk_add_f32 v[82:83], v[86:87], v[82:83]
	s_nop 0
	v_pk_add_f32 v[86:87], v[84:85], v[82:83]
	s_nop 0
	v_pk_add_f32 v[84:85], v[86:87], v[84:85] neg_lo:[0,1] neg_hi:[0,1]
	v_pk_mul_f32 v[88:89], v[86:87], v[86:87]
	v_pk_add_f32 v[82:83], v[82:83], v[84:85] neg_lo:[0,1] neg_hi:[0,1]
	v_pk_fma_f32 v[90:91], v[88:89], s[28:29], v[66:67] op_sel_hi:[1,0,0]
	v_ldexp_f32 v93, v83, 1
	v_add_f32_e32 v83, v12, v80
	v_max_f32_e32 v80, 0, v83
	v_mul_f32_e64 v83, |v83|, s2
	v_exp_f32_e32 v129, v83
	v_ldexp_f32 v84, v86, 1
	v_pk_fma_f32 v[90:91], v[88:89], v[90:91], s[30:31] op_sel_hi:[1,1,0]
	v_ldexp_f32 v85, v87, 1
	v_add_f32_e32 v83, 1.0, v129
	v_pk_mul_f32 v[86:87], v[86:87], v[88:89]
	v_add_f32_e32 v88, -1.0, v83
	v_sub_f32_e32 v89, v88, v83
	v_add_f32_e32 v89, 1.0, v89
	v_sub_f32_e32 v88, v129, v88
	v_add_f32_e32 v92, v88, v89
	v_frexp_mant_f32_e32 v88, v83
	v_cmp_gt_f32_e32 vcc, s26, v88
	v_cvt_f64_f32_e32 v[88:89], v83
	v_frexp_exp_i32_f64_e32 v88, v[88:89]
	v_subbrev_co_u32_e32 v130, vcc, 0, v88, vcc
	v_sub_u32_e32 v89, 0, v130
	v_ldexp_f32 v88, v83, v89
	v_add_f32_e32 v83, v13, v81
	v_max_f32_e32 v81, 0, v83
	v_mul_f32_e64 v83, |v83|, s2
	v_exp_f32_e32 v131, v83
	v_ldexp_f32 v94, v92, v89
	v_pk_mul_f32 v[86:87], v[86:87], v[90:91]
	v_ldexp_f32 v82, v82, 1
	v_add_f32_e32 v83, 1.0, v131
	v_add_f32_e32 v89, -1.0, v83
	v_sub_f32_e32 v92, v89, v83
	v_add_f32_e32 v92, 1.0, v92
	v_sub_f32_e32 v89, v131, v89
	v_add_f32_e32 v92, v89, v92
	v_frexp_mant_f32_e32 v89, v83
	v_cvt_f64_f32_e32 v[98:99], v83
	v_cmp_gt_f32_e32 vcc, s26, v89
	v_frexp_exp_i32_f64_e32 v89, v[98:99]
	v_pk_add_f32 v[90:91], v[84:85], v[86:87]
; __device__ __forceinline__ float softplusf(float x) { return fmaxf(x, 0.f) + log1pf(__expf(-fabsf(x))); }
; __device__ void phaseA_tile(const Params& p, int l, int mt, int nt, char* smem) {
;     ...
;                 for (int j = 0; j < 2; ++j) {
;                     const int c = j * 16 + g4 * 4;
;                     const float4 db = *(const float4*)(p.dt_bias + l * 32 + c);
;                     const f32x4 v = acc[i][j];
;                     *(float4*)(p.dtb + (size_t)row * 32 + c) =
;                         make_float4(softplusf(v[0] + db.x), softplusf(v[1] + db.y), softplusf(v[2] + db.z), softplusf(v[3] + db.w));
;                 }
	v_subbrev_co_u32_e32 v132, vcc, 0, v89, vcc
	v_sub_u32_e32 v95, 0, v132
	v_ldexp_f32 v89, v83, v95
	v_pk_add_f32 v[98:99], v[88:89], 1.0 op_sel_hi:[1,0]
	v_ldexp_f32 v95, v92, v95
	v_pk_add_f32 v[100:101], v[98:99], -1.0 op_sel_hi:[1,0]
	v_pk_add_f32 v[112:113], v[88:89], -1.0 op_sel_hi:[1,0]
	v_pk_add_f32 v[100:101], v[88:89], v[100:101] neg_lo:[0,1] neg_hi:[0,1]
	v_pk_add_f32 v[114:115], v[112:113], 1.0 op_sel_hi:[1,0]
	v_pk_add_f32 v[100:101], v[94:95], v[100:101]
	v_pk_add_f32 v[88:89], v[88:89], v[114:115] neg_lo:[0,1] neg_hi:[0,1]
	v_pk_add_f32 v[102:103], v[98:99], v[100:101]
	v_pk_add_f32 v[88:89], v[94:95], v[88:89]
	v_rcp_f32_e32 v110, v102
	v_rcp_f32_e32 v111, v103
	v_pk_add_f32 v[94:95], v[112:113], v[88:89]
	v_pk_add_f32 v[98:99], v[102:103], v[98:99] neg_lo:[0,1] neg_hi:[0,1]
	v_pk_add_f32 v[112:113], v[94:95], v[112:113] neg_lo:[0,1] neg_hi:[0,1]
	v_pk_add_f32 v[98:99], v[100:101], v[98:99] neg_lo:[0,1] neg_hi:[0,1]
	v_pk_mul_f32 v[100:101], v[94:95], v[110:111]
	v_pk_add_f32 v[88:89], v[88:89], v[112:113] neg_lo:[0,1] neg_hi:[0,1]
	v_pk_mul_f32 v[112:113], v[102:103], v[100:101]
	v_pk_add_f32 v[84:85], v[90:91], v[84:85] neg_lo:[0,1] neg_hi:[0,1]
	v_pk_fma_f32 v[114:115], v[100:101], v[102:103], v[112:113] neg_lo:[0,0,1] neg_hi:[0,0,1]
	v_pk_add_f32 v[84:85], v[86:87], v[84:85] neg_lo:[0,1] neg_hi:[0,1]
	v_pk_fma_f32 v[114:115], v[100:101], v[98:99], v[114:115]
	v_mov_b32_e32 v87, v85
	v_pk_add_f32 v[116:117], v[112:113], v[114:115]
	v_mov_b32_e32 v83, v93
	v_pk_add_f32 v[118:119], v[94:95], v[116:117] neg_lo:[0,1] neg_hi:[0,1]
	v_pk_add_f32 v[112:113], v[116:117], v[112:113] neg_lo:[0,1] neg_hi:[0,1]
	v_pk_add_f32 v[94:95], v[94:95], v[118:119] neg_lo:[0,1] neg_hi:[0,1]
	v_mov_b32_e32 v124, v90
	v_pk_add_f32 v[94:95], v[94:95], v[116:117] neg_lo:[0,1] neg_hi:[0,1]
	v_cmp_neq_f32_e32 vcc, s8, v97
	v_pk_add_f32 v[88:89], v[88:89], v[94:95]
	v_pk_add_f32 v[94:95], v[112:113], v[114:115] neg_lo:[0,1] neg_hi:[0,1]
	s_nop 0
	v_pk_add_f32 v[88:89], v[94:95], v[88:89]
	s_nop 0
	v_pk_add_f32 v[94:95], v[118:119], v[88:89]
	s_nop 0
	v_pk_mul_f32 v[112:113], v[110:111], v[94:95]
	s_nop 0
	v_pk_mul_f32 v[114:115], v[102:103], v[112:113]
	s_nop 0
	v_pk_fma_f32 v[102:103], v[112:113], v[102:103], v[114:115] neg_lo:[0,0,1] neg_hi:[0,0,1]
	s_nop 0
	v_pk_fma_f32 v[98:99], v[112:113], v[98:99], v[102:103]
	v_pk_add_f32 v[102:103], v[118:119], v[94:95] neg_lo:[0,1] neg_hi:[0,1]
	s_nop 0
	v_pk_add_f32 v[88:89], v[88:89], v[102:103]
	v_pk_add_f32 v[102:103], v[114:115], v[98:99]
	s_nop 0
	v_pk_add_f32 v[116:117], v[94:95], v[102:103] neg_lo:[0,1] neg_hi:[0,1]
	v_pk_add_f32 v[114:115], v[102:103], v[114:115] neg_lo:[0,1] neg_hi:[0,1]
	v_pk_add_f32 v[94:95], v[94:95], v[116:117] neg_lo:[0,1] neg_hi:[0,1]
	s_nop 0
	v_pk_add_f32 v[94:95], v[94:95], v[102:103] neg_lo:[0,1] neg_hi:[0,1]
	s_nop 0
	v_pk_add_f32 v[88:89], v[88:89], v[94:95]
	v_pk_add_f32 v[94:95], v[114:115], v[98:99] neg_lo:[0,1] neg_hi:[0,1]
	s_nop 0
	v_pk_add_f32 v[88:89], v[94:95], v[88:89]
	v_pk_add_f32 v[94:95], v[100:101], v[112:113]
	v_pk_add_f32 v[88:89], v[116:117], v[88:89]
	v_pk_add_f32 v[98:99], v[94:95], v[100:101] neg_lo:[0,1] neg_hi:[0,1]
	v_pk_mul_f32 v[88:89], v[110:111], v[88:89]
	v_pk_add_f32 v[98:99], v[112:113], v[98:99] neg_lo:[0,1] neg_hi:[0,1]
	s_nop 0
	v_pk_add_f32 v[88:89], v[98:99], v[88:89]
	s_nop 0
	v_pk_add_f32 v[98:99], v[94:95], v[88:89]
	s_nop 0
	v_pk_mul_f32 v[100:101], v[98:99], v[98:99]
	v_pk_add_f32 v[94:95], v[98:99], v[94:95] neg_lo:[0,1] neg_hi:[0,1]
	v_pk_fma_f32 v[102:103], v[100:101], s[28:29], v[66:67] op_sel_hi:[1,0,0]
	v_pk_add_f32 v[88:89], v[88:89], v[94:95] neg_lo:[0,1] neg_hi:[0,1]
	v_ldexp_f32 v94, v98, 1
	v_pk_fma_f32 v[102:103], v[100:101], v[102:103], s[30:31] op_sel_hi:[1,1,0]
	v_ldexp_f32 v95, v99, 1
	v_pk_mul_f32 v[98:99], v[98:99], v[100:101]
	v_cvt_f32_i32_e32 v101, v121
	v_cvt_f32_i32_e32 v100, v120
	v_ldexp_f32 v111, v89, 1
	v_ldexp_f32 v88, v88, 1
	v_mov_b32_e32 v89, v111
	v_pk_mul_f32 v[112:113], v[100:101], s[12:13] op_sel_hi:[1,0]
	s_nop 0
	v_pk_fma_f32 v[114:115], v[100:101], s[12:13], v[112:113] op_sel_hi:[1,0,1] neg_lo:[0,0,1] neg_hi:[0,0,1]
	v_mov_b32_e32 v86, v112
	v_pk_fma_f32 v[100:101], v[100:101], s[14:15], v[114:115] op_sel_hi:[1,0,1]
	v_mov_b32_e32 v121, v113
	v_mov_b32_e32 v92, v100
	v_pk_add_f32 v[86:87], v[86:87], v[92:93]
	v_pk_add_f32 v[92:93], v[82:83], v[84:85]
	v_mov_b32_e32 v85, v91
	v_mov_b32_e32 v83, v93
	v_pk_add_f32 v[114:115], v[112:113], v[100:101]
	v_pk_add_f32 v[82:83], v[82:83], v[84:85]
	v_pk_add_f32 v[84:85], v[90:91], v[92:93]
	v_mov_b32_e32 v125, v115
	v_pk_add_f32 v[116:117], v[114:115], v[84:85]
	v_mov_b32_e32 v122, v84
	v_mov_b32_e32 v123, v117
	v_pk_add_f32 v[122:123], v[122:123], v[124:125] neg_lo:[0,1] neg_hi:[0,1]
	v_mov_b32_e32 v118, v116
	v_mov_b32_e32 v119, v115
	v_mov_b32_e32 v120, v114
	v_mov_b32_e32 v124, v114
	v_mov_b32_e32 v125, v117
	v_mov_b32_e32 v113, v123
	v_pk_add_f32 v[118:119], v[118:119], v[120:121] neg_lo:[0,1] neg_hi:[0,1]
	v_mov_b32_e32 v120, v84
	v_mov_b32_e32 v121, v101
	v_pk_add_f32 v[112:113], v[124:125], v[112:113] neg_lo:[0,1] neg_hi:[0,1]
	v_pk_add_f32 v[120:121], v[120:121], v[118:119] neg_lo:[0,1] neg_hi:[0,1]
	v_mov_b32_e32 v124, v112
	v_mov_b32_e32 v125, v119
	v_mov_b32_e32 v126, v116
	v_mov_b32_e32 v127, v85
	v_mov_b32_e32 v119, v91
	v_pk_add_f32 v[124:125], v[100:101], v[124:125] neg_lo:[0,1] neg_hi:[0,1]
	v_pk_add_f32 v[118:119], v[126:127], v[118:119] neg_lo:[0,1] neg_hi:[0,1]
	v_mov_b32_e32 v101, v115
	v_pk_add_f32 v[84:85], v[84:85], v[90:91] neg_lo:[0,1] neg_hi:[0,1]
	v_pk_add_f32 v[86:87], v[86:87], v[118:119] neg_lo:[0,1] neg_hi:[0,1]
; __device__ __forceinline__ float softplusf(float x) { return fmaxf(x, 0.f) + log1pf(__expf(-fabsf(x))); }
; __device__ void phaseA_tile(const Params& p, int l, int mt, int nt, char* smem) {
;     ...
;                 for (int j = 0; j < 2; ++j) {
;                     const int c = j * 16 + g4 * 4;
;                     const float4 db = *(const float4*)(p.dt_bias + l * 32 + c);
;                     const f32x4 v = acc[i][j];
;                     *(float4*)(p.dtb + (size_t)row * 32 + c) =
;                         make_float4(softplusf(v[0] + db.x), softplusf(v[1] + db.y), softplusf(v[2] + db.z), softplusf(v[3] + db.w));
;                 }
	v_pk_add_f32 v[90:91], v[100:101], v[112:113] neg_lo:[0,1] neg_hi:[0,1]
	v_pk_add_f32 v[82:83], v[82:83], v[122:123] neg_lo:[0,1] neg_hi:[0,1]
	v_pk_add_f32 v[84:85], v[92:93], v[84:85] neg_lo:[0,1] neg_hi:[0,1]
	v_pk_add_f32 v[92:93], v[82:83], v[90:91]
	v_mov_b32_e32 v91, v121
	v_mov_b32_e32 v83, v87
	v_pk_add_f32 v[100:101], v[120:121], v[86:87]
	v_pk_add_f32 v[82:83], v[90:91], v[82:83]
	v_mov_b32_e32 v86, v92
	v_pk_add_f32 v[82:83], v[82:83], v[124:125] neg_lo:[0,1] neg_hi:[0,1]
	v_mov_b32_e32 v87, v101
	v_pk_add_f32 v[86:87], v[86:87], v[82:83] neg_lo:[0,1] neg_hi:[0,1]
	v_pk_add_f32 v[82:83], v[84:85], v[82:83] neg_lo:[0,1] neg_hi:[0,1]
	v_pk_add_f32 v[86:87], v[90:91], v[86:87] neg_lo:[0,1] neg_hi:[0,1]
	v_pk_add_f32 v[84:85], v[100:101], v[92:93]
	v_pk_add_f32 v[82:83], v[82:83], v[86:87]
	v_pk_add_f32 v[86:87], v[116:117], v[84:85]
	s_nop 0
	v_pk_add_f32 v[90:91], v[86:87], v[116:117] neg_lo:[0,1] neg_hi:[0,1]
	s_nop 0
	v_pk_add_f32 v[84:85], v[84:85], v[90:91] neg_lo:[0,1] neg_hi:[0,1]
	s_nop 0
	v_pk_add_f32 v[82:83], v[82:83], v[84:85]
	s_nop 0
	v_pk_add_f32 v[82:83], v[86:87], v[82:83]
	v_pk_mul_f32 v[86:87], v[98:99], v[102:103]
	v_cndmask_b32_e32 v82, v160, v82, vcc
	v_cmp_neq_f32_e32 vcc, s8, v128
	v_pk_add_f32 v[90:91], v[94:95], v[86:87]
	s_nop 0
	v_cndmask_b32_e32 v83, v160, v83, vcc
	v_cmp_ngt_f32_e32 vcc, -1.0, v128
	v_pk_add_f32 v[94:95], v[90:91], v[94:95] neg_lo:[0,1] neg_hi:[0,1]
	v_mov_b32_e32 v114, v90
	v_cndmask_b32_e32 v83, v161, v83, vcc
	v_cmp_ngt_f32_e32 vcc, -1.0, v97
	v_pk_add_f32 v[86:87], v[86:87], v[94:95] neg_lo:[0,1] neg_hi:[0,1]
	s_nop 0
	v_cndmask_b32_e32 v82, v161, v82, vcc
	v_cmp_neq_f32_e32 vcc, -1.0, v97
	v_pk_add_f32 v[98:99], v[88:89], v[86:87]
	v_mov_b32_e32 v95, v87
	v_cndmask_b32_e32 v82, v162, v82, vcc
	v_cmp_neq_f32_e32 vcc, -1.0, v128
	v_mov_b32_e32 v89, v99
	v_mov_b32_e32 v87, v91
	v_cndmask_b32_e32 v83, v162, v83, vcc
	v_cmp_lt_f32_e64 vcc, |v97|, s9
	v_cndmask_b32_e64 v83, v83, v128, s[0:1]
	v_pk_add_f32 v[86:87], v[88:89], v[86:87]
	v_cndmask_b32_e32 v82, v82, v97, vcc
	v_pk_add_f32 v[78:79], v[78:79], v[82:83]
	v_cvt_f32_i32_e32 v83, v132
	v_cvt_f32_i32_e32 v82, v130
	v_pk_add_f32 v[88:89], v[90:91], v[98:99]
	v_cmp_neq_f32_e32 vcc, s8, v129
	v_mov_b32_e32 v112, v88
	v_pk_mul_f32 v[84:85], v[82:83], s[12:13] op_sel_hi:[1,0]
	v_mov_b32_e32 v117, v89
	v_pk_fma_f32 v[92:93], v[82:83], s[12:13], v[84:85] op_sel_hi:[1,0,1] neg_lo:[0,0,1] neg_hi:[0,0,1]
	v_mov_b32_e32 v94, v84
	v_pk_fma_f32 v[82:83], v[82:83], s[14:15], v[92:93] op_sel_hi:[1,0,1]
	v_cmp_lt_f32_e64 s[0:1], |v131|, s9
	v_pk_add_f32 v[92:93], v[84:85], v[82:83]
	v_mov_b32_e32 v110, v82
	v_pk_add_f32 v[100:101], v[92:93], v[88:89]
	v_mov_b32_e32 v115, v93
	v_mov_b32_e32 v113, v101
	v_pk_add_f32 v[112:113], v[112:113], v[114:115] neg_lo:[0,1] neg_hi:[0,1]
	v_pk_add_f32 v[94:95], v[94:95], v[110:111]
	v_mov_b32_e32 v102, v100
	v_mov_b32_e32 v103, v93
	v_mov_b32_e32 v110, v92
	v_mov_b32_e32 v111, v85
	v_mov_b32_e32 v114, v92
	v_mov_b32_e32 v115, v101
	v_mov_b32_e32 v85, v113
	v_pk_add_f32 v[102:103], v[102:103], v[110:111] neg_lo:[0,1] neg_hi:[0,1]
	v_mov_b32_e32 v110, v88
	v_mov_b32_e32 v111, v83
	v_pk_add_f32 v[84:85], v[114:115], v[84:85] neg_lo:[0,1] neg_hi:[0,1]
	v_pk_add_f32 v[110:111], v[110:111], v[102:103] neg_lo:[0,1] neg_hi:[0,1]
	v_mov_b32_e32 v114, v84
	v_mov_b32_e32 v115, v103
	v_mov_b32_e32 v116, v100
	v_mov_b32_e32 v103, v91
	v_pk_add_f32 v[114:115], v[82:83], v[114:115] neg_lo:[0,1] neg_hi:[0,1]
	v_pk_add_f32 v[102:103], v[116:117], v[102:103] neg_lo:[0,1] neg_hi:[0,1]
	v_mov_b32_e32 v83, v93
	v_pk_add_f32 v[88:89], v[88:89], v[90:91] neg_lo:[0,1] neg_hi:[0,1]
	v_pk_add_f32 v[90:91], v[94:95], v[102:103] neg_lo:[0,1] neg_hi:[0,1]
	v_pk_add_f32 v[82:83], v[82:83], v[84:85] neg_lo:[0,1] neg_hi:[0,1]
	v_pk_add_f32 v[84:85], v[86:87], v[112:113] neg_lo:[0,1] neg_hi:[0,1]
	v_pk_add_f32 v[92:93], v[110:111], v[90:91]
	v_pk_add_f32 v[86:87], v[84:85], v[82:83]
	v_mov_b32_e32 v83, v111
	v_mov_b32_e32 v85, v91
	v_pk_add_f32 v[84:85], v[82:83], v[84:85]
	v_mov_b32_e32 v90, v86
	v_pk_add_f32 v[84:85], v[84:85], v[114:115] neg_lo:[0,1] neg_hi:[0,1]
	v_mov_b32_e32 v91, v93
	v_pk_add_f32 v[88:89], v[98:99], v[88:89] neg_lo:[0,1] neg_hi:[0,1]
	v_pk_add_f32 v[90:91], v[90:91], v[84:85] neg_lo:[0,1] neg_hi:[0,1]
	v_pk_add_f32 v[84:85], v[88:89], v[84:85] neg_lo:[0,1] neg_hi:[0,1]
	v_pk_add_f32 v[82:83], v[82:83], v[90:91] neg_lo:[0,1] neg_hi:[0,1]
	s_nop 0
	v_pk_add_f32 v[82:83], v[84:85], v[82:83]
	v_pk_add_f32 v[84:85], v[92:93], v[86:87]
	s_nop 0
	v_pk_add_f32 v[86:87], v[100:101], v[84:85]
	s_nop 0
	v_pk_add_f32 v[88:89], v[86:87], v[100:101] neg_lo:[0,1] neg_hi:[0,1]
	s_nop 0
	v_pk_add_f32 v[84:85], v[84:85], v[88:89] neg_lo:[0,1] neg_hi:[0,1]
	s_nop 0
	v_pk_add_f32 v[82:83], v[82:83], v[84:85]
	s_nop 0
	v_pk_add_f32 v[82:83], v[86:87], v[82:83]
	s_nop 0
	v_cndmask_b32_e32 v82, v160, v82, vcc
	v_cmp_neq_f32_e32 vcc, s8, v131
	s_nop 1
	v_cndmask_b32_e32 v83, v160, v83, vcc
	v_cmp_ngt_f32_e32 vcc, -1.0, v131
	s_nop 1
	v_cndmask_b32_e32 v83, v161, v83, vcc
	v_cmp_ngt_f32_e32 vcc, -1.0, v129
	s_nop 1
	v_cndmask_b32_e32 v82, v161, v82, vcc
	v_cmp_neq_f32_e32 vcc, -1.0, v129
	s_nop 1
	v_cndmask_b32_e32 v82, v162, v82, vcc
	v_cmp_neq_f32_e32 vcc, -1.0, v131
	s_nop 1
	v_cndmask_b32_e32 v83, v162, v83, vcc
	v_cmp_lt_f32_e64 vcc, |v129|, s9
	v_cndmask_b32_e64 v83, v83, v131, s[0:1]
	s_nop 0
	v_cndmask_b32_e32 v82, v82, v129, vcc
	v_pk_add_f32 v[80:81], v[80:81], v[82:83]
	global_store_dwordx4 v[76:77], v[78:81], off offset:64
	global_load_dwordx4 v[76:79], v0, s[78:79]
	s_waitcnt vmcnt(0)
; __device__ __forceinline__ float logsigf(float x) { return fminf(x, 0.f) - log1pf(__expf(-fabsf(x))); }
; __device__ void phaseA_tile(const Params& p, int l, int mt, int nt, char* smem) {
;     ...
;                     const int c = g4 * 4;
;                     const float4 fb = *(const float4*)(p.b_f + l * 16 + c);
;                     const f32x4 v = acc[i][2];
;                     float4 lf = make_float4(logsigf(v[0] + fb.x), logsigf(v[1] + fb.y), logsigf(v[2] + fb.z), logsigf(v[3] + fb.w));
;                     float* o = samp ? (p.out + O_LFS + ((size_t)l * TSM + (row - TP)) * 16 + c)
;                                     : (p.out + O_LFP + ((size_t)l * TP + row) * 16 + c);
;                     *(float4*)o = lf;
;                     *(float4*)(lf_s + rl * 16 + c) = lf;
;                 }
	v_add_f32_e32 v80, v6, v76
	v_min_f32_e32 v76, 0, v80
	v_mul_f32_e64 v80, |v80|, s2
	v_exp_f32_e32 v97, v80
	s_nop 0
	v_add_f32_e32 v82, 1.0, v97
	v_add_f32_e32 v80, -1.0, v82
	v_sub_f32_e32 v81, v80, v82
	v_add_f32_e32 v81, 1.0, v81
	v_sub_f32_e32 v80, v97, v80
	v_add_f32_e32 v83, v80, v81
	v_frexp_mant_f32_e32 v80, v82
	v_cmp_gt_f32_e32 vcc, s26, v80
	v_cvt_f64_f32_e32 v[80:81], v82
	v_frexp_exp_i32_f64_e32 v80, v[80:81]
	v_subbrev_co_u32_e32 v118, vcc, 0, v80, vcc
	v_sub_u32_e32 v81, 0, v118
	v_ldexp_f32 v80, v82, v81
	v_ldexp_f32 v82, v83, v81
	v_add_f32_e32 v81, v7, v77
	v_min_f32_e32 v77, 0, v81
	v_mul_f32_e64 v81, |v81|, s2
	v_exp_f32_e32 v124, v81
	s_nop 0
	v_add_f32_e32 v81, 1.0, v124
	v_add_f32_e32 v83, -1.0, v81
	v_sub_f32_e32 v84, v83, v81
	v_add_f32_e32 v84, 1.0, v84
	v_sub_f32_e32 v83, v124, v83
	v_add_f32_e32 v83, v83, v84
	v_frexp_mant_f32_e32 v84, v81
	v_cmp_gt_f32_e32 vcc, s26, v84
	v_cvt_f64_f32_e32 v[84:85], v81
	v_frexp_exp_i32_f64_e32 v84, v[84:85]
	v_subbrev_co_u32_e32 v119, vcc, 0, v84, vcc
	v_sub_u32_e32 v84, 0, v119
	v_ldexp_f32 v81, v81, v84
	v_ldexp_f32 v83, v83, v84
	v_pk_add_f32 v[84:85], v[80:81], 1.0 op_sel_hi:[1,0]
	v_pk_add_f32 v[92:93], v[80:81], -1.0 op_sel_hi:[1,0]
	v_pk_add_f32 v[86:87], v[84:85], -1.0 op_sel_hi:[1,0]
	v_pk_add_f32 v[94:95], v[92:93], 1.0 op_sel_hi:[1,0]
	v_pk_add_f32 v[86:87], v[80:81], v[86:87] neg_lo:[0,1] neg_hi:[0,1]
	v_pk_add_f32 v[80:81], v[80:81], v[94:95] neg_lo:[0,1] neg_hi:[0,1]
	v_pk_add_f32 v[86:87], v[82:83], v[86:87]
	v_pk_add_f32 v[80:81], v[82:83], v[80:81]
	v_pk_add_f32 v[88:89], v[84:85], v[86:87]
	v_pk_add_f32 v[82:83], v[92:93], v[80:81]
	v_rcp_f32_e32 v90, v88
	v_rcp_f32_e32 v91, v89
	v_pk_add_f32 v[84:85], v[88:89], v[84:85] neg_lo:[0,1] neg_hi:[0,1]
	v_pk_add_f32 v[92:93], v[82:83], v[92:93] neg_lo:[0,1] neg_hi:[0,1]
	v_pk_add_f32 v[84:85], v[86:87], v[84:85] neg_lo:[0,1] neg_hi:[0,1]
	v_pk_mul_f32 v[86:87], v[82:83], v[90:91]
	v_pk_add_f32 v[80:81], v[80:81], v[92:93] neg_lo:[0,1] neg_hi:[0,1]
	v_pk_mul_f32 v[92:93], v[88:89], v[86:87]
	v_cmp_lt_f32_e64 s[0:1], |v124|, s9
	v_pk_fma_f32 v[94:95], v[86:87], v[88:89], v[92:93] neg_lo:[0,0,1] neg_hi:[0,0,1]
	s_nop 0
	v_pk_fma_f32 v[94:95], v[86:87], v[84:85], v[94:95]
	s_nop 0
	v_pk_add_f32 v[98:99], v[92:93], v[94:95]
	s_nop 0
	v_pk_add_f32 v[100:101], v[82:83], v[98:99] neg_lo:[0,1] neg_hi:[0,1]
	v_pk_add_f32 v[92:93], v[98:99], v[92:93] neg_lo:[0,1] neg_hi:[0,1]
	v_pk_add_f32 v[82:83], v[82:83], v[100:101] neg_lo:[0,1] neg_hi:[0,1]
	s_nop 0
	v_pk_add_f32 v[82:83], v[82:83], v[98:99] neg_lo:[0,1] neg_hi:[0,1]
	s_nop 0
	v_pk_add_f32 v[80:81], v[80:81], v[82:83]
	v_pk_add_f32 v[82:83], v[92:93], v[94:95] neg_lo:[0,1] neg_hi:[0,1]
	s_nop 0
	v_pk_add_f32 v[80:81], v[82:83], v[80:81]
	s_nop 0
	v_pk_add_f32 v[82:83], v[100:101], v[80:81]
	s_nop 0
	v_pk_mul_f32 v[92:93], v[90:91], v[82:83]
	s_nop 0
	v_pk_mul_f32 v[94:95], v[88:89], v[92:93]
	s_nop 0
	v_pk_fma_f32 v[88:89], v[92:93], v[88:89], v[94:95] neg_lo:[0,0,1] neg_hi:[0,0,1]
	s_nop 0
	v_pk_fma_f32 v[84:85], v[92:93], v[84:85], v[88:89]
	v_pk_add_f32 v[88:89], v[100:101], v[82:83] neg_lo:[0,1] neg_hi:[0,1]
	s_nop 0
	v_pk_add_f32 v[80:81], v[80:81], v[88:89]
	v_pk_add_f32 v[88:89], v[94:95], v[84:85]
	s_nop 0
	v_pk_add_f32 v[98:99], v[82:83], v[88:89] neg_lo:[0,1] neg_hi:[0,1]
	v_pk_add_f32 v[94:95], v[88:89], v[94:95] neg_lo:[0,1] neg_hi:[0,1]
	v_pk_add_f32 v[82:83], v[82:83], v[98:99] neg_lo:[0,1] neg_hi:[0,1]
	s_nop 0
	v_pk_add_f32 v[82:83], v[82:83], v[88:89] neg_lo:[0,1] neg_hi:[0,1]
	s_nop 0
	v_pk_add_f32 v[80:81], v[80:81], v[82:83]
	v_pk_add_f32 v[82:83], v[94:95], v[84:85] neg_lo:[0,1] neg_hi:[0,1]
	s_nop 0
	v_pk_add_f32 v[80:81], v[82:83], v[80:81]
	v_pk_add_f32 v[82:83], v[86:87], v[92:93]
	v_pk_add_f32 v[80:81], v[98:99], v[80:81]
	v_pk_add_f32 v[84:85], v[82:83], v[86:87] neg_lo:[0,1] neg_hi:[0,1]
	v_pk_mul_f32 v[80:81], v[90:91], v[80:81]
	v_pk_add_f32 v[84:85], v[92:93], v[84:85] neg_lo:[0,1] neg_hi:[0,1]
	s_nop 0
	v_pk_add_f32 v[80:81], v[84:85], v[80:81]
	s_nop 0
	v_pk_add_f32 v[84:85], v[82:83], v[80:81]
	s_nop 0
	v_pk_add_f32 v[82:83], v[84:85], v[82:83] neg_lo:[0,1] neg_hi:[0,1]
	v_pk_mul_f32 v[86:87], v[84:85], v[84:85]
	v_pk_add_f32 v[80:81], v[80:81], v[82:83] neg_lo:[0,1] neg_hi:[0,1]
	v_pk_fma_f32 v[88:89], v[86:87], s[28:29], v[66:67] op_sel_hi:[1,0,0]
	v_ldexp_f32 v91, v81, 1
	v_add_f32_e32 v81, v8, v78
	v_min_f32_e32 v78, 0, v81
	v_mul_f32_e64 v81, |v81|, s2
	v_exp_f32_e32 v125, v81
	v_ldexp_f32 v82, v84, 1
	v_pk_fma_f32 v[88:89], v[86:87], v[88:89], s[30:31] op_sel_hi:[1,1,0]
	v_ldexp_f32 v83, v85, 1
	v_add_f32_e32 v81, 1.0, v125
	v_pk_mul_f32 v[84:85], v[84:85], v[86:87]
	v_add_f32_e32 v86, -1.0, v81
	v_sub_f32_e32 v87, v86, v81
	v_add_f32_e32 v87, 1.0, v87
	v_sub_f32_e32 v86, v125, v86
	v_add_f32_e32 v90, v86, v87
	v_frexp_mant_f32_e32 v86, v81
	v_cmp_gt_f32_e32 vcc, s26, v86
	v_cvt_f64_f32_e32 v[86:87], v81
	v_frexp_exp_i32_f64_e32 v86, v[86:87]
	v_subbrev_co_u32_e32 v126, vcc, 0, v86, vcc
	v_sub_u32_e32 v87, 0, v126
	v_ldexp_f32 v86, v81, v87
	v_add_f32_e32 v81, v9, v79
	v_min_f32_e32 v79, 0, v81
	v_mul_f32_e64 v81, |v81|, s2
	v_exp_f32_e32 v127, v81
	v_ldexp_f32 v92, v90, v87
	v_pk_mul_f32 v[84:85], v[84:85], v[88:89]
	v_ldexp_f32 v80, v80, 1
	v_add_f32_e32 v81, 1.0, v127
	v_add_f32_e32 v87, -1.0, v81
	v_sub_f32_e32 v90, v87, v81
	v_add_f32_e32 v90, 1.0, v90
	v_sub_f32_e32 v87, v127, v87
	v_add_f32_e32 v90, v87, v90
	v_frexp_mant_f32_e32 v87, v81
	v_cvt_f64_f32_e32 v[94:95], v81
	v_cmp_gt_f32_e32 vcc, s26, v87
	v_frexp_exp_i32_f64_e32 v87, v[94:95]
	v_pk_add_f32 v[88:89], v[82:83], v[84:85]
	v_subbrev_co_u32_e32 v128, vcc, 0, v87, vcc
; __device__ __forceinline__ float logsigf(float x) { return fminf(x, 0.f) - log1pf(__expf(-fabsf(x))); }
; __device__ void phaseA_tile(const Params& p, int l, int mt, int nt, char* smem) {
;     ...
;                     const int c = g4 * 4;
;                     const float4 fb = *(const float4*)(p.b_f + l * 16 + c);
;                     const f32x4 v = acc[i][2];
;                     float4 lf = make_float4(logsigf(v[0] + fb.x), logsigf(v[1] + fb.y), logsigf(v[2] + fb.z), logsigf(v[3] + fb.w));
;                     float* o = samp ? (p.out + O_LFS + ((size_t)l * TSM + (row - TP)) * 16 + c)
;                                     : (p.out + O_LFP + ((size_t)l * TP + row) * 16 + c);
;                     *(float4*)o = lf;
;                     *(float4*)(lf_s + rl * 16 + c) = lf;
;                 }
	v_sub_u32_e32 v93, 0, v128
	v_ldexp_f32 v87, v81, v93
	v_pk_add_f32 v[94:95], v[86:87], 1.0 op_sel_hi:[1,0]
	v_ldexp_f32 v93, v90, v93
	v_pk_add_f32 v[98:99], v[94:95], -1.0 op_sel_hi:[1,0]
	v_pk_add_f32 v[110:111], v[86:87], -1.0 op_sel_hi:[1,0]
	v_pk_add_f32 v[98:99], v[86:87], v[98:99] neg_lo:[0,1] neg_hi:[0,1]
	v_pk_add_f32 v[112:113], v[110:111], 1.0 op_sel_hi:[1,0]
	v_pk_add_f32 v[98:99], v[92:93], v[98:99]
	v_pk_add_f32 v[86:87], v[86:87], v[112:113] neg_lo:[0,1] neg_hi:[0,1]
	v_pk_add_f32 v[100:101], v[94:95], v[98:99]
	v_pk_add_f32 v[86:87], v[92:93], v[86:87]
	v_rcp_f32_e32 v102, v100
	v_rcp_f32_e32 v103, v101
	v_pk_add_f32 v[92:93], v[110:111], v[86:87]
	v_pk_add_f32 v[94:95], v[100:101], v[94:95] neg_lo:[0,1] neg_hi:[0,1]
	v_pk_add_f32 v[110:111], v[92:93], v[110:111] neg_lo:[0,1] neg_hi:[0,1]
	v_pk_add_f32 v[94:95], v[98:99], v[94:95] neg_lo:[0,1] neg_hi:[0,1]
	v_pk_mul_f32 v[98:99], v[92:93], v[102:103]
	v_pk_add_f32 v[86:87], v[86:87], v[110:111] neg_lo:[0,1] neg_hi:[0,1]
	v_pk_mul_f32 v[110:111], v[100:101], v[98:99]
	v_pk_add_f32 v[82:83], v[88:89], v[82:83] neg_lo:[0,1] neg_hi:[0,1]
	v_pk_fma_f32 v[112:113], v[98:99], v[100:101], v[110:111] neg_lo:[0,0,1] neg_hi:[0,0,1]
	v_pk_add_f32 v[82:83], v[84:85], v[82:83] neg_lo:[0,1] neg_hi:[0,1]
	v_pk_fma_f32 v[112:113], v[98:99], v[94:95], v[112:113]
	v_mov_b32_e32 v85, v83
	v_pk_add_f32 v[114:115], v[110:111], v[112:113]
	v_mov_b32_e32 v81, v91
	v_pk_add_f32 v[116:117], v[92:93], v[114:115] neg_lo:[0,1] neg_hi:[0,1]
	v_pk_add_f32 v[110:111], v[114:115], v[110:111] neg_lo:[0,1] neg_hi:[0,1]
	v_pk_add_f32 v[92:93], v[92:93], v[116:117] neg_lo:[0,1] neg_hi:[0,1]
	v_mov_b32_e32 v120, v88
	v_pk_add_f32 v[92:93], v[92:93], v[114:115] neg_lo:[0,1] neg_hi:[0,1]
	v_cmp_neq_f32_e32 vcc, s8, v97
	v_pk_add_f32 v[86:87], v[86:87], v[92:93]
	v_pk_add_f32 v[92:93], v[110:111], v[112:113] neg_lo:[0,1] neg_hi:[0,1]
	s_nop 0
	v_pk_add_f32 v[86:87], v[92:93], v[86:87]
	s_nop 0
	v_pk_add_f32 v[92:93], v[116:117], v[86:87]
	s_nop 0
	v_pk_mul_f32 v[110:111], v[102:103], v[92:93]
	s_nop 0
	v_pk_mul_f32 v[112:113], v[100:101], v[110:111]
	s_nop 0
	v_pk_fma_f32 v[100:101], v[110:111], v[100:101], v[112:113] neg_lo:[0,0,1] neg_hi:[0,0,1]
	s_nop 0
	v_pk_fma_f32 v[94:95], v[110:111], v[94:95], v[100:101]
	v_pk_add_f32 v[100:101], v[116:117], v[92:93] neg_lo:[0,1] neg_hi:[0,1]
	s_nop 0
	v_pk_add_f32 v[86:87], v[86:87], v[100:101]
	v_pk_add_f32 v[100:101], v[112:113], v[94:95]
	s_nop 0
	v_pk_add_f32 v[114:115], v[92:93], v[100:101] neg_lo:[0,1] neg_hi:[0,1]
	v_pk_add_f32 v[112:113], v[100:101], v[112:113] neg_lo:[0,1] neg_hi:[0,1]
	v_pk_add_f32 v[92:93], v[92:93], v[114:115] neg_lo:[0,1] neg_hi:[0,1]
	s_nop 0
	v_pk_add_f32 v[92:93], v[92:93], v[100:101] neg_lo:[0,1] neg_hi:[0,1]
	s_nop 0
	v_pk_add_f32 v[86:87], v[86:87], v[92:93]
	v_pk_add_f32 v[92:93], v[112:113], v[94:95] neg_lo:[0,1] neg_hi:[0,1]
	s_nop 0
	v_pk_add_f32 v[86:87], v[92:93], v[86:87]
	v_pk_add_f32 v[92:93], v[98:99], v[110:111]
	v_pk_add_f32 v[86:87], v[114:115], v[86:87]
	v_pk_add_f32 v[94:95], v[92:93], v[98:99] neg_lo:[0,1] neg_hi:[0,1]
	v_pk_mul_f32 v[86:87], v[102:103], v[86:87]
	v_pk_add_f32 v[94:95], v[110:111], v[94:95] neg_lo:[0,1] neg_hi:[0,1]
	s_nop 0
	v_pk_add_f32 v[86:87], v[94:95], v[86:87]
	s_nop 0
	v_pk_add_f32 v[94:95], v[92:93], v[86:87]
	s_nop 0
	v_pk_mul_f32 v[98:99], v[94:95], v[94:95]
	v_pk_add_f32 v[92:93], v[94:95], v[92:93] neg_lo:[0,1] neg_hi:[0,1]
	v_pk_fma_f32 v[66:67], v[98:99], s[28:29], v[66:67] op_sel_hi:[1,0,0]
	v_pk_add_f32 v[86:87], v[86:87], v[92:93] neg_lo:[0,1] neg_hi:[0,1]
	v_pk_fma_f32 v[100:101], v[98:99], v[66:67], s[30:31] op_sel_hi:[1,1,0]
	v_add_u32_e32 v66, 0xffff8000, v68
	v_ashrrev_i32_e32 v67, 31, v66
	v_cndmask_b32_e64 v67, v69, v67, s[60:61]
	v_cndmask_b32_e64 v66, v68, v66, s[60:61]
	v_cvt_f32_i32_e32 v69, v119
	v_cvt_f32_i32_e32 v68, v118
	v_ldexp_f32 v92, v94, 1
	v_ldexp_f32 v93, v95, 1
	v_pk_mul_f32 v[94:95], v[94:95], v[98:99]
	v_pk_mul_f32 v[98:99], v[68:69], s[12:13] op_sel_hi:[1,0]
	v_ldexp_f32 v103, v87, 1
	v_pk_fma_f32 v[110:111], v[68:69], s[12:13], v[98:99] op_sel_hi:[1,0,1] neg_lo:[0,0,1] neg_hi:[0,0,1]
	v_mov_b32_e32 v84, v98
	v_pk_fma_f32 v[68:69], v[68:69], s[14:15], v[110:111] op_sel_hi:[1,0,1]
	v_mov_b32_e32 v117, v99
	v_mov_b32_e32 v90, v68
	v_pk_add_f32 v[84:85], v[84:85], v[90:91]
	v_pk_add_f32 v[90:91], v[80:81], v[82:83]
	v_mov_b32_e32 v83, v89
	v_mov_b32_e32 v81, v91
	v_pk_add_f32 v[110:111], v[98:99], v[68:69]
	v_pk_add_f32 v[80:81], v[80:81], v[82:83]
	v_pk_add_f32 v[82:83], v[88:89], v[90:91]
	v_mov_b32_e32 v121, v111
	v_pk_add_f32 v[112:113], v[110:111], v[82:83]
	v_mov_b32_e32 v118, v82
	v_mov_b32_e32 v119, v113
	v_pk_add_f32 v[118:119], v[118:119], v[120:121] neg_lo:[0,1] neg_hi:[0,1]
	v_mov_b32_e32 v114, v112
	v_mov_b32_e32 v115, v111
	v_mov_b32_e32 v116, v110
	v_mov_b32_e32 v120, v110
	v_mov_b32_e32 v121, v113
	v_mov_b32_e32 v99, v119
	v_pk_add_f32 v[114:115], v[114:115], v[116:117] neg_lo:[0,1] neg_hi:[0,1]
	v_mov_b32_e32 v116, v82
	v_mov_b32_e32 v117, v69
	v_pk_add_f32 v[98:99], v[120:121], v[98:99] neg_lo:[0,1] neg_hi:[0,1]
	v_pk_add_f32 v[116:117], v[116:117], v[114:115] neg_lo:[0,1] neg_hi:[0,1]
	v_mov_b32_e32 v120, v98
	v_mov_b32_e32 v121, v115
	v_mov_b32_e32 v122, v112
	v_mov_b32_e32 v123, v83
	v_mov_b32_e32 v115, v89
	v_pk_add_f32 v[120:121], v[68:69], v[120:121] neg_lo:[0,1] neg_hi:[0,1]
	v_pk_add_f32 v[114:115], v[122:123], v[114:115] neg_lo:[0,1] neg_hi:[0,1]
	v_mov_b32_e32 v69, v111
	v_pk_add_f32 v[84:85], v[84:85], v[114:115] neg_lo:[0,1] neg_hi:[0,1]
	v_pk_add_f32 v[68:69], v[68:69], v[98:99] neg_lo:[0,1] neg_hi:[0,1]
; __device__ __forceinline__ float logsigf(float x) { return fminf(x, 0.f) - log1pf(__expf(-fabsf(x))); }
; __device__ void phaseA_tile(const Params& p, int l, int mt, int nt, char* smem) {
;     ...
;                     const int c = g4 * 4;
;                     const float4 fb = *(const float4*)(p.b_f + l * 16 + c);
;                     const f32x4 v = acc[i][2];
;                     float4 lf = make_float4(logsigf(v[0] + fb.x), logsigf(v[1] + fb.y), logsigf(v[2] + fb.z), logsigf(v[3] + fb.w));
;                     float* o = samp ? (p.out + O_LFS + ((size_t)l * TSM + (row - TP)) * 16 + c)
;                                     : (p.out + O_LFP + ((size_t)l * TP + row) * 16 + c);
;                     *(float4*)o = lf;
;                     *(float4*)(lf_s + rl * 16 + c) = lf;
;                 }
	v_pk_add_f32 v[80:81], v[80:81], v[118:119] neg_lo:[0,1] neg_hi:[0,1]
	v_pk_add_f32 v[82:83], v[82:83], v[88:89] neg_lo:[0,1] neg_hi:[0,1]
	v_pk_add_f32 v[88:89], v[80:81], v[68:69]
	v_mov_b32_e32 v69, v117
	v_mov_b32_e32 v81, v85
	v_pk_add_f32 v[82:83], v[90:91], v[82:83] neg_lo:[0,1] neg_hi:[0,1]
	v_pk_add_f32 v[90:91], v[116:117], v[84:85]
	v_pk_add_f32 v[80:81], v[68:69], v[80:81]
	v_mov_b32_e32 v84, v88
	v_pk_add_f32 v[80:81], v[80:81], v[120:121] neg_lo:[0,1] neg_hi:[0,1]
	v_mov_b32_e32 v85, v91
	v_pk_add_f32 v[84:85], v[84:85], v[80:81] neg_lo:[0,1] neg_hi:[0,1]
	v_pk_add_f32 v[80:81], v[82:83], v[80:81] neg_lo:[0,1] neg_hi:[0,1]
	v_pk_add_f32 v[68:69], v[68:69], v[84:85] neg_lo:[0,1] neg_hi:[0,1]
	v_ldexp_f32 v86, v86, 1
	v_pk_add_f32 v[68:69], v[80:81], v[68:69]
	v_pk_add_f32 v[80:81], v[90:91], v[88:89]
	v_mov_b32_e32 v87, v103
	v_pk_add_f32 v[82:83], v[112:113], v[80:81]
	v_lshlrev_b64 v[66:67], 6, v[66:67]
	v_pk_add_f32 v[84:85], v[82:83], v[112:113] neg_lo:[0,1] neg_hi:[0,1]
	v_lshl_add_u64 v[66:67], s[6:7], 0, v[66:67]
	v_pk_add_f32 v[80:81], v[80:81], v[84:85] neg_lo:[0,1] neg_hi:[0,1]
	v_lshl_add_u64 v[66:67], v[66:67], 0, v[0:1]
	v_pk_add_f32 v[68:69], v[68:69], v[80:81]
	v_lshl_or_b32 v0, v71, 6, v0
	v_pk_add_f32 v[68:69], v[82:83], v[68:69]
	v_pk_mul_f32 v[82:83], v[94:95], v[100:101]
	v_cndmask_b32_e32 v68, v160, v68, vcc
	v_cmp_neq_f32_e32 vcc, s8, v124
	v_pk_add_f32 v[84:85], v[92:93], v[82:83]
	s_nop 0
	v_cndmask_b32_e32 v69, v160, v69, vcc
	v_cmp_ngt_f32_e32 vcc, -1.0, v124
	v_pk_add_f32 v[90:91], v[84:85], v[92:93] neg_lo:[0,1] neg_hi:[0,1]
	v_mov_b32_e32 v110, v84
	v_cndmask_b32_e32 v69, v161, v69, vcc
	v_cmp_ngt_f32_e32 vcc, -1.0, v97
	v_pk_add_f32 v[82:83], v[82:83], v[90:91] neg_lo:[0,1] neg_hi:[0,1]
	s_nop 0
	v_cndmask_b32_e32 v68, v161, v68, vcc
	v_cmp_neq_f32_e32 vcc, -1.0, v97
	v_pk_add_f32 v[92:93], v[86:87], v[82:83]
	v_mov_b32_e32 v91, v83
	v_cndmask_b32_e32 v68, v162, v68, vcc
	v_cmp_neq_f32_e32 vcc, -1.0, v124
	v_mov_b32_e32 v87, v93
	v_mov_b32_e32 v83, v85
	v_cndmask_b32_e32 v69, v162, v69, vcc
	v_cmp_lt_f32_e64 vcc, |v97|, s9
	v_cndmask_b32_e64 v69, v69, v124, s[0:1]
	v_pk_add_f32 v[82:83], v[86:87], v[82:83]
	v_cndmask_b32_e32 v68, v68, v97, vcc
	v_pk_add_f32 v[76:77], v[76:77], v[68:69] neg_lo:[0,1] neg_hi:[0,1]
	v_cvt_f32_i32_e32 v69, v128
	v_cvt_f32_i32_e32 v68, v126
	v_pk_add_f32 v[86:87], v[84:85], v[92:93]
	v_cmp_neq_f32_e32 vcc, s8, v125
	v_mov_b32_e32 v113, v87
	v_pk_mul_f32 v[80:81], v[68:69], s[12:13] op_sel_hi:[1,0]
	v_cmp_lt_f32_e64 s[0:1], |v127|, s9
	v_pk_fma_f32 v[88:89], v[68:69], s[12:13], v[80:81] op_sel_hi:[1,0,1] neg_lo:[0,0,1] neg_hi:[0,0,1]
	v_mov_b32_e32 v90, v80
	v_pk_fma_f32 v[68:69], v[68:69], s[14:15], v[88:89] op_sel_hi:[1,0,1]
	v_mov_b32_e32 v101, v81
	v_pk_add_f32 v[88:89], v[80:81], v[68:69]
	v_mov_b32_e32 v102, v68
	v_pk_add_f32 v[94:95], v[88:89], v[86:87]
	v_pk_add_f32 v[90:91], v[90:91], v[102:103]
	v_mov_b32_e32 v102, v86
	v_mov_b32_e32 v103, v95
	v_mov_b32_e32 v111, v89
	v_pk_add_f32 v[102:103], v[102:103], v[110:111] neg_lo:[0,1] neg_hi:[0,1]
	v_mov_b32_e32 v98, v94
	v_mov_b32_e32 v99, v89
	v_mov_b32_e32 v100, v88
	v_mov_b32_e32 v110, v88
	v_mov_b32_e32 v111, v95
	v_mov_b32_e32 v81, v103
	v_pk_add_f32 v[98:99], v[98:99], v[100:101] neg_lo:[0,1] neg_hi:[0,1]
	v_mov_b32_e32 v100, v86
	v_mov_b32_e32 v101, v69
	v_pk_add_f32 v[80:81], v[110:111], v[80:81] neg_lo:[0,1] neg_hi:[0,1]
	v_pk_add_f32 v[100:101], v[100:101], v[98:99] neg_lo:[0,1] neg_hi:[0,1]
	v_mov_b32_e32 v110, v80
	v_mov_b32_e32 v111, v99
	v_mov_b32_e32 v112, v94
	v_mov_b32_e32 v99, v85
	v_pk_add_f32 v[110:111], v[68:69], v[110:111] neg_lo:[0,1] neg_hi:[0,1]
	v_pk_add_f32 v[98:99], v[112:113], v[98:99] neg_lo:[0,1] neg_hi:[0,1]
	v_mov_b32_e32 v69, v89
	v_pk_add_f32 v[84:85], v[86:87], v[84:85] neg_lo:[0,1] neg_hi:[0,1]
	v_pk_add_f32 v[86:87], v[90:91], v[98:99] neg_lo:[0,1] neg_hi:[0,1]
	v_pk_add_f32 v[68:69], v[68:69], v[80:81] neg_lo:[0,1] neg_hi:[0,1]
	v_pk_add_f32 v[80:81], v[82:83], v[102:103] neg_lo:[0,1] neg_hi:[0,1]
	v_pk_add_f32 v[88:89], v[100:101], v[86:87]
	v_pk_add_f32 v[82:83], v[80:81], v[68:69]
	v_mov_b32_e32 v69, v101
	v_mov_b32_e32 v81, v87
	v_pk_add_f32 v[80:81], v[68:69], v[80:81]
	v_mov_b32_e32 v86, v82
	v_pk_add_f32 v[80:81], v[80:81], v[110:111] neg_lo:[0,1] neg_hi:[0,1]
	v_mov_b32_e32 v87, v89
	v_pk_add_f32 v[84:85], v[92:93], v[84:85] neg_lo:[0,1] neg_hi:[0,1]
	v_pk_add_f32 v[86:87], v[86:87], v[80:81] neg_lo:[0,1] neg_hi:[0,1]
	v_pk_add_f32 v[80:81], v[84:85], v[80:81] neg_lo:[0,1] neg_hi:[0,1]
	v_pk_add_f32 v[68:69], v[68:69], v[86:87] neg_lo:[0,1] neg_hi:[0,1]
	s_nop 0
	v_pk_add_f32 v[68:69], v[80:81], v[68:69]
	v_pk_add_f32 v[80:81], v[88:89], v[82:83]
	s_nop 0
	v_pk_add_f32 v[82:83], v[94:95], v[80:81]
	s_nop 0
	v_pk_add_f32 v[84:85], v[82:83], v[94:95] neg_lo:[0,1] neg_hi:[0,1]
	s_nop 0
	v_pk_add_f32 v[80:81], v[80:81], v[84:85] neg_lo:[0,1] neg_hi:[0,1]
	s_nop 0
	v_pk_add_f32 v[68:69], v[68:69], v[80:81]
	s_nop 0
	v_pk_add_f32 v[68:69], v[82:83], v[68:69]
	s_nop 0
	v_cndmask_b32_e32 v68, v160, v68, vcc
	v_cmp_neq_f32_e32 vcc, s8, v127
	s_nop 1
	v_cndmask_b32_e32 v69, v160, v69, vcc
	v_cmp_ngt_f32_e32 vcc, -1.0, v127
	s_nop 1
	v_cndmask_b32_e32 v69, v161, v69, vcc
	v_cmp_ngt_f32_e32 vcc, -1.0, v125
	s_nop 1
	v_cndmask_b32_e32 v68, v161, v68, vcc
	v_cmp_neq_f32_e32 vcc, -1.0, v125
	s_nop 1
	v_cndmask_b32_e32 v68, v162, v68, vcc
	v_cmp_neq_f32_e32 vcc, -1.0, v127
	s_nop 1
	v_cndmask_b32_e32 v69, v162, v69, vcc
	v_cmp_lt_f32_e64 vcc, |v125|, s9
	v_cndmask_b32_e64 v69, v69, v127, s[0:1]
	s_nop 0
	v_cndmask_b32_e32 v68, v68, v125, vcc
	v_pk_add_f32 v[78:79], v[78:79], v[68:69] neg_lo:[0,1] neg_hi:[0,1]
	global_store_dwordx4 v[66:67], v[76:79], off
	ds_write_b128 v0, v[76:79]

; #define MFMA(a, b, c) __builtin_amdgcn_mfma_f32_16x16x32_bf16((a), (b), (c), 0, 0, 0)
; template <int AMODE>
; __device__ __forceinline__ void gemm_kloop(f32x4 (&acc)[4][4], const u16* __restrict__ A, int lda,
;                                            const u16* __restrict__ Bt, int ldb, int K, char* smem,
;                                            const float* __restrict__ ssq_rows) {
;     ...
;     for (int kt = 0; kt < nk; ++kt) {
;         const int buf = kt & 1;
;         if (kt + 1 < nk) GLOAD(kt + 1, buf ^ 1);
;         const char* ab = As + buf * 16384 + (wr * 64 + r) * 128;
;         const char* bb = Bs + buf * 16384 + (wc * 64 + r) * 128;
;         bf16x8 af[2][4], bfr[2][4];
; #pragma unroll
;         for (int ks = 0; ks < 2; ++ks) {
;             const int co = ((ks * 4 + g4) ^ (r & 7)) << 4;
; #pragma unroll
;             for (int i = 0; i < 4; ++i) af[ks][i] = ld_frag(ab + i * 2048 + co);
; #pragma unroll
;             for (int j = 0; j < 4; ++j) bfr[ks][j] = ld_frag(bb + j * 2048 + co);
;         }
;         __builtin_amdgcn_sched_barrier(0);
;         __builtin_amdgcn_s_setprio(1);
; #pragma unroll
;         for (int ks = 0; ks < 2; ++ks)
; #pragma unroll
;             for (int i = 0; i < 4; ++i)
; #pragma unroll
;                 for (int j = 0; j < 4; ++j) acc[i][j] = MFMA(bfr[ks][j], af[ks][i], acc[i][j]);
;         __builtin_amdgcn_s_setprio(0);
;         __builtin_amdgcn_sched_barrier(0);
;         if (kt + 1 < nk) LSTORE(buf ^ 1);
;         asm volatile("s_waitcnt vmcnt(0)" ::: "memory");
;         __syncthreads();
;     }
.LBB0_707:
	s_setprio 1
	s_and_b32 s18, s17, 0x4000
	s_xor_b32 s19, s18, 0x4000
	v_add_u32_e32 v0, s19, v70
	v_add_u32_e32 v75, 0x8000, v0
	v_lshl_add_u64 v[76:77], v[66:67], 0, s[12:13]
	v_readfirstlane_b32 s19, v75
	v_lshl_add_u64 v[78:79], v[76:77], 0, s[62:63]
	v_lshl_add_u64 v[80:81], v[68:69], 0, s[12:13]
	s_mov_b32 m0, s19
	v_readfirstlane_b32 s19, v0
	v_add_u32_e32 v75, 0x9000, v0
	v_lshl_add_u64 v[82:83], v[80:81], 0, s[62:63]
	global_load_lds_dwordx4 v[78:79], off
	s_mov_b32 m0, s19
	v_readfirstlane_b32 s19, v75
	v_add_u32_e32 v75, 0x1000, v0
	global_load_lds_dwordx4 v[82:83], off
	v_lshl_add_u64 v[78:79], v[76:77], 0, s[64:65]
	s_mov_b32 m0, s19
	v_readfirstlane_b32 s19, v75
	v_add_u32_e32 v75, 0xa000, v0
	global_load_lds_dwordx4 v[78:79], off
	v_lshl_add_u64 v[78:79], v[80:81], 0, s[64:65]
	s_mov_b32 m0, s19
	v_readfirstlane_b32 s19, v75
	v_add_u32_e32 v75, 0x2000, v0
	global_load_lds_dwordx4 v[78:79], off
	v_lshl_add_u64 v[78:79], v[76:77], 0, s[20:21]
	s_mov_b32 m0, s19
	v_readfirstlane_b32 s19, v75
	v_add_u32_e32 v75, 0xb000, v0
	global_load_lds_dwordx4 v[78:79], off
	v_lshl_add_u64 v[78:79], v[80:81], 0, s[20:21]
	s_mov_b32 m0, s19
	v_readfirstlane_b32 s19, v75
	v_add_u32_e32 v0, 0x3000, v0
	global_load_lds_dwordx4 v[78:79], off
	v_lshl_add_u64 v[76:77], v[76:77], 0, s[22:23]
	s_mov_b32 m0, s19
	v_readfirstlane_b32 s19, v0
	global_load_lds_dwordx4 v[76:77], off
	v_lshl_add_u64 v[76:77], v[80:81], 0, s[22:23]
	s_mov_b32 m0, s19
	v_add_u32_e32 v0, s18, v72
	global_load_lds_dwordx4 v[76:77], off
	v_or_b32_e32 v75, s18, v71
	v_add_u32_e32 v90, v0, v74
	v_add_u32_e32 v102, v75, v74
	v_add_u32_e32 v0, v0, v73
	ds_read_b128 v[76:79], v90
	ds_read_b128 v[80:83], v90 offset:2048
	ds_read_b128 v[84:87], v90 offset:4096
	ds_read_b128 v[90:93], v90 offset:6144
	ds_read_b128 v[94:97], v102 offset:32768
	ds_read_b128 v[98:101], v102 offset:34816
	ds_read_b128 v[110:113], v102 offset:36864
	ds_read_b128 v[114:117], v102 offset:38912
	ds_read_b128 v[118:121], v0
	ds_read_b128 v[122:125], v0 offset:2048
	ds_read_b128 v[126:129], v0 offset:4096
	ds_read_b128 v[130:133], v0 offset:6144
	v_add_u32_e32 v0, v75, v73
	ds_read_b128 v[134:137], v0 offset:32768
	ds_read_b128 v[142:145], v0 offset:34816
	ds_read_b128 v[146:149], v0 offset:36864
	ds_read_b128 v[150:153], v0 offset:38912
	s_setprio 0
	s_waitcnt lgkmcnt(0)
	v_mfma_f32_16x16x32_bf16 v[62:65], v[94:97], v[76:79], v[62:65]
	v_mfma_f32_16x16x32_bf16 v[58:61], v[98:101], v[76:79], v[58:61]
	v_mfma_f32_16x16x32_bf16 v[54:57], v[110:113], v[76:79], v[54:57]
	v_mfma_f32_16x16x32_bf16 v[50:53], v[114:117], v[76:79], v[50:53]
	v_mfma_f32_16x16x32_bf16 v[46:49], v[94:97], v[80:83], v[46:49]
	v_mfma_f32_16x16x32_bf16 v[42:45], v[98:101], v[80:83], v[42:45]
	v_mfma_f32_16x16x32_bf16 v[38:41], v[110:113], v[80:83], v[38:41]
	v_mfma_f32_16x16x32_bf16 v[34:37], v[114:117], v[80:83], v[34:37]
	v_mfma_f32_16x16x32_bf16 v[30:33], v[94:97], v[84:87], v[30:33]
	v_mfma_f32_16x16x32_bf16 v[26:29], v[98:101], v[84:87], v[26:29]
	v_mfma_f32_16x16x32_bf16 v[22:25], v[110:113], v[84:87], v[22:25]
	v_mfma_f32_16x16x32_bf16 v[18:21], v[114:117], v[84:87], v[18:21]
	v_mfma_f32_16x16x32_bf16 v[14:17], v[94:97], v[90:93], v[14:17]
	v_mfma_f32_16x16x32_bf16 v[10:13], v[98:101], v[90:93], v[10:13]
	v_mfma_f32_16x16x32_bf16 v[6:9], v[110:113], v[90:93], v[6:9]
	v_mfma_f32_16x16x32_bf16 v[2:5], v[114:117], v[90:93], v[2:5]
	v_mfma_f32_16x16x32_bf16 v[62:65], v[134:137], v[118:121], v[62:65]
	v_mfma_f32_16x16x32_bf16 v[58:61], v[142:145], v[118:121], v[58:61]
	v_mfma_f32_16x16x32_bf16 v[54:57], v[146:149], v[118:121], v[54:57]
	v_mfma_f32_16x16x32_bf16 v[50:53], v[150:153], v[118:121], v[50:53]
	v_mfma_f32_16x16x32_bf16 v[46:49], v[134:137], v[122:125], v[46:49]
	v_mfma_f32_16x16x32_bf16 v[42:45], v[142:145], v[122:125], v[42:45]
	v_mfma_f32_16x16x32_bf16 v[38:41], v[146:149], v[122:125], v[38:41]
	v_mfma_f32_16x16x32_bf16 v[34:37], v[150:153], v[122:125], v[34:37]
	v_mfma_f32_16x16x32_bf16 v[30:33], v[134:137], v[126:129], v[30:33]
	v_mfma_f32_16x16x32_bf16 v[26:29], v[142:145], v[126:129], v[26:29]
	v_mfma_f32_16x16x32_bf16 v[22:25], v[146:149], v[126:129], v[22:25]
	v_mfma_f32_16x16x32_bf16 v[18:21], v[150:153], v[126:129], v[18:21]
	v_mfma_f32_16x16x32_bf16 v[14:17], v[134:137], v[130:133], v[14:17]
	v_mfma_f32_16x16x32_bf16 v[10:13], v[142:145], v[130:133], v[10:13]
	v_mfma_f32_16x16x32_bf16 v[6:9], v[146:149], v[130:133], v[6:9]
	v_mfma_f32_16x16x32_bf16 v[2:5], v[150:153], v[130:133], v[2:5]
	s_nop 0
	s_waitcnt vmcnt(0)
	s_add_u32 s12, s12, 0x80
	s_addc_u32 s13, s13, 0
	s_addk_i32 s17, 0x4000
	s_cmpk_eq_i32 s12, 0xf80
	s_waitcnt vmcnt(0)
	s_barrier
	s_cbranch_scc0 .LBB0_707
; __device__ __forceinline__ float bf_lo(unsigned u) { return __uint_as_float(u << 16); }
; __device__ __forceinline__ float bf_hi(unsigned u) { return __uint_as_float(u & 0xffff0000u); }
; __device__ __forceinline__ float frcp(float x) { return __builtin_amdgcn_rcpf(x); }
; #define MFMA(a, b, c) __builtin_amdgcn_mfma_f32_16x16x32_bf16((a), (b), (c), 0, 0, 0)
; template <int AMODE>
; __device__ __forceinline__ void gemm_kloop(f32x4 (&acc)[4][4], const u16* __restrict__ A, int lda,
;                                            const u16* __restrict__ Bt, int ldb, int K, char* smem,
;                                            const float* __restrict__ ssq_rows) {
;     ...
; #pragma unroll
;         for (int ks = 0; ks < 2; ++ks) {
;             const int co = ((ks * 4 + g4) ^ (r & 7)) << 4;
; #pragma unroll
;             for (int i = 0; i < 4; ++i) af[ks][i] = ld_frag(ab + i * 2048 + co);
; #pragma unroll
;             for (int j = 0; j < 4; ++j) bfr[ks][j] = ld_frag(bb + j * 2048 + co);
;         }
;         __builtin_amdgcn_sched_barrier(0);
;         __builtin_amdgcn_s_setprio(1);
; #pragma unroll
;         for (int ks = 0; ks < 2; ++ks)
; #pragma unroll
;             for (int i = 0; i < 4; ++i)
; #pragma unroll
;                 for (int j = 0; j < 4; ++j) acc[i][j] = MFMA(bfr[ks][j], af[ks][i], acc[i][j]);
; __device__ void phaseC1(const Params& p, int l, char* smem) {
;     ...
; #pragma unroll
;         for (int i = 0; i < 4; ++i) {
;             const size_t row = (size_t)(m0 + wr * 64 + i * 16 + r);
; #pragma unroll
;             for (int j = 0; j < 4; ++j) {
;                 const int col = n0 + wc * 64 + j * 16 + g4 * 4;
;                 const uint2 gm = *(const uint2*)(p.gmb + row * 1024 + col);
;                 const uint2 ga = *(const uint2*)(p.gab + row * 1024 + col);
;                 acc[i][j][0] *= bf_lo(gm.x) * frcp(bf_lo(ga.x)); acc[i][j][1] *= bf_hi(gm.x) * frcp(bf_hi(ga.x));
;                 acc[i][j][2] *= bf_lo(gm.y) * frcp(bf_lo(ga.y)); acc[i][j][3] *= bf_hi(gm.y) * frcp(bf_hi(ga.y));
;             }
;         }
	v_add_u32_e32 v0, v72, v74
	ds_read_b128 v[66:69], v0 offset:16384
	ds_read_b128 v[76:79], v0 offset:18432
	ds_read_b128 v[80:83], v0 offset:20480
	ds_read_b128 v[84:87], v0 offset:22528
	v_add_u32_e32 v0, v71, v74
	ds_read_b128 v[90:93], v0 offset:49152
	ds_read_b128 v[94:97], v0 offset:51200
	ds_read_b128 v[98:101], v0 offset:53248
	ds_read_b128 v[110:113], v0 offset:55296
	v_add_u32_e32 v0, v72, v73
	ds_read_b128 v[114:117], v0 offset:16384
	ds_read_b128 v[118:121], v0 offset:18432
	ds_read_b128 v[122:125], v0 offset:20480
	ds_read_b128 v[126:129], v0 offset:22528
	v_add_u32_e32 v0, v71, v73
	ds_read_b128 v[70:73], v0 offset:49152
	ds_read_b128 v[130:133], v0 offset:51200
	ds_read_b128 v[134:137], v0 offset:53248
	ds_read_b128 v[142:145], v0 offset:55296
	s_setprio 1
	s_waitcnt lgkmcnt(11)
	v_mfma_f32_16x16x32_bf16 v[62:65], v[90:93], v[66:69], v[62:65]
	s_waitcnt lgkmcnt(10)
	v_mfma_f32_16x16x32_bf16 v[58:61], v[94:97], v[66:69], v[58:61]
	s_waitcnt lgkmcnt(9)
	v_mfma_f32_16x16x32_bf16 v[54:57], v[98:101], v[66:69], v[54:57]
	s_waitcnt lgkmcnt(8)
	v_mfma_f32_16x16x32_bf16 v[50:53], v[110:113], v[66:69], v[50:53]
	v_mfma_f32_16x16x32_bf16 v[46:49], v[90:93], v[76:79], v[46:49]
	v_mfma_f32_16x16x32_bf16 v[42:45], v[94:97], v[76:79], v[42:45]
	v_mfma_f32_16x16x32_bf16 v[38:41], v[98:101], v[76:79], v[38:41]
	v_mfma_f32_16x16x32_bf16 v[34:37], v[110:113], v[76:79], v[34:37]
	v_mfma_f32_16x16x32_bf16 v[66:69], v[90:93], v[80:83], v[30:33]
	v_mfma_f32_16x16x32_bf16 v[26:29], v[94:97], v[80:83], v[26:29]
	v_mfma_f32_16x16x32_bf16 v[74:77], v[98:101], v[80:83], v[22:25]
	v_mfma_f32_16x16x32_bf16 v[78:81], v[110:113], v[80:83], v[18:21]
	v_mfma_f32_16x16x32_bf16 v[90:93], v[90:93], v[84:87], v[14:17]
	v_mfma_f32_16x16x32_bf16 v[10:13], v[94:97], v[84:87], v[10:13]
	v_mfma_f32_16x16x32_bf16 v[6:9], v[98:101], v[84:87], v[6:9]
	v_mfma_f32_16x16x32_bf16 v[2:5], v[110:113], v[84:87], v[2:5]
	s_waitcnt lgkmcnt(3)
	v_mfma_f32_16x16x32_bf16 v[82:85], v[70:73], v[114:117], v[62:65]
	s_waitcnt lgkmcnt(2)
	v_mfma_f32_16x16x32_bf16 v[94:97], v[130:133], v[114:117], v[58:61]
	s_waitcnt lgkmcnt(1)
	v_mfma_f32_16x16x32_bf16 v[98:101], v[134:137], v[114:117], v[54:57]
	s_waitcnt lgkmcnt(0)
	v_mfma_f32_16x16x32_bf16 v[14:17], v[142:145], v[114:117], v[50:53]
	v_mfma_f32_16x16x32_bf16 v[18:21], v[70:73], v[118:121], v[46:49]
	v_mfma_f32_16x16x32_bf16 v[22:25], v[130:133], v[118:121], v[42:45]
	v_mfma_f32_16x16x32_bf16 v[30:33], v[134:137], v[118:121], v[38:41]
	v_mfma_f32_16x16x32_bf16 v[38:41], v[142:145], v[118:121], v[34:37]
	v_mfma_f32_16x16x32_bf16 v[46:49], v[70:73], v[122:125], v[66:69]
	v_mfma_f32_16x16x32_bf16 v[54:57], v[130:133], v[122:125], v[26:29]
	v_mfma_f32_16x16x32_bf16 v[62:65], v[134:137], v[122:125], v[74:77]
	v_mfma_f32_16x16x32_bf16 v[58:61], v[142:145], v[122:125], v[78:81]
	v_mfma_f32_16x16x32_bf16 v[50:53], v[70:73], v[126:129], v[90:93]
	v_mfma_f32_16x16x32_bf16 v[42:45], v[130:133], v[126:129], v[10:13]
	v_mfma_f32_16x16x32_bf16 v[34:37], v[134:137], v[126:129], v[6:9]
	v_mfma_f32_16x16x32_bf16 v[26:29], v[142:145], v[126:129], v[2:5]
	s_setprio 0
	v_add_u32_e32 v80, s8, v88
	s_nop 0
	v_or_b32_e32 v2, s6, v89
	v_ashrrev_i32_e32 v81, 31, v80
	v_readlane_b32 s40, v214, 50
	v_ashrrev_i32_e32 v3, 31, v2
	v_lshlrev_b64 v[4:5], 11, v[80:81]
	v_readlane_b32 s50, v214, 60
	v_readlane_b32 s51, v214, 61
	v_readlane_b32 s52, v214, 62
	v_readlane_b32 s53, v214, 63
	v_lshl_add_u64 v[6:7], s[50:51], 0, v[4:5]
	v_lshlrev_b64 v[66:67], 1, v[2:3]
	v_lshl_add_u64 v[4:5], s[52:53], 0, v[4:5]
	v_lshl_add_u64 v[68:69], v[4:5], 0, v[66:67]
	s_waitcnt vmcnt(0)
	s_barrier
	global_load_dwordx2 v[4:5], v[68:69], off
	v_lshl_add_u64 v[72:73], v[6:7], 0, v[66:67]
	global_load_dwordx2 v[228:229], v[72:73], off
	global_load_dwordx2 v[230:231], v[72:73], off offset:32
	global_load_dwordx2 v[232:233], v[68:69], off offset:32
	global_load_dwordx2 v[234:235], v[72:73], off offset:64
	global_load_dwordx2 v[236:237], v[68:69], off offset:64
	global_load_dwordx2 v[238:239], v[72:73], off offset:96
	global_load_dwordx2 v[240:241], v[68:69], off offset:96
	v_lshlrev_b64 v[70:71], 10, v[80:81]
	v_readlane_b32 s41, v214, 51
	v_readlane_b32 s42, v214, 52
	v_readlane_b32 s43, v214, 53
	v_readlane_b32 s44, v214, 54
	v_readlane_b32 s45, v214, 55
	v_readlane_b32 s46, v214, 56
	v_readlane_b32 s47, v214, 57
	v_readlane_b32 s48, v214, 58
	v_readlane_b32 s49, v214, 59
	v_readlane_b32 s54, v213, 0
	s_lshl_b64 s[8:9], s[8:9], 11
	v_readlane_b32 s55, v213, 1
	s_add_u32 s12, s54, s8
	s_addc_u32 s13, s55, s9
	s_lshl_b64 s[10:11], s[10:11], 11
	s_waitcnt vmcnt(7)
	v_lshlrev_b32_e32 v0, 16, v4
	v_rcp_f32_e32 v8, v0
	v_and_b32_e32 v0, 0xffff0000, v4
	v_rcp_f32_e32 v9, v0
	v_lshlrev_b32_e32 v0, 16, v5
	v_rcp_f32_e32 v4, v0
	v_and_b32_e32 v0, 0xffff0000, v5
	v_rcp_f32_e32 v5, v0
	s_waitcnt vmcnt(6)
	v_lshlrev_b32_e32 v6, 16, v228
	v_and_b32_e32 v7, 0xffff0000, v228
	v_lshlrev_b32_e32 v2, 16, v229
	v_and_b32_e32 v3, 0xffff0000, v229
	v_pk_mul_f32 v[6:7], v[8:9], v[6:7]
	v_pk_mul_f32 v[2:3], v[4:5], v[2:3]
	s_nop 0
	v_pk_mul_f32 v[4:5], v[84:85], v[2:3]
	v_pk_mul_f32 v[2:3], v[82:83], v[6:7]
	s_waitcnt vmcnt(5)
	v_lshlrev_b32_e32 v10, 16, v230
	s_waitcnt vmcnt(4)
	v_lshlrev_b32_e32 v0, 16, v232
	v_rcp_f32_e32 v12, v0
	v_and_b32_e32 v0, 0xffff0000, v232
	v_rcp_f32_e32 v13, v0
	v_lshlrev_b32_e32 v0, 16, v233
	v_rcp_f32_e32 v8, v0
	v_and_b32_e32 v0, 0xffff0000, v233
	v_rcp_f32_e32 v9, v0
	v_and_b32_e32 v11, 0xffff0000, v230
	v_lshlrev_b32_e32 v6, 16, v231
	v_and_b32_e32 v7, 0xffff0000, v231
	v_pk_mul_f32 v[10:11], v[12:13], v[10:11]
	v_pk_mul_f32 v[6:7], v[8:9], v[6:7]
	s_nop 0
	v_pk_mul_f32 v[8:9], v[96:97], v[6:7]
	v_pk_mul_f32 v[6:7], v[94:95], v[10:11]
	v_mov_b32_e32 v96, v141
	s_waitcnt vmcnt(3)
; __device__ __forceinline__ float bf_lo(unsigned u) { return __uint_as_float(u << 16); }
; __device__ __forceinline__ float bf_hi(unsigned u) { return __uint_as_float(u & 0xffff0000u); }
; __device__ __forceinline__ float frcp(float x) { return __builtin_amdgcn_rcpf(x); }
; __device__ void phaseC1(const Params& p, int l, char* smem) {
;     ...
; #pragma unroll
;         for (int i = 0; i < 4; ++i) {
;             const size_t row = (size_t)(m0 + wr * 64 + i * 16 + r);
; #pragma unroll
;             for (int j = 0; j < 4; ++j) {
;                 const int col = n0 + wc * 64 + j * 16 + g4 * 4;
;                 const uint2 gm = *(const uint2*)(p.gmb + row * 1024 + col);
;                 const uint2 ga = *(const uint2*)(p.gab + row * 1024 + col);
;                 acc[i][j][0] *= bf_lo(gm.x) * frcp(bf_lo(ga.x)); acc[i][j][1] *= bf_hi(gm.x) * frcp(bf_hi(ga.x));
;                 acc[i][j][2] *= bf_lo(gm.y) * frcp(bf_lo(ga.y)); acc[i][j][3] *= bf_hi(gm.y) * frcp(bf_hi(ga.y));
;             }
;         }
	v_lshlrev_b32_e32 v74, 16, v234
	s_waitcnt vmcnt(2)
	v_lshlrev_b32_e32 v0, 16, v236
	v_rcp_f32_e32 v76, v0
	v_and_b32_e32 v0, 0xffff0000, v236
	v_rcp_f32_e32 v77, v0
	v_lshlrev_b32_e32 v0, 16, v237
	v_rcp_f32_e32 v12, v0
	v_and_b32_e32 v0, 0xffff0000, v237
	v_rcp_f32_e32 v13, v0
	v_and_b32_e32 v75, 0xffff0000, v234
	v_lshlrev_b32_e32 v10, 16, v235
	v_and_b32_e32 v11, 0xffff0000, v235
	v_pk_mul_f32 v[74:75], v[76:77], v[74:75]
	v_pk_mul_f32 v[10:11], v[12:13], v[10:11]
	s_nop 0
	v_pk_mul_f32 v[12:13], v[100:101], v[10:11]
	v_pk_mul_f32 v[10:11], v[98:99], v[74:75]
	s_nop 0
	s_waitcnt vmcnt(1)
	v_lshlrev_b32_e32 v76, 16, v238
	s_waitcnt vmcnt(0)
	v_lshlrev_b32_e32 v0, 16, v240
	v_rcp_f32_e32 v78, v0
	v_and_b32_e32 v0, 0xffff0000, v240
	v_rcp_f32_e32 v79, v0
	v_lshlrev_b32_e32 v0, 16, v241
	v_rcp_f32_e32 v74, v0
	v_and_b32_e32 v0, 0xffff0000, v241
	v_rcp_f32_e32 v75, v0
	v_and_b32_e32 v77, 0xffff0000, v238
	v_lshlrev_b32_e32 v72, 16, v239
	v_and_b32_e32 v73, 0xffff0000, v239
	v_pk_mul_f32 v[72:73], v[74:75], v[72:73]
	v_pk_mul_f32 v[76:77], v[78:79], v[76:77]
	v_pk_mul_f32 v[16:17], v[16:17], v[72:73]
	v_or_b32_e32 v72, 16, v80
	v_ashrrev_i32_e32 v73, 31, v72
	v_lshlrev_b64 v[74:75], 10, v[72:73]
	v_lshlrev_b64 v[72:73], 11, v[72:73]
	v_pk_mul_f32 v[14:15], v[14:15], v[76:77]
	v_lshl_add_u64 v[76:77], s[50:51], 0, v[72:73]
	v_lshl_add_u64 v[72:73], s[52:53], 0, v[72:73]
	v_lshl_add_u64 v[72:73], v[72:73], 0, v[66:67]
	global_load_dwordx2 v[82:83], v[72:73], off
	v_lshl_add_u64 v[76:77], v[76:77], 0, v[66:67]
	global_load_dwordx2 v[228:229], v[76:77], off
	global_load_dwordx2 v[230:231], v[76:77], off offset:32
	global_load_dwordx2 v[232:233], v[72:73], off offset:32
	global_load_dwordx2 v[234:235], v[76:77], off offset:64
	global_load_dwordx2 v[236:237], v[72:73], off offset:64
	global_load_dwordx2 v[238:239], v[76:77], off offset:96
	global_load_dwordx2 v[240:241], v[72:73], off offset:96
	s_waitcnt vmcnt(7)
	v_lshlrev_b32_e32 v0, 16, v82
	v_rcp_f32_e32 v86, v0
	v_and_b32_e32 v0, 0xffff0000, v82
	v_rcp_f32_e32 v87, v0
	v_lshlrev_b32_e32 v0, 16, v83
	v_rcp_f32_e32 v82, v0
	v_and_b32_e32 v0, 0xffff0000, v83
	v_rcp_f32_e32 v83, v0
	s_waitcnt vmcnt(6)
	v_lshlrev_b32_e32 v84, 16, v228
	v_and_b32_e32 v85, 0xffff0000, v228
	v_lshlrev_b32_e32 v78, 16, v229
	v_and_b32_e32 v79, 0xffff0000, v229
	v_pk_mul_f32 v[78:79], v[82:83], v[78:79]
	v_pk_mul_f32 v[84:85], v[86:87], v[84:85]
	v_pk_mul_f32 v[20:21], v[20:21], v[78:79]
	v_pk_mul_f32 v[18:19], v[18:19], v[84:85]
	s_waitcnt vmcnt(5)
	v_lshlrev_b32_e32 v84, 16, v230
	s_waitcnt vmcnt(4)
	v_lshlrev_b32_e32 v0, 16, v232
	v_rcp_f32_e32 v86, v0
	v_and_b32_e32 v0, 0xffff0000, v232
	v_rcp_f32_e32 v87, v0
	v_lshlrev_b32_e32 v0, 16, v233
	v_rcp_f32_e32 v82, v0
	v_and_b32_e32 v0, 0xffff0000, v233
	v_rcp_f32_e32 v83, v0
	v_and_b32_e32 v85, 0xffff0000, v230
	v_lshlrev_b32_e32 v78, 16, v231
	v_and_b32_e32 v79, 0xffff0000, v231
	v_pk_mul_f32 v[78:79], v[82:83], v[78:79]
	v_pk_mul_f32 v[84:85], v[86:87], v[84:85]
	v_pk_mul_f32 v[24:25], v[24:25], v[78:79]
	v_pk_mul_f32 v[22:23], v[22:23], v[84:85]
	s_waitcnt vmcnt(3)
	v_lshlrev_b32_e32 v84, 16, v234
	s_waitcnt vmcnt(2)
	v_lshlrev_b32_e32 v0, 16, v236
	v_rcp_f32_e32 v86, v0
	v_and_b32_e32 v0, 0xffff0000, v236
	v_rcp_f32_e32 v87, v0
	v_lshlrev_b32_e32 v0, 16, v237
	v_rcp_f32_e32 v82, v0
	v_and_b32_e32 v0, 0xffff0000, v237
	v_rcp_f32_e32 v83, v0
	v_and_b32_e32 v85, 0xffff0000, v234
	v_lshlrev_b32_e32 v78, 16, v235
	v_and_b32_e32 v79, 0xffff0000, v235
	v_pk_mul_f32 v[78:79], v[82:83], v[78:79]
	v_pk_mul_f32 v[84:85], v[86:87], v[84:85]
	v_pk_mul_f32 v[32:33], v[32:33], v[78:79]
	s_nop 0
	v_pk_mul_f32 v[30:31], v[30:31], v[84:85]
	s_waitcnt vmcnt(1)
	v_lshlrev_b32_e32 v82, 16, v238
	s_waitcnt vmcnt(0)
	v_lshlrev_b32_e32 v0, 16, v240
	v_rcp_f32_e32 v84, v0
	v_and_b32_e32 v0, 0xffff0000, v240
	v_rcp_f32_e32 v85, v0
	v_lshlrev_b32_e32 v0, 16, v241
	v_rcp_f32_e32 v78, v0
	v_and_b32_e32 v0, 0xffff0000, v241
	v_rcp_f32_e32 v79, v0
	v_and_b32_e32 v83, 0xffff0000, v238
	v_lshlrev_b32_e32 v76, 16, v239
	v_and_b32_e32 v77, 0xffff0000, v239
	v_pk_mul_f32 v[76:77], v[78:79], v[76:77]
	v_pk_mul_f32 v[82:83], v[84:85], v[82:83]
	v_pk_mul_f32 v[40:41], v[40:41], v[76:77]
	v_or_b32_e32 v76, 32, v80
	v_ashrrev_i32_e32 v77, 31, v76
	v_lshlrev_b64 v[78:79], 10, v[76:77]
	v_lshlrev_b64 v[76:77], 11, v[76:77]
	v_pk_mul_f32 v[38:39], v[38:39], v[82:83]
	v_lshl_add_u64 v[82:83], s[50:51], 0, v[76:77]
	v_lshl_add_u64 v[76:77], s[52:53], 0, v[76:77]
	v_lshl_add_u64 v[76:77], v[76:77], 0, v[66:67]
	global_load_dwordx2 v[86:87], v[76:77], off
	v_lshl_add_u64 v[82:83], v[82:83], 0, v[66:67]
	global_load_dwordx2 v[228:229], v[82:83], off
	global_load_dwordx2 v[230:231], v[82:83], off offset:32
	global_load_dwordx2 v[232:233], v[76:77], off offset:32
	global_load_dwordx2 v[234:235], v[82:83], off offset:64
	global_load_dwordx2 v[236:237], v[76:77], off offset:64
	global_load_dwordx2 v[238:239], v[82:83], off offset:96
	global_load_dwordx2 v[240:241], v[76:77], off offset:96
	v_or_b32_e32 v80, 48, v80
	v_ashrrev_i32_e32 v81, 31, v80
	s_waitcnt vmcnt(7)
	v_lshlrev_b32_e32 v0, 16, v86
	v_rcp_f32_e32 v92, v0
	v_and_b32_e32 v0, 0xffff0000, v86
	v_rcp_f32_e32 v93, v0
	v_lshlrev_b32_e32 v0, 16, v87
	v_rcp_f32_e32 v86, v0
	v_and_b32_e32 v0, 0xffff0000, v87
	v_rcp_f32_e32 v87, v0
	s_waitcnt vmcnt(6)
	v_lshlrev_b32_e32 v90, 16, v228
	v_and_b32_e32 v91, 0xffff0000, v228
	v_lshlrev_b32_e32 v84, 16, v229
	v_and_b32_e32 v85, 0xffff0000, v229
	v_pk_mul_f32 v[84:85], v[86:87], v[84:85]
	v_pk_mul_f32 v[90:91], v[92:93], v[90:91]
	v_pk_mul_f32 v[48:49], v[48:49], v[84:85]
	v_pk_mul_f32 v[46:47], v[46:47], v[90:91]
	s_waitcnt vmcnt(5)
; __device__ __forceinline__ float bf_lo(unsigned u) { return __uint_as_float(u << 16); }
; __device__ __forceinline__ float bf_hi(unsigned u) { return __uint_as_float(u & 0xffff0000u); }
; __device__ __forceinline__ float frcp(float x) { return __builtin_amdgcn_rcpf(x); }
; __device__ void phaseC1(const Params& p, int l, char* smem) {
;     ...
; #pragma unroll
;         for (int i = 0; i < 4; ++i) {
;             const size_t row = (size_t)(m0 + wr * 64 + i * 16 + r);
; #pragma unroll
;             for (int j = 0; j < 4; ++j) {
;                 const int col = n0 + wc * 64 + j * 16 + g4 * 4;
;                 const uint2 gm = *(const uint2*)(p.gmb + row * 1024 + col);
;                 const uint2 ga = *(const uint2*)(p.gab + row * 1024 + col);
;                 acc[i][j][0] *= bf_lo(gm.x) * frcp(bf_lo(ga.x)); acc[i][j][1] *= bf_hi(gm.x) * frcp(bf_hi(ga.x));
;                 acc[i][j][2] *= bf_lo(gm.y) * frcp(bf_lo(ga.y)); acc[i][j][3] *= bf_hi(gm.y) * frcp(bf_hi(ga.y));
;             }
;         }
	v_lshlrev_b32_e32 v90, 16, v230
	s_waitcnt vmcnt(4)
	v_lshlrev_b32_e32 v0, 16, v232
	v_rcp_f32_e32 v92, v0
	v_and_b32_e32 v0, 0xffff0000, v232
	v_rcp_f32_e32 v93, v0
	v_lshlrev_b32_e32 v0, 16, v233
	v_rcp_f32_e32 v86, v0
	v_and_b32_e32 v0, 0xffff0000, v233
	v_rcp_f32_e32 v87, v0
	v_and_b32_e32 v91, 0xffff0000, v230
	v_lshlrev_b32_e32 v84, 16, v231
	v_and_b32_e32 v85, 0xffff0000, v231
	v_pk_mul_f32 v[84:85], v[86:87], v[84:85]
	v_pk_mul_f32 v[90:91], v[92:93], v[90:91]
	v_pk_mul_f32 v[56:57], v[56:57], v[84:85]
	v_pk_mul_f32 v[54:55], v[54:55], v[90:91]
	s_waitcnt vmcnt(3)
	v_lshlrev_b32_e32 v90, 16, v234
	s_waitcnt vmcnt(2)
	v_lshlrev_b32_e32 v0, 16, v236
	v_rcp_f32_e32 v92, v0
	v_and_b32_e32 v0, 0xffff0000, v236
	v_rcp_f32_e32 v93, v0
	v_lshlrev_b32_e32 v0, 16, v237
	v_rcp_f32_e32 v86, v0
	v_and_b32_e32 v0, 0xffff0000, v237
	v_rcp_f32_e32 v87, v0
	v_and_b32_e32 v91, 0xffff0000, v234
	v_lshlrev_b32_e32 v84, 16, v235
	v_and_b32_e32 v85, 0xffff0000, v235
	v_pk_mul_f32 v[84:85], v[86:87], v[84:85]
	v_pk_mul_f32 v[90:91], v[92:93], v[90:91]
	v_pk_mul_f32 v[64:65], v[64:65], v[84:85]
	s_nop 0
	v_pk_mul_f32 v[62:63], v[62:63], v[90:91]
	s_waitcnt vmcnt(1)
	v_lshlrev_b32_e32 v86, 16, v238
	s_waitcnt vmcnt(0)
	v_lshlrev_b32_e32 v0, 16, v240
	v_rcp_f32_e32 v90, v0
	v_and_b32_e32 v0, 0xffff0000, v240
	v_rcp_f32_e32 v91, v0
	v_lshlrev_b32_e32 v0, 16, v241
	v_rcp_f32_e32 v84, v0
	v_and_b32_e32 v0, 0xffff0000, v241
	v_rcp_f32_e32 v85, v0
	v_and_b32_e32 v87, 0xffff0000, v238
	v_lshlrev_b32_e32 v82, 16, v239
	v_and_b32_e32 v83, 0xffff0000, v239
	v_pk_mul_f32 v[82:83], v[84:85], v[82:83]
	v_pk_mul_f32 v[86:87], v[90:91], v[86:87]
	v_pk_mul_f32 v[60:61], v[60:61], v[82:83]
	v_lshlrev_b64 v[82:83], 10, v[80:81]
	v_lshlrev_b64 v[80:81], 11, v[80:81]
	v_lshl_add_u64 v[84:85], s[50:51], 0, v[80:81]
	v_lshl_add_u64 v[80:81], s[52:53], 0, v[80:81]
	v_lshl_add_u64 v[80:81], v[80:81], 0, v[66:67]
	global_load_dwordx2 v[90:91], v[80:81], off
	v_lshl_add_u64 v[84:85], v[84:85], 0, v[66:67]
	v_pk_mul_f32 v[58:59], v[58:59], v[86:87]
	global_load_dwordx2 v[228:229], v[84:85], off
	global_load_dwordx2 v[230:231], v[84:85], off offset:32
	global_load_dwordx2 v[232:233], v[80:81], off offset:32
	global_load_dwordx2 v[234:235], v[84:85], off offset:64
	global_load_dwordx2 v[236:237], v[80:81], off offset:64
	global_load_dwordx2 v[238:239], v[84:85], off offset:96
	global_load_dwordx2 v[240:241], v[80:81], off offset:96
	v_readlane_b32 s36, v214, 34
	v_readlane_b32 s38, v214, 36
	v_readlane_b32 s39, v214, 37
	s_add_u32 s10, s38, s10
	s_addc_u32 s11, s39, s11
	s_lshl_b64 s[6:7], s[6:7], 11
	v_readlane_b32 s37, v214, 35
	v_readlane_b32 s40, v214, 38
	v_readlane_b32 s41, v214, 39
	v_readlane_b32 s42, v214, 40
	v_readlane_b32 s43, v214, 41
	v_readlane_b32 s44, v214, 42
	v_readlane_b32 s45, v214, 43
	v_readlane_b32 s46, v214, 44
	v_readlane_b32 s47, v214, 45
	v_readlane_b32 s48, v214, 46
	v_readlane_b32 s49, v214, 47
	v_readlane_b32 s50, v214, 48
	v_readlane_b32 s51, v214, 49
	s_waitcnt vmcnt(7)
	v_lshlrev_b32_e32 v0, 16, v90
	v_rcp_f32_e32 v94, v0
	v_and_b32_e32 v0, 0xffff0000, v90
	v_rcp_f32_e32 v95, v0
	v_lshlrev_b32_e32 v0, 16, v91
	v_rcp_f32_e32 v90, v0
	v_and_b32_e32 v0, 0xffff0000, v91
	v_rcp_f32_e32 v91, v0
	s_waitcnt vmcnt(6)
	v_lshlrev_b32_e32 v92, 16, v228
	v_and_b32_e32 v93, 0xffff0000, v228
	v_lshlrev_b32_e32 v86, 16, v229
	v_and_b32_e32 v87, 0xffff0000, v229
	v_pk_mul_f32 v[86:87], v[90:91], v[86:87]
	v_pk_mul_f32 v[92:93], v[94:95], v[92:93]
	v_pk_mul_f32 v[52:53], v[52:53], v[86:87]
	v_pk_mul_f32 v[50:51], v[50:51], v[92:93]
	s_waitcnt vmcnt(5)
	v_lshlrev_b32_e32 v92, 16, v230
	s_waitcnt vmcnt(4)
	v_lshlrev_b32_e32 v0, 16, v232
	v_rcp_f32_e32 v94, v0
	v_and_b32_e32 v0, 0xffff0000, v232
	v_rcp_f32_e32 v95, v0
	v_lshlrev_b32_e32 v0, 16, v233
	v_rcp_f32_e32 v90, v0
	v_and_b32_e32 v0, 0xffff0000, v233
	v_rcp_f32_e32 v91, v0
	v_and_b32_e32 v93, 0xffff0000, v230
	v_lshlrev_b32_e32 v86, 16, v231
	v_and_b32_e32 v87, 0xffff0000, v231
	v_pk_mul_f32 v[86:87], v[90:91], v[86:87]
	v_pk_mul_f32 v[92:93], v[94:95], v[92:93]
	v_pk_mul_f32 v[44:45], v[44:45], v[86:87]
	v_pk_mul_f32 v[42:43], v[42:43], v[92:93]
	s_waitcnt vmcnt(3)
	v_lshlrev_b32_e32 v92, 16, v234
	s_waitcnt vmcnt(2)
	v_lshlrev_b32_e32 v0, 16, v236
	v_rcp_f32_e32 v94, v0
	v_and_b32_e32 v0, 0xffff0000, v236
	v_rcp_f32_e32 v95, v0
	v_lshlrev_b32_e32 v0, 16, v237
	v_rcp_f32_e32 v90, v0
	v_and_b32_e32 v0, 0xffff0000, v237
	v_rcp_f32_e32 v91, v0
	v_and_b32_e32 v93, 0xffff0000, v234
	v_lshlrev_b32_e32 v86, 16, v235
	v_and_b32_e32 v87, 0xffff0000, v235
	v_pk_mul_f32 v[86:87], v[90:91], v[86:87]
	v_pk_mul_f32 v[92:93], v[94:95], v[92:93]
	v_pk_mul_f32 v[36:37], v[36:37], v[86:87]
	s_nop 0
	v_pk_mul_f32 v[34:35], v[34:35], v[92:93]
	s_waitcnt vmcnt(1)
	v_lshlrev_b32_e32 v90, 16, v238
	s_waitcnt vmcnt(0)
; __device__ __forceinline__ float bf_lo(unsigned u) { return __uint_as_float(u << 16); }
; __device__ __forceinline__ float bf_hi(unsigned u) { return __uint_as_float(u & 0xffff0000u); }
; __device__ __forceinline__ float frcp(float x) { return __builtin_amdgcn_rcpf(x); }
; template <int AMODE>
; __device__ __forceinline__ void gemm_kloop(f32x4 (&acc)[4][4], const u16* __restrict__ A, int lda,
;                                            const u16* __restrict__ Bt, int ldb, int K, char* smem,
;                                            const float* __restrict__ ssq_rows) {
;     ...
;     GLOAD(0, 0);
;     LSTORE(0);
;     asm volatile("s_waitcnt vmcnt(0)" ::: "memory");
;     __syncthreads();
;     for (int kt = 0; kt < nk; ++kt) {
;         const int buf = kt & 1;
;         if (kt + 1 < nk) GLOAD(kt + 1, buf ^ 1);
;         const char* ab = As + buf * 16384 + (wr * 64 + r) * 128;
;         const char* bb = Bs + buf * 16384 + (wc * 64 + r) * 128;
;         bf16x8 af[2][4], bfr[2][4];
; #pragma unroll
;         for (int ks = 0; ks < 2; ++ks) {
;             const int co = ((ks * 4 + g4) ^ (r & 7)) << 4;
; #pragma unroll
;             for (int i = 0; i < 4; ++i) af[ks][i] = ld_frag(ab + i * 2048 + co);
; #pragma unroll
;             for (int j = 0; j < 4; ++j) bfr[ks][j] = ld_frag(bb + j * 2048 + co);
;         }
; __device__ void phaseC1(const Params& p, int l, char* smem) {
;     ...
;                 acc[i][j][0] *= bf_lo(gm.x) * frcp(bf_lo(ga.x)); acc[i][j][1] *= bf_hi(gm.x) * frcp(bf_hi(ga.x));
;                 acc[i][j][2] *= bf_lo(gm.y) * frcp(bf_lo(ga.y)); acc[i][j][3] *= bf_hi(gm.y) * frcp(bf_hi(ga.y));
;             }
;         }
;         gemm_kloop<0>(acc, p.yab + (size_t)m0 * 1024, 1024, p.wt_a + ((size_t)l * 1024 + n0) * 1024, 1024, 1024, smem, nullptr);
	v_lshlrev_b32_e32 v0, 16, v240
	v_rcp_f32_e32 v92, v0
	v_and_b32_e32 v0, 0xffff0000, v240
	v_rcp_f32_e32 v93, v0
	v_lshlrev_b32_e32 v0, 16, v241
	v_rcp_f32_e32 v86, v0
	v_and_b32_e32 v0, 0xffff0000, v241
	v_rcp_f32_e32 v87, v0
	v_and_b32_e32 v91, 0xffff0000, v238
	v_lshlrev_b32_e32 v84, 16, v239
	v_and_b32_e32 v85, 0xffff0000, v239
	v_pk_mul_f32 v[84:85], v[86:87], v[84:85]
	v_ashrrev_i32_e32 v94, 6, v96
	v_bfe_u32 v0, v96, 3, 3
	v_pk_mul_f32 v[28:29], v[28:29], v[84:85]
	v_lshl_or_b32 v84, v94, 3, v0
	v_ashrrev_i32_e32 v85, 31, v84
	v_pk_mul_f32 v[90:91], v[92:93], v[90:91]
	v_bitop3_b32 v0, v0, v96, 7 bitop3:0x78
	v_lshlrev_b64 v[86:87], 11, v[84:85]
	v_pk_mul_f32 v[26:27], v[26:27], v[90:91]
	v_lshlrev_b32_e32 v0, 4, v0
	v_lshl_add_u64 v[90:91], s[10:11], 0, v[86:87]
	v_lshl_add_u64 v[92:93], v[90:91], 0, v[0:1]
	v_lshlrev_b32_e32 v90, 10, v94
	v_add_u32_e32 v91, 0x8000, v90
	v_lshl_add_u64 v[84:85], s[12:13], 0, v[86:87]
	v_readfirstlane_b32 s10, v91
	s_mov_b32 m0, s10
	v_readfirstlane_b32 s10, v90
	v_add_u32_e32 v91, 0x9000, v90
	v_lshl_add_u64 v[84:85], v[84:85], 0, v[0:1]
	global_load_lds_dwordx4 v[92:93], off
	s_mov_b32 m0, s10
	s_mov_b64 s[12:13], 0x10000
	v_readfirstlane_b32 s10, v91
	v_add_u32_e32 v91, 0x1000, v90
	global_load_lds_dwordx4 v[84:85], off
	v_lshl_add_u64 v[94:95], v[92:93], 0, s[12:13]
	s_mov_b32 m0, s10
	v_readfirstlane_b32 s10, v91
	v_add_u32_e32 v91, 0xa000, v90
	global_load_lds_dwordx4 v[94:95], off
	v_lshl_add_u64 v[94:95], v[84:85], 0, s[12:13]
	s_mov_b32 m0, s10
	s_mov_b64 s[12:13], 0x20000
	v_readfirstlane_b32 s10, v91
	v_add_u32_e32 v91, 0x2000, v90
	global_load_lds_dwordx4 v[94:95], off
	v_lshl_add_u64 v[94:95], v[92:93], 0, s[12:13]
	s_mov_b32 m0, s10
	v_readfirstlane_b32 s10, v91
	v_add_u32_e32 v91, 0xb000, v90
	global_load_lds_dwordx4 v[94:95], off
	v_lshl_add_u64 v[94:95], v[84:85], 0, s[12:13]
	s_mov_b32 m0, s10
	s_mov_b64 s[12:13], 0x30000
	v_readfirstlane_b32 s10, v91
	v_add_u32_e32 v91, 0x3000, v90
	global_load_lds_dwordx4 v[94:95], off
	v_lshl_add_u64 v[92:93], v[92:93], 0, s[12:13]
	s_mov_b32 m0, s10
	v_readfirstlane_b32 s10, v91
	global_load_lds_dwordx4 v[92:93], off
	v_lshl_add_u64 v[84:85], v[84:85], 0, s[12:13]
	s_mov_b32 m0, s10
	v_lshrrev_b32_e32 v91, 1, v96
	global_load_lds_dwordx4 v[84:85], off
	v_and_b32_e32 v85, 15, v96
	s_mov_b32 s10, 0x1ffffc0
	v_and_or_b32 v85, v91, s10, v85
	v_and_b32_e32 v97, 7, v96
	v_bfe_u32 v84, v96, 4, 2
	v_lshlrev_b32_e32 v92, 7, v85
	v_lshlrev_b32_e32 v85, 7, v96
	v_and_b32_e32 v91, 0x2780, v85
	v_bitop3_b32 v85, v84, v96, 7 bitop3:0x78
	v_bitop3_b32 v84, v84, v97, 4 bitop3:0x36
	s_waitcnt vmcnt(0)
	v_lshlrev_b32_e32 v94, 4, v85
	v_lshlrev_b32_e32 v93, 4, v84
	v_lshl_add_u64 v[84:85], s[6:7], 0, v[86:87]
	v_lshl_add_u64 v[86:87], s[8:9], 0, v[86:87]
	v_or_b32_e32 v84, v84, v0
	v_or_b32_e32 v86, v86, v0
	v_lshl_add_u64 v[84:85], s[4:5], 0, v[84:85]
	v_lshl_add_u64 v[86:87], s[54:55], 0, v[86:87]
	s_mov_b64 s[6:7], 0
	s_mov_b32 s8, 0
	s_waitcnt vmcnt(0) lgkmcnt(0)
	s_barrier
.LBB0_709:
	s_setprio 1
	s_and_b32 s9, s8, 0x4000
	s_xor_b32 s10, s9, 0x4000
	v_add_u32_e32 v0, s10, v90
	v_add_u32_e32 v95, 0x8000, v0
	v_lshl_add_u64 v[96:97], v[84:85], 0, s[6:7]
	v_readfirstlane_b32 s10, v95
	v_lshl_add_u64 v[98:99], v[96:97], 0, s[62:63]
	v_lshl_add_u64 v[100:101], v[86:87], 0, s[6:7]
	s_mov_b32 m0, s10
	v_readfirstlane_b32 s10, v0
	v_add_u32_e32 v95, 0x9000, v0
	v_lshl_add_u64 v[102:103], v[100:101], 0, s[62:63]
	global_load_lds_dwordx4 v[98:99], off
	s_mov_b32 m0, s10
	v_readfirstlane_b32 s10, v95
	v_add_u32_e32 v95, 0x1000, v0
	global_load_lds_dwordx4 v[102:103], off
	v_lshl_add_u64 v[98:99], v[96:97], 0, s[68:69]
	s_mov_b32 m0, s10
	v_readfirstlane_b32 s10, v95
	v_add_u32_e32 v95, 0xa000, v0
	global_load_lds_dwordx4 v[98:99], off
	v_lshl_add_u64 v[98:99], v[100:101], 0, s[68:69]
	s_mov_b32 m0, s10
	v_readfirstlane_b32 s10, v95
	v_add_u32_e32 v95, 0x2000, v0
	global_load_lds_dwordx4 v[98:99], off
	v_lshl_add_u64 v[98:99], v[96:97], 0, s[64:65]
	s_mov_b32 m0, s10
	v_readfirstlane_b32 s10, v95
	v_add_u32_e32 v95, 0xb000, v0
	global_load_lds_dwordx4 v[98:99], off
	v_lshl_add_u64 v[98:99], v[100:101], 0, s[64:65]
	s_mov_b32 m0, s10
	v_readfirstlane_b32 s10, v95
	v_add_u32_e32 v0, 0x3000, v0
	global_load_lds_dwordx4 v[98:99], off
	v_lshl_add_u64 v[96:97], v[96:97], 0, s[66:67]
	s_mov_b32 m0, s10
	v_readfirstlane_b32 s10, v0
	global_load_lds_dwordx4 v[96:97], off
	v_lshl_add_u64 v[96:97], v[100:101], 0, s[66:67]
	s_mov_b32 m0, s10
	v_add_u32_e32 v0, s9, v92
	global_load_lds_dwordx4 v[96:97], off
	v_or_b32_e32 v95, s9, v91
	v_add_u32_e32 v114, v0, v94
	v_add_u32_e32 v130, v95, v94
	v_add_u32_e32 v0, v0, v93
	ds_read_b128 v[96:99], v114
	ds_read_b128 v[100:103], v114 offset:2048
	ds_read_b128 v[110:113], v114 offset:4096
	ds_read_b128 v[114:117], v114 offset:6144
	ds_read_b128 v[118:121], v130 offset:32768
	ds_read_b128 v[122:125], v130 offset:34816
	ds_read_b128 v[126:129], v130 offset:36864
	ds_read_b128 v[130:133], v130 offset:38912
	ds_read_b128 v[134:137], v0
	ds_read_b128 v[142:145], v0 offset:2048
	ds_read_b128 v[146:149], v0 offset:4096
	ds_read_b128 v[150:153], v0 offset:6144
	v_add_u32_e32 v0, v95, v93
	ds_read_b128 v[172:175], v0 offset:32768
	ds_read_b128 v[176:179], v0 offset:34816
	ds_read_b128 v[180:183], v0 offset:36864
	ds_read_b128 v[184:187], v0 offset:38912
	s_setprio 0
	s_waitcnt lgkmcnt(0)
; #define MFMA(a, b, c) __builtin_amdgcn_mfma_f32_16x16x32_bf16((a), (b), (c), 0, 0, 0)
; template <int AMODE>
; __device__ __forceinline__ void gemm_kloop(f32x4 (&acc)[4][4], const u16* __restrict__ A, int lda,
;                                            const u16* __restrict__ Bt, int ldb, int K, char* smem,
;                                            const float* __restrict__ ssq_rows) {
;     ...
;         __builtin_amdgcn_sched_barrier(0);
;         __builtin_amdgcn_s_setprio(1);
; #pragma unroll
;         for (int ks = 0; ks < 2; ++ks)
; #pragma unroll
;             for (int i = 0; i < 4; ++i)
; #pragma unroll
;                 for (int j = 0; j < 4; ++j) acc[i][j] = MFMA(bfr[ks][j], af[ks][i], acc[i][j]);
;         __builtin_amdgcn_s_setprio(0);
;         __builtin_amdgcn_sched_barrier(0);
;         if (kt + 1 < nk) LSTORE(buf ^ 1);
;         asm volatile("s_waitcnt vmcnt(0)" ::: "memory");
;         __syncthreads();
;     }
	v_mfma_f32_16x16x32_bf16 v[2:5], v[118:121], v[96:99], v[2:5]
	v_mfma_f32_16x16x32_bf16 v[6:9], v[122:125], v[96:99], v[6:9]
	v_mfma_f32_16x16x32_bf16 v[10:13], v[126:129], v[96:99], v[10:13]
	v_mfma_f32_16x16x32_bf16 v[14:17], v[130:133], v[96:99], v[14:17]
	v_mfma_f32_16x16x32_bf16 v[18:21], v[118:121], v[100:103], v[18:21]
	v_mfma_f32_16x16x32_bf16 v[22:25], v[122:125], v[100:103], v[22:25]
	v_mfma_f32_16x16x32_bf16 v[30:33], v[126:129], v[100:103], v[30:33]
	v_mfma_f32_16x16x32_bf16 v[38:41], v[130:133], v[100:103], v[38:41]
	v_mfma_f32_16x16x32_bf16 v[46:49], v[118:121], v[110:113], v[46:49]
	v_mfma_f32_16x16x32_bf16 v[54:57], v[122:125], v[110:113], v[54:57]
	v_mfma_f32_16x16x32_bf16 v[62:65], v[126:129], v[110:113], v[62:65]
	v_mfma_f32_16x16x32_bf16 v[58:61], v[130:133], v[110:113], v[58:61]
	v_mfma_f32_16x16x32_bf16 v[50:53], v[118:121], v[114:117], v[50:53]
	v_mfma_f32_16x16x32_bf16 v[42:45], v[122:125], v[114:117], v[42:45]
	v_mfma_f32_16x16x32_bf16 v[34:37], v[126:129], v[114:117], v[34:37]
	v_mfma_f32_16x16x32_bf16 v[26:29], v[130:133], v[114:117], v[26:29]
	v_mfma_f32_16x16x32_bf16 v[2:5], v[172:175], v[134:137], v[2:5]
	v_mfma_f32_16x16x32_bf16 v[6:9], v[176:179], v[134:137], v[6:9]
	v_mfma_f32_16x16x32_bf16 v[10:13], v[180:183], v[134:137], v[10:13]
	v_mfma_f32_16x16x32_bf16 v[14:17], v[184:187], v[134:137], v[14:17]
	v_mfma_f32_16x16x32_bf16 v[18:21], v[172:175], v[142:145], v[18:21]
	v_mfma_f32_16x16x32_bf16 v[22:25], v[176:179], v[142:145], v[22:25]
	v_mfma_f32_16x16x32_bf16 v[30:33], v[180:183], v[142:145], v[30:33]
	v_mfma_f32_16x16x32_bf16 v[38:41], v[184:187], v[142:145], v[38:41]
	v_mfma_f32_16x16x32_bf16 v[46:49], v[172:175], v[146:149], v[46:49]
	v_mfma_f32_16x16x32_bf16 v[54:57], v[176:179], v[146:149], v[54:57]
	v_mfma_f32_16x16x32_bf16 v[62:65], v[180:183], v[146:149], v[62:65]
	v_mfma_f32_16x16x32_bf16 v[58:61], v[184:187], v[146:149], v[58:61]
	v_mfma_f32_16x16x32_bf16 v[50:53], v[172:175], v[150:153], v[50:53]
	v_mfma_f32_16x16x32_bf16 v[42:45], v[176:179], v[150:153], v[42:45]
	v_mfma_f32_16x16x32_bf16 v[34:37], v[180:183], v[150:153], v[34:37]
	v_mfma_f32_16x16x32_bf16 v[26:29], v[184:187], v[150:153], v[26:29]
	s_nop 0
	s_waitcnt vmcnt(0)
	s_add_u32 s6, s6, 0x80
	s_addc_u32 s7, s7, 0
	s_addk_i32 s8, 0x4000
	s_cmpk_eq_i32 s6, 0x780
	s_waitcnt vmcnt(0)
	s_barrier
	s_cbranch_scc0 .LBB0_709
	v_add_u32_e32 v0, v92, v94
	ds_read_b128 v[84:87], v0 offset:16384
	ds_read_b128 v[96:99], v0 offset:18432
	ds_read_b128 v[100:103], v0 offset:20480
	ds_read_b128 v[110:113], v0 offset:22528
	v_add_u32_e32 v0, v91, v94
	ds_read_b128 v[114:117], v0 offset:49152
	ds_read_b128 v[118:121], v0 offset:51200
	ds_read_b128 v[122:125], v0 offset:53248
	ds_read_b128 v[126:129], v0 offset:55296
	v_add_u32_e32 v0, v92, v93
	ds_read_b128 v[130:133], v0 offset:16384
	ds_read_b128 v[134:137], v0 offset:18432
	ds_read_b128 v[142:145], v0 offset:20480
	ds_read_b128 v[146:149], v0 offset:22528
	v_add_u32_e32 v0, v91, v93
	ds_read_b128 v[90:93], v0 offset:49152
	ds_read_b128 v[150:153], v0 offset:51200
	ds_read_b128 v[172:175], v0 offset:53248
	ds_read_b128 v[176:179], v0 offset:55296
	s_setprio 1
	s_waitcnt lgkmcnt(11)
	v_mfma_f32_16x16x32_bf16 v[2:5], v[114:117], v[84:87], v[2:5]
	s_waitcnt lgkmcnt(10)
	v_mfma_f32_16x16x32_bf16 v[6:9], v[118:121], v[84:87], v[6:9]
	s_waitcnt lgkmcnt(9)
	v_mfma_f32_16x16x32_bf16 v[10:13], v[122:125], v[84:87], v[10:13]
	s_waitcnt lgkmcnt(8)
	v_mfma_f32_16x16x32_bf16 v[14:17], v[126:129], v[84:87], v[14:17]
	v_mfma_f32_16x16x32_bf16 v[18:21], v[114:117], v[96:99], v[18:21]
	v_mfma_f32_16x16x32_bf16 v[22:25], v[118:121], v[96:99], v[22:25]
	v_mfma_f32_16x16x32_bf16 v[30:33], v[122:125], v[96:99], v[30:33]
	v_mfma_f32_16x16x32_bf16 v[84:87], v[126:129], v[96:99], v[38:41]
	v_mfma_f32_16x16x32_bf16 v[46:49], v[114:117], v[100:103], v[46:49]
	v_mfma_f32_16x16x32_bf16 v[54:57], v[118:121], v[100:103], v[54:57]
	v_mfma_f32_16x16x32_bf16 v[62:65], v[122:125], v[100:103], v[62:65]
	v_mfma_f32_16x16x32_bf16 v[58:61], v[126:129], v[100:103], v[58:61]
	v_mfma_f32_16x16x32_bf16 v[50:53], v[114:117], v[110:113], v[50:53]
	v_mfma_f32_16x16x32_bf16 v[94:97], v[118:121], v[110:113], v[42:45]
	v_mfma_f32_16x16x32_bf16 v[98:101], v[122:125], v[110:113], v[34:37]
	v_mfma_f32_16x16x32_bf16 v[110:113], v[126:129], v[110:113], v[26:29]
	s_waitcnt lgkmcnt(3)
	v_mfma_f32_16x16x32_bf16 v[114:117], v[90:93], v[130:133], v[2:5]
	s_waitcnt lgkmcnt(2)
	v_mfma_f32_16x16x32_bf16 v[118:121], v[150:153], v[130:133], v[6:9]
	s_waitcnt lgkmcnt(1)
	v_mfma_f32_16x16x32_bf16 v[122:125], v[172:175], v[130:133], v[10:13]
	s_waitcnt lgkmcnt(0)
	v_mfma_f32_16x16x32_bf16 v[126:129], v[176:179], v[130:133], v[14:17]
	v_mfma_f32_16x16x32_bf16 v[130:133], v[90:93], v[134:137], v[18:21]
	v_mfma_f32_16x16x32_bf16 v[42:45], v[150:153], v[134:137], v[22:25]
	v_mfma_f32_16x16x32_bf16 v[38:41], v[172:175], v[134:137], v[30:33]
	v_mfma_f32_16x16x32_bf16 v[34:37], v[176:179], v[134:137], v[84:87]
	v_mfma_f32_16x16x32_bf16 v[30:33], v[90:93], v[142:145], v[46:49]
	v_mfma_f32_16x16x32_bf16 v[26:29], v[150:153], v[142:145], v[54:57]
	v_mfma_f32_16x16x32_bf16 v[22:25], v[172:175], v[142:145], v[62:65]
	v_mfma_f32_16x16x32_bf16 v[18:21], v[176:179], v[142:145], v[58:61]
	v_mfma_f32_16x16x32_bf16 v[14:17], v[90:93], v[146:149], v[50:53]
	v_mfma_f32_16x16x32_bf16 v[10:13], v[150:153], v[146:149], v[94:97]
	v_mfma_f32_16x16x32_bf16 v[6:9], v[172:175], v[146:149], v[98:101]
	v_mfma_f32_16x16x32_bf16 v[2:5], v[176:179], v[146:149], v[110:113]
	s_setprio 0
	s_waitcnt vmcnt(0)
	s_barrier
; __device__ __forceinline__ float bf_lo(unsigned u) { return __uint_as_float(u << 16); }
; __device__ __forceinline__ float bf_hi(unsigned u) { return __uint_as_float(u & 0xffff0000u); }
; __device__ void phaseC1(const Params& p, int l, char* smem) {
;     ...
; #pragma unroll
;         for (int i = 0; i < 4; ++i) {
;             const size_t row = (size_t)(m0 + wr * 64 + i * 16 + r);
; #pragma unroll
;             for (int j = 0; j < 4; ++j) {
;                 const int col = n0 + wc * 64 + j * 16 + g4 * 4;
;                 const uint2 ga = *(const uint2*)(p.gab + row * 1024 + col);
;                 *(uint2*)(p.ub + row * 1024 + col) =
;                     make_uint2(pk2(acc[i][j][0] * bf_lo(ga.x), acc[i][j][1] * bf_hi(ga.x)),
;                                pk2(acc[i][j][2] * bf_lo(ga.y), acc[i][j][3] * bf_hi(ga.y)));
;             }
;         }
	global_load_dwordx2 v[228:229], v[68:69], off
	global_load_dwordx2 v[230:231], v[68:69], off offset:32
	global_load_dwordx2 v[232:233], v[68:69], off offset:64
	global_load_dwordx2 v[234:235], v[68:69], off offset:96
	v_readlane_b32 s36, v213, 4
	v_readlane_b32 s37, v213, 5
	v_readlane_b32 s38, v213, 6
	v_readlane_b32 s39, v213, 7
	v_readlane_b32 s40, v213, 8
	v_readlane_b32 s41, v213, 9
	v_readlane_b32 s42, v213, 10
	v_readlane_b32 s43, v213, 11
	v_readlane_b32 s44, v213, 12
	v_readlane_b32 s45, v213, 13
	v_readlane_b32 s46, v213, 14
	v_readlane_b32 s47, v213, 15
	v_readlane_b32 s48, v213, 16
	v_readlane_b32 s49, v213, 17
	v_readlane_b32 s50, v213, 18
	v_readlane_b32 s51, v213, 19
	s_waitcnt vmcnt(3)
	v_lshlrev_b32_e32 v48, 16, v228
	v_and_b32_e32 v49, 0xffff0000, v228
	v_pk_mul_f32 v[48:49], v[114:115], v[48:49]
	s_nop 0
	v_cvt_pk_bf16_f32 v46, v48, v49
	v_lshlrev_b32_e32 v48, 16, v229
	v_and_b32_e32 v49, 0xffff0000, v229
	v_pk_mul_f32 v[48:49], v[116:117], v[48:49]
	s_nop 0
	v_cvt_pk_bf16_f32 v47, v48, v49
	v_lshl_add_u64 v[48:49], v[70:71], 1, s[36:37]
	v_lshl_add_u64 v[48:49], v[48:49], 0, v[66:67]
	global_store_dwordx2 v[48:49], v[46:47], off
	s_waitcnt vmcnt(3)
	v_lshlrev_b32_e32 v50, 16, v230
	v_and_b32_e32 v51, 0xffff0000, v230
	v_pk_mul_f32 v[50:51], v[118:119], v[50:51]
	s_nop 0
	v_cvt_pk_bf16_f32 v46, v50, v51
	v_lshlrev_b32_e32 v50, 16, v231
	v_and_b32_e32 v51, 0xffff0000, v231
	v_pk_mul_f32 v[50:51], v[120:121], v[50:51]
	s_nop 0
	v_cvt_pk_bf16_f32 v47, v50, v51
	global_store_dwordx2 v[48:49], v[46:47], off offset:32
	s_waitcnt vmcnt(3)
	v_lshlrev_b32_e32 v50, 16, v232
	v_and_b32_e32 v51, 0xffff0000, v232
	v_pk_mul_f32 v[50:51], v[122:123], v[50:51]
	s_nop 0
	v_cvt_pk_bf16_f32 v46, v50, v51
	v_lshlrev_b32_e32 v50, 16, v233
	v_and_b32_e32 v51, 0xffff0000, v233
	v_pk_mul_f32 v[50:51], v[124:125], v[50:51]
	s_nop 0
	v_cvt_pk_bf16_f32 v47, v50, v51
	global_store_dwordx2 v[48:49], v[46:47], off offset:64
	s_waitcnt vmcnt(3)
	v_lshlrev_b32_e32 v50, 16, v234
	v_and_b32_e32 v51, 0xffff0000, v234
	v_pk_mul_f32 v[50:51], v[126:127], v[50:51]
	s_nop 0
	v_cvt_pk_bf16_f32 v46, v50, v51
	v_lshlrev_b32_e32 v50, 16, v235
	v_and_b32_e32 v51, 0xffff0000, v235
	v_pk_mul_f32 v[50:51], v[128:129], v[50:51]
	s_nop 0
	v_cvt_pk_bf16_f32 v47, v50, v51
	global_store_dwordx2 v[48:49], v[46:47], off offset:96
	global_load_dwordx2 v[228:229], v[72:73], off
	global_load_dwordx2 v[230:231], v[72:73], off offset:32
	global_load_dwordx2 v[232:233], v[72:73], off offset:64
	global_load_dwordx2 v[234:235], v[72:73], off offset:96
	s_waitcnt vmcnt(3)
	v_lshlrev_b32_e32 v48, 16, v228
	v_and_b32_e32 v49, 0xffff0000, v228
	v_pk_mul_f32 v[48:49], v[130:131], v[48:49]
	s_nop 0
	v_cvt_pk_bf16_f32 v46, v48, v49
	v_lshlrev_b32_e32 v48, 16, v229
	v_and_b32_e32 v49, 0xffff0000, v229
	v_pk_mul_f32 v[48:49], v[132:133], v[48:49]
	s_nop 0
	v_cvt_pk_bf16_f32 v47, v48, v49
	v_lshl_add_u64 v[48:49], v[74:75], 1, s[36:37]
	v_lshl_add_u64 v[48:49], v[48:49], 0, v[66:67]
	global_store_dwordx2 v[48:49], v[46:47], off
	s_waitcnt vmcnt(3)
	v_lshlrev_b32_e32 v50, 16, v230
	v_and_b32_e32 v51, 0xffff0000, v230
	v_lshlrev_b32_e32 v46, 16, v231
	v_and_b32_e32 v47, 0xffff0000, v231
	v_pk_mul_f32 v[42:43], v[42:43], v[50:51]
	v_pk_mul_f32 v[44:45], v[44:45], v[46:47]
	v_cvt_pk_bf16_f32 v42, v42, v43
	v_cvt_pk_bf16_f32 v43, v44, v45
	global_store_dwordx2 v[48:49], v[42:43], off offset:32
	s_waitcnt vmcnt(3)
	v_lshlrev_b32_e32 v44, 16, v232
	v_and_b32_e32 v45, 0xffff0000, v232
	v_lshlrev_b32_e32 v42, 16, v233
	v_and_b32_e32 v43, 0xffff0000, v233
	v_pk_mul_f32 v[38:39], v[38:39], v[44:45]
	v_pk_mul_f32 v[40:41], v[40:41], v[42:43]
	v_cvt_pk_bf16_f32 v38, v38, v39
	v_cvt_pk_bf16_f32 v39, v40, v41
	global_store_dwordx2 v[48:49], v[38:39], off offset:64
	s_waitcnt vmcnt(3)
; __device__ __forceinline__ float bf_lo(unsigned u) { return __uint_as_float(u << 16); }
; __device__ __forceinline__ float bf_hi(unsigned u) { return __uint_as_float(u & 0xffff0000u); }
; __device__ void phaseC1(const Params& p, int l, char* smem) {
;     ...
; #pragma unroll
;         for (int i = 0; i < 4; ++i) {
;             const size_t row = (size_t)(m0 + wr * 64 + i * 16 + r);
; #pragma unroll
;             for (int j = 0; j < 4; ++j) {
;                 const int col = n0 + wc * 64 + j * 16 + g4 * 4;
;                 const uint2 ga = *(const uint2*)(p.gab + row * 1024 + col);
;                 *(uint2*)(p.ub + row * 1024 + col) =
;                     make_uint2(pk2(acc[i][j][0] * bf_lo(ga.x), acc[i][j][1] * bf_hi(ga.x)),
;                                pk2(acc[i][j][2] * bf_lo(ga.y), acc[i][j][3] * bf_hi(ga.y)));
;             }
;         }
	v_lshlrev_b32_e32 v40, 16, v234
	v_and_b32_e32 v41, 0xffff0000, v234
	v_lshlrev_b32_e32 v38, 16, v235
	v_and_b32_e32 v39, 0xffff0000, v235
	v_pk_mul_f32 v[34:35], v[34:35], v[40:41]
	v_pk_mul_f32 v[36:37], v[36:37], v[38:39]
	v_cvt_pk_bf16_f32 v34, v34, v35
	v_cvt_pk_bf16_f32 v35, v36, v37
	global_store_dwordx2 v[48:49], v[34:35], off offset:96
	global_load_dwordx2 v[228:229], v[76:77], off
	global_load_dwordx2 v[230:231], v[76:77], off offset:32
	global_load_dwordx2 v[232:233], v[76:77], off offset:64
	global_load_dwordx2 v[234:235], v[76:77], off offset:96
	s_waitcnt vmcnt(3)
	v_lshlrev_b32_e32 v36, 16, v228
	v_and_b32_e32 v37, 0xffff0000, v228
	v_lshlrev_b32_e32 v34, 16, v229
	v_and_b32_e32 v35, 0xffff0000, v229
	v_pk_mul_f32 v[30:31], v[30:31], v[36:37]
	v_pk_mul_f32 v[32:33], v[32:33], v[34:35]
	v_cvt_pk_bf16_f32 v30, v30, v31
	v_cvt_pk_bf16_f32 v31, v32, v33
	v_lshl_add_u64 v[32:33], v[78:79], 1, s[36:37]
	v_lshl_add_u64 v[32:33], v[32:33], 0, v[66:67]
	global_store_dwordx2 v[32:33], v[30:31], off
	s_waitcnt vmcnt(3)
	v_lshlrev_b32_e32 v34, 16, v230
	v_and_b32_e32 v35, 0xffff0000, v230
	v_lshlrev_b32_e32 v30, 16, v231
	v_and_b32_e32 v31, 0xffff0000, v231
	v_pk_mul_f32 v[26:27], v[26:27], v[34:35]
	v_pk_mul_f32 v[28:29], v[28:29], v[30:31]
	v_cvt_pk_bf16_f32 v26, v26, v27
	v_cvt_pk_bf16_f32 v27, v28, v29
	global_store_dwordx2 v[32:33], v[26:27], off offset:32
	s_waitcnt vmcnt(3)
	v_lshlrev_b32_e32 v28, 16, v232
	v_and_b32_e32 v29, 0xffff0000, v232
	v_lshlrev_b32_e32 v26, 16, v233
	v_and_b32_e32 v27, 0xffff0000, v233
	v_pk_mul_f32 v[22:23], v[22:23], v[28:29]
	v_pk_mul_f32 v[24:25], v[24:25], v[26:27]
	v_cvt_pk_bf16_f32 v22, v22, v23
	v_cvt_pk_bf16_f32 v23, v24, v25
	global_store_dwordx2 v[32:33], v[22:23], off offset:64
	s_waitcnt vmcnt(3)
	v_lshlrev_b32_e32 v24, 16, v234
	v_and_b32_e32 v25, 0xffff0000, v234
	v_lshlrev_b32_e32 v22, 16, v235
	v_and_b32_e32 v23, 0xffff0000, v235
	v_pk_mul_f32 v[18:19], v[18:19], v[24:25]
	v_pk_mul_f32 v[20:21], v[20:21], v[22:23]
	v_cvt_pk_bf16_f32 v18, v18, v19
	v_cvt_pk_bf16_f32 v19, v20, v21
	global_store_dwordx2 v[32:33], v[18:19], off offset:96
	global_load_dwordx2 v[228:229], v[80:81], off
	global_load_dwordx2 v[230:231], v[80:81], off offset:32
	global_load_dwordx2 v[232:233], v[80:81], off offset:64
	global_load_dwordx2 v[234:235], v[80:81], off offset:96
	s_waitcnt vmcnt(3)
	v_lshlrev_b32_e32 v20, 16, v228
	v_and_b32_e32 v21, 0xffff0000, v228
	v_lshlrev_b32_e32 v18, 16, v229
	v_and_b32_e32 v19, 0xffff0000, v229
	v_pk_mul_f32 v[14:15], v[14:15], v[20:21]
	v_pk_mul_f32 v[16:17], v[16:17], v[18:19]
	v_cvt_pk_bf16_f32 v14, v14, v15
	v_cvt_pk_bf16_f32 v15, v16, v17
	v_lshl_add_u64 v[16:17], v[82:83], 1, s[36:37]
	v_lshl_add_u64 v[16:17], v[16:17], 0, v[66:67]
	global_store_dwordx2 v[16:17], v[14:15], off
	v_readlane_b32 s36, v213, 38
	s_movk_i32 s37, 0x6ff
	s_waitcnt vmcnt(3)
	v_lshlrev_b32_e32 v18, 16, v230
	v_and_b32_e32 v19, 0xffff0000, v230
	v_lshlrev_b32_e32 v14, 16, v231
	v_and_b32_e32 v15, 0xffff0000, v231
	v_pk_mul_f32 v[10:11], v[10:11], v[18:19]
	v_pk_mul_f32 v[12:13], v[12:13], v[14:15]
	v_cvt_pk_bf16_f32 v10, v10, v11
	v_cvt_pk_bf16_f32 v11, v12, v13
	global_store_dwordx2 v[16:17], v[10:11], off offset:32
	s_waitcnt vmcnt(3)
	v_lshlrev_b32_e32 v12, 16, v232
	v_and_b32_e32 v13, 0xffff0000, v232
	v_lshlrev_b32_e32 v10, 16, v233
	v_and_b32_e32 v11, 0xffff0000, v233
	v_pk_mul_f32 v[6:7], v[6:7], v[12:13]
	v_pk_mul_f32 v[8:9], v[8:9], v[10:11]
	v_cvt_pk_bf16_f32 v6, v6, v7
	v_cvt_pk_bf16_f32 v7, v8, v9
	global_store_dwordx2 v[16:17], v[6:7], off offset:64
	s_waitcnt vmcnt(3)
	v_lshlrev_b32_e32 v8, 16, v234
	v_and_b32_e32 v9, 0xffff0000, v234
	v_lshlrev_b32_e32 v6, 16, v235
	v_and_b32_e32 v7, 0xffff0000, v235
	v_pk_mul_f32 v[2:3], v[2:3], v[8:9]
	v_pk_mul_f32 v[4:5], v[4:5], v[6:7]
	v_cvt_pk_bf16_f32 v2, v2, v3
	v_cvt_pk_bf16_f32 v3, v4, v5
	global_store_dwordx2 v[16:17], v[2:3], off offset:96
	s_branch .LBB0_698

; #define MFMA(a, b, c) __builtin_amdgcn_mfma_f32_16x16x32_bf16((a), (b), (c), 0, 0, 0)
; template <int AMODE>
; __device__ __forceinline__ void gemm_kloop(f32x4 (&acc)[4][4], const u16* __restrict__ A, int lda,
;                                            const u16* __restrict__ Bt, int ldb, int K, char* smem,
;                                            const float* __restrict__ ssq_rows) {
;     ...
;     for (int kt = 0; kt < nk; ++kt) {
;         const int buf = kt & 1;
;         if (kt + 1 < nk) GLOAD(kt + 1, buf ^ 1);
;         const char* ab = As + buf * 16384 + (wr * 64 + r) * 128;
;         const char* bb = Bs + buf * 16384 + (wc * 64 + r) * 128;
;         bf16x8 af[2][4], bfr[2][4];
; #pragma unroll
;         for (int ks = 0; ks < 2; ++ks) {
;             const int co = ((ks * 4 + g4) ^ (r & 7)) << 4;
; #pragma unroll
;             for (int i = 0; i < 4; ++i) af[ks][i] = ld_frag(ab + i * 2048 + co);
; #pragma unroll
;             for (int j = 0; j < 4; ++j) bfr[ks][j] = ld_frag(bb + j * 2048 + co);
;         }
;         __builtin_amdgcn_sched_barrier(0);
;         __builtin_amdgcn_s_setprio(1);
; #pragma unroll
;         for (int ks = 0; ks < 2; ++ks)
; #pragma unroll
;             for (int i = 0; i < 4; ++i)
; #pragma unroll
;                 for (int j = 0; j < 4; ++j) acc[i][j] = MFMA(bfr[ks][j], af[ks][i], acc[i][j]);
;         __builtin_amdgcn_s_setprio(0);
;         __builtin_amdgcn_sched_barrier(0);
;         if (kt + 1 < nk) LSTORE(buf ^ 1);
;         asm volatile("s_waitcnt vmcnt(0)" ::: "memory");
;         __syncthreads();
;     }
.LBB0_756:
	s_setprio 1
	s_and_b32 s7, s1, 0x4000
	s_xor_b32 s13, s7, 0x4000
	v_add_u32_e32 v0, s13, v70
	v_add_u32_e32 v86, 0x8000, v0
	v_lshl_add_u64 v[78:79], v[66:67], 0, s[8:9]
	v_readfirstlane_b32 s13, v86
	v_lshl_add_u64 v[80:81], v[78:79], 0, s[62:63]
	v_lshl_add_u64 v[82:83], v[68:69], 0, s[8:9]
	s_mov_b32 m0, s13
	v_readfirstlane_b32 s13, v0
	v_lshl_add_u64 v[84:85], v[82:83], 0, s[62:63]
	global_load_lds_dwordx4 v[80:81], off
	s_mov_b32 m0, s13
	v_lshl_add_u64 v[80:81], v[78:79], 0, s[68:69]
	global_load_lds_dwordx4 v[84:85], off
	v_add_u32_e32 v84, 0x9000, v0
	v_or_b32_e32 v102, s7, v71
	v_readfirstlane_b32 s13, v84
	v_add_u32_e32 v84, 0x1000, v0
	s_mov_b32 m0, s13
	v_readfirstlane_b32 s13, v84
	v_add_u32_e32 v84, 0xa000, v0
	global_load_lds_dwordx4 v[80:81], off
	v_lshl_add_u64 v[80:81], v[82:83], 0, s[68:69]
	s_mov_b32 m0, s13
	v_readfirstlane_b32 s13, v84
	v_add_u32_e32 v84, 0x2000, v0
	global_load_lds_dwordx4 v[80:81], off
	v_lshl_add_u64 v[80:81], v[78:79], 0, s[64:65]
	s_mov_b32 m0, s13
	v_readfirstlane_b32 s13, v84
	global_load_lds_dwordx4 v[80:81], off
	v_lshl_add_u64 v[80:81], v[82:83], 0, s[64:65]
	s_mov_b32 m0, s13
	v_lshl_add_u64 v[78:79], v[78:79], 0, s[66:67]
	global_load_lds_dwordx4 v[80:81], off
	v_add_u32_e32 v80, 0xb000, v0
	v_add_u32_e32 v0, 0x3000, v0
	v_readfirstlane_b32 s13, v80
	s_mov_b32 m0, s13
	v_readfirstlane_b32 s13, v0
	global_load_lds_dwordx4 v[78:79], off
	v_lshl_add_u64 v[78:79], v[82:83], 0, s[66:67]
	s_mov_b32 m0, s13
	v_add_u32_e32 v0, s7, v72
	global_load_lds_dwordx4 v[78:79], off
	v_add_u32_e32 v90, v0, v77
	v_add_u32_e32 v103, v102, v77
	v_add_u32_e32 v0, v0, v73
	ds_read_b128 v[78:81], v90
	ds_read_b128 v[82:85], v90 offset:2048
	ds_read_b128 v[86:89], v90 offset:4096
	ds_read_b128 v[90:93], v90 offset:6144
	ds_read_b128 v[94:97], v103 offset:32768
	ds_read_b128 v[98:101], v103 offset:34816
	ds_read_b128 v[110:113], v103 offset:36864
	ds_read_b128 v[114:117], v103 offset:38912
	ds_read_b128 v[118:121], v0
	ds_read_b128 v[122:125], v0 offset:2048
	ds_read_b128 v[126:129], v0 offset:4096
	ds_read_b128 v[130:133], v0 offset:6144
	v_add_u32_e32 v0, v102, v73
	ds_read_b128 v[134:137], v0 offset:32768
	ds_read_b128 v[142:145], v0 offset:34816
	ds_read_b128 v[146:149], v0 offset:36864
	ds_read_b128 v[150:153], v0 offset:38912
	s_setprio 0
	s_waitcnt lgkmcnt(0)
	v_mfma_f32_16x16x32_bf16 v[62:65], v[94:97], v[78:81], v[62:65]
	v_mfma_f32_16x16x32_bf16 v[58:61], v[98:101], v[78:81], v[58:61]
	v_mfma_f32_16x16x32_bf16 v[54:57], v[110:113], v[78:81], v[54:57]
	v_mfma_f32_16x16x32_bf16 v[50:53], v[114:117], v[78:81], v[50:53]
	v_mfma_f32_16x16x32_bf16 v[46:49], v[94:97], v[82:85], v[46:49]
	v_mfma_f32_16x16x32_bf16 v[42:45], v[98:101], v[82:85], v[42:45]
	v_mfma_f32_16x16x32_bf16 v[38:41], v[110:113], v[82:85], v[38:41]
	v_mfma_f32_16x16x32_bf16 v[34:37], v[114:117], v[82:85], v[34:37]
	v_mfma_f32_16x16x32_bf16 v[30:33], v[94:97], v[86:89], v[30:33]
	v_mfma_f32_16x16x32_bf16 v[26:29], v[98:101], v[86:89], v[26:29]
	v_mfma_f32_16x16x32_bf16 v[22:25], v[110:113], v[86:89], v[22:25]
	v_mfma_f32_16x16x32_bf16 v[18:21], v[114:117], v[86:89], v[18:21]
	v_mfma_f32_16x16x32_bf16 v[14:17], v[94:97], v[90:93], v[14:17]
	v_mfma_f32_16x16x32_bf16 v[10:13], v[98:101], v[90:93], v[10:13]
	v_mfma_f32_16x16x32_bf16 v[6:9], v[110:113], v[90:93], v[6:9]
	v_mfma_f32_16x16x32_bf16 v[2:5], v[114:117], v[90:93], v[2:5]
	v_mfma_f32_16x16x32_bf16 v[62:65], v[134:137], v[118:121], v[62:65]
	v_mfma_f32_16x16x32_bf16 v[58:61], v[142:145], v[118:121], v[58:61]
	v_mfma_f32_16x16x32_bf16 v[54:57], v[146:149], v[118:121], v[54:57]
	v_mfma_f32_16x16x32_bf16 v[50:53], v[150:153], v[118:121], v[50:53]
	v_mfma_f32_16x16x32_bf16 v[46:49], v[134:137], v[122:125], v[46:49]
	v_mfma_f32_16x16x32_bf16 v[42:45], v[142:145], v[122:125], v[42:45]
	v_mfma_f32_16x16x32_bf16 v[38:41], v[146:149], v[122:125], v[38:41]
	v_mfma_f32_16x16x32_bf16 v[34:37], v[150:153], v[122:125], v[34:37]
	v_mfma_f32_16x16x32_bf16 v[30:33], v[134:137], v[126:129], v[30:33]
	v_mfma_f32_16x16x32_bf16 v[26:29], v[142:145], v[126:129], v[26:29]
	v_mfma_f32_16x16x32_bf16 v[22:25], v[146:149], v[126:129], v[22:25]
	v_mfma_f32_16x16x32_bf16 v[18:21], v[150:153], v[126:129], v[18:21]
	v_mfma_f32_16x16x32_bf16 v[14:17], v[134:137], v[130:133], v[14:17]
	v_mfma_f32_16x16x32_bf16 v[10:13], v[142:145], v[130:133], v[10:13]
	v_mfma_f32_16x16x32_bf16 v[6:9], v[146:149], v[130:133], v[6:9]
	v_mfma_f32_16x16x32_bf16 v[2:5], v[150:153], v[130:133], v[2:5]
	s_nop 0
	s_waitcnt vmcnt(0)
	s_add_u32 s8, s8, 0x80
	s_addc_u32 s9, s9, 0
	s_addk_i32 s1, 0x4000
	s_cmpk_eq_i32 s8, 0x780
	s_waitcnt vmcnt(0)
	s_barrier
; #define MFMA(a, b, c) __builtin_amdgcn_mfma_f32_16x16x32_bf16((a), (b), (c), 0, 0, 0)
; template <int AMODE>
; __device__ __forceinline__ void gemm_kloop(f32x4 (&acc)[4][4], const u16* __restrict__ A, int lda,
;                                            const u16* __restrict__ Bt, int ldb, int K, char* smem,
;                                            const float* __restrict__ ssq_rows) {
;     ...
;         for (int ks = 0; ks < 2; ++ks)
; #pragma unroll
;             for (int i = 0; i < 4; ++i)
; #pragma unroll
;                 for (int j = 0; j < 4; ++j) acc[i][j] = MFMA(bfr[ks][j], af[ks][i], acc[i][j]);
;         __builtin_amdgcn_s_setprio(0);
;         __builtin_amdgcn_sched_barrier(0);
;         if (kt + 1 < nk) LSTORE(buf ^ 1);
;         asm volatile("s_waitcnt vmcnt(0)" ::: "memory");
;         __syncthreads();
;     }
; __device__ void phaseC2(const Params& p, int l, char* smem) {
;     ...
; #pragma unroll
;         for (int i = 0; i < 4; ++i) {
;             const size_t row = (size_t)(m0 + wr * 64 + i * 16 + r);
;             const float* xr;
;             if (l == 0) xr = (row < TP) ? (p.x_prompt + row * 1024) : (p.x_sample + (row - TP) * 1024);
;             else xr = p.out + O_Y + row * 1024;
	s_cbranch_scc0 .LBB0_756
	v_add_u32_e32 v0, v72, v77
	ds_read_b128 v[66:69], v0 offset:16384
	ds_read_b128 v[78:81], v0 offset:18432
	ds_read_b128 v[82:85], v0 offset:20480
	ds_read_b128 v[86:89], v0 offset:22528
	v_add_u32_e32 v0, v71, v77
	ds_read_b128 v[90:93], v0 offset:49152
	ds_read_b128 v[94:97], v0 offset:51200
	ds_read_b128 v[98:101], v0 offset:53248
	ds_read_b128 v[110:113], v0 offset:55296
	v_add_u32_e32 v0, v72, v73
	ds_read_b128 v[114:117], v0 offset:16384
	ds_read_b128 v[118:121], v0 offset:18432
	ds_read_b128 v[122:125], v0 offset:20480
	ds_read_b128 v[126:129], v0 offset:22528
	v_add_u32_e32 v0, v71, v73
	ds_read_b128 v[70:73], v0 offset:49152
	ds_read_b128 v[130:133], v0 offset:51200
	ds_read_b128 v[134:137], v0 offset:53248
	ds_read_b128 v[142:145], v0 offset:55296
	s_setprio 1
	s_waitcnt lgkmcnt(11)
	v_mfma_f32_16x16x32_bf16 v[62:65], v[90:93], v[66:69], v[62:65]
	s_waitcnt lgkmcnt(10)
	v_mfma_f32_16x16x32_bf16 v[58:61], v[94:97], v[66:69], v[58:61]
	s_waitcnt lgkmcnt(9)
	v_mfma_f32_16x16x32_bf16 v[54:57], v[98:101], v[66:69], v[54:57]
	s_waitcnt lgkmcnt(8)
	v_mfma_f32_16x16x32_bf16 v[50:53], v[110:113], v[66:69], v[50:53]
	v_mfma_f32_16x16x32_bf16 v[46:49], v[90:93], v[78:81], v[46:49]
	v_mfma_f32_16x16x32_bf16 v[42:45], v[94:97], v[78:81], v[42:45]
	v_mfma_f32_16x16x32_bf16 v[38:41], v[98:101], v[78:81], v[38:41]
	v_mfma_f32_16x16x32_bf16 v[34:37], v[110:113], v[78:81], v[34:37]
	v_mfma_f32_16x16x32_bf16 v[30:33], v[90:93], v[82:85], v[30:33]
	v_mfma_f32_16x16x32_bf16 v[26:29], v[94:97], v[82:85], v[26:29]
	v_mfma_f32_16x16x32_bf16 v[22:25], v[98:101], v[82:85], v[22:25]
	v_mfma_f32_16x16x32_bf16 v[18:21], v[110:113], v[82:85], v[18:21]
	v_mfma_f32_16x16x32_bf16 v[14:17], v[90:93], v[86:89], v[14:17]
	v_mfma_f32_16x16x32_bf16 v[10:13], v[94:97], v[86:89], v[10:13]
	v_mfma_f32_16x16x32_bf16 v[6:9], v[98:101], v[86:89], v[6:9]
	v_mfma_f32_16x16x32_bf16 v[2:5], v[110:113], v[86:89], v[2:5]
	s_waitcnt lgkmcnt(3)
	v_mfma_f32_16x16x32_bf16 v[62:65], v[70:73], v[114:117], v[62:65]
	s_waitcnt lgkmcnt(2)
	v_mfma_f32_16x16x32_bf16 v[58:61], v[130:133], v[114:117], v[58:61]
	s_waitcnt lgkmcnt(1)
	v_mfma_f32_16x16x32_bf16 v[54:57], v[134:137], v[114:117], v[54:57]
	s_waitcnt lgkmcnt(0)
	v_mfma_f32_16x16x32_bf16 v[50:53], v[142:145], v[114:117], v[50:53]
	v_mfma_f32_16x16x32_bf16 v[46:49], v[70:73], v[118:121], v[46:49]
	v_mfma_f32_16x16x32_bf16 v[42:45], v[130:133], v[118:121], v[42:45]
	v_mfma_f32_16x16x32_bf16 v[38:41], v[134:137], v[118:121], v[38:41]
	v_mfma_f32_16x16x32_bf16 v[34:37], v[142:145], v[118:121], v[34:37]
	v_mfma_f32_16x16x32_bf16 v[30:33], v[70:73], v[122:125], v[30:33]
	v_mfma_f32_16x16x32_bf16 v[26:29], v[130:133], v[122:125], v[26:29]
	v_mfma_f32_16x16x32_bf16 v[22:25], v[134:137], v[122:125], v[22:25]
	v_mfma_f32_16x16x32_bf16 v[18:21], v[142:145], v[122:125], v[18:21]
	v_mfma_f32_16x16x32_bf16 v[14:17], v[70:73], v[126:129], v[14:17]
	v_mfma_f32_16x16x32_bf16 v[10:13], v[130:133], v[126:129], v[10:13]
	v_mfma_f32_16x16x32_bf16 v[6:9], v[134:137], v[126:129], v[6:9]
	v_mfma_f32_16x16x32_bf16 v[2:5], v[142:145], v[126:129], v[2:5]
	s_setprio 0
	v_add_u32_e32 v0, s0, v75
	s_waitcnt vmcnt(0)
	v_or_b32_e32 v66, v0, v74
	v_ashrrev_i32_e32 v67, 31, v66
	v_readlane_b32 s80, v213, 44
	v_lshlrev_b64 v[70:71], 12, v[66:67]
	s_mov_b64 s[0:1], -1
	s_and_b64 vcc, exec, s[74:75]
	v_readlane_b32 s81, v213, 45
	v_readlane_b32 s82, v213, 46
	v_readlane_b32 s83, v213, 47
	v_readlane_b32 s84, v213, 48
	v_readlane_b32 s85, v213, 49
	v_readlane_b32 s86, v213, 50
	v_readlane_b32 s87, v213, 51
	v_readlane_b32 s88, v213, 52
	v_readlane_b32 s89, v213, 53
	v_readlane_b32 s90, v213, 54
	v_readlane_b32 s91, v213, 55
	v_readlane_b32 s92, v213, 56
	v_readlane_b32 s93, v213, 57
	s_barrier
	v_readlane_b32 s94, v213, 58
	v_readlane_b32 s95, v213, 59
	s_cbranch_vccz .LBB0_759
	v_readlane_b32 s16, v214, 0
	v_readlane_b32 s26, v214, 10
	v_readlane_b32 s27, v214, 11
	v_readlane_b32 s17, v214, 1
	v_readlane_b32 s18, v214, 2
	v_readlane_b32 s19, v214, 3
	v_readlane_b32 s20, v214, 4
	v_readlane_b32 s21, v214, 5
	v_readlane_b32 s22, v214, 6
	v_readlane_b32 s23, v214, 7
	v_readlane_b32 s24, v214, 8
	v_readlane_b32 s25, v214, 9
	v_readlane_b32 s28, v214, 12
	v_readlane_b32 s29, v214, 13
	v_readlane_b32 s30, v214, 14
	v_readlane_b32 s31, v214, 15
	v_lshl_add_u64 v[72:73], s[26:27], 0, v[70:71]
	s_mov_b64 s[0:1], 0
